# GEMM B-operand (weight tile) LDS-DMA loads marked sc1 to bypass L1 so the A tile shared by co-resident blocks stays L1-resident
# speedup vs baseline: 1.0064x; 1.0064x over previous
; __device__ __forceinline__ int ltid() { int t = (int)threadIdx.x; asm volatile("" : "+v"(t)); return t; }
; #define ISSUE(k0, bf) do { char* A_ = lw + (bf) * BUF; \
;     _Pragma("unroll") for (int i_ = 0; i_ < 4; ++i_) { glds16(al.ptr(lrow + 32 * i_, (k0) + cg), A_ + i_ * 4096); glds16(bl.ptr(lrow + 32 * i_, (k0) + cg), A_ + ABYTES + i_ * 4096); } \
;     if (HALO) { if (wid == 0) glds16(gh + (k0), A_ + 16384); } } while (0)
; template <bool HALO, class AL, class BL>
; __device__ __forceinline__ void gemm_core(f32x16 (&acc)[2][2], f32x16& hacc, const AL& al, const BL& bl, int K, char* lds,
;                                           const u16* halo0, const u16* halo1, int brow0, int brow1) {
;     ...
;   const int tid = ltid(), lane = tid & 63, wid = tid >> 6, wr = wid >> 1, r32 = lane & 31, hi = lane >> 5;
;   const int lrow = tid >> 3, cg = ((tid & 7) ^ ((lrow >> 1) & 7)) * 8;
;   const u16* gh = nullptr;
;   if (HALO) { const int c = ((lane & 7) ^ ((lane >> 4) & 7)) * 8; gh = ((lane < 8) ? halo0 : halo1) + c; }
;   char* lw = lds + tid * 16;
;     ...
;   const int sa = ((wr * 64 + r32) >> 1) & 7, sb0 = ((brow0 + r32) >> 1) & 7, sb1 = ((brow1 + r32) >> 1) & 7, sh = (r32 >> 1) & 7;
;   const int oa = (wr * 64 + r32) * 128, ob0 = ABYTES + (brow0 + r32) * 128, ob1 = ABYTES + (brow1 + r32) * 128, oh = (128 + r32) * 128;
;   __syncthreads();
;   ISSUE(0, 0);
;   const int nk = K >> 6;
;   for (int kt = 0; kt < nk; ++kt) {
;     asm volatile("s_waitcnt vmcnt(0)" ::: "memory");
;     __syncthreads();
;     if (kt + 1 < nk) ISSUE((kt + 1) * 64, (kt + 1) & 1);
; __device__ __forceinline__ bool tile_at(int it, int nM, int nN, int& tm, int& tn) {
;   const int total = nM * nN, per = (total + 7) / 8, x = blockIdx.x & 7, lb = blockIdx.x >> 3, nlb = gridDim.x >> 3;
;   const int i = lb + it * nlb; if (i >= per) return false;
;   const int idx = x * per + i; if (idx >= total) return false;
;   const int grp = idx / (8 * nN), rem = idx - grp * 8 * nN;
;   tm = grp * 8 + (rem & 7); tn = rem >> 3; return true;
.LBB0_155:
	v_readlane_b32 vcc_lo, v253, 21
	s_or_b32 s3, s80, vcc_lo
	s_lshr_b32 s6, s3, 3
	s_and_b32 s6, s6, 0xf8
	s_lshl_b32 s7, s6, 3
	s_and_b32 s81, s80, 7
	s_sub_i32 s3, s3, s7
	s_or_b32 s85, s6, s81
	s_ashr_i32 s62, s3, 3
	s_lshl_b32 s3, s85, 18
	s_add_u32 s18, s40, s3
	v_mov_b32_e32 v1, v229
	s_waitcnt vmcnt(6)
	v_mov_b32_e32 v6, v229
	s_addc_u32 s19, s41, 0
	s_ashr_i32 s63, s62, 31
	s_lshl_b64 s[6:7], s[62:63], 18
	v_and_b32_e32 v7, 31, v6
	v_ashrrev_i32_e32 v0, 3, v6
	v_lshrrev_b32_e32 v2, 4, v6
	v_readlane_b32 s3, v255, 19
	v_xor_b32_e32 v4, v2, v6
	s_waitcnt vmcnt(5)
	v_and_or_b32 v10, v1, 64, v7
	v_ashrrev_i32_e32 v1, 31, v0
	s_add_u32 s64, s3, s6
	v_readlane_b32 s3, v255, 20
	v_lshlrev_b64 v[0:1], 11, v[0:1]
	v_lshlrev_b32_e32 v4, 4, v4
	s_addc_u32 s65, s3, s7
	v_lshl_add_u32 v96, v6, 4, 0
	v_lshl_add_u64 v[2:3], s[18:19], 0, v[0:1]
	v_and_b32_e32 v200, 0x70, v4
	v_add_u32_e32 v101, 0x4000, v96
	s_waitcnt vmcnt(0)
	v_lshl_add_u64 v[66:67], v[2:3], 0, v[200:201]
	v_readfirstlane_b32 s83, v96
	v_lshl_add_u64 v[2:3], s[64:65], 0, v[0:1]
	s_mov_b64 s[6:7], 0x10000
	s_mov_b32 m0, s83
	v_lshl_add_u64 v[64:65], v[2:3], 0, v[200:201]
	v_readfirstlane_b32 s42, v101
	v_lshl_add_u64 v[2:3], v[0:1], 0, s[6:7]
	v_add_u32_e32 v102, 0x1000, v96
	s_barrier
	global_load_lds_dwordx4 v[66:67], off
	s_mov_b32 m0, s42
	v_lshl_add_u64 v[4:5], s[18:19], 0, v[2:3]
	v_readfirstlane_b32 s43, v102
	v_lshl_add_u64 v[2:3], s[64:65], 0, v[2:3]
	v_add_u32_e32 v103, 0x5000, v96
	s_mov_b64 s[6:7], 0x20000
	global_load_lds_dwordx4 v[64:65], off sc1
	v_lshl_add_u64 v[70:71], v[4:5], 0, v[200:201]
	s_mov_b32 m0, s43
	v_lshl_add_u64 v[68:69], v[2:3], 0, v[200:201]
	v_readfirstlane_b32 s70, v103
	v_lshl_add_u64 v[2:3], v[0:1], 0, s[6:7]
	v_add_u32_e32 v88, 0x2000, v96
	s_mov_b64 s[72:73], 0x30000
	global_load_lds_dwordx4 v[70:71], off
	s_mov_b32 m0, s70
	v_lshl_add_u64 v[4:5], s[18:19], 0, v[2:3]
	v_readfirstlane_b32 s3, v88
	v_lshl_add_u64 v[2:3], s[64:65], 0, v[2:3]
	v_add_u32_e32 v89, 0x6000, v96
	v_lshl_add_u64 v[0:1], v[0:1], 0, s[72:73]
	v_lshrrev_b32_e32 v8, 5, v6
	v_bfe_u32 v11, v6, 1, 3
	global_load_lds_dwordx4 v[68:69], off sc1
	v_lshl_add_u64 v[74:75], v[4:5], 0, v[200:201]
	s_mov_b32 m0, s3
	v_lshl_add_u64 v[72:73], v[2:3], 0, v[200:201]
	v_readfirstlane_b32 s6, v89
	v_lshl_add_u64 v[2:3], s[18:19], 0, v[0:1]
	v_add_u32_e32 v90, 0x3000, v96
	v_lshl_add_u64 v[0:1], s[64:65], 0, v[0:1]
	global_load_lds_dwordx4 v[74:75], off
	s_mov_b32 m0, s6
	v_readfirstlane_b32 s7, v90
	v_lshl_add_u64 v[76:77], v[0:1], 0, v[200:201]
	v_add_u32_e32 v91, 0x7000, v96
	v_bfe_u32 v0, v6, 5, 1
	v_bitop3_b32 v1, v8, v11, 1 bitop3:0x6c
	global_load_lds_dwordx4 v[72:73], off sc1
	v_lshl_add_u64 v[78:79], v[2:3], 0, v[200:201]
	s_mov_b32 m0, s7
	v_readfirstlane_b32 s8, v91
	v_lshlrev_b32_e32 v8, 4, v1
	v_bitop3_b32 v1, v0, v11, 2 bitop3:0x36
	v_add_u32_e32 v93, 0x8000, v96
	global_load_lds_dwordx4 v[78:79], off
	s_mov_b32 m0, s8
	v_lshlrev_b32_e32 v81, 4, v1
	v_bitop3_b32 v1, v0, v11, 4 bitop3:0x36
	v_bitop3_b32 v0, v0, v11, 6 bitop3:0x36
	v_add_u32_e32 v92, 0xc000, v96
	v_readfirstlane_b32 s18, v93
	global_load_lds_dwordx4 v[76:77], off sc1
	v_lshlrev_b32_e32 v84, 4, v1
	v_lshlrev_b32_e32 v120, 4, v0
	v_lshl_add_u64 v[0:1], v[66:67], 0, s[78:79]
	s_mov_b32 m0, s18
	v_readfirstlane_b32 s19, v92
	v_add_u32_e32 v94, 0x9000, v96
	s_waitcnt vmcnt(0)
	s_waitcnt vmcnt(0) lgkmcnt(0)
	s_barrier
	global_load_lds_dwordx4 v[0:1], off
	v_lshl_add_u64 v[0:1], v[64:65], 0, s[78:79]
	s_mov_b32 m0, s19
	v_readfirstlane_b32 s33, v94
	v_add_u32_e32 v95, 0xd000, v96
	global_load_lds_dwordx4 v[0:1], off sc1
	v_lshl_add_u64 v[0:1], v[70:71], 0, s[78:79]
	s_mov_b32 m0, s33
	v_readfirstlane_b32 s72, v95
	v_add_u32_e32 v97, 0xa000, v96
	global_load_lds_dwordx4 v[0:1], off
	v_lshl_add_u64 v[0:1], v[68:69], 0, s[78:79]
	s_mov_b32 m0, s72
	v_readfirstlane_b32 s73, v97
	v_add_u32_e32 v98, 0xe000, v96
	global_load_lds_dwordx4 v[0:1], off sc1
	v_lshl_add_u64 v[0:1], v[74:75], 0, s[78:79]
	s_mov_b32 m0, s73
	v_readfirstlane_b32 s92, v98
	v_add_u32_e32 v99, 0xb000, v96
	v_lshrrev_b32_e32 v9, 1, v6
	s_mov_b32 s52, 0x1ffffc0
	global_load_lds_dwordx4 v[0:1], off
	v_lshl_add_u64 v[0:1], v[72:73], 0, s[78:79]
	s_mov_b32 m0, s92
	v_readfirstlane_b32 s69, v99
	v_add_u32_e32 v100, 0xf000, v96
	v_and_or_b32 v2, v9, s52, v7
	global_load_lds_dwordx4 v[0:1], off sc1
	v_lshl_add_u64 v[0:1], v[78:79], 0, s[78:79]
	s_mov_b32 m0, s69
	v_readfirstlane_b32 s82, v100
	global_load_lds_dwordx4 v[0:1], off
	v_lshl_add_u64 v[0:1], v[76:77], 0, s[78:79]
	s_mov_b32 m0, s82
	v_lshl_add_u32 v87, v2, 7, 0
	v_lshl_add_u32 v121, v10, 7, 0
	global_load_lds_dwordx4 v[0:1], off sc1
	v_add_u32_e32 v80, v87, v8
	v_add_u32_e32 v82, v121, v8
	ds_read_b128 v[0:3], v80
	ds_read_b128 v[4:7], v80 offset:4096
	ds_read_b128 v[8:11], v82 offset:16384
	ds_read_b128 v[12:15], v82 offset:20480
	s_waitcnt lgkmcnt(0)
	v_mfma_f32_32x32x16_bf16 v[48:63], v[0:3], v[8:11], 0
	v_add_u32_e32 v85, v87, v81
	v_add_u32_e32 v83, v121, v81
	ds_read_b128 v[104:107], v85
	ds_read_b128 v[108:111], v85 offset:4096
	ds_read_b128 v[112:115], v83 offset:16384
	ds_read_b128 v[116:119], v83 offset:20480
	v_add_u32_e32 v86, v87, v84
	v_add_u32_e32 v84, v121, v84
	v_add_u32_e32 v87, v87, v120
	v_mfma_f32_32x32x16_bf16 v[32:47], v[0:3], v[12:15], 0
	v_add_u32_e32 v81, v121, v120
	s_mov_b32 m0, s83
	v_readfirstlane_b32 s64, v88
	v_readfirstlane_b32 s65, v89
	v_lshl_add_u64 v[88:89], v[78:79], 0, s[88:89]
	s_mul_i32 s81, s81, 0xb0000
	s_mov_b32 s94, 0x1ffffc0
	v_mfma_f32_32x32x16_bf16 v[16:31], v[4:7], v[8:11], 0
	v_mfma_f32_32x32x16_bf16 v[0:15], v[4:7], v[12:15], 0
	s_waitcnt lgkmcnt(0)
	v_mfma_f32_32x32x16_bf16 v[48:63], v[104:107], v[112:115], v[48:63]
	v_mfma_f32_32x32x16_bf16 v[32:47], v[104:107], v[116:119], v[32:47]
	v_mfma_f32_32x32x16_bf16 v[16:31], v[108:111], v[112:115], v[16:31]
	v_mfma_f32_32x32x16_bf16 v[0:15], v[108:111], v[116:119], v[0:15]
	ds_read_b128 v[104:107], v86
	ds_read_b128 v[108:111], v86 offset:4096
	ds_read_b128 v[112:115], v84 offset:16384
	ds_read_b128 v[116:119], v84 offset:20480
	s_waitcnt lgkmcnt(0)
	v_mfma_f32_32x32x16_bf16 v[48:63], v[104:107], v[112:115], v[48:63]
	v_mfma_f32_32x32x16_bf16 v[32:47], v[104:107], v[116:119], v[32:47]
	v_mfma_f32_32x32x16_bf16 v[16:31], v[108:111], v[112:115], v[16:31]
	v_mfma_f32_32x32x16_bf16 v[0:15], v[108:111], v[116:119], v[0:15]
	ds_read_b128 v[104:107], v87
	ds_read_b128 v[108:111], v87 offset:4096
	ds_read_b128 v[112:115], v81 offset:16384
	ds_read_b128 v[116:119], v81 offset:20480
	s_waitcnt vmcnt(0)
	s_waitcnt vmcnt(0) lgkmcnt(0)
	s_barrier
; #define MFMA(a, b, c) __builtin_amdgcn_mfma_f32_32x32x16_bf16(a, b, c, 0, 0, 0)
; #define ISSUE(k0, bf) do { char* A_ = lw + (bf) * BUF; \
;     _Pragma("unroll") for (int i_ = 0; i_ < 4; ++i_) { glds16(al.ptr(lrow + 32 * i_, (k0) + cg), A_ + i_ * 4096); glds16(bl.ptr(lrow + 32 * i_, (k0) + cg), A_ + ABYTES + i_ * 4096); } \
;     if (HALO) { if (wid == 0) glds16(gh + (k0), A_ + 16384); } } while (0)
; template <bool HALO, class AL, class BL>
; __device__ __forceinline__ void gemm_core(f32x16 (&acc)[2][2], f32x16& hacc, const AL& al, const BL& bl, int K, char* lds,
;                                           const u16* halo0, const u16* halo1, int brow0, int brow1) {
;     ...
;   for (int kt = 0; kt < nk; ++kt) {
;     asm volatile("s_waitcnt vmcnt(0)" ::: "memory");
;     __syncthreads();
;     if (kt + 1 < nk) ISSUE((kt + 1) * 64, (kt + 1) & 1);
;     const char* T = lds + (kt & 1) * BUF;
; #pragma unroll
;     for (int kk = 0; kk < 4; ++kk) {
;       const int c = kk * 2 + hi;
;       bf16x8 a0 = *(const bf16x8*)(T + oa + ((c ^ sa) << 4));
;       bf16x8 a1 = *(const bf16x8*)(T + oa + 4096 + ((c ^ sa) << 4));
;       bf16x8 b0 = *(const bf16x8*)(T + ob0 + ((c ^ sb0) << 4));
;       bf16x8 b1 = *(const bf16x8*)(T + ob1 + ((c ^ sb1) << 4));
;       acc[0][0] = MFMA(a0, b0, acc[0][0]); acc[0][1] = MFMA(a0, b1, acc[0][1]);
;       acc[1][0] = MFMA(a1, b0, acc[1][0]); acc[1][1] = MFMA(a1, b1, acc[1][1]);
;       if (HALO) { bf16x8 ah = *(const bf16x8*)(T + oh + ((c ^ sh) << 4)); hacc = MFMA(ah, b0, hacc); }
;     }
	v_mfma_f32_32x32x16_bf16 v[48:63], v[104:107], v[112:115], v[48:63]
	v_mfma_f32_32x32x16_bf16 v[32:47], v[104:107], v[116:119], v[32:47]
	v_lshl_add_u64 v[104:105], v[66:67], 0, s[24:25]
	global_load_lds_dwordx4 v[104:105], off
	v_lshl_add_u64 v[104:105], v[64:65], 0, s[24:25]
	s_mov_b32 m0, s42
	s_nop 0
	global_load_lds_dwordx4 v[104:105], off sc1
	v_lshl_add_u64 v[104:105], v[70:71], 0, s[24:25]
	s_mov_b32 m0, s43
	v_mfma_f32_32x32x16_bf16 v[16:31], v[108:111], v[112:115], v[16:31]
	global_load_lds_dwordx4 v[104:105], off
	v_lshl_add_u64 v[104:105], v[68:69], 0, s[24:25]
	s_mov_b32 m0, s70
	s_nop 0
	global_load_lds_dwordx4 v[104:105], off sc1
	v_lshl_add_u64 v[104:105], v[74:75], 0, s[24:25]
	s_mov_b32 m0, s3
	v_mfma_f32_32x32x16_bf16 v[0:15], v[108:111], v[116:119], v[0:15]
	global_load_lds_dwordx4 v[104:105], off
	v_lshl_add_u64 v[104:105], v[72:73], 0, s[24:25]
	s_mov_b32 m0, s6
	s_nop 0
	global_load_lds_dwordx4 v[104:105], off sc1
	v_lshl_add_u64 v[104:105], v[78:79], 0, s[24:25]
	s_mov_b32 m0, s7
	s_nop 0
	global_load_lds_dwordx4 v[104:105], off
	v_lshl_add_u64 v[104:105], v[76:77], 0, s[24:25]
	s_mov_b32 m0, s8
	s_nop 0
	global_load_lds_dwordx4 v[104:105], off sc1
	ds_read_b128 v[104:107], v80 offset:32768
	ds_read_b128 v[108:111], v80 offset:36864
	ds_read_b128 v[112:115], v82 offset:49152
	ds_read_b128 v[116:119], v82 offset:53248
	s_waitcnt lgkmcnt(0)
	v_mfma_f32_32x32x16_bf16 v[48:63], v[104:107], v[112:115], v[48:63]
	s_mov_b32 m0, s18
	v_mfma_f32_32x32x16_bf16 v[32:47], v[104:107], v[116:119], v[32:47]
	v_mfma_f32_32x32x16_bf16 v[16:31], v[108:111], v[112:115], v[16:31]
	v_mfma_f32_32x32x16_bf16 v[0:15], v[108:111], v[116:119], v[0:15]
	ds_read_b128 v[104:107], v85 offset:32768
	ds_read_b128 v[108:111], v85 offset:36864
	ds_read_b128 v[112:115], v83 offset:49152
	ds_read_b128 v[116:119], v83 offset:53248
	s_waitcnt lgkmcnt(0)
	v_mfma_f32_32x32x16_bf16 v[48:63], v[104:107], v[112:115], v[48:63]
	v_mfma_f32_32x32x16_bf16 v[32:47], v[104:107], v[116:119], v[32:47]
	v_mfma_f32_32x32x16_bf16 v[16:31], v[108:111], v[112:115], v[16:31]
	v_mfma_f32_32x32x16_bf16 v[0:15], v[108:111], v[116:119], v[0:15]
	ds_read_b128 v[104:107], v86 offset:32768
	ds_read_b128 v[108:111], v86 offset:36864
	ds_read_b128 v[112:115], v84 offset:49152
	ds_read_b128 v[116:119], v84 offset:53248
	s_waitcnt lgkmcnt(0)
	v_mfma_f32_32x32x16_bf16 v[48:63], v[104:107], v[112:115], v[48:63]
	v_mfma_f32_32x32x16_bf16 v[32:47], v[104:107], v[116:119], v[32:47]
	v_mfma_f32_32x32x16_bf16 v[16:31], v[108:111], v[112:115], v[16:31]
	v_mfma_f32_32x32x16_bf16 v[0:15], v[108:111], v[116:119], v[0:15]
	ds_read_b128 v[104:107], v87 offset:32768
	ds_read_b128 v[108:111], v87 offset:36864
	ds_read_b128 v[112:115], v81 offset:49152
	ds_read_b128 v[116:119], v81 offset:53248
	s_waitcnt vmcnt(0)
	s_waitcnt vmcnt(0) lgkmcnt(0)
	s_barrier
	v_mfma_f32_32x32x16_bf16 v[48:63], v[104:107], v[112:115], v[48:63]
	v_mfma_f32_32x32x16_bf16 v[32:47], v[104:107], v[116:119], v[32:47]
	v_lshl_add_u64 v[104:105], v[66:67], 0, s[74:75]
	global_load_lds_dwordx4 v[104:105], off
	v_lshl_add_u64 v[104:105], v[64:65], 0, s[74:75]
	s_mov_b32 m0, s19
	s_nop 0
	global_load_lds_dwordx4 v[104:105], off sc1
	v_lshl_add_u64 v[104:105], v[70:71], 0, s[74:75]
	s_mov_b32 m0, s33
	v_mfma_f32_32x32x16_bf16 v[16:31], v[108:111], v[112:115], v[16:31]
	global_load_lds_dwordx4 v[104:105], off
	v_lshl_add_u64 v[104:105], v[68:69], 0, s[74:75]
	s_mov_b32 m0, s72
	s_nop 0
	global_load_lds_dwordx4 v[104:105], off sc1
	v_lshl_add_u64 v[104:105], v[74:75], 0, s[74:75]
	s_mov_b32 m0, s73
	v_mfma_f32_32x32x16_bf16 v[0:15], v[108:111], v[116:119], v[0:15]
	global_load_lds_dwordx4 v[104:105], off
	v_lshl_add_u64 v[104:105], v[72:73], 0, s[74:75]
	s_mov_b32 m0, s92
	s_nop 0
	global_load_lds_dwordx4 v[104:105], off sc1
	v_lshl_add_u64 v[104:105], v[78:79], 0, s[74:75]
	s_mov_b32 m0, s69
	s_nop 0
	global_load_lds_dwordx4 v[104:105], off
	v_lshl_add_u64 v[104:105], v[76:77], 0, s[74:75]
	s_mov_b32 m0, s82
	s_nop 0
	global_load_lds_dwordx4 v[104:105], off sc1
	ds_read_b128 v[104:107], v80
	ds_read_b128 v[108:111], v80 offset:4096
	ds_read_b128 v[112:115], v82 offset:16384
	ds_read_b128 v[116:119], v82 offset:20480
	s_waitcnt lgkmcnt(0)
	v_mfma_f32_32x32x16_bf16 v[48:63], v[104:107], v[112:115], v[48:63]
	s_mov_b32 m0, s83
	v_mfma_f32_32x32x16_bf16 v[32:47], v[104:107], v[116:119], v[32:47]
	v_mfma_f32_32x32x16_bf16 v[16:31], v[108:111], v[112:115], v[16:31]
	v_mfma_f32_32x32x16_bf16 v[0:15], v[108:111], v[116:119], v[0:15]
	ds_read_b128 v[104:107], v85
	ds_read_b128 v[108:111], v85 offset:4096
	ds_read_b128 v[112:115], v83 offset:16384
	ds_read_b128 v[116:119], v83 offset:20480
	s_waitcnt lgkmcnt(0)
	v_mfma_f32_32x32x16_bf16 v[48:63], v[104:107], v[112:115], v[48:63]
	v_mfma_f32_32x32x16_bf16 v[32:47], v[104:107], v[116:119], v[32:47]
	v_mfma_f32_32x32x16_bf16 v[16:31], v[108:111], v[112:115], v[16:31]
	v_mfma_f32_32x32x16_bf16 v[0:15], v[108:111], v[116:119], v[0:15]
	ds_read_b128 v[104:107], v86
	ds_read_b128 v[108:111], v86 offset:4096
	ds_read_b128 v[112:115], v84 offset:16384
	ds_read_b128 v[116:119], v84 offset:20480
	s_waitcnt lgkmcnt(0)
	v_mfma_f32_32x32x16_bf16 v[48:63], v[104:107], v[112:115], v[48:63]
	v_mfma_f32_32x32x16_bf16 v[32:47], v[104:107], v[116:119], v[32:47]
	v_mfma_f32_32x32x16_bf16 v[16:31], v[108:111], v[112:115], v[16:31]
	v_mfma_f32_32x32x16_bf16 v[0:15], v[108:111], v[116:119], v[0:15]
	ds_read_b128 v[104:107], v87
	ds_read_b128 v[108:111], v87 offset:4096
	ds_read_b128 v[112:115], v81 offset:16384
	ds_read_b128 v[116:119], v81 offset:20480
	s_waitcnt vmcnt(0)
	s_waitcnt vmcnt(0) lgkmcnt(0)
	s_barrier
; #define MFMA(a, b, c) __builtin_amdgcn_mfma_f32_32x32x16_bf16(a, b, c, 0, 0, 0)
; #define ISSUE(k0, bf) do { char* A_ = lw + (bf) * BUF; \
;     _Pragma("unroll") for (int i_ = 0; i_ < 4; ++i_) { glds16(al.ptr(lrow + 32 * i_, (k0) + cg), A_ + i_ * 4096); glds16(bl.ptr(lrow + 32 * i_, (k0) + cg), A_ + ABYTES + i_ * 4096); } \
;     if (HALO) { if (wid == 0) glds16(gh + (k0), A_ + 16384); } } while (0)
; template <bool HALO, class AL, class BL>
; __device__ __forceinline__ void gemm_core(f32x16 (&acc)[2][2], f32x16& hacc, const AL& al, const BL& bl, int K, char* lds,
;                                           const u16* halo0, const u16* halo1, int brow0, int brow1) {
;     ...
;   for (int kt = 0; kt < nk; ++kt) {
;     asm volatile("s_waitcnt vmcnt(0)" ::: "memory");
;     __syncthreads();
;     if (kt + 1 < nk) ISSUE((kt + 1) * 64, (kt + 1) & 1);
;     const char* T = lds + (kt & 1) * BUF;
; #pragma unroll
;     for (int kk = 0; kk < 4; ++kk) {
;       const int c = kk * 2 + hi;
;       bf16x8 a0 = *(const bf16x8*)(T + oa + ((c ^ sa) << 4));
;       bf16x8 a1 = *(const bf16x8*)(T + oa + 4096 + ((c ^ sa) << 4));
;       bf16x8 b0 = *(const bf16x8*)(T + ob0 + ((c ^ sb0) << 4));
;       bf16x8 b1 = *(const bf16x8*)(T + ob1 + ((c ^ sb1) << 4));
;       acc[0][0] = MFMA(a0, b0, acc[0][0]); acc[0][1] = MFMA(a0, b1, acc[0][1]);
;       acc[1][0] = MFMA(a1, b0, acc[1][0]); acc[1][1] = MFMA(a1, b1, acc[1][1]);
;       if (HALO) { bf16x8 ah = *(const bf16x8*)(T + oh + ((c ^ sh) << 4)); hacc = MFMA(ah, b0, hacc); }
;     }
	v_mfma_f32_32x32x16_bf16 v[48:63], v[104:107], v[112:115], v[48:63]
	v_mfma_f32_32x32x16_bf16 v[32:47], v[104:107], v[116:119], v[32:47]
	v_lshl_add_u64 v[104:105], v[66:67], 0, s[20:21]
	global_load_lds_dwordx4 v[104:105], off
	v_lshl_add_u64 v[104:105], v[64:65], 0, s[20:21]
	s_mov_b32 m0, s42
	s_nop 0
	global_load_lds_dwordx4 v[104:105], off sc1
	v_lshl_add_u64 v[104:105], v[70:71], 0, s[20:21]
	s_mov_b32 m0, s43
	v_mfma_f32_32x32x16_bf16 v[16:31], v[108:111], v[112:115], v[16:31]
	global_load_lds_dwordx4 v[104:105], off
	v_lshl_add_u64 v[104:105], v[68:69], 0, s[20:21]
	s_mov_b32 m0, s70
	s_nop 0
	global_load_lds_dwordx4 v[104:105], off sc1
	v_lshl_add_u64 v[104:105], v[74:75], 0, s[20:21]
	s_mov_b32 m0, s3
	v_mfma_f32_32x32x16_bf16 v[0:15], v[108:111], v[116:119], v[0:15]
	global_load_lds_dwordx4 v[104:105], off
	v_lshl_add_u64 v[104:105], v[72:73], 0, s[20:21]
	s_mov_b32 m0, s6
	s_nop 0
	global_load_lds_dwordx4 v[104:105], off sc1
	v_lshl_add_u64 v[104:105], v[78:79], 0, s[20:21]
	s_mov_b32 m0, s7
	s_nop 0
	global_load_lds_dwordx4 v[104:105], off
	v_lshl_add_u64 v[104:105], v[76:77], 0, s[20:21]
	s_mov_b32 m0, s8
	s_nop 0
	global_load_lds_dwordx4 v[104:105], off sc1
	ds_read_b128 v[104:107], v80 offset:32768
	ds_read_b128 v[108:111], v80 offset:36864
	ds_read_b128 v[112:115], v82 offset:49152
	ds_read_b128 v[116:119], v82 offset:53248
	s_waitcnt lgkmcnt(0)
	v_mfma_f32_32x32x16_bf16 v[48:63], v[104:107], v[112:115], v[48:63]
	s_mov_b32 m0, s18
	v_mfma_f32_32x32x16_bf16 v[32:47], v[104:107], v[116:119], v[32:47]
	v_mfma_f32_32x32x16_bf16 v[16:31], v[108:111], v[112:115], v[16:31]
	v_mfma_f32_32x32x16_bf16 v[0:15], v[108:111], v[116:119], v[0:15]
	ds_read_b128 v[104:107], v85 offset:32768
	ds_read_b128 v[108:111], v85 offset:36864
	ds_read_b128 v[112:115], v83 offset:49152
	ds_read_b128 v[116:119], v83 offset:53248
	s_waitcnt lgkmcnt(0)
	v_mfma_f32_32x32x16_bf16 v[48:63], v[104:107], v[112:115], v[48:63]
	v_mfma_f32_32x32x16_bf16 v[32:47], v[104:107], v[116:119], v[32:47]
	v_mfma_f32_32x32x16_bf16 v[16:31], v[108:111], v[112:115], v[16:31]
	v_mfma_f32_32x32x16_bf16 v[0:15], v[108:111], v[116:119], v[0:15]
	ds_read_b128 v[104:107], v86 offset:32768
	ds_read_b128 v[108:111], v86 offset:36864
	ds_read_b128 v[112:115], v84 offset:49152
	ds_read_b128 v[116:119], v84 offset:53248
	s_waitcnt lgkmcnt(0)
	v_mfma_f32_32x32x16_bf16 v[48:63], v[104:107], v[112:115], v[48:63]
	v_mfma_f32_32x32x16_bf16 v[32:47], v[104:107], v[116:119], v[32:47]
	v_mfma_f32_32x32x16_bf16 v[16:31], v[108:111], v[112:115], v[16:31]
	v_mfma_f32_32x32x16_bf16 v[0:15], v[108:111], v[116:119], v[0:15]
	ds_read_b128 v[104:107], v87 offset:32768
	ds_read_b128 v[108:111], v87 offset:36864
	ds_read_b128 v[112:115], v81 offset:49152
	ds_read_b128 v[116:119], v81 offset:53248
	s_waitcnt vmcnt(0)
	s_waitcnt vmcnt(0) lgkmcnt(0)
	s_barrier
	v_mfma_f32_32x32x16_bf16 v[48:63], v[104:107], v[112:115], v[48:63]
	v_mfma_f32_32x32x16_bf16 v[32:47], v[104:107], v[116:119], v[32:47]
	v_lshl_add_u64 v[104:105], v[66:67], 0, s[86:87]
	global_load_lds_dwordx4 v[104:105], off
	v_lshl_add_u64 v[104:105], v[64:65], 0, s[86:87]
	s_mov_b32 m0, s19
	s_nop 0
	global_load_lds_dwordx4 v[104:105], off sc1
	v_lshl_add_u64 v[104:105], v[70:71], 0, s[86:87]
	s_mov_b32 m0, s33
	v_mfma_f32_32x32x16_bf16 v[16:31], v[108:111], v[112:115], v[16:31]
	global_load_lds_dwordx4 v[104:105], off
	v_lshl_add_u64 v[104:105], v[68:69], 0, s[86:87]
	s_mov_b32 m0, s72
	s_nop 0
	global_load_lds_dwordx4 v[104:105], off sc1
	v_lshl_add_u64 v[104:105], v[74:75], 0, s[86:87]
	s_mov_b32 m0, s73
	v_mfma_f32_32x32x16_bf16 v[0:15], v[108:111], v[116:119], v[0:15]
	global_load_lds_dwordx4 v[104:105], off
	v_lshl_add_u64 v[104:105], v[72:73], 0, s[86:87]
	s_mov_b32 m0, s92
	s_nop 0
	global_load_lds_dwordx4 v[104:105], off sc1
	v_lshl_add_u64 v[104:105], v[78:79], 0, s[86:87]
	s_mov_b32 m0, s69
	s_nop 0
	global_load_lds_dwordx4 v[104:105], off
	v_lshl_add_u64 v[104:105], v[76:77], 0, s[86:87]
	s_mov_b32 m0, s82
	s_nop 0
	global_load_lds_dwordx4 v[104:105], off sc1
	ds_read_b128 v[104:107], v80
	ds_read_b128 v[108:111], v80 offset:4096
	ds_read_b128 v[112:115], v82 offset:16384
	ds_read_b128 v[116:119], v82 offset:20480
	s_waitcnt lgkmcnt(0)
	v_mfma_f32_32x32x16_bf16 v[48:63], v[104:107], v[112:115], v[48:63]
	s_mov_b32 m0, s83
	v_mfma_f32_32x32x16_bf16 v[32:47], v[104:107], v[116:119], v[32:47]
	v_mfma_f32_32x32x16_bf16 v[16:31], v[108:111], v[112:115], v[16:31]
	v_mfma_f32_32x32x16_bf16 v[0:15], v[108:111], v[116:119], v[0:15]
	ds_read_b128 v[104:107], v85
	ds_read_b128 v[108:111], v85 offset:4096
	ds_read_b128 v[112:115], v83 offset:16384
	ds_read_b128 v[116:119], v83 offset:20480
	s_waitcnt lgkmcnt(0)
	v_mfma_f32_32x32x16_bf16 v[48:63], v[104:107], v[112:115], v[48:63]
	v_mfma_f32_32x32x16_bf16 v[32:47], v[104:107], v[116:119], v[32:47]
	v_mfma_f32_32x32x16_bf16 v[16:31], v[108:111], v[112:115], v[16:31]
	v_mfma_f32_32x32x16_bf16 v[0:15], v[108:111], v[116:119], v[0:15]
	ds_read_b128 v[104:107], v86
	ds_read_b128 v[108:111], v86 offset:4096
	ds_read_b128 v[112:115], v84 offset:16384
	ds_read_b128 v[116:119], v84 offset:20480
	s_waitcnt lgkmcnt(0)
	v_mfma_f32_32x32x16_bf16 v[48:63], v[104:107], v[112:115], v[48:63]
	v_mfma_f32_32x32x16_bf16 v[32:47], v[104:107], v[116:119], v[32:47]
	v_mfma_f32_32x32x16_bf16 v[16:31], v[108:111], v[112:115], v[16:31]
	v_mfma_f32_32x32x16_bf16 v[0:15], v[108:111], v[116:119], v[0:15]
	ds_read_b128 v[104:107], v87
	ds_read_b128 v[108:111], v87 offset:4096
	ds_read_b128 v[112:115], v81 offset:16384
	ds_read_b128 v[116:119], v81 offset:20480
	s_waitcnt vmcnt(0)
	s_waitcnt vmcnt(0) lgkmcnt(0)
	s_barrier
; #define MFMA(a, b, c) __builtin_amdgcn_mfma_f32_32x32x16_bf16(a, b, c, 0, 0, 0)
; #define ISSUE(k0, bf) do { char* A_ = lw + (bf) * BUF; \
;     _Pragma("unroll") for (int i_ = 0; i_ < 4; ++i_) { glds16(al.ptr(lrow + 32 * i_, (k0) + cg), A_ + i_ * 4096); glds16(bl.ptr(lrow + 32 * i_, (k0) + cg), A_ + ABYTES + i_ * 4096); } \
;     if (HALO) { if (wid == 0) glds16(gh + (k0), A_ + 16384); } } while (0)
; template <bool HALO, class AL, class BL>
; __device__ __forceinline__ void gemm_core(f32x16 (&acc)[2][2], f32x16& hacc, const AL& al, const BL& bl, int K, char* lds,
;                                           const u16* halo0, const u16* halo1, int brow0, int brow1) {
;     ...
;   for (int kt = 0; kt < nk; ++kt) {
;     asm volatile("s_waitcnt vmcnt(0)" ::: "memory");
;     __syncthreads();
;     if (kt + 1 < nk) ISSUE((kt + 1) * 64, (kt + 1) & 1);
;     const char* T = lds + (kt & 1) * BUF;
; #pragma unroll
;     for (int kk = 0; kk < 4; ++kk) {
;       const int c = kk * 2 + hi;
;       bf16x8 a0 = *(const bf16x8*)(T + oa + ((c ^ sa) << 4));
;       bf16x8 a1 = *(const bf16x8*)(T + oa + 4096 + ((c ^ sa) << 4));
;       bf16x8 b0 = *(const bf16x8*)(T + ob0 + ((c ^ sb0) << 4));
;       bf16x8 b1 = *(const bf16x8*)(T + ob1 + ((c ^ sb1) << 4));
;       acc[0][0] = MFMA(a0, b0, acc[0][0]); acc[0][1] = MFMA(a0, b1, acc[0][1]);
;       acc[1][0] = MFMA(a1, b0, acc[1][0]); acc[1][1] = MFMA(a1, b1, acc[1][1]);
;       if (HALO) { bf16x8 ah = *(const bf16x8*)(T + oh + ((c ^ sh) << 4)); hacc = MFMA(ah, b0, hacc); }
;     }
	v_mfma_f32_32x32x16_bf16 v[48:63], v[104:107], v[112:115], v[48:63]
	v_mfma_f32_32x32x16_bf16 v[32:47], v[104:107], v[116:119], v[32:47]
	v_lshl_add_u64 v[104:105], v[66:67], 0, s[30:31]
	global_load_lds_dwordx4 v[104:105], off
	v_lshl_add_u64 v[104:105], v[64:65], 0, s[30:31]
	s_mov_b32 m0, s42
	v_readfirstlane_b32 s42, v90
	global_load_lds_dwordx4 v[104:105], off sc1
	v_lshl_add_u64 v[104:105], v[70:71], 0, s[30:31]
	s_mov_b32 m0, s43
	v_mfma_f32_32x32x16_bf16 v[16:31], v[108:111], v[112:115], v[16:31]
	global_load_lds_dwordx4 v[104:105], off
	v_lshl_add_u64 v[104:105], v[68:69], 0, s[30:31]
	s_mov_b32 m0, s70
	v_readfirstlane_b32 s43, v91
	global_load_lds_dwordx4 v[104:105], off sc1
	v_lshl_add_u64 v[104:105], v[74:75], 0, s[30:31]
	s_mov_b32 m0, s3
	v_mfma_f32_32x32x16_bf16 v[0:15], v[108:111], v[116:119], v[0:15]
	global_load_lds_dwordx4 v[104:105], off
	v_lshl_add_u64 v[104:105], v[72:73], 0, s[30:31]
	s_mov_b32 m0, s6
	s_nop 0
	global_load_lds_dwordx4 v[104:105], off sc1
	v_lshl_add_u64 v[104:105], v[78:79], 0, s[30:31]
	s_mov_b32 m0, s7
	s_nop 0
	global_load_lds_dwordx4 v[104:105], off
	v_lshl_add_u64 v[104:105], v[76:77], 0, s[30:31]
	s_mov_b32 m0, s8
	s_nop 0
	global_load_lds_dwordx4 v[104:105], off sc1
	ds_read_b128 v[104:107], v80 offset:32768
	ds_read_b128 v[108:111], v80 offset:36864
	ds_read_b128 v[112:115], v82 offset:49152
	ds_read_b128 v[116:119], v82 offset:53248
	s_waitcnt lgkmcnt(0)
	v_mfma_f32_32x32x16_bf16 v[48:63], v[104:107], v[112:115], v[48:63]
	s_mov_b32 m0, s18
	v_readfirstlane_b32 s18, v94
	v_mfma_f32_32x32x16_bf16 v[32:47], v[104:107], v[116:119], v[32:47]
	v_mfma_f32_32x32x16_bf16 v[16:31], v[108:111], v[112:115], v[16:31]
	v_mfma_f32_32x32x16_bf16 v[0:15], v[108:111], v[116:119], v[0:15]
	ds_read_b128 v[104:107], v85 offset:32768
	ds_read_b128 v[108:111], v85 offset:36864
	ds_read_b128 v[112:115], v83 offset:49152
	ds_read_b128 v[116:119], v83 offset:53248
	s_waitcnt lgkmcnt(0)
	v_mfma_f32_32x32x16_bf16 v[48:63], v[104:107], v[112:115], v[48:63]
	v_mfma_f32_32x32x16_bf16 v[32:47], v[104:107], v[116:119], v[32:47]
	v_mfma_f32_32x32x16_bf16 v[16:31], v[108:111], v[112:115], v[16:31]
	v_mfma_f32_32x32x16_bf16 v[0:15], v[108:111], v[116:119], v[0:15]
	ds_read_b128 v[104:107], v86 offset:32768
	ds_read_b128 v[108:111], v86 offset:36864
	ds_read_b128 v[112:115], v84 offset:49152
	ds_read_b128 v[116:119], v84 offset:53248
	s_waitcnt lgkmcnt(0)
	v_mfma_f32_32x32x16_bf16 v[48:63], v[104:107], v[112:115], v[48:63]
	v_mfma_f32_32x32x16_bf16 v[32:47], v[104:107], v[116:119], v[32:47]
	v_mfma_f32_32x32x16_bf16 v[16:31], v[108:111], v[112:115], v[16:31]
	v_mfma_f32_32x32x16_bf16 v[0:15], v[108:111], v[116:119], v[0:15]
	ds_read_b128 v[104:107], v87 offset:32768
	ds_read_b128 v[108:111], v87 offset:36864
	ds_read_b128 v[112:115], v81 offset:49152
	ds_read_b128 v[116:119], v81 offset:53248
	s_waitcnt vmcnt(0)
	s_waitcnt vmcnt(0) lgkmcnt(0)
	s_barrier
	v_mfma_f32_32x32x16_bf16 v[48:63], v[104:107], v[112:115], v[48:63]
	v_mfma_f32_32x32x16_bf16 v[32:47], v[104:107], v[116:119], v[32:47]
	v_lshl_add_u64 v[104:105], v[66:67], 0, s[4:5]
	global_load_lds_dwordx4 v[104:105], off
	v_lshl_add_u64 v[104:105], v[64:65], 0, s[4:5]
	s_mov_b32 m0, s19
	v_readfirstlane_b32 s19, v95
	global_load_lds_dwordx4 v[104:105], off sc1
	v_lshl_add_u64 v[104:105], v[70:71], 0, s[4:5]
	s_mov_b32 m0, s33
	v_mfma_f32_32x32x16_bf16 v[16:31], v[108:111], v[112:115], v[16:31]
	global_load_lds_dwordx4 v[104:105], off
	v_lshl_add_u64 v[104:105], v[68:69], 0, s[4:5]
	s_mov_b32 m0, s72
	v_readfirstlane_b32 s33, v93
	global_load_lds_dwordx4 v[104:105], off sc1
	v_lshl_add_u64 v[104:105], v[74:75], 0, s[4:5]
	s_mov_b32 m0, s73
	v_mfma_f32_32x32x16_bf16 v[0:15], v[108:111], v[116:119], v[0:15]
	global_load_lds_dwordx4 v[104:105], off
	v_lshl_add_u64 v[104:105], v[72:73], 0, s[4:5]
	s_mov_b32 m0, s92
	v_readfirstlane_b32 s92, v101
	global_load_lds_dwordx4 v[104:105], off sc1
	v_lshl_add_u64 v[104:105], v[78:79], 0, s[4:5]
	s_mov_b32 m0, s69
	v_readfirstlane_b32 s69, v102
	global_load_lds_dwordx4 v[104:105], off
	v_lshl_add_u64 v[104:105], v[76:77], 0, s[4:5]
	s_mov_b32 m0, s82
	v_readfirstlane_b32 s82, v96
	global_load_lds_dwordx4 v[104:105], off sc1
	ds_read_b128 v[104:107], v80
	ds_read_b128 v[108:111], v80 offset:4096
	ds_read_b128 v[112:115], v82 offset:16384
	ds_read_b128 v[116:119], v82 offset:20480
	s_waitcnt lgkmcnt(0)
	v_mfma_f32_32x32x16_bf16 v[48:63], v[104:107], v[112:115], v[48:63]
	s_mov_b32 m0, s82
	v_readfirstlane_b32 s73, v103
	v_lshl_add_u64 v[102:103], v[74:75], 0, s[66:67]
	v_readfirstlane_b32 s72, v92
	v_lshl_add_u64 v[92:93], v[70:71], 0, s[26:27]
	v_mfma_f32_32x32x16_bf16 v[32:47], v[104:107], v[116:119], v[32:47]
	v_mfma_f32_32x32x16_bf16 v[16:31], v[108:111], v[112:115], v[16:31]
	v_mfma_f32_32x32x16_bf16 v[0:15], v[108:111], v[116:119], v[0:15]
	ds_read_b128 v[104:107], v85
	ds_read_b128 v[108:111], v85 offset:4096
	ds_read_b128 v[112:115], v83 offset:16384
	ds_read_b128 v[116:119], v83 offset:20480
	s_waitcnt lgkmcnt(0)
	v_mfma_f32_32x32x16_bf16 v[48:63], v[104:107], v[112:115], v[48:63]
	v_mfma_f32_32x32x16_bf16 v[32:47], v[104:107], v[116:119], v[32:47]
	v_mfma_f32_32x32x16_bf16 v[16:31], v[108:111], v[112:115], v[16:31]
	v_mfma_f32_32x32x16_bf16 v[0:15], v[108:111], v[116:119], v[0:15]
	ds_read_b128 v[104:107], v86
	ds_read_b128 v[108:111], v86 offset:4096
	ds_read_b128 v[112:115], v84 offset:16384
	ds_read_b128 v[116:119], v84 offset:20480
	s_waitcnt lgkmcnt(0)
	v_mfma_f32_32x32x16_bf16 v[48:63], v[104:107], v[112:115], v[48:63]
	v_mfma_f32_32x32x16_bf16 v[32:47], v[104:107], v[116:119], v[32:47]
	v_mfma_f32_32x32x16_bf16 v[16:31], v[108:111], v[112:115], v[16:31]
	v_mfma_f32_32x32x16_bf16 v[0:15], v[108:111], v[116:119], v[0:15]
	ds_read_b128 v[104:107], v87
	ds_read_b128 v[108:111], v87 offset:4096
	ds_read_b128 v[112:115], v81 offset:16384
	ds_read_b128 v[116:119], v81 offset:20480
	s_waitcnt vmcnt(0)
	s_waitcnt vmcnt(0) lgkmcnt(0)
	s_barrier
; #define MFMA(a, b, c) __builtin_amdgcn_mfma_f32_32x32x16_bf16(a, b, c, 0, 0, 0)
; #define ISSUE(k0, bf) do { char* A_ = lw + (bf) * BUF; \
;     _Pragma("unroll") for (int i_ = 0; i_ < 4; ++i_) { glds16(al.ptr(lrow + 32 * i_, (k0) + cg), A_ + i_ * 4096); glds16(bl.ptr(lrow + 32 * i_, (k0) + cg), A_ + ABYTES + i_ * 4096); } \
;     if (HALO) { if (wid == 0) glds16(gh + (k0), A_ + 16384); } } while (0)
; template <bool HALO, class AL, class BL>
; __device__ __forceinline__ void gemm_core(f32x16 (&acc)[2][2], f32x16& hacc, const AL& al, const BL& bl, int K, char* lds,
;                                           const u16* halo0, const u16* halo1, int brow0, int brow1) {
;     ...
;   for (int kt = 0; kt < nk; ++kt) {
;     asm volatile("s_waitcnt vmcnt(0)" ::: "memory");
;     __syncthreads();
;     if (kt + 1 < nk) ISSUE((kt + 1) * 64, (kt + 1) & 1);
;     const char* T = lds + (kt & 1) * BUF;
; #pragma unroll
;     for (int kk = 0; kk < 4; ++kk) {
;       const int c = kk * 2 + hi;
;       bf16x8 a0 = *(const bf16x8*)(T + oa + ((c ^ sa) << 4));
;       bf16x8 a1 = *(const bf16x8*)(T + oa + 4096 + ((c ^ sa) << 4));
;       bf16x8 b0 = *(const bf16x8*)(T + ob0 + ((c ^ sb0) << 4));
;       bf16x8 b1 = *(const bf16x8*)(T + ob1 + ((c ^ sb1) << 4));
;       acc[0][0] = MFMA(a0, b0, acc[0][0]); acc[0][1] = MFMA(a0, b1, acc[0][1]);
;       acc[1][0] = MFMA(a1, b0, acc[1][0]); acc[1][1] = MFMA(a1, b1, acc[1][1]);
;       if (HALO) { bf16x8 ah = *(const bf16x8*)(T + oh + ((c ^ sh) << 4)); hacc = MFMA(ah, b0, hacc); }
;     }
	v_mfma_f32_32x32x16_bf16 v[48:63], v[104:107], v[112:115], v[48:63]
	v_mfma_f32_32x32x16_bf16 v[32:47], v[104:107], v[116:119], v[32:47]
	v_lshl_add_u64 v[104:105], v[66:67], 0, s[66:67]
	global_load_lds_dwordx4 v[104:105], off
	v_lshl_add_u64 v[104:105], v[64:65], 0, s[66:67]
	s_mov_b32 m0, s92
	s_nop 0
	global_load_lds_dwordx4 v[104:105], off sc1
	v_lshl_add_u64 v[104:105], v[70:71], 0, s[66:67]
	s_mov_b32 m0, s69
	v_mfma_f32_32x32x16_bf16 v[16:31], v[108:111], v[112:115], v[16:31]
	global_load_lds_dwordx4 v[104:105], off
	v_lshl_add_u64 v[104:105], v[68:69], 0, s[66:67]
	s_mov_b32 m0, s73
	s_nop 0
	global_load_lds_dwordx4 v[104:105], off sc1
	s_mov_b32 m0, s3
	v_mfma_f32_32x32x16_bf16 v[0:15], v[108:111], v[116:119], v[0:15]
	global_load_lds_dwordx4 v[102:103], off
	v_lshl_add_u64 v[102:103], v[72:73], 0, s[66:67]
	s_mov_b32 m0, s6
	v_readfirstlane_b32 s3, v99
	global_load_lds_dwordx4 v[102:103], off sc1
	v_lshl_add_u64 v[102:103], v[78:79], 0, s[66:67]
	s_mov_b32 m0, s7
	v_readfirstlane_b32 s7, v97
	global_load_lds_dwordx4 v[102:103], off
	v_lshl_add_u64 v[102:103], v[76:77], 0, s[66:67]
	s_mov_b32 m0, s8
	v_readfirstlane_b32 s8, v98
	global_load_lds_dwordx4 v[102:103], off sc1
	ds_read_b128 v[102:105], v80 offset:32768
	ds_read_b128 v[106:109], v80 offset:36864
	ds_read_b128 v[110:113], v82 offset:49152
	ds_read_b128 v[114:117], v82 offset:53248
	s_waitcnt lgkmcnt(0)
	v_mfma_f32_32x32x16_bf16 v[48:63], v[102:105], v[110:113], v[48:63]
	s_mov_b32 m0, s33
	v_readfirstlane_b32 s6, v100
	v_mfma_f32_32x32x16_bf16 v[32:47], v[102:105], v[114:117], v[32:47]
	v_mfma_f32_32x32x16_bf16 v[16:31], v[106:109], v[110:113], v[16:31]
	v_mfma_f32_32x32x16_bf16 v[0:15], v[106:109], v[114:117], v[0:15]
	ds_read_b128 v[102:105], v85 offset:32768
	ds_read_b128 v[106:109], v85 offset:36864
	ds_read_b128 v[110:113], v83 offset:49152
	ds_read_b128 v[114:117], v83 offset:53248
	s_waitcnt lgkmcnt(0)
	v_mfma_f32_32x32x16_bf16 v[48:63], v[102:105], v[110:113], v[48:63]
	v_mfma_f32_32x32x16_bf16 v[32:47], v[102:105], v[114:117], v[32:47]
	v_mfma_f32_32x32x16_bf16 v[16:31], v[106:109], v[110:113], v[16:31]
	v_mfma_f32_32x32x16_bf16 v[0:15], v[106:109], v[114:117], v[0:15]
	ds_read_b128 v[102:105], v86 offset:32768
	ds_read_b128 v[106:109], v86 offset:36864
	ds_read_b128 v[110:113], v84 offset:49152
	ds_read_b128 v[114:117], v84 offset:53248
	s_waitcnt lgkmcnt(0)
	v_mfma_f32_32x32x16_bf16 v[48:63], v[102:105], v[110:113], v[48:63]
	v_mfma_f32_32x32x16_bf16 v[32:47], v[102:105], v[114:117], v[32:47]
	v_mfma_f32_32x32x16_bf16 v[16:31], v[106:109], v[110:113], v[16:31]
	v_mfma_f32_32x32x16_bf16 v[0:15], v[106:109], v[114:117], v[0:15]
	ds_read_b128 v[102:105], v87 offset:32768
	ds_read_b128 v[106:109], v87 offset:36864
	ds_read_b128 v[110:113], v81 offset:49152
	ds_read_b128 v[114:117], v81 offset:53248
	s_waitcnt vmcnt(0)
	s_waitcnt vmcnt(0) lgkmcnt(0)
	s_barrier
	v_mfma_f32_32x32x16_bf16 v[48:63], v[102:105], v[110:113], v[48:63]
	v_mfma_f32_32x32x16_bf16 v[32:47], v[102:105], v[114:117], v[32:47]
	v_lshl_add_u64 v[102:103], v[66:67], 0, s[26:27]
	global_load_lds_dwordx4 v[102:103], off
	v_lshl_add_u64 v[102:103], v[64:65], 0, s[26:27]
	s_mov_b32 m0, s72
	s_nop 0
	global_load_lds_dwordx4 v[102:103], off sc1
	s_mov_b32 m0, s18
	v_mfma_f32_32x32x16_bf16 v[16:31], v[106:109], v[110:113], v[16:31]
	global_load_lds_dwordx4 v[92:93], off
	v_lshl_add_u64 v[92:93], v[68:69], 0, s[26:27]
	s_mov_b32 m0, s19
	s_nop 0
	global_load_lds_dwordx4 v[92:93], off sc1
	v_lshl_add_u64 v[92:93], v[74:75], 0, s[26:27]
	s_mov_b32 m0, s7
	v_mfma_f32_32x32x16_bf16 v[0:15], v[106:109], v[114:117], v[0:15]
	global_load_lds_dwordx4 v[92:93], off
	v_lshl_add_u64 v[92:93], v[72:73], 0, s[26:27]
	s_mov_b32 m0, s8
	s_nop 0
	global_load_lds_dwordx4 v[92:93], off sc1
	v_lshl_add_u64 v[92:93], v[78:79], 0, s[26:27]
	s_mov_b32 m0, s3
	s_nop 0
	global_load_lds_dwordx4 v[92:93], off
	v_lshl_add_u64 v[92:93], v[76:77], 0, s[26:27]
	s_mov_b32 m0, s6
	s_nop 0
	global_load_lds_dwordx4 v[92:93], off sc1
	ds_read_b128 v[92:95], v80
	ds_read_b128 v[96:99], v80 offset:4096
	ds_read_b128 v[100:103], v82 offset:16384
	ds_read_b128 v[104:107], v82 offset:20480
	s_waitcnt lgkmcnt(0)
	v_mfma_f32_32x32x16_bf16 v[48:63], v[92:95], v[100:103], v[48:63]
	s_mov_b32 m0, s82
	v_mfma_f32_32x32x16_bf16 v[32:47], v[92:95], v[104:107], v[32:47]
	v_mfma_f32_32x32x16_bf16 v[16:31], v[96:99], v[100:103], v[16:31]
	v_mfma_f32_32x32x16_bf16 v[0:15], v[96:99], v[104:107], v[0:15]
	ds_read_b128 v[92:95], v85
	ds_read_b128 v[96:99], v85 offset:4096
	ds_read_b128 v[100:103], v83 offset:16384
	ds_read_b128 v[104:107], v83 offset:20480
	s_waitcnt lgkmcnt(0)
	v_mfma_f32_32x32x16_bf16 v[48:63], v[92:95], v[100:103], v[48:63]
	v_mfma_f32_32x32x16_bf16 v[32:47], v[92:95], v[104:107], v[32:47]
	v_mfma_f32_32x32x16_bf16 v[16:31], v[96:99], v[100:103], v[16:31]
	v_mfma_f32_32x32x16_bf16 v[0:15], v[96:99], v[104:107], v[0:15]
	ds_read_b128 v[92:95], v86
	ds_read_b128 v[96:99], v86 offset:4096
	ds_read_b128 v[100:103], v84 offset:16384
	ds_read_b128 v[104:107], v84 offset:20480
	s_waitcnt lgkmcnt(0)
	v_mfma_f32_32x32x16_bf16 v[48:63], v[92:95], v[100:103], v[48:63]
	v_mfma_f32_32x32x16_bf16 v[32:47], v[92:95], v[104:107], v[32:47]
	v_mfma_f32_32x32x16_bf16 v[16:31], v[96:99], v[100:103], v[16:31]
	v_mfma_f32_32x32x16_bf16 v[0:15], v[96:99], v[104:107], v[0:15]
	ds_read_b128 v[92:95], v87
	ds_read_b128 v[96:99], v87 offset:4096
	ds_read_b128 v[100:103], v81 offset:16384
	ds_read_b128 v[104:107], v81 offset:20480
	s_waitcnt vmcnt(0)
	s_waitcnt vmcnt(0) lgkmcnt(0)
	s_barrier
; #define MFMA(a, b, c) __builtin_amdgcn_mfma_f32_32x32x16_bf16(a, b, c, 0, 0, 0)
; #define ISSUE(k0, bf) do { char* A_ = lw + (bf) * BUF; \
;     _Pragma("unroll") for (int i_ = 0; i_ < 4; ++i_) { glds16(al.ptr(lrow + 32 * i_, (k0) + cg), A_ + i_ * 4096); glds16(bl.ptr(lrow + 32 * i_, (k0) + cg), A_ + ABYTES + i_ * 4096); } \
;     if (HALO) { if (wid == 0) glds16(gh + (k0), A_ + 16384); } } while (0)
; template <bool HALO, class AL, class BL>
; __device__ __forceinline__ void gemm_core(f32x16 (&acc)[2][2], f32x16& hacc, const AL& al, const BL& bl, int K, char* lds,
;                                           const u16* halo0, const u16* halo1, int brow0, int brow1) {
;     ...
;   for (int kt = 0; kt < nk; ++kt) {
;     asm volatile("s_waitcnt vmcnt(0)" ::: "memory");
;     __syncthreads();
;     if (kt + 1 < nk) ISSUE((kt + 1) * 64, (kt + 1) & 1);
;     const char* T = lds + (kt & 1) * BUF;
; #pragma unroll
;     for (int kk = 0; kk < 4; ++kk) {
;       const int c = kk * 2 + hi;
;       bf16x8 a0 = *(const bf16x8*)(T + oa + ((c ^ sa) << 4));
;       bf16x8 a1 = *(const bf16x8*)(T + oa + 4096 + ((c ^ sa) << 4));
;       bf16x8 b0 = *(const bf16x8*)(T + ob0 + ((c ^ sb0) << 4));
;       bf16x8 b1 = *(const bf16x8*)(T + ob1 + ((c ^ sb1) << 4));
;       acc[0][0] = MFMA(a0, b0, acc[0][0]); acc[0][1] = MFMA(a0, b1, acc[0][1]);
;       acc[1][0] = MFMA(a1, b0, acc[1][0]); acc[1][1] = MFMA(a1, b1, acc[1][1]);
;       if (HALO) { bf16x8 ah = *(const bf16x8*)(T + oh + ((c ^ sh) << 4)); hacc = MFMA(ah, b0, hacc); }
;     }
	v_mfma_f32_32x32x16_bf16 v[48:63], v[92:95], v[100:103], v[48:63]
	v_mfma_f32_32x32x16_bf16 v[32:47], v[92:95], v[104:107], v[32:47]
	v_lshl_add_u64 v[92:93], v[66:67], 0, s[88:89]
	global_load_lds_dwordx4 v[92:93], off
	v_lshl_add_u64 v[92:93], v[64:65], 0, s[88:89]
	s_mov_b32 m0, s92
	s_nop 0
	global_load_lds_dwordx4 v[92:93], off sc1
	v_lshl_add_u64 v[92:93], v[70:71], 0, s[88:89]
	s_mov_b32 m0, s69
	v_mfma_f32_32x32x16_bf16 v[16:31], v[96:99], v[100:103], v[16:31]
	global_load_lds_dwordx4 v[92:93], off
	v_lshl_add_u64 v[92:93], v[68:69], 0, s[88:89]
	s_mov_b32 m0, s73
	s_nop 0
	global_load_lds_dwordx4 v[92:93], off sc1
	v_lshl_add_u64 v[92:93], v[74:75], 0, s[88:89]
	s_mov_b32 m0, s64
	v_mfma_f32_32x32x16_bf16 v[0:15], v[96:99], v[104:107], v[0:15]
	global_load_lds_dwordx4 v[92:93], off
	v_lshl_add_u64 v[92:93], v[72:73], 0, s[88:89]
	s_mov_b32 m0, s65
	s_nop 0
	global_load_lds_dwordx4 v[92:93], off sc1
	s_mov_b32 m0, s42
	s_nop 0
	global_load_lds_dwordx4 v[88:89], off
	v_lshl_add_u64 v[88:89], v[76:77], 0, s[88:89]
	s_mov_b32 m0, s43
	s_nop 0
	global_load_lds_dwordx4 v[88:89], off sc1
	ds_read_b128 v[88:91], v80 offset:32768
	ds_read_b128 v[92:95], v80 offset:36864
	ds_read_b128 v[96:99], v82 offset:49152
	ds_read_b128 v[100:103], v82 offset:53248
	s_waitcnt lgkmcnt(0)
	v_mfma_f32_32x32x16_bf16 v[48:63], v[88:91], v[96:99], v[48:63]
	s_mov_b32 m0, s33
	v_mfma_f32_32x32x16_bf16 v[32:47], v[88:91], v[100:103], v[32:47]
	v_mfma_f32_32x32x16_bf16 v[16:31], v[92:95], v[96:99], v[16:31]
	v_mfma_f32_32x32x16_bf16 v[0:15], v[92:95], v[100:103], v[0:15]
	ds_read_b128 v[88:91], v85 offset:32768
	ds_read_b128 v[92:95], v85 offset:36864
	ds_read_b128 v[96:99], v83 offset:49152
	ds_read_b128 v[100:103], v83 offset:53248
	s_waitcnt lgkmcnt(0)
	v_mfma_f32_32x32x16_bf16 v[48:63], v[88:91], v[96:99], v[48:63]
	v_mfma_f32_32x32x16_bf16 v[32:47], v[88:91], v[100:103], v[32:47]
	v_mfma_f32_32x32x16_bf16 v[16:31], v[92:95], v[96:99], v[16:31]
	v_mfma_f32_32x32x16_bf16 v[0:15], v[92:95], v[100:103], v[0:15]
	ds_read_b128 v[88:91], v86 offset:32768
	ds_read_b128 v[92:95], v86 offset:36864
	ds_read_b128 v[96:99], v84 offset:49152
	ds_read_b128 v[100:103], v84 offset:53248
	s_waitcnt lgkmcnt(0)
	v_mfma_f32_32x32x16_bf16 v[48:63], v[88:91], v[96:99], v[48:63]
	v_mfma_f32_32x32x16_bf16 v[32:47], v[88:91], v[100:103], v[32:47]
	v_mfma_f32_32x32x16_bf16 v[16:31], v[92:95], v[96:99], v[16:31]
	v_mfma_f32_32x32x16_bf16 v[0:15], v[92:95], v[100:103], v[0:15]
	ds_read_b128 v[88:91], v87 offset:32768
	ds_read_b128 v[92:95], v87 offset:36864
	ds_read_b128 v[96:99], v81 offset:49152
	ds_read_b128 v[100:103], v81 offset:53248
	s_waitcnt vmcnt(0)
	s_waitcnt vmcnt(0) lgkmcnt(0)
	s_barrier
	v_mfma_f32_32x32x16_bf16 v[48:63], v[88:91], v[96:99], v[48:63]
	v_mfma_f32_32x32x16_bf16 v[32:47], v[88:91], v[100:103], v[32:47]
	v_lshl_add_u64 v[88:89], v[66:67], 0, s[22:23]
	global_load_lds_dwordx4 v[88:89], off
	v_lshl_add_u64 v[88:89], v[64:65], 0, s[22:23]
	s_mov_b32 m0, s72
	s_nop 0
	global_load_lds_dwordx4 v[88:89], off sc1
	v_lshl_add_u64 v[88:89], v[70:71], 0, s[22:23]
	s_mov_b32 m0, s18
	v_mfma_f32_32x32x16_bf16 v[16:31], v[92:95], v[96:99], v[16:31]
	global_load_lds_dwordx4 v[88:89], off
	v_lshl_add_u64 v[88:89], v[68:69], 0, s[22:23]
	s_mov_b32 m0, s19
	s_nop 0
	global_load_lds_dwordx4 v[88:89], off sc1
	v_lshl_add_u64 v[88:89], v[74:75], 0, s[22:23]
	s_mov_b32 m0, s7
	v_mfma_f32_32x32x16_bf16 v[0:15], v[92:95], v[100:103], v[0:15]
	global_load_lds_dwordx4 v[88:89], off
	v_lshl_add_u64 v[88:89], v[72:73], 0, s[22:23]
	s_mov_b32 m0, s8
	s_nop 0
	global_load_lds_dwordx4 v[88:89], off sc1
	v_lshl_add_u64 v[88:89], v[78:79], 0, s[22:23]
	s_mov_b32 m0, s3
	s_nop 0
	global_load_lds_dwordx4 v[88:89], off
	v_lshl_add_u64 v[88:89], v[76:77], 0, s[22:23]
	s_mov_b32 m0, s6
	s_nop 0
	global_load_lds_dwordx4 v[88:89], off sc1
	ds_read_b128 v[88:91], v80
	ds_read_b128 v[92:95], v80 offset:4096
	ds_read_b128 v[96:99], v82 offset:16384
	ds_read_b128 v[100:103], v82 offset:20480
	s_waitcnt lgkmcnt(0)
	v_mfma_f32_32x32x16_bf16 v[48:63], v[88:91], v[96:99], v[48:63]
	s_mov_b32 m0, s82
	v_mfma_f32_32x32x16_bf16 v[32:47], v[88:91], v[100:103], v[32:47]
	v_mfma_f32_32x32x16_bf16 v[16:31], v[92:95], v[96:99], v[16:31]
	v_mfma_f32_32x32x16_bf16 v[0:15], v[92:95], v[100:103], v[0:15]
	ds_read_b128 v[88:91], v85
	ds_read_b128 v[92:95], v85 offset:4096
	ds_read_b128 v[96:99], v83 offset:16384
	ds_read_b128 v[100:103], v83 offset:20480
	s_waitcnt lgkmcnt(0)
	v_mfma_f32_32x32x16_bf16 v[48:63], v[88:91], v[96:99], v[48:63]
	v_mfma_f32_32x32x16_bf16 v[32:47], v[88:91], v[100:103], v[32:47]
	v_mfma_f32_32x32x16_bf16 v[16:31], v[92:95], v[96:99], v[16:31]
	v_mfma_f32_32x32x16_bf16 v[0:15], v[92:95], v[100:103], v[0:15]
	ds_read_b128 v[88:91], v86
	ds_read_b128 v[92:95], v86 offset:4096
	ds_read_b128 v[96:99], v84 offset:16384
	ds_read_b128 v[100:103], v84 offset:20480
	s_waitcnt lgkmcnt(0)
	v_mfma_f32_32x32x16_bf16 v[48:63], v[88:91], v[96:99], v[48:63]
	v_mfma_f32_32x32x16_bf16 v[32:47], v[88:91], v[100:103], v[32:47]
	v_mfma_f32_32x32x16_bf16 v[16:31], v[92:95], v[96:99], v[16:31]
	v_mfma_f32_32x32x16_bf16 v[0:15], v[92:95], v[100:103], v[0:15]
	ds_read_b128 v[88:91], v87
	ds_read_b128 v[92:95], v87 offset:4096
	ds_read_b128 v[96:99], v81 offset:16384
	ds_read_b128 v[100:103], v81 offset:20480
	s_waitcnt vmcnt(0)
	s_waitcnt vmcnt(0) lgkmcnt(0)
	s_barrier
; #define MFMA(a, b, c) __builtin_amdgcn_mfma_f32_32x32x16_bf16(a, b, c, 0, 0, 0)
; #define ISSUE(k0, bf) do { char* A_ = lw + (bf) * BUF; \
;     _Pragma("unroll") for (int i_ = 0; i_ < 4; ++i_) { glds16(al.ptr(lrow + 32 * i_, (k0) + cg), A_ + i_ * 4096); glds16(bl.ptr(lrow + 32 * i_, (k0) + cg), A_ + ABYTES + i_ * 4096); } \
;     if (HALO) { if (wid == 0) glds16(gh + (k0), A_ + 16384); } } while (0)
; template <bool HALO, class AL, class BL>
; __device__ __forceinline__ void gemm_core(f32x16 (&acc)[2][2], f32x16& hacc, const AL& al, const BL& bl, int K, char* lds,
;                                           const u16* halo0, const u16* halo1, int brow0, int brow1) {
;     ...
;   for (int kt = 0; kt < nk; ++kt) {
;     asm volatile("s_waitcnt vmcnt(0)" ::: "memory");
;     __syncthreads();
;     if (kt + 1 < nk) ISSUE((kt + 1) * 64, (kt + 1) & 1);
;     const char* T = lds + (kt & 1) * BUF;
; #pragma unroll
;     for (int kk = 0; kk < 4; ++kk) {
;       const int c = kk * 2 + hi;
;       bf16x8 a0 = *(const bf16x8*)(T + oa + ((c ^ sa) << 4));
;       bf16x8 a1 = *(const bf16x8*)(T + oa + 4096 + ((c ^ sa) << 4));
;       bf16x8 b0 = *(const bf16x8*)(T + ob0 + ((c ^ sb0) << 4));
;       bf16x8 b1 = *(const bf16x8*)(T + ob1 + ((c ^ sb1) << 4));
;       acc[0][0] = MFMA(a0, b0, acc[0][0]); acc[0][1] = MFMA(a0, b1, acc[0][1]);
;       acc[1][0] = MFMA(a1, b0, acc[1][0]); acc[1][1] = MFMA(a1, b1, acc[1][1]);
;       if (HALO) { bf16x8 ah = *(const bf16x8*)(T + oh + ((c ^ sh) << 4)); hacc = MFMA(ah, b0, hacc); }
;     }
	v_mfma_f32_32x32x16_bf16 v[48:63], v[88:91], v[96:99], v[48:63]
	v_mfma_f32_32x32x16_bf16 v[32:47], v[88:91], v[100:103], v[32:47]
	v_lshl_add_u64 v[88:89], v[66:67], 0, s[90:91]
	global_load_lds_dwordx4 v[88:89], off
	v_lshl_add_u64 v[88:89], v[64:65], 0, s[90:91]
	s_mov_b32 m0, s92
	s_nop 0
	global_load_lds_dwordx4 v[88:89], off sc1
	v_lshl_add_u64 v[88:89], v[70:71], 0, s[90:91]
	s_mov_b32 m0, s69
	v_mfma_f32_32x32x16_bf16 v[16:31], v[92:95], v[96:99], v[16:31]
	global_load_lds_dwordx4 v[88:89], off
	v_lshl_add_u64 v[88:89], v[68:69], 0, s[90:91]
	s_mov_b32 m0, s73
	s_nop 0
	global_load_lds_dwordx4 v[88:89], off sc1
	v_lshl_add_u64 v[88:89], v[74:75], 0, s[90:91]
	s_mov_b32 m0, s64
	v_mfma_f32_32x32x16_bf16 v[0:15], v[92:95], v[100:103], v[0:15]
	global_load_lds_dwordx4 v[88:89], off
	v_lshl_add_u64 v[88:89], v[72:73], 0, s[90:91]
	s_mov_b32 m0, s65
	s_nop 0
	global_load_lds_dwordx4 v[88:89], off sc1
	v_lshl_add_u64 v[88:89], v[78:79], 0, s[90:91]
	s_mov_b32 m0, s42
	s_nop 0
	global_load_lds_dwordx4 v[88:89], off
	v_lshl_add_u64 v[88:89], v[76:77], 0, s[90:91]
	s_mov_b32 m0, s43
	s_nop 0
	global_load_lds_dwordx4 v[88:89], off sc1
	ds_read_b128 v[88:91], v80 offset:32768
	ds_read_b128 v[92:95], v80 offset:36864
	ds_read_b128 v[96:99], v82 offset:49152
	ds_read_b128 v[100:103], v82 offset:53248
	s_waitcnt lgkmcnt(0)
	v_mfma_f32_32x32x16_bf16 v[48:63], v[88:91], v[96:99], v[48:63]
	s_mov_b32 m0, s33
	v_mfma_f32_32x32x16_bf16 v[32:47], v[88:91], v[100:103], v[32:47]
	v_mfma_f32_32x32x16_bf16 v[16:31], v[92:95], v[96:99], v[16:31]
	v_mfma_f32_32x32x16_bf16 v[0:15], v[92:95], v[100:103], v[0:15]
	ds_read_b128 v[88:91], v85 offset:32768
	ds_read_b128 v[92:95], v85 offset:36864
	ds_read_b128 v[96:99], v83 offset:49152
	ds_read_b128 v[100:103], v83 offset:53248
	s_waitcnt lgkmcnt(0)
	v_mfma_f32_32x32x16_bf16 v[48:63], v[88:91], v[96:99], v[48:63]
	v_mfma_f32_32x32x16_bf16 v[32:47], v[88:91], v[100:103], v[32:47]
	v_mfma_f32_32x32x16_bf16 v[16:31], v[92:95], v[96:99], v[16:31]
	v_mfma_f32_32x32x16_bf16 v[0:15], v[92:95], v[100:103], v[0:15]
	ds_read_b128 v[88:91], v86 offset:32768
	ds_read_b128 v[92:95], v86 offset:36864
	ds_read_b128 v[96:99], v84 offset:49152
	ds_read_b128 v[100:103], v84 offset:53248
	s_waitcnt lgkmcnt(0)
	v_mfma_f32_32x32x16_bf16 v[48:63], v[88:91], v[96:99], v[48:63]
	v_mfma_f32_32x32x16_bf16 v[32:47], v[88:91], v[100:103], v[32:47]
	v_mfma_f32_32x32x16_bf16 v[16:31], v[92:95], v[96:99], v[16:31]
	v_mfma_f32_32x32x16_bf16 v[0:15], v[92:95], v[100:103], v[0:15]
	ds_read_b128 v[88:91], v87 offset:32768
	ds_read_b128 v[92:95], v87 offset:36864
	ds_read_b128 v[96:99], v81 offset:49152
	ds_read_b128 v[100:103], v81 offset:53248
	s_waitcnt vmcnt(0)
	s_waitcnt vmcnt(0) lgkmcnt(0)
	s_barrier
	v_mfma_f32_32x32x16_bf16 v[48:63], v[88:91], v[96:99], v[48:63]
	v_mfma_f32_32x32x16_bf16 v[32:47], v[88:91], v[100:103], v[32:47]
	v_lshl_add_u64 v[88:89], v[66:67], 0, s[0:1]
	global_load_lds_dwordx4 v[88:89], off
	v_lshl_add_u64 v[88:89], v[64:65], 0, s[0:1]
	s_mov_b32 m0, s72
	s_nop 0
	global_load_lds_dwordx4 v[88:89], off sc1
	v_lshl_add_u64 v[88:89], v[70:71], 0, s[0:1]
	s_mov_b32 m0, s18
	v_mfma_f32_32x32x16_bf16 v[16:31], v[92:95], v[96:99], v[16:31]
	global_load_lds_dwordx4 v[88:89], off
	v_lshl_add_u64 v[88:89], v[68:69], 0, s[0:1]
	s_mov_b32 m0, s19
	s_nop 0
	global_load_lds_dwordx4 v[88:89], off sc1
	v_lshl_add_u64 v[88:89], v[74:75], 0, s[0:1]
	s_mov_b32 m0, s7
	v_mfma_f32_32x32x16_bf16 v[0:15], v[92:95], v[100:103], v[0:15]
	global_load_lds_dwordx4 v[88:89], off
	v_lshl_add_u64 v[88:89], v[72:73], 0, s[0:1]
	s_mov_b32 m0, s8
	s_nop 0
	global_load_lds_dwordx4 v[88:89], off sc1
	v_lshl_add_u64 v[88:89], v[78:79], 0, s[0:1]
	s_mov_b32 m0, s3
	s_nop 0
	global_load_lds_dwordx4 v[88:89], off
	v_lshl_add_u64 v[88:89], v[76:77], 0, s[0:1]
	s_mov_b32 m0, s6
	s_nop 0
	global_load_lds_dwordx4 v[88:89], off sc1
	ds_read_b128 v[88:91], v80
	ds_read_b128 v[92:95], v80 offset:4096
	ds_read_b128 v[96:99], v82 offset:16384
	ds_read_b128 v[100:103], v82 offset:20480
	s_waitcnt lgkmcnt(0)
	v_mfma_f32_32x32x16_bf16 v[48:63], v[88:91], v[96:99], v[48:63]
	s_mov_b32 m0, s82
	v_mfma_f32_32x32x16_bf16 v[32:47], v[88:91], v[100:103], v[32:47]
	v_mfma_f32_32x32x16_bf16 v[16:31], v[92:95], v[96:99], v[16:31]
	v_mfma_f32_32x32x16_bf16 v[0:15], v[92:95], v[100:103], v[0:15]
	ds_read_b128 v[88:91], v85
	ds_read_b128 v[92:95], v85 offset:4096
	ds_read_b128 v[96:99], v83 offset:16384
	ds_read_b128 v[100:103], v83 offset:20480
	s_waitcnt lgkmcnt(0)
	v_mfma_f32_32x32x16_bf16 v[48:63], v[88:91], v[96:99], v[48:63]
	v_mfma_f32_32x32x16_bf16 v[32:47], v[88:91], v[100:103], v[32:47]
	v_mfma_f32_32x32x16_bf16 v[16:31], v[92:95], v[96:99], v[16:31]
	v_mfma_f32_32x32x16_bf16 v[0:15], v[92:95], v[100:103], v[0:15]
	ds_read_b128 v[88:91], v86
	ds_read_b128 v[92:95], v86 offset:4096
	ds_read_b128 v[96:99], v84 offset:16384
	ds_read_b128 v[100:103], v84 offset:20480
	s_waitcnt lgkmcnt(0)
	v_mfma_f32_32x32x16_bf16 v[48:63], v[88:91], v[96:99], v[48:63]
	v_mfma_f32_32x32x16_bf16 v[32:47], v[88:91], v[100:103], v[32:47]
	v_mfma_f32_32x32x16_bf16 v[16:31], v[92:95], v[96:99], v[16:31]
	v_mfma_f32_32x32x16_bf16 v[0:15], v[92:95], v[100:103], v[0:15]
	ds_read_b128 v[88:91], v87
	ds_read_b128 v[92:95], v87 offset:4096
	ds_read_b128 v[96:99], v81 offset:16384
	ds_read_b128 v[100:103], v81 offset:20480
	s_waitcnt vmcnt(0)
	s_waitcnt vmcnt(0) lgkmcnt(0)
	s_barrier
; #define MFMA(a, b, c) __builtin_amdgcn_mfma_f32_32x32x16_bf16(a, b, c, 0, 0, 0)
; #define ISSUE(k0, bf) do { char* A_ = lw + (bf) * BUF; \
;     _Pragma("unroll") for (int i_ = 0; i_ < 4; ++i_) { glds16(al.ptr(lrow + 32 * i_, (k0) + cg), A_ + i_ * 4096); glds16(bl.ptr(lrow + 32 * i_, (k0) + cg), A_ + ABYTES + i_ * 4096); } \
;     if (HALO) { if (wid == 0) glds16(gh + (k0), A_ + 16384); } } while (0)
; template <bool HALO, class AL, class BL>
; __device__ __forceinline__ void gemm_core(f32x16 (&acc)[2][2], f32x16& hacc, const AL& al, const BL& bl, int K, char* lds,
;                                           const u16* halo0, const u16* halo1, int brow0, int brow1) {
;     ...
;   for (int kt = 0; kt < nk; ++kt) {
;     asm volatile("s_waitcnt vmcnt(0)" ::: "memory");
;     __syncthreads();
;     if (kt + 1 < nk) ISSUE((kt + 1) * 64, (kt + 1) & 1);
;     const char* T = lds + (kt & 1) * BUF;
; #pragma unroll
;     for (int kk = 0; kk < 4; ++kk) {
;       const int c = kk * 2 + hi;
;       bf16x8 a0 = *(const bf16x8*)(T + oa + ((c ^ sa) << 4));
;       bf16x8 a1 = *(const bf16x8*)(T + oa + 4096 + ((c ^ sa) << 4));
;       bf16x8 b0 = *(const bf16x8*)(T + ob0 + ((c ^ sb0) << 4));
;       bf16x8 b1 = *(const bf16x8*)(T + ob1 + ((c ^ sb1) << 4));
;       acc[0][0] = MFMA(a0, b0, acc[0][0]); acc[0][1] = MFMA(a0, b1, acc[0][1]);
;       acc[1][0] = MFMA(a1, b0, acc[1][0]); acc[1][1] = MFMA(a1, b1, acc[1][1]);
;       if (HALO) { bf16x8 ah = *(const bf16x8*)(T + oh + ((c ^ sh) << 4)); hacc = MFMA(ah, b0, hacc); }
;     }
	v_mfma_f32_32x32x16_bf16 v[48:63], v[88:91], v[96:99], v[48:63]
	v_mfma_f32_32x32x16_bf16 v[32:47], v[88:91], v[100:103], v[32:47]
	v_lshl_add_u64 v[88:89], v[66:67], 0, s[34:35]
	global_load_lds_dwordx4 v[88:89], off
	v_lshl_add_u64 v[88:89], v[64:65], 0, s[34:35]
	s_mov_b32 m0, s92
	v_lshl_add_u64 v[66:67], v[66:67], 0, s[38:39]
	global_load_lds_dwordx4 v[88:89], off sc1
	v_lshl_add_u64 v[88:89], v[70:71], 0, s[34:35]
	s_mov_b32 m0, s69
	v_mfma_f32_32x32x16_bf16 v[0:15], v[92:95], v[100:103], v[0:15]
	global_load_lds_dwordx4 v[88:89], off
	v_lshl_add_u64 v[88:89], v[68:69], 0, s[34:35]
	s_mov_b32 m0, s73
	v_lshl_add_u64 v[64:65], v[64:65], 0, s[38:39]
	global_load_lds_dwordx4 v[88:89], off sc1
	v_lshl_add_u64 v[88:89], v[74:75], 0, s[34:35]
	s_mov_b32 m0, s64
	v_mfma_f32_32x32x16_bf16 v[16:31], v[92:95], v[96:99], v[16:31]
	global_load_lds_dwordx4 v[88:89], off
	v_lshl_add_u64 v[88:89], v[72:73], 0, s[34:35]
	s_mov_b32 m0, s65
	s_nop 0
	global_load_lds_dwordx4 v[88:89], off sc1
	v_lshl_add_u64 v[88:89], v[78:79], 0, s[34:35]
	s_mov_b32 m0, s42
	s_nop 0
	global_load_lds_dwordx4 v[88:89], off
	v_lshl_add_u64 v[88:89], v[76:77], 0, s[34:35]
	s_mov_b32 m0, s43
	s_nop 0
	global_load_lds_dwordx4 v[88:89], off sc1
	ds_read_b128 v[88:91], v80 offset:32768
	ds_read_b128 v[92:95], v80 offset:36864
	ds_read_b128 v[96:99], v82 offset:49152
	ds_read_b128 v[100:103], v82 offset:53248
	s_waitcnt lgkmcnt(0)
	v_mfma_f32_32x32x16_bf16 v[0:15], v[92:95], v[100:103], v[0:15]
	s_mov_b32 m0, s33
	v_mfma_f32_32x32x16_bf16 v[48:63], v[88:91], v[96:99], v[48:63]
	v_mfma_f32_32x32x16_bf16 v[32:47], v[88:91], v[100:103], v[32:47]
	v_mfma_f32_32x32x16_bf16 v[16:31], v[92:95], v[96:99], v[16:31]
	ds_read_b128 v[88:91], v85 offset:32768
	ds_read_b128 v[92:95], v85 offset:36864
	ds_read_b128 v[96:99], v83 offset:49152
	ds_read_b128 v[100:103], v83 offset:53248
	s_waitcnt lgkmcnt(0)
	v_mfma_f32_32x32x16_bf16 v[0:15], v[92:95], v[100:103], v[0:15]
	v_mfma_f32_32x32x16_bf16 v[48:63], v[88:91], v[96:99], v[48:63]
	v_mfma_f32_32x32x16_bf16 v[32:47], v[88:91], v[100:103], v[32:47]
	v_mfma_f32_32x32x16_bf16 v[16:31], v[92:95], v[96:99], v[16:31]
	ds_read_b128 v[88:91], v86 offset:32768
	ds_read_b128 v[92:95], v86 offset:36864
	ds_read_b128 v[96:99], v84 offset:49152
	ds_read_b128 v[100:103], v84 offset:53248
	s_waitcnt lgkmcnt(0)
	v_mfma_f32_32x32x16_bf16 v[0:15], v[92:95], v[100:103], v[0:15]
	v_mfma_f32_32x32x16_bf16 v[48:63], v[88:91], v[96:99], v[48:63]
	v_mfma_f32_32x32x16_bf16 v[32:47], v[88:91], v[100:103], v[32:47]
	v_mfma_f32_32x32x16_bf16 v[16:31], v[92:95], v[96:99], v[16:31]
	ds_read_b128 v[88:91], v87 offset:32768
	ds_read_b128 v[92:95], v87 offset:36864
	ds_read_b128 v[96:99], v81 offset:49152
	ds_read_b128 v[100:103], v81 offset:53248
	s_waitcnt vmcnt(0)
	s_waitcnt vmcnt(0) lgkmcnt(0)
	s_barrier
	global_load_lds_dwordx4 v[66:67], off
	s_mov_b32 m0, s72
	v_mfma_f32_32x32x16_bf16 v[0:15], v[92:95], v[100:103], v[0:15]
	global_load_lds_dwordx4 v[64:65], off sc1
	v_lshl_add_u64 v[64:65], v[70:71], 0, s[38:39]
	s_mov_b32 m0, s18
	s_nop 0
	global_load_lds_dwordx4 v[64:65], off
	v_lshl_add_u64 v[64:65], v[68:69], 0, s[38:39]
	s_mov_b32 m0, s19
	v_mfma_f32_32x32x16_bf16 v[48:63], v[88:91], v[96:99], v[48:63]
	global_load_lds_dwordx4 v[64:65], off sc1
	v_lshl_add_u64 v[64:65], v[74:75], 0, s[38:39]
	s_mov_b32 m0, s7
	s_mov_b64 s[18:19], 0x4000
	global_load_lds_dwordx4 v[64:65], off
	v_lshl_add_u64 v[64:65], v[72:73], 0, s[38:39]
	s_mov_b32 m0, s8
	v_mfma_f32_32x32x16_bf16 v[32:47], v[88:91], v[100:103], v[32:47]
	global_load_lds_dwordx4 v[64:65], off sc1
	v_lshl_add_u64 v[64:65], v[78:79], 0, s[38:39]
	s_mov_b32 m0, s3
	s_lshl_b32 s3, s85, 16
	global_load_lds_dwordx4 v[64:65], off
	v_lshl_add_u64 v[64:65], v[76:77], 0, s[38:39]
	s_mov_b32 m0, s6
	v_mfma_f32_32x32x16_bf16 v[16:31], v[92:95], v[96:99], v[16:31]
	global_load_lds_dwordx4 v[64:65], off sc1
	ds_read_b128 v[64:67], v80
	ds_read_b128 v[68:71], v80 offset:4096
	ds_read_b128 v[72:75], v82 offset:16384
	ds_read_b128 v[76:79], v82 offset:20480
	v_readlane_b32 s6, v255, 23
	s_add_u32 s72, s6, s3
	v_readlane_b32 s3, v255, 24
	s_addc_u32 s73, s3, 0
	s_waitcnt lgkmcnt(0)
	v_mfma_f32_32x32x16_bf16 v[0:15], v[68:71], v[76:79], v[0:15]
	s_lshl_b64 s[6:7], s[62:63], 16
	v_readlane_b32 s3, v255, 21
	s_add_u32 s6, s3, s6
	v_readlane_b32 s3, v255, 22
	s_addc_u32 s7, s3, s7
	v_mfma_f32_32x32x16_bf16 v[48:63], v[64:67], v[72:75], v[48:63]
	v_mfma_f32_32x32x16_bf16 v[32:47], v[64:67], v[76:79], v[32:47]
	v_mfma_f32_32x32x16_bf16 v[16:31], v[68:71], v[72:75], v[16:31]
	ds_read_b128 v[64:67], v85
	ds_read_b128 v[68:71], v85 offset:4096
	ds_read_b128 v[72:75], v83 offset:16384
	ds_read_b128 v[76:79], v83 offset:20480
	s_waitcnt lgkmcnt(0)
	v_mfma_f32_32x32x16_bf16 v[0:15], v[68:71], v[76:79], v[0:15]
	v_mfma_f32_32x32x16_bf16 v[48:63], v[64:67], v[72:75], v[48:63]
	v_mfma_f32_32x32x16_bf16 v[32:47], v[64:67], v[76:79], v[32:47]
	v_mfma_f32_32x32x16_bf16 v[16:31], v[68:71], v[72:75], v[16:31]
	ds_read_b128 v[64:67], v86
	ds_read_b128 v[68:71], v86 offset:4096
	ds_read_b128 v[72:75], v84 offset:16384
	ds_read_b128 v[76:79], v84 offset:20480
	s_waitcnt lgkmcnt(0)
	v_mfma_f32_32x32x16_bf16 v[0:15], v[68:71], v[76:79], v[0:15]
	v_mfma_f32_32x32x16_bf16 v[48:63], v[64:67], v[72:75], v[48:63]
	v_mfma_f32_32x32x16_bf16 v[32:47], v[64:67], v[76:79], v[32:47]
	v_mfma_f32_32x32x16_bf16 v[16:31], v[68:71], v[72:75], v[16:31]
	ds_read_b128 v[64:67], v87
	ds_read_b128 v[68:71], v87 offset:4096
	ds_read_b128 v[72:75], v81 offset:16384
	ds_read_b128 v[76:79], v81 offset:20480
	s_waitcnt vmcnt(0)
	s_waitcnt vmcnt(0) lgkmcnt(0)
	s_barrier
; __device__ __forceinline__ float sigmoidf_(float x) { return __builtin_amdgcn_rcpf(1.f + __expf(-x)); }
; #define MFMA(a, b, c) __builtin_amdgcn_mfma_f32_32x32x16_bf16(a, b, c, 0, 0, 0)
; #define ISSUE(k0, bf) do { char* A_ = lw + (bf) * BUF; \
;     _Pragma("unroll") for (int i_ = 0; i_ < 4; ++i_) { glds16(al.ptr(lrow + 32 * i_, (k0) + cg), A_ + i_ * 4096); glds16(bl.ptr(lrow + 32 * i_, (k0) + cg), A_ + ABYTES + i_ * 4096); } \
;     if (HALO) { if (wid == 0) glds16(gh + (k0), A_ + 16384); } } while (0)
; template <bool HALO, class AL, class BL>
; __device__ __forceinline__ void gemm_core(f32x16 (&acc)[2][2], f32x16& hacc, const AL& al, const BL& bl, int K, char* lds,
;                                           const u16* halo0, const u16* halo1, int brow0, int brow1) {
;     ...
;   for (int kt = 0; kt < nk; ++kt) {
;     asm volatile("s_waitcnt vmcnt(0)" ::: "memory");
;     __syncthreads();
;     if (kt + 1 < nk) ISSUE((kt + 1) * 64, (kt + 1) & 1);
;     const char* T = lds + (kt & 1) * BUF;
; #pragma unroll
;     for (int kk = 0; kk < 4; ++kk) {
;       const int c = kk * 2 + hi;
;       bf16x8 a0 = *(const bf16x8*)(T + oa + ((c ^ sa) << 4));
;       bf16x8 a1 = *(const bf16x8*)(T + oa + 4096 + ((c ^ sa) << 4));
;       bf16x8 b0 = *(const bf16x8*)(T + ob0 + ((c ^ sb0) << 4));
;       bf16x8 b1 = *(const bf16x8*)(T + ob1 + ((c ^ sb1) << 4));
;       acc[0][0] = MFMA(a0, b0, acc[0][0]); acc[0][1] = MFMA(a0, b1, acc[0][1]);
;       acc[1][0] = MFMA(a1, b0, acc[1][0]); acc[1][1] = MFMA(a1, b1, acc[1][1]);
;       if (HALO) { bf16x8 ah = *(const bf16x8*)(T + oh + ((c ^ sh) << 4)); hacc = MFMA(ah, b0, hacc); }
;     }
; __device__ __forceinline__ void phase_ffn_down(const P& p, int layer, char* lds) {
;     ...
;     { LdBf al{xb + (long)tm * 128 * DM, DM}, bl{wg + (long)tn * 128 * DM, DM}; gemm_plain(acc, al, bl, DM, lds); }
; #pragma unroll
;     for (int mi = 0; mi < 2; ++mi)
; #pragma unroll
;       for (int ni = 0; ni < 2; ++ni)
; #pragma unroll
;         for (int r = 0; r < 16; ++r) acc[mi][ni][r] = sigmoidf_(acc[mi][ni][r]);
	v_mfma_f32_32x32x16_bf16 v[0:15], v[68:71], v[76:79], v[0:15]
	v_mfma_f32_32x32x16_bf16 v[48:63], v[64:67], v[72:75], v[48:63]
	v_mfma_f32_32x32x16_bf16 v[32:47], v[64:67], v[76:79], v[32:47]
	v_mfma_f32_32x32x16_bf16 v[16:31], v[68:71], v[72:75], v[16:31]
	ds_read_b128 v[64:67], v80 offset:32768
	ds_read_b128 v[68:71], v80 offset:36864
	ds_read_b128 v[72:75], v82 offset:49152
	ds_read_b128 v[76:79], v82 offset:53248
	s_waitcnt lgkmcnt(0)
	v_mfma_f32_32x32x16_bf16 v[0:15], v[68:71], v[76:79], v[0:15]
	v_mfma_f32_32x32x16_bf16 v[48:63], v[64:67], v[72:75], v[48:63]
	v_mfma_f32_32x32x16_bf16 v[32:47], v[64:67], v[76:79], v[32:47]
	v_mfma_f32_32x32x16_bf16 v[16:31], v[68:71], v[72:75], v[16:31]
	ds_read_b128 v[64:67], v85 offset:32768
	ds_read_b128 v[68:71], v85 offset:36864
	ds_read_b128 v[72:75], v83 offset:49152
	ds_read_b128 v[76:79], v83 offset:53248
	s_waitcnt lgkmcnt(0)
	v_mfma_f32_32x32x16_bf16 v[0:15], v[68:71], v[76:79], v[0:15]
	v_mfma_f32_32x32x16_bf16 v[48:63], v[64:67], v[72:75], v[48:63]
	v_mfma_f32_32x32x16_bf16 v[32:47], v[64:67], v[76:79], v[32:47]
	v_mfma_f32_32x32x16_bf16 v[16:31], v[68:71], v[72:75], v[16:31]
	ds_read_b128 v[64:67], v86 offset:32768
	ds_read_b128 v[68:71], v86 offset:36864
	ds_read_b128 v[72:75], v84 offset:49152
	ds_read_b128 v[76:79], v84 offset:53248
	s_waitcnt lgkmcnt(0)
	v_mfma_f32_32x32x16_bf16 v[0:15], v[68:71], v[76:79], v[0:15]
	v_mfma_f32_32x32x16_bf16 v[48:63], v[64:67], v[72:75], v[48:63]
	v_mfma_f32_32x32x16_bf16 v[32:47], v[64:67], v[76:79], v[32:47]
	v_mfma_f32_32x32x16_bf16 v[16:31], v[68:71], v[72:75], v[16:31]
	ds_read_b128 v[64:67], v87 offset:32768
	ds_read_b128 v[68:71], v87 offset:36864
	ds_read_b128 v[72:75], v81 offset:49152
	ds_read_b128 v[76:79], v81 offset:53248
	s_waitcnt lgkmcnt(0)
	v_mfma_f32_32x32x16_bf16 v[0:15], v[68:71], v[76:79], v[0:15]
	v_mfma_f32_32x32x16_bf16 v[16:31], v[68:71], v[72:75], v[16:31]
	s_nop 10
	v_mul_f32_e32 v0, 0xbfb8aa3b, v0
	v_exp_f32_e32 v0, v0
	s_nop 0
	v_add_f32_e32 v0, 1.0, v0
	v_rcp_f32_e32 v110, v0
	v_mul_f32_e32 v0, 0xbfb8aa3b, v1
	v_exp_f32_e32 v0, v0
	v_mul_f32_e32 v16, 0xbfb8aa3b, v16
	v_exp_f32_e32 v16, v16
	v_mov_b32_e32 v1, v229
	v_add_f32_e32 v0, 1.0, v0
	v_rcp_f32_e32 v111, v0
	v_mul_f32_e32 v0, 0xbfb8aa3b, v2
	v_exp_f32_e32 v0, v0
	v_add_f32_e32 v16, 1.0, v16
	v_rcp_f32_e32 v96, v16
	v_mul_f32_e32 v16, 0xbfb8aa3b, v17
	v_add_f32_e32 v0, 1.0, v0
	v_rcp_f32_e32 v114, v0
	v_mul_f32_e32 v0, 0xbfb8aa3b, v3
	v_exp_f32_e32 v0, v0
	v_exp_f32_e32 v16, v16
	v_mfma_f32_32x32x16_bf16 v[48:63], v[64:67], v[72:75], v[48:63]
	v_add_f32_e32 v0, 1.0, v0
	v_rcp_f32_e32 v115, v0
	v_mul_f32_e32 v0, 0xbfb8aa3b, v4
	v_exp_f32_e32 v0, v0
	v_add_f32_e32 v16, 1.0, v16
	v_rcp_f32_e32 v97, v16
	v_mul_f32_e32 v16, 0xbfb8aa3b, v18
	v_add_f32_e32 v0, 1.0, v0
	v_rcp_f32_e32 v116, v0
	v_mul_f32_e32 v0, 0xbfb8aa3b, v5
	v_exp_f32_e32 v0, v0
	v_exp_f32_e32 v16, v16
	v_mfma_f32_32x32x16_bf16 v[32:47], v[64:67], v[76:79], v[32:47]
	v_mul_f32_e32 v48, 0xbfb8aa3b, v48
	v_add_f32_e32 v0, 1.0, v0
	v_rcp_f32_e32 v117, v0
	v_mul_f32_e32 v0, 0xbfb8aa3b, v6
	v_exp_f32_e32 v0, v0
	v_add_f32_e32 v16, 1.0, v16
	v_rcp_f32_e32 v98, v16
	v_mul_f32_e32 v16, 0xbfb8aa3b, v19
	v_add_f32_e32 v0, 1.0, v0
	v_rcp_f32_e32 v118, v0
	v_mul_f32_e32 v0, 0xbfb8aa3b, v7
	v_exp_f32_e32 v0, v0
	v_exp_f32_e32 v16, v16
	v_mov_b32_e32 v6, v229
	v_add_f32_e32 v0, 1.0, v0
	v_add_f32_e32 v16, 1.0, v16
	v_rcp_f32_e32 v119, v0
	v_mul_f32_e32 v0, 0xbfb8aa3b, v8
	v_rcp_f32_e32 v99, v16
	v_mul_f32_e32 v16, 0xbfb8aa3b, v20
	v_exp_f32_e32 v0, v0
	v_exp_f32_e32 v16, v16
	v_and_b32_e32 v7, 31, v6
	v_lshrrev_b32_e32 v2, 4, v6
	v_add_f32_e32 v0, 1.0, v0
	v_add_f32_e32 v16, 1.0, v16
	v_rcp_f32_e32 v120, v0
	v_mul_f32_e32 v0, 0xbfb8aa3b, v9
	v_rcp_f32_e32 v100, v16
	v_mul_f32_e32 v16, 0xbfb8aa3b, v21
	v_exp_f32_e32 v0, v0
	v_exp_f32_e32 v16, v16
	v_xor_b32_e32 v4, v2, v6
	v_lshlrev_b32_e32 v4, 4, v4
	v_add_f32_e32 v0, 1.0, v0
	v_add_f32_e32 v16, 1.0, v16
	v_rcp_f32_e32 v121, v0
	v_mul_f32_e32 v0, 0xbfb8aa3b, v10
	v_rcp_f32_e32 v101, v16
	v_mul_f32_e32 v16, 0xbfb8aa3b, v22
	v_exp_f32_e32 v0, v0
	v_exp_f32_e32 v16, v16
	v_and_b32_e32 v200, 0x70, v4
	v_lshl_add_u32 v9, v6, 4, 0
	v_add_f32_e32 v0, 1.0, v0
	v_add_f32_e32 v16, 1.0, v16
	v_rcp_f32_e32 v122, v0
	v_mul_f32_e32 v0, 0xbfb8aa3b, v11
	v_rcp_f32_e32 v102, v16
	v_mul_f32_e32 v16, 0xbfb8aa3b, v23
	v_exp_f32_e32 v0, v0
	v_exp_f32_e32 v16, v16
	v_and_or_b32 v11, v1, 64, v7
	v_add_u32_e32 v5, 0x4000, v9
	v_add_f32_e32 v0, 1.0, v0
	v_add_f32_e32 v16, 1.0, v16
	v_rcp_f32_e32 v123, v0
	v_mul_f32_e32 v0, 0xbfb8aa3b, v12
	v_rcp_f32_e32 v103, v16
	v_mul_f32_e32 v16, 0xbfb8aa3b, v24
	v_exp_f32_e32 v0, v0
	v_exp_f32_e32 v16, v16
	v_readfirstlane_b32 s43, v5
	v_readfirstlane_b32 s42, v9
	v_add_f32_e32 v0, 1.0, v0
	v_add_f32_e32 v16, 1.0, v16
	v_rcp_f32_e32 v124, v0
	v_mul_f32_e32 v0, 0xbfb8aa3b, v13
	v_rcp_f32_e32 v104, v16
	v_mul_f32_e32 v16, 0xbfb8aa3b, v25
	v_exp_f32_e32 v0, v0
	v_exp_f32_e32 v16, v16
	s_mov_b32 m0, s42
	v_add_f32_e32 v0, 1.0, v0
	v_add_f32_e32 v16, 1.0, v16
	v_rcp_f32_e32 v125, v0
	v_mul_f32_e32 v0, 0xbfb8aa3b, v14
	v_rcp_f32_e32 v105, v16
	v_mul_f32_e32 v16, 0xbfb8aa3b, v26
	v_exp_f32_e32 v0, v0
	v_exp_f32_e32 v16, v16
	s_barrier
; __device__ __forceinline__ float sigmoidf_(float x) { return __builtin_amdgcn_rcpf(1.f + __expf(-x)); }
; #define ISSUE(k0, bf) do { char* A_ = lw + (bf) * BUF; \
;     _Pragma("unroll") for (int i_ = 0; i_ < 4; ++i_) { glds16(al.ptr(lrow + 32 * i_, (k0) + cg), A_ + i_ * 4096); glds16(bl.ptr(lrow + 32 * i_, (k0) + cg), A_ + ABYTES + i_ * 4096); } \
;     if (HALO) { if (wid == 0) glds16(gh + (k0), A_ + 16384); } } while (0)
; template <bool HALO, class AL, class BL>
; __device__ __forceinline__ void gemm_core(f32x16 (&acc)[2][2], f32x16& hacc, const AL& al, const BL& bl, int K, char* lds,
;                                           const u16* halo0, const u16* halo1, int brow0, int brow1) {
;     ...
;   const int sa = ((wr * 64 + r32) >> 1) & 7, sb0 = ((brow0 + r32) >> 1) & 7, sb1 = ((brow1 + r32) >> 1) & 7, sh = (r32 >> 1) & 7;
;   const int oa = (wr * 64 + r32) * 128, ob0 = ABYTES + (brow0 + r32) * 128, ob1 = ABYTES + (brow1 + r32) * 128, oh = (128 + r32) * 128;
;   __syncthreads();
;   ISSUE(0, 0);
; __device__ __forceinline__ void phase_ffn_down(const P& p, int layer, char* lds) {
;     ...
; #pragma unroll
;     for (int mi = 0; mi < 2; ++mi)
; #pragma unroll
;       for (int ni = 0; ni < 2; ++ni)
; #pragma unroll
;         for (int r = 0; r < 16; ++r) acc[mi][ni][r] = sigmoidf_(acc[mi][ni][r]);
;     f32x16 acc2[2][2] = {};
;     { LdBf al{pb + (long)tm * 128 * 256, 256}; LdBf bl{wp + (long)tn * 128 * 256, 256}; gemm_plain(acc2, al, bl, 256, lds); }
	v_add_f32_e32 v0, 1.0, v0
	v_add_f32_e32 v16, 1.0, v16
	v_rcp_f32_e32 v126, v0
	v_mul_f32_e32 v0, 0xbfb8aa3b, v15
	v_rcp_f32_e32 v106, v16
	v_mul_f32_e32 v16, 0xbfb8aa3b, v27
	v_exp_f32_e32 v0, v0
	v_exp_f32_e32 v16, v16
	v_lshrrev_b32_e32 v8, 5, v6
	v_bfe_u32 v12, v6, 1, 3
	v_add_f32_e32 v0, 1.0, v0
	v_add_f32_e32 v16, 1.0, v16
	v_rcp_f32_e32 v127, v0
	v_ashrrev_i32_e32 v0, 3, v6
	v_rcp_f32_e32 v107, v16
	v_mul_f32_e32 v16, 0xbfb8aa3b, v28
	v_ashrrev_i32_e32 v1, 31, v0
	v_exp_f32_e32 v16, v16
	v_lshlrev_b64 v[0:1], 9, v[0:1]
	v_lshl_add_u64 v[2:3], s[72:73], 0, v[0:1]
	v_lshl_add_u64 v[130:131], v[2:3], 0, v[200:201]
	v_lshl_add_u64 v[2:3], s[6:7], 0, v[0:1]
	v_lshl_add_u64 v[128:129], v[2:3], 0, v[200:201]
	v_lshl_add_u64 v[2:3], v[0:1], 0, s[18:19]
	v_add_f32_e32 v16, 1.0, v16
	v_lshl_add_u64 v[4:5], s[72:73], 0, v[2:3]
	v_lshl_add_u64 v[2:3], s[6:7], 0, v[2:3]
	v_rcp_f32_e32 v108, v16
	v_mul_f32_e32 v16, 0xbfb8aa3b, v29
	v_lshl_add_u64 v[134:135], v[2:3], 0, v[200:201]
	v_add_u32_e32 v2, 0x5000, v9
	v_exp_f32_e32 v16, v16
	v_lshl_add_u64 v[132:133], v[4:5], 0, v[200:201]
	v_add_u32_e32 v4, 0x1000, v9
	v_readfirstlane_b32 s65, v2
	v_lshl_add_u64 v[2:3], v[0:1], 0, s[36:37]
	global_load_lds_dwordx4 v[130:131], off
	s_mov_b32 m0, s43
	v_readfirstlane_b32 s64, v4
	v_lshl_add_u64 v[4:5], s[72:73], 0, v[2:3]
	v_lshl_add_u64 v[2:3], s[6:7], 0, v[2:3]
	s_mov_b64 s[18:19], 0xc000
	global_load_lds_dwordx4 v[128:129], off sc1
	s_mov_b32 m0, s64
	v_lshl_add_u64 v[136:137], v[4:5], 0, v[200:201]
	v_add_u32_e32 v4, 0x2000, v9
	v_lshl_add_u64 v[138:139], v[2:3], 0, v[200:201]
	v_add_u32_e32 v2, 0x6000, v9
	v_lshl_add_u64 v[0:1], v[0:1], 0, s[18:19]
	global_load_lds_dwordx4 v[132:133], off
	s_mov_b32 m0, s65
	v_readfirstlane_b32 s69, v4
	v_readfirstlane_b32 s70, v2
	v_lshl_add_u64 v[2:3], s[72:73], 0, v[0:1]
	v_lshl_add_u64 v[0:1], s[6:7], 0, v[0:1]
	v_add_f32_e32 v16, 1.0, v16
	global_load_lds_dwordx4 v[134:135], off sc1
	s_mov_b32 m0, s69
	v_lshl_add_u64 v[140:141], v[2:3], 0, v[200:201]
	v_add_u32_e32 v2, 0x3000, v9
	v_lshl_add_u64 v[142:143], v[0:1], 0, v[200:201]
	v_add_u32_e32 v0, 0x7000, v9
	v_rcp_f32_e32 v109, v16
	v_mul_f32_e32 v16, 0xbfb8aa3b, v30
	global_load_lds_dwordx4 v[136:137], off
	s_mov_b32 m0, s70
	v_readfirstlane_b32 s71, v2
	v_readfirstlane_b32 s72, v0
	v_bfe_u32 v0, v6, 5, 1
	v_bitop3_b32 v1, v8, v12, 1 bitop3:0x6c
	v_exp_f32_e32 v16, v16
	global_load_lds_dwordx4 v[138:139], off sc1
	s_mov_b32 m0, s71
	v_lshlrev_b32_e32 v3, 4, v1
	v_bitop3_b32 v1, v0, v12, 2 bitop3:0x36
	v_add_u32_e32 v4, 0x8000, v9
	global_load_lds_dwordx4 v[140:141], off
	s_mov_b32 m0, s72
	v_lshlrev_b32_e32 v148, 4, v1
	v_bitop3_b32 v1, v0, v12, 4 bitop3:0x36
	v_bitop3_b32 v0, v0, v12, 6 bitop3:0x36
	v_add_u32_e32 v5, 0xc000, v9
	v_readfirstlane_b32 s3, v4
	global_load_lds_dwordx4 v[142:143], off sc1
	v_lshlrev_b32_e32 v166, 4, v1
	v_lshlrev_b32_e32 v168, 4, v0
	v_lshl_add_u64 v[0:1], v[130:131], 0, s[78:79]
	s_mov_b32 m0, s3
	v_readfirstlane_b32 s6, v5
	v_add_u32_e32 v4, 0x9000, v9
	s_waitcnt vmcnt(0)
	s_waitcnt vmcnt(0) lgkmcnt(0)
	s_barrier
	global_load_lds_dwordx4 v[0:1], off
	v_lshl_add_u64 v[0:1], v[128:129], 0, s[78:79]
	s_mov_b32 m0, s6
	v_readfirstlane_b32 s7, v4
	v_add_u32_e32 v4, 0xd000, v9
	v_add_f32_e32 v16, 1.0, v16
	global_load_lds_dwordx4 v[0:1], off sc1
	v_lshl_add_u64 v[0:1], v[132:133], 0, s[78:79]
	s_mov_b32 m0, s7
	v_readfirstlane_b32 s8, v4
	v_add_u32_e32 v4, 0xa000, v9
	v_rcp_f32_e32 v112, v16
	v_mul_f32_e32 v16, 0xbfb8aa3b, v31
	global_load_lds_dwordx4 v[0:1], off
	v_lshl_add_u64 v[0:1], v[134:135], 0, s[78:79]
	s_mov_b32 m0, s8
	v_readfirstlane_b32 s18, v4
	v_add_u32_e32 v4, 0xe000, v9
	v_exp_f32_e32 v16, v16
	global_load_lds_dwordx4 v[0:1], off sc1
	v_lshl_add_u64 v[0:1], v[136:137], 0, s[78:79]
	s_mov_b32 m0, s18
	v_readfirstlane_b32 s19, v4
	v_add_u32_e32 v4, 0xb000, v9
	v_lshrrev_b32_e32 v10, 1, v6
	global_load_lds_dwordx4 v[0:1], off
	v_lshl_add_u64 v[0:1], v[138:139], 0, s[78:79]
	s_mov_b32 m0, s19
	v_readfirstlane_b32 s33, v4
	v_add_u32_e32 v4, 0xf000, v9
	v_and_or_b32 v2, v10, s52, v7
	global_load_lds_dwordx4 v[0:1], off sc1
	v_lshl_add_u64 v[0:1], v[140:141], 0, s[78:79]
	s_mov_b32 m0, s33
	v_readfirstlane_b32 s63, v4
	global_load_lds_dwordx4 v[0:1], off
	v_lshl_add_u64 v[0:1], v[142:143], 0, s[78:79]
	s_mov_b32 m0, s63
	v_lshl_add_u32 v169, v2, 7, 0
	v_lshl_add_u32 v170, v11, 7, 0
	v_add_f32_e32 v16, 1.0, v16
	global_load_lds_dwordx4 v[0:1], off sc1
	v_add_u32_e32 v147, v169, v3
	v_add_u32_e32 v146, v170, v3
	v_rcp_f32_e32 v113, v16
	ds_read_b128 v[16:19], v147
	ds_read_b128 v[64:67], v147 offset:4096
	ds_read_b128 v[68:71], v146 offset:16384
	ds_read_b128 v[72:75], v146 offset:20480
	s_waitcnt lgkmcnt(0)
	v_mfma_f32_32x32x16_bf16 v[0:15], v[16:19], v[68:71], 0
	v_add_u32_e32 v149, v169, v148
	v_add_u32_e32 v148, v170, v148
	ds_read_b128 v[150:153], v149
	ds_read_b128 v[154:157], v149 offset:4096
	ds_read_b128 v[158:161], v148 offset:16384
	ds_read_b128 v[162:165], v148 offset:20480
	s_mov_b32 m0, s42
	v_mul_f32_e32 v49, 0xbfb8aa3b, v49
	v_mul_f32_e32 v58, 0xbfb8aa3b, v58
	v_mfma_f32_32x32x16_bf16 v[16:31], v[16:19], v[72:75], 0
	v_mul_f32_e32 v59, 0xbfb8aa3b, v59
	v_exp_f32_e32 v48, v48
	v_exp_f32_e32 v49, v49
	v_mul_f32_e32 v56, 0xbfb8aa3b, v56
	v_mul_f32_e32 v57, 0xbfb8aa3b, v57
	v_exp_f32_e32 v58, v58
	v_exp_f32_e32 v59, v59
	v_mfma_f32_32x32x16_bf16 v[80:95], v[64:67], v[68:71], 0
	v_mul_f32_e32 v60, 0xbfb8aa3b, v60
	v_mul_f32_e32 v61, 0xbfb8aa3b, v61
	v_mul_f32_e32 v54, 0xbfb8aa3b, v54
	v_mul_f32_e32 v55, 0xbfb8aa3b, v55
	v_exp_f32_e32 v56, v56
	v_exp_f32_e32 v57, v57
	v_exp_f32_e32 v60, v60
	v_mfma_f32_32x32x16_bf16 v[64:79], v[64:67], v[72:75], 0
	v_exp_f32_e32 v61, v61
	v_mul_f32_e32 v52, 0xbfb8aa3b, v52
	v_mul_f32_e32 v53, 0xbfb8aa3b, v53
	v_exp_f32_e32 v54, v54
	v_exp_f32_e32 v55, v55
	v_mul_f32_e32 v50, 0xbfb8aa3b, v50
	v_mul_f32_e32 v51, 0xbfb8aa3b, v51
	s_waitcnt lgkmcnt(0)
; __device__ __forceinline__ float sigmoidf_(float x) { return __builtin_amdgcn_rcpf(1.f + __expf(-x)); }
; #define MFMA(a, b, c) __builtin_amdgcn_mfma_f32_32x32x16_bf16(a, b, c, 0, 0, 0)
; #define ISSUE(k0, bf) do { char* A_ = lw + (bf) * BUF; \
;     _Pragma("unroll") for (int i_ = 0; i_ < 4; ++i_) { glds16(al.ptr(lrow + 32 * i_, (k0) + cg), A_ + i_ * 4096); glds16(bl.ptr(lrow + 32 * i_, (k0) + cg), A_ + ABYTES + i_ * 4096); } \
;     if (HALO) { if (wid == 0) glds16(gh + (k0), A_ + 16384); } } while (0)
; template <bool HALO, class AL, class BL>
; __device__ __forceinline__ void gemm_core(f32x16 (&acc)[2][2], f32x16& hacc, const AL& al, const BL& bl, int K, char* lds,
;                                           const u16* halo0, const u16* halo1, int brow0, int brow1) {
;     ...
;   for (int kt = 0; kt < nk; ++kt) {
;     asm volatile("s_waitcnt vmcnt(0)" ::: "memory");
;     __syncthreads();
;     if (kt + 1 < nk) ISSUE((kt + 1) * 64, (kt + 1) & 1);
;     const char* T = lds + (kt & 1) * BUF;
; #pragma unroll
;     for (int kk = 0; kk < 4; ++kk) {
;       const int c = kk * 2 + hi;
;       bf16x8 a0 = *(const bf16x8*)(T + oa + ((c ^ sa) << 4));
;       bf16x8 a1 = *(const bf16x8*)(T + oa + 4096 + ((c ^ sa) << 4));
;       bf16x8 b0 = *(const bf16x8*)(T + ob0 + ((c ^ sb0) << 4));
;       bf16x8 b1 = *(const bf16x8*)(T + ob1 + ((c ^ sb1) << 4));
;       acc[0][0] = MFMA(a0, b0, acc[0][0]); acc[0][1] = MFMA(a0, b1, acc[0][1]);
;       acc[1][0] = MFMA(a1, b0, acc[1][0]); acc[1][1] = MFMA(a1, b1, acc[1][1]);
;       if (HALO) { bf16x8 ah = *(const bf16x8*)(T + oh + ((c ^ sh) << 4)); hacc = MFMA(ah, b0, hacc); }
;     }
; __device__ __forceinline__ void phase_ffn_down(const P& p, int layer, char* lds) {
;     ...
; #pragma unroll
;     for (int mi = 0; mi < 2; ++mi)
; #pragma unroll
;       for (int ni = 0; ni < 2; ++ni)
; #pragma unroll
;         for (int r = 0; r < 16; ++r) acc[mi][ni][r] = sigmoidf_(acc[mi][ni][r]);
	v_mfma_f32_32x32x16_bf16 v[0:15], v[150:153], v[158:161], v[0:15]
	v_exp_f32_e32 v52, v52
	v_exp_f32_e32 v53, v53
	v_add_f32_e32 v48, 1.0, v48
	v_add_f32_e32 v49, 1.0, v49
	v_exp_f32_e32 v50, v50
	v_exp_f32_e32 v51, v51
	v_add_f32_e32 v58, 1.0, v58
	v_mfma_f32_32x32x16_bf16 v[16:31], v[150:153], v[162:165], v[16:31]
	v_add_u32_e32 v151, v169, v166
	v_add_u32_e32 v150, v170, v166
	v_add_f32_e32 v59, 1.0, v59
	v_rcp_f32_e32 v48, v48
	v_rcp_f32_e32 v49, v49
	v_add_f32_e32 v56, 1.0, v56
	v_add_f32_e32 v57, 1.0, v57
	v_mfma_f32_32x32x16_bf16 v[80:95], v[154:157], v[158:161], v[80:95]
	v_rcp_f32_e32 v58, v58
	v_rcp_f32_e32 v59, v59
	v_add_f32_e32 v60, 1.0, v60
	v_add_f32_e32 v61, 1.0, v61
	v_mul_f32_e32 v62, 0xbfb8aa3b, v62
	v_mul_f32_e32 v63, 0xbfb8aa3b, v63
	v_add_f32_e32 v54, 1.0, v54
	v_mfma_f32_32x32x16_bf16 v[64:79], v[154:157], v[162:165], v[64:79]
	ds_read_b128 v[152:155], v151
	ds_read_b128 v[156:159], v151 offset:4096
	ds_read_b128 v[160:163], v150 offset:16384
	ds_read_b128 v[164:167], v150 offset:20480
	v_add_f32_e32 v55, 1.0, v55
	v_rcp_f32_e32 v56, v56
	v_rcp_f32_e32 v57, v57
	v_rcp_f32_e32 v60, v60
	v_rcp_f32_e32 v61, v61
	s_waitcnt lgkmcnt(0)
	v_mfma_f32_32x32x16_bf16 v[0:15], v[152:155], v[160:163], v[0:15]
	v_exp_f32_e32 v62, v62
	v_exp_f32_e32 v63, v63
	v_add_f32_e32 v52, 1.0, v52
	v_add_f32_e32 v53, 1.0, v53
	v_rcp_f32_e32 v54, v54
	v_rcp_f32_e32 v55, v55
	v_mul_f32_e32 v32, 0xbfb8aa3b, v32
	v_mfma_f32_32x32x16_bf16 v[16:31], v[152:155], v[164:167], v[16:31]
	v_add_u32_e32 v153, v169, v168
	v_add_u32_e32 v152, v170, v168
	v_mul_f32_e32 v33, 0xbfb8aa3b, v33
	v_add_f32_e32 v50, 1.0, v50
	v_add_f32_e32 v51, 1.0, v51
	v_rcp_f32_e32 v52, v52
	v_rcp_f32_e32 v53, v53
	v_mfma_f32_32x32x16_bf16 v[80:95], v[156:159], v[160:163], v[80:95]
	v_exp_f32_e32 v32, v32
	v_exp_f32_e32 v33, v33
	v_rcp_f32_e32 v50, v50
	v_rcp_f32_e32 v51, v51
	v_add_f32_e32 v62, 1.0, v62
	v_add_f32_e32 v63, 1.0, v63
	v_rcp_f32_e32 v62, v62
	v_mfma_f32_32x32x16_bf16 v[64:79], v[156:159], v[164:167], v[64:79]
	ds_read_b128 v[154:157], v153
	ds_read_b128 v[158:161], v153 offset:4096
	ds_read_b128 v[162:165], v152 offset:16384
	ds_read_b128 v[166:169], v152 offset:20480
	s_waitcnt vmcnt(0)
	s_waitcnt vmcnt(0) lgkmcnt(0)
	s_barrier
	v_rcp_f32_e32 v63, v63
	v_mfma_f32_32x32x16_bf16 v[0:15], v[154:157], v[162:165], v[0:15]
	v_add_f32_e32 v32, 1.0, v32
	v_add_f32_e32 v33, 1.0, v33
	v_rcp_f32_e32 v32, v32
	v_rcp_f32_e32 v33, v33
	v_mul_f32_e32 v34, 0xbfb8aa3b, v34
	v_mul_f32_e32 v35, 0xbfb8aa3b, v35
	v_mul_f32_e32 v36, 0xbfb8aa3b, v36
	v_mfma_f32_32x32x16_bf16 v[16:31], v[154:157], v[166:169], v[16:31]
	v_lshl_add_u64 v[154:155], v[130:131], 0, s[24:25]
	global_load_lds_dwordx4 v[154:155], off
	v_lshl_add_u64 v[154:155], v[128:129], 0, s[24:25]
	s_mov_b32 m0, s43
	v_lshl_add_u64 v[130:131], v[130:131], 0, s[74:75]
	global_load_lds_dwordx4 v[154:155], off sc1
	v_lshl_add_u64 v[154:155], v[132:133], 0, s[24:25]
	s_mov_b32 m0, s64
	v_mfma_f32_32x32x16_bf16 v[64:79], v[158:161], v[166:169], v[64:79]
	global_load_lds_dwordx4 v[154:155], off
	v_lshl_add_u64 v[154:155], v[134:135], 0, s[24:25]
	s_mov_b32 m0, s65
	v_lshl_add_u64 v[128:129], v[128:129], 0, s[74:75]
	global_load_lds_dwordx4 v[154:155], off sc1
	v_lshl_add_u64 v[154:155], v[136:137], 0, s[24:25]
	s_mov_b32 m0, s69
	v_mfma_f32_32x32x16_bf16 v[80:95], v[158:161], v[162:165], v[80:95]
	global_load_lds_dwordx4 v[154:155], off
	v_lshl_add_u64 v[154:155], v[138:139], 0, s[24:25]
	s_mov_b32 m0, s70
	v_mul_f32_e32 v37, 0xbfb8aa3b, v37
	global_load_lds_dwordx4 v[154:155], off sc1
	v_lshl_add_u64 v[154:155], v[140:141], 0, s[24:25]
	s_mov_b32 m0, s71
	v_mul_f32_e32 v38, 0xbfb8aa3b, v38
	global_load_lds_dwordx4 v[154:155], off
	v_lshl_add_u64 v[154:155], v[142:143], 0, s[24:25]
	s_mov_b32 m0, s72
	v_mul_f32_e32 v39, 0xbfb8aa3b, v39
	global_load_lds_dwordx4 v[154:155], off sc1
	ds_read_b128 v[154:157], v147 offset:32768
	ds_read_b128 v[158:161], v147 offset:36864
	ds_read_b128 v[162:165], v146 offset:49152
	ds_read_b128 v[166:169], v146 offset:53248
	s_waitcnt lgkmcnt(0)
	v_mfma_f32_32x32x16_bf16 v[0:15], v[154:157], v[162:165], v[0:15]
	s_mov_b32 m0, s3
	s_mul_i32 s3, s85, 0xb0000
	v_mul_f32_e32 v40, 0xbfb8aa3b, v40
	v_mul_f32_e32 v41, 0xbfb8aa3b, v41
	v_mul_f32_e32 v42, 0xbfb8aa3b, v42
	v_mul_f32_e32 v43, 0xbfb8aa3b, v43
	v_mul_f32_e32 v44, 0xbfb8aa3b, v44
	v_mfma_f32_32x32x16_bf16 v[64:79], v[158:161], v[166:169], v[64:79]
	v_mul_f32_e32 v45, 0xbfb8aa3b, v45
	v_mul_f32_e32 v46, 0xbfb8aa3b, v46
	v_mul_f32_e32 v47, 0xbfb8aa3b, v47
	v_exp_f32_e32 v34, v34
	v_exp_f32_e32 v35, v35
	v_exp_f32_e32 v36, v36
	v_exp_f32_e32 v37, v37
	v_mfma_f32_32x32x16_bf16 v[16:31], v[154:157], v[166:169], v[16:31]
	v_exp_f32_e32 v38, v38
	v_exp_f32_e32 v39, v39
	v_exp_f32_e32 v40, v40
	v_exp_f32_e32 v41, v41
	v_exp_f32_e32 v42, v42
	v_exp_f32_e32 v43, v43
	v_exp_f32_e32 v44, v44
	v_mfma_f32_32x32x16_bf16 v[80:95], v[158:161], v[162:165], v[80:95]
	ds_read_b128 v[154:157], v149 offset:32768
	ds_read_b128 v[158:161], v149 offset:36864
	ds_read_b128 v[162:165], v148 offset:49152
	ds_read_b128 v[166:169], v148 offset:53248
	v_exp_f32_e32 v45, v45
	v_exp_f32_e32 v46, v46
	v_exp_f32_e32 v47, v47
	v_add_f32_e32 v34, 1.0, v34
	v_add_f32_e32 v35, 1.0, v35
	v_add_f32_e32 v36, 1.0, v36
	s_waitcnt lgkmcnt(0)
	v_mfma_f32_32x32x16_bf16 v[0:15], v[154:157], v[162:165], v[0:15]
	v_add_f32_e32 v37, 1.0, v37
	v_add_f32_e32 v38, 1.0, v38
	v_add_f32_e32 v39, 1.0, v39
	v_add_f32_e32 v40, 1.0, v40
	v_add_f32_e32 v41, 1.0, v41
	v_add_f32_e32 v42, 1.0, v42
	v_add_f32_e32 v43, 1.0, v43
	v_mfma_f32_32x32x16_bf16 v[64:79], v[158:161], v[166:169], v[64:79]
	v_add_f32_e32 v44, 1.0, v44
	v_add_f32_e32 v45, 1.0, v45
	v_add_f32_e32 v46, 1.0, v46
	v_add_f32_e32 v47, 1.0, v47
	v_rcp_f32_e32 v34, v34
	v_rcp_f32_e32 v35, v35
	v_rcp_f32_e32 v36, v36
	v_mfma_f32_32x32x16_bf16 v[16:31], v[154:157], v[166:169], v[16:31]
	v_rcp_f32_e32 v37, v37
	v_rcp_f32_e32 v38, v38
	v_rcp_f32_e32 v39, v39
	v_rcp_f32_e32 v40, v40
	v_rcp_f32_e32 v41, v41
	v_rcp_f32_e32 v42, v42
	v_rcp_f32_e32 v43, v43
	v_mfma_f32_32x32x16_bf16 v[80:95], v[158:161], v[162:165], v[80:95]
	ds_read_b128 v[154:157], v151 offset:32768
	ds_read_b128 v[158:161], v151 offset:36864
	ds_read_b128 v[162:165], v150 offset:49152
	ds_read_b128 v[166:169], v150 offset:53248
	v_rcp_f32_e32 v44, v44
	v_rcp_f32_e32 v45, v45
	v_rcp_f32_e32 v46, v46
	v_rcp_f32_e32 v47, v47
	s_waitcnt lgkmcnt(0)
	v_mfma_f32_32x32x16_bf16 v[0:15], v[154:157], v[162:165], v[0:15]
	v_mfma_f32_32x32x16_bf16 v[64:79], v[158:161], v[166:169], v[64:79]
	v_mfma_f32_32x32x16_bf16 v[16:31], v[154:157], v[166:169], v[16:31]
	v_mfma_f32_32x32x16_bf16 v[80:95], v[158:161], v[162:165], v[80:95]
	ds_read_b128 v[154:157], v153 offset:32768
	ds_read_b128 v[158:161], v153 offset:36864
	ds_read_b128 v[162:165], v152 offset:49152
	ds_read_b128 v[166:169], v152 offset:53248
	s_waitcnt vmcnt(0)
	s_waitcnt vmcnt(0) lgkmcnt(0)
	s_barrier
; #define MFMA(a, b, c) __builtin_amdgcn_mfma_f32_32x32x16_bf16(a, b, c, 0, 0, 0)
; #define ISSUE(k0, bf) do { char* A_ = lw + (bf) * BUF; \
;     _Pragma("unroll") for (int i_ = 0; i_ < 4; ++i_) { glds16(al.ptr(lrow + 32 * i_, (k0) + cg), A_ + i_ * 4096); glds16(bl.ptr(lrow + 32 * i_, (k0) + cg), A_ + ABYTES + i_ * 4096); } \
;     if (HALO) { if (wid == 0) glds16(gh + (k0), A_ + 16384); } } while (0)
; template <bool HALO, class AL, class BL>
; __device__ __forceinline__ void gemm_core(f32x16 (&acc)[2][2], f32x16& hacc, const AL& al, const BL& bl, int K, char* lds,
;                                           const u16* halo0, const u16* halo1, int brow0, int brow1) {
;     ...
;   for (int kt = 0; kt < nk; ++kt) {
;     asm volatile("s_waitcnt vmcnt(0)" ::: "memory");
;     __syncthreads();
;     if (kt + 1 < nk) ISSUE((kt + 1) * 64, (kt + 1) & 1);
;     const char* T = lds + (kt & 1) * BUF;
; #pragma unroll
;     for (int kk = 0; kk < 4; ++kk) {
;       const int c = kk * 2 + hi;
;       bf16x8 a0 = *(const bf16x8*)(T + oa + ((c ^ sa) << 4));
;       bf16x8 a1 = *(const bf16x8*)(T + oa + 4096 + ((c ^ sa) << 4));
;       bf16x8 b0 = *(const bf16x8*)(T + ob0 + ((c ^ sb0) << 4));
;       bf16x8 b1 = *(const bf16x8*)(T + ob1 + ((c ^ sb1) << 4));
;       acc[0][0] = MFMA(a0, b0, acc[0][0]); acc[0][1] = MFMA(a0, b1, acc[0][1]);
;       acc[1][0] = MFMA(a1, b0, acc[1][0]); acc[1][1] = MFMA(a1, b1, acc[1][1]);
;       if (HALO) { bf16x8 ah = *(const bf16x8*)(T + oh + ((c ^ sh) << 4)); hacc = MFMA(ah, b0, hacc); }
;     }
; __device__ __forceinline__ void phase_ffn_down(const P& p, int layer, char* lds) {
;     ...
; #pragma unroll
;     for (int mi = 0; mi < 2; ++mi)
; #pragma unroll
;       for (int ni = 0; ni < 2; ++ni) acc[mi][ni] = acc[mi][ni] * acc2[mi][ni];
;     { LdBf al{ab + (long)tm * 128 * DFF, DFF}, bl{wd + (long)tn * 128 * DFF, DFF}; gemm_plain(acc, al, bl, DFF, lds); }
	global_load_lds_dwordx4 v[130:131], off
	s_mov_b32 m0, s6
	v_mfma_f32_32x32x16_bf16 v[0:15], v[154:157], v[162:165], v[0:15]
	global_load_lds_dwordx4 v[128:129], off sc1
	v_lshl_add_u64 v[128:129], v[132:133], 0, s[74:75]
	s_mov_b32 m0, s7
	s_add_u32 s6, s53, s3
	global_load_lds_dwordx4 v[128:129], off
	v_lshl_add_u64 v[128:129], v[134:135], 0, s[74:75]
	s_mov_b32 m0, s8
	v_mfma_f32_32x32x16_bf16 v[64:79], v[158:161], v[166:169], v[64:79]
	global_load_lds_dwordx4 v[128:129], off sc1
	v_lshl_add_u64 v[128:129], v[136:137], 0, s[74:75]
	s_mov_b32 m0, s18
	s_addc_u32 s7, s95, 0
	global_load_lds_dwordx4 v[128:129], off
	v_lshl_add_u64 v[128:129], v[138:139], 0, s[74:75]
	s_mov_b32 m0, s19
	v_mfma_f32_32x32x16_bf16 v[16:31], v[154:157], v[166:169], v[16:31]
	global_load_lds_dwordx4 v[128:129], off sc1
	v_lshl_add_u64 v[128:129], v[140:141], 0, s[74:75]
	s_mov_b32 m0, s33
	s_mul_i32 s8, s62, 0xb0000
	global_load_lds_dwordx4 v[128:129], off
	v_lshl_add_u64 v[128:129], v[142:143], 0, s[74:75]
	s_mov_b32 m0, s63
	v_mfma_f32_32x32x16_bf16 v[80:95], v[158:161], v[162:165], v[80:95]
	global_load_lds_dwordx4 v[128:129], off sc1
	ds_read_b128 v[128:131], v147
	ds_read_b128 v[132:135], v147 offset:4096
	ds_read_b128 v[136:139], v146 offset:16384
	ds_read_b128 v[140:143], v146 offset:20480
	s_mul_hi_i32 s3, s62, 0xb0000
	s_add_u32 s18, vcc_hi, s8
	v_readlane_b32 s8, v255, 15
	s_addc_u32 s19, s8, s3
	s_waitcnt lgkmcnt(0)
	v_mfma_f32_32x32x16_bf16 v[0:15], v[128:131], v[136:139], v[0:15]
	v_mfma_f32_32x32x16_bf16 v[64:79], v[132:135], v[140:143], v[64:79]
	v_mfma_f32_32x32x16_bf16 v[16:31], v[128:131], v[140:143], v[16:31]
	v_mfma_f32_32x32x16_bf16 v[80:95], v[132:135], v[136:139], v[80:95]
	ds_read_b128 v[128:131], v149
	ds_read_b128 v[132:135], v149 offset:4096
	ds_read_b128 v[136:139], v148 offset:16384
	ds_read_b128 v[140:143], v148 offset:20480
	s_waitcnt lgkmcnt(0)
	v_mfma_f32_32x32x16_bf16 v[0:15], v[128:131], v[136:139], v[0:15]
	v_mfma_f32_32x32x16_bf16 v[64:79], v[132:135], v[140:143], v[64:79]
	v_mfma_f32_32x32x16_bf16 v[16:31], v[128:131], v[140:143], v[16:31]
	v_mfma_f32_32x32x16_bf16 v[80:95], v[132:135], v[136:139], v[80:95]
	ds_read_b128 v[128:131], v151
	ds_read_b128 v[132:135], v151 offset:4096
	ds_read_b128 v[136:139], v150 offset:16384
	ds_read_b128 v[140:143], v150 offset:20480
	s_waitcnt lgkmcnt(0)
	v_mfma_f32_32x32x16_bf16 v[0:15], v[128:131], v[136:139], v[0:15]
	v_mfma_f32_32x32x16_bf16 v[64:79], v[132:135], v[140:143], v[64:79]
	v_mfma_f32_32x32x16_bf16 v[16:31], v[128:131], v[140:143], v[16:31]
	v_mfma_f32_32x32x16_bf16 v[80:95], v[132:135], v[136:139], v[80:95]
	ds_read_b128 v[128:131], v153
	ds_read_b128 v[132:135], v153 offset:4096
	ds_read_b128 v[136:139], v152 offset:16384
	ds_read_b128 v[140:143], v152 offset:20480
	s_waitcnt vmcnt(0)
	s_waitcnt vmcnt(0) lgkmcnt(0)
	s_barrier
	v_mfma_f32_32x32x16_bf16 v[0:15], v[128:131], v[136:139], v[0:15]
	v_mfma_f32_32x32x16_bf16 v[64:79], v[132:135], v[140:143], v[64:79]
	v_mfma_f32_32x32x16_bf16 v[16:31], v[128:131], v[140:143], v[16:31]
	v_mfma_f32_32x32x16_bf16 v[80:95], v[132:135], v[136:139], v[80:95]
	ds_read_b128 v[128:131], v147 offset:32768
	ds_read_b128 v[132:135], v147 offset:36864
	ds_read_b128 v[136:139], v146 offset:49152
	ds_read_b128 v[140:143], v146 offset:53248
	s_waitcnt lgkmcnt(1)
	v_mfma_f32_32x32x16_bf16 v[0:15], v[128:131], v[136:139], v[0:15]
	s_waitcnt lgkmcnt(0)
	v_mfma_f32_32x32x16_bf16 v[64:79], v[132:135], v[140:143], v[64:79]
	v_mfma_f32_32x32x16_bf16 v[16:31], v[128:131], v[140:143], v[16:31]
	v_mfma_f32_32x32x16_bf16 v[80:95], v[132:135], v[136:139], v[80:95]
	ds_read_b128 v[128:131], v149 offset:32768
	ds_read_b128 v[132:135], v149 offset:36864
	ds_read_b128 v[136:139], v148 offset:49152
	ds_read_b128 v[140:143], v148 offset:53248
	s_waitcnt lgkmcnt(1)
	v_mfma_f32_32x32x16_bf16 v[0:15], v[128:131], v[136:139], v[0:15]
	s_waitcnt lgkmcnt(0)
	v_mfma_f32_32x32x16_bf16 v[64:79], v[132:135], v[140:143], v[64:79]
	v_mfma_f32_32x32x16_bf16 v[16:31], v[128:131], v[140:143], v[16:31]
	v_mfma_f32_32x32x16_bf16 v[80:95], v[132:135], v[136:139], v[80:95]
	ds_read_b128 v[128:131], v151 offset:32768
	ds_read_b128 v[132:135], v151 offset:36864
	ds_read_b128 v[136:139], v150 offset:49152
	ds_read_b128 v[140:143], v150 offset:53248
	s_waitcnt lgkmcnt(1)
	v_mfma_f32_32x32x16_bf16 v[0:15], v[128:131], v[136:139], v[0:15]
	s_waitcnt lgkmcnt(0)
	v_mfma_f32_32x32x16_bf16 v[64:79], v[132:135], v[140:143], v[64:79]
	v_mfma_f32_32x32x16_bf16 v[16:31], v[128:131], v[140:143], v[16:31]
	v_mfma_f32_32x32x16_bf16 v[80:95], v[132:135], v[136:139], v[80:95]
	ds_read_b128 v[128:131], v153 offset:32768
	ds_read_b128 v[132:135], v153 offset:36864
	ds_read_b128 v[136:139], v152 offset:49152
	ds_read_b128 v[140:143], v152 offset:53248
	s_waitcnt lgkmcnt(1)
	v_mfma_f32_32x32x16_bf16 v[0:15], v[128:131], v[136:139], v[0:15]
	s_waitcnt lgkmcnt(0)
	v_mfma_f32_32x32x16_bf16 v[64:79], v[132:135], v[140:143], v[64:79]
	s_nop 9
	v_mul_f32_e64 v58, v58, v10
	v_mul_f32_e64 v59, v59, v11
	v_mul_f32_e64 v48, v48, v0
	v_mul_f32_e64 v49, v49, v1
	v_mul_f32_e64 v60, v60, v12
	v_mul_f32_e64 v61, v61, v13
	v_pk_mul_f32 v[56:57], v[56:57], v[8:9]
	v_pk_mul_f32 v[54:55], v[54:55], v[6:7]
	v_pk_mul_f32 v[52:53], v[52:53], v[4:5]
	v_pk_mul_f32 v[50:51], v[50:51], v[2:3]
	v_mfma_f32_32x32x16_bf16 v[16:31], v[128:131], v[140:143], v[16:31]
	v_mul_f32_e64 v10, v122, v74
	v_mul_f32_e64 v11, v123, v75
	v_mul_f32_e64 v0, v110, v64
	v_mul_f32_e64 v1, v111, v65
	v_mov_b32_e32 v64, v229
	v_mov_b32_e32 v75, v229
	v_pk_mul_f32 v[12:13], v[124:125], v[76:77]
	v_pk_mul_f32 v[8:9], v[120:121], v[72:73]
	v_mfma_f32_32x32x16_bf16 v[80:95], v[132:135], v[136:139], v[80:95]
	v_mul_f32_e64 v6, v118, v70
	v_mul_f32_e64 v7, v119, v71
	v_and_b32_e32 v72, 31, v75
	v_lshrrev_b32_e32 v77, 4, v75
	v_xor_b32_e32 v70, v77, v75
	v_and_or_b32 v64, v64, 64, v72
	v_pk_mul_f32 v[4:5], v[116:117], v[68:69]
	v_ashrrev_i32_e32 v76, 3, v75
	v_lshl_add_u32 v69, v75, 4, 0
	v_lshlrev_b32_e32 v68, 7, v64
	v_mov_b64_e32 v[64:65], s[6:7]
	v_lshlrev_b32_e32 v70, 4, v70
	v_pk_mul_f32 v[2:3], v[114:115], v[66:67]
	v_mad_i64_i32 v[66:67], s[6:7], v76, s9, v[64:65]
	v_and_b32_e32 v200, 0x70, v70
	v_readfirstlane_b32 s3, v69
	v_lshl_add_u64 v[66:67], v[66:67], 0, v[200:201]
	s_mov_b32 m0, s3
	v_pk_mul_f32 v[62:63], v[62:63], v[14:15]
	v_pk_mul_f32 v[14:15], v[126:127], v[78:79]
	s_barrier
; #define ISSUE(k0, bf) do { char* A_ = lw + (bf) * BUF; \
;     _Pragma("unroll") for (int i_ = 0; i_ < 4; ++i_) { glds16(al.ptr(lrow + 32 * i_, (k0) + cg), A_ + i_ * 4096); glds16(bl.ptr(lrow + 32 * i_, (k0) + cg), A_ + ABYTES + i_ * 4096); } \
;     if (HALO) { if (wid == 0) glds16(gh + (k0), A_ + 16384); } } while (0)
; template <bool HALO, class AL, class BL>
; __device__ __forceinline__ void gemm_core(f32x16 (&acc)[2][2], f32x16& hacc, const AL& al, const BL& bl, int K, char* lds,
;                                           const u16* halo0, const u16* halo1, int brow0, int brow1) {
;     ...
;   const int sa = ((wr * 64 + r32) >> 1) & 7, sb0 = ((brow0 + r32) >> 1) & 7, sb1 = ((brow1 + r32) >> 1) & 7, sh = (r32 >> 1) & 7;
;   const int oa = (wr * 64 + r32) * 128, ob0 = ABYTES + (brow0 + r32) * 128, ob1 = ABYTES + (brow1 + r32) * 128, oh = (128 + r32) * 128;
;   __syncthreads();
;   ISSUE(0, 0);
;   const int nk = K >> 6;
;   for (int kt = 0; kt < nk; ++kt) {
;     asm volatile("s_waitcnt vmcnt(0)" ::: "memory");
;     __syncthreads();
;     if (kt + 1 < nk) ISSUE((kt + 1) * 64, (kt + 1) & 1);
; __device__ __forceinline__ void phase_ffn_down(const P& p, int layer, char* lds) {
;     ...
; #pragma unroll
;     for (int mi = 0; mi < 2; ++mi)
; #pragma unroll
;       for (int ni = 0; ni < 2; ++ni) acc[mi][ni] = acc[mi][ni] * acc2[mi][ni];
;     { LdBf al{ab + (long)tm * 128 * DFF, DFF}, bl{wd + (long)tn * 128 * DFF, DFF}; gemm_plain(acc, al, bl, DFF, lds); }
	v_add_u32_e32 v79, 0x4000, v69
	global_load_lds_dwordx4 v[66:67], off
	v_mov_b64_e32 v[66:67], s[18:19]
	v_mad_i64_i32 v[70:71], s[6:7], v76, s9, v[66:67]
	v_readfirstlane_b32 s3, v79
	v_pk_mul_f32 v[32:33], v[32:33], v[16:17]
	v_pk_mul_f32 v[16:17], v[96:97], v[80:81]
	v_lshl_add_u64 v[70:71], v[70:71], 0, v[200:201]
	s_mov_b32 m0, s3
	v_add_u32_e32 v79, 32, v76
	v_add_u32_e32 v80, 0x1000, v69
	global_load_lds_dwordx4 v[70:71], off sc1
	v_mad_i64_i32 v[70:71], s[6:7], v79, s9, v[64:65]
	v_readfirstlane_b32 s3, v80
	v_lshl_add_u64 v[70:71], v[70:71], 0, v[200:201]
	s_mov_b32 m0, s3
	v_add_u32_e32 v80, 0x2000, v69
	global_load_lds_dwordx4 v[70:71], off
	v_mad_i64_i32 v[70:71], s[6:7], v79, s9, v[66:67]
	v_add_u32_e32 v79, 0x5000, v69
	v_lshl_add_u64 v[70:71], v[70:71], 0, v[200:201]
	v_readfirstlane_b32 s3, v79
	s_mov_b32 m0, s3
	v_add_u32_e32 v79, 64, v76
	global_load_lds_dwordx4 v[70:71], off sc1
	v_mad_i64_i32 v[70:71], s[6:7], v79, s9, v[64:65]
	v_readfirstlane_b32 s3, v80
	v_lshl_add_u64 v[70:71], v[70:71], 0, v[200:201]
	s_mov_b32 m0, s3
	v_lshrrev_b32_e32 v74, 1, v75
	global_load_lds_dwordx4 v[70:71], off
	v_mad_i64_i32 v[70:71], s[6:7], v79, s9, v[66:67]
	v_add_u32_e32 v79, 0x6000, v69
	v_lshl_add_u64 v[70:71], v[70:71], 0, v[200:201]
	v_readfirstlane_b32 s3, v79
	s_mov_b32 m0, s3
	v_lshrrev_b32_e32 v73, 5, v75
	global_load_lds_dwordx4 v[70:71], off sc1
	v_add_u32_e32 v70, 0x60, v76
	v_add_u32_e32 v71, 0x3000, v69
	v_mad_i64_i32 v[64:65], s[6:7], v70, s9, v[64:65]
	v_readfirstlane_b32 s3, v71
	v_lshl_add_u64 v[64:65], v[64:65], 0, v[200:201]
	s_mov_b32 m0, s3
	v_bfe_u32 v78, v75, 1, 3
	global_load_lds_dwordx4 v[64:65], off
	v_mad_i64_i32 v[64:65], s[6:7], v70, s9, v[66:67]
	v_add_u32_e32 v66, 0x7000, v69
	v_lshl_add_u64 v[64:65], v[64:65], 0, v[200:201]
	v_readfirstlane_b32 s3, v66
	s_mov_b32 m0, s3
	s_add_i32 s3, vcc_lo, s80
	global_load_lds_dwordx4 v[64:65], off sc1
	v_and_or_b32 v65, v74, s52, v72
	v_bfe_u32 v64, v75, 5, 1
	v_lshlrev_b32_e32 v74, 7, v65
	v_bitop3_b32 v65, v73, v78, 1 bitop3:0x6c
	v_lshlrev_b32_e32 v73, 4, v65
	v_bitop3_b32 v65, v64, v78, 2 bitop3:0x36
	v_lshlrev_b32_e32 v72, 4, v65
	v_bitop3_b32 v65, v64, v78, 4 bitop3:0x36
	v_bitop3_b32 v64, v64, v78, 6 bitop3:0x36
	s_bfe_u32 s3, s3, 0x50006
	v_lshlrev_b32_e32 v70, 4, v64
	v_mad_i64_i32 v[66:67], s[6:7], v76, s9, 0
	v_mov_b32_e32 v64, 0xb0000
	s_mul_i32 s3, s3, 0x580000
	v_lshlrev_b32_e32 v71, 4, v65
	v_mad_i64_i32 v[64:65], s[6:7], s62, v64, v[66:67]
	v_bitop3_b32 v75, v77, 7, v75 bitop3:0x48
	s_add_i32 s3, s3, s81
	v_lshlrev_b32_e32 v75, 4, v75
	s_add_u32 s6, s50, s3
	v_or_b32_e32 v64, v64, v75
	v_or_b32_e32 v66, v66, v75
	s_addc_u32 s7, s51, 0
	v_pk_mul_f32 v[46:47], v[46:47], v[30:31]
	v_pk_mul_f32 v[44:45], v[44:45], v[28:29]
	v_pk_mul_f32 v[42:43], v[42:43], v[26:27]
	v_pk_mul_f32 v[40:41], v[40:41], v[24:25]
	v_pk_mul_f32 v[38:39], v[38:39], v[22:23]
	v_pk_mul_f32 v[36:37], v[36:37], v[20:21]
	v_pk_mul_f32 v[34:35], v[34:35], v[18:19]
	v_pk_mul_f32 v[30:31], v[112:113], v[94:95]
	v_pk_mul_f32 v[28:29], v[108:109], v[92:93]
	v_pk_mul_f32 v[26:27], v[106:107], v[90:91]
	v_pk_mul_f32 v[24:25], v[104:105], v[88:89]
	v_pk_mul_f32 v[22:23], v[102:103], v[86:87]
	v_pk_mul_f32 v[20:21], v[100:101], v[84:85]
	v_pk_mul_f32 v[18:19], v[98:99], v[82:83]
	v_lshl_add_u64 v[64:65], s[54:55], 0, v[64:65]
	v_lshl_add_u64 v[66:67], s[6:7], 0, v[66:67]
	s_mov_b64 s[80:81], 0
	s_mov_b32 s6, 0
.LBB0_156:
	s_add_i32 s3, s6, 0x8000
	s_and_b32 s7, s3, 0x8000
	v_add_u32_e32 v75, s7, v69
	v_lshl_add_u64 v[76:77], v[66:67], 0, s[80:81]
	s_mov_b64 s[18:19], 0xa0cff80
	v_readfirstlane_b32 s7, v75
	v_add_u32_e32 v82, 0x4000, v75
	v_lshl_add_u64 v[78:79], v[76:77], 0, s[18:19]
	s_mov_b32 m0, s7
	s_waitcnt vmcnt(0)
	s_waitcnt vmcnt(0) lgkmcnt(0)
	s_barrier
	global_load_lds_dwordx4 v[78:79], off
	v_lshl_add_u64 v[78:79], v[64:65], 0, s[80:81]
	s_mov_b64 s[18:19], 0x2500080
	v_readfirstlane_b32 s7, v82
	v_add_u32_e32 v82, 0x1000, v75
	v_lshl_add_u64 v[80:81], v[78:79], 0, s[18:19]
	s_mov_b32 m0, s7
	s_mov_b64 s[18:19], 0xa0fbf80
	v_readfirstlane_b32 s7, v82
	v_add_u32_e32 v82, 0x5000, v75
	global_load_lds_dwordx4 v[80:81], off sc1
	v_lshl_add_u64 v[80:81], v[76:77], 0, s[18:19]
	s_mov_b32 m0, s7
	s_mov_b64 s[18:19], 0x252c080
	v_readfirstlane_b32 s7, v82
	v_add_u32_e32 v82, 0x2000, v75
	global_load_lds_dwordx4 v[80:81], off
	v_lshl_add_u64 v[80:81], v[78:79], 0, s[18:19]
	s_mov_b32 m0, s7
	s_mov_b64 s[18:19], 0xa127f80
	v_readfirstlane_b32 s7, v82
	v_add_u32_e32 v82, 0x6000, v75
	global_load_lds_dwordx4 v[80:81], off sc1
	v_lshl_add_u64 v[80:81], v[76:77], 0, s[18:19]
	s_mov_b32 m0, s7
	s_mov_b64 s[18:19], 0x2558080
	v_readfirstlane_b32 s7, v82
	global_load_lds_dwordx4 v[80:81], off
	v_lshl_add_u64 v[80:81], v[78:79], 0, s[18:19]
	s_mov_b32 m0, s7
	s_mov_b64 s[18:19], 0xa153f80
	global_load_lds_dwordx4 v[80:81], off sc1
	v_add_u32_e32 v80, 0x3000, v75
	v_add_u32_e32 v75, 0x7000, v75
	v_readfirstlane_b32 s7, v80
	v_lshl_add_u64 v[76:77], v[76:77], 0, s[18:19]
	s_mov_b32 m0, s7
	s_mov_b64 s[18:19], 0x2584080
	v_readfirstlane_b32 s7, v75
	global_load_lds_dwordx4 v[76:77], off
	v_lshl_add_u64 v[76:77], v[78:79], 0, s[18:19]
	s_mov_b32 m0, s7
	s_and_b32 s6, s6, 0x8000
	global_load_lds_dwordx4 v[76:77], off sc1
	s_add_i32 s6, s6, 0
	v_add_u32_e32 v75, s6, v74
	v_add_u32_e32 v92, s6, v68
	v_add_u32_e32 v80, v75, v73
	v_add_u32_e32 v88, v92, v73
	ds_read_b128 v[76:79], v80
	ds_read_b128 v[80:83], v80 offset:4096
	ds_read_b128 v[84:87], v88 offset:16384
	ds_read_b128 v[88:91], v88 offset:20480
	s_waitcnt lgkmcnt(0)
; __device__ __forceinline__ float bf2f(u16 v) { return __uint_as_float(((unsigned)v) << 16); }
; __device__ __forceinline__ int opq() { int z = 0; asm volatile("" : "+v"(z)); return z; }
; #define SBAR() __builtin_amdgcn_sched_barrier(0)
; #define MFMA(a, b, c) __builtin_amdgcn_mfma_f32_32x32x16_bf16(a, b, c, 0, 0, 0)
; #define ISSUE(k0, bf) do { char* A_ = lw + (bf) * BUF; \
;     _Pragma("unroll") for (int i_ = 0; i_ < 4; ++i_) { glds16(al.ptr(lrow + 32 * i_, (k0) + cg), A_ + i_ * 4096); glds16(bl.ptr(lrow + 32 * i_, (k0) + cg), A_ + ABYTES + i_ * 4096); } \
;     if (HALO) { if (wid == 0) glds16(gh + (k0), A_ + 16384); } } while (0)
; template <bool HALO, class AL, class BL>
; __device__ __forceinline__ void gemm_core(f32x16 (&acc)[2][2], f32x16& hacc, const AL& al, const BL& bl, int K, char* lds,
;                                           const u16* halo0, const u16* halo1, int brow0, int brow1) {
;     ...
;   for (int kt = 0; kt < nk; ++kt) {
;     asm volatile("s_waitcnt vmcnt(0)" ::: "memory");
;     __syncthreads();
;     if (kt + 1 < nk) ISSUE((kt + 1) * 64, (kt + 1) & 1);
;     const char* T = lds + (kt & 1) * BUF;
; #pragma unroll
;     for (int kk = 0; kk < 4; ++kk) {
;       const int c = kk * 2 + hi;
;       bf16x8 a0 = *(const bf16x8*)(T + oa + ((c ^ sa) << 4));
;       bf16x8 a1 = *(const bf16x8*)(T + oa + 4096 + ((c ^ sa) << 4));
;       bf16x8 b0 = *(const bf16x8*)(T + ob0 + ((c ^ sb0) << 4));
;       bf16x8 b1 = *(const bf16x8*)(T + ob1 + ((c ^ sb1) << 4));
;       acc[0][0] = MFMA(a0, b0, acc[0][0]); acc[0][1] = MFMA(a0, b1, acc[0][1]);
;       acc[1][0] = MFMA(a1, b0, acc[1][0]); acc[1][1] = MFMA(a1, b1, acc[1][1]);
;       if (HALO) { bf16x8 ah = *(const bf16x8*)(T + oh + ((c ^ sh) << 4)); hacc = MFMA(ah, b0, hacc); }
;     }
; __device__ __forceinline__ void phase_ffn_down(const P& p, int layer, char* lds) {
;     ...
;     const unsigned rb = (unsigned)(tm * 128 + wr * 64 + 4 * hi + opq());
; #pragma unroll
;     for (int mi = 0; mi < 2; ++mi) {
; #pragma unroll
;       for (int ni = 0; ni < 2; ++ni)
; #pragma unroll
;         for (int r = 0; r < 16; ++r) {
;           const unsigned row = rb + mi * 32 + (r & 3) + 8 * (r >> 2); const unsigned col = tn * 128 + wc * 64 + ni * 32 + r32;
;           ((_Float16*)(p.ws + OFF_PRE2))[row * DM + col] = (_Float16)(ALPHA * bf2f(xb[row * DM + col]) + acc[mi][ni][r]);
;         }
;       SBAR();
;     }
	v_mfma_f32_32x32x16_bf16 v[48:63], v[76:79], v[84:87], v[48:63]
	s_add_u32 s80, s80, 0x80
	s_addc_u32 s81, s81, 0
	s_cmpk_lg_i32 s80, 0x1580
	s_mov_b32 s6, s3
	v_mfma_f32_32x32x16_bf16 v[32:47], v[76:79], v[88:91], v[32:47]
	v_mfma_f32_32x32x16_bf16 v[16:31], v[80:83], v[84:87], v[16:31]
	v_mfma_f32_32x32x16_bf16 v[0:15], v[80:83], v[88:91], v[0:15]
	v_add_u32_e32 v80, v75, v72
	v_add_u32_e32 v88, v92, v72
	ds_read_b128 v[76:79], v80
	ds_read_b128 v[80:83], v80 offset:4096
	ds_read_b128 v[84:87], v88 offset:16384
	ds_read_b128 v[88:91], v88 offset:20480
	s_waitcnt lgkmcnt(0)
	v_mfma_f32_32x32x16_bf16 v[48:63], v[76:79], v[84:87], v[48:63]
	v_mfma_f32_32x32x16_bf16 v[32:47], v[76:79], v[88:91], v[32:47]
	v_mfma_f32_32x32x16_bf16 v[16:31], v[80:83], v[84:87], v[16:31]
	v_mfma_f32_32x32x16_bf16 v[0:15], v[80:83], v[88:91], v[0:15]
	v_add_u32_e32 v80, v75, v71
	v_add_u32_e32 v88, v92, v71
	ds_read_b128 v[76:79], v80
	ds_read_b128 v[80:83], v80 offset:4096
	ds_read_b128 v[84:87], v88 offset:16384
	ds_read_b128 v[88:91], v88 offset:20480
	v_add_u32_e32 v75, v75, v70
	s_waitcnt lgkmcnt(0)
	v_mfma_f32_32x32x16_bf16 v[48:63], v[76:79], v[84:87], v[48:63]
	v_mfma_f32_32x32x16_bf16 v[32:47], v[76:79], v[88:91], v[32:47]
	v_mfma_f32_32x32x16_bf16 v[16:31], v[80:83], v[84:87], v[16:31]
	v_mfma_f32_32x32x16_bf16 v[0:15], v[80:83], v[88:91], v[0:15]
	ds_read_b128 v[76:79], v75
	ds_read_b128 v[80:83], v75 offset:4096
	v_add_u32_e32 v75, v92, v70
	ds_read_b128 v[84:87], v75 offset:16384
	ds_read_b128 v[88:91], v75 offset:20480
	s_waitcnt lgkmcnt(0)
	v_mfma_f32_32x32x16_bf16 v[48:63], v[76:79], v[84:87], v[48:63]
	v_mfma_f32_32x32x16_bf16 v[32:47], v[76:79], v[88:91], v[32:47]
	v_mfma_f32_32x32x16_bf16 v[16:31], v[80:83], v[84:87], v[16:31]
	v_mfma_f32_32x32x16_bf16 v[0:15], v[80:83], v[88:91], v[0:15]
	s_cbranch_scc1 .LBB0_156
	v_add_u32_e32 v69, 0, v74
	v_add_u32_e32 v68, 0, v68
	v_add_u32_e32 v74, v69, v73
	v_add_u32_e32 v73, v68, v73
	s_waitcnt vmcnt(0)
	s_waitcnt vmcnt(0)
	s_barrier
	ds_read_b128 v[64:67], v74 offset:32768
	ds_read_b128 v[74:77], v74 offset:36864
	ds_read_b128 v[78:81], v73 offset:49152
	ds_read_b128 v[82:85], v73 offset:53248
	s_waitcnt lgkmcnt(1)
	v_mfma_f32_32x32x16_bf16 v[48:63], v[64:67], v[78:81], v[48:63]
	v_add_u32_e32 v73, v69, v72
	v_add_u32_e32 v72, v68, v72
	s_waitcnt lgkmcnt(0)
	v_mfma_f32_32x32x16_bf16 v[32:47], v[64:67], v[82:85], v[32:47]
	v_mfma_f32_32x32x16_bf16 v[16:31], v[74:77], v[78:81], v[16:31]
	v_mfma_f32_32x32x16_bf16 v[0:15], v[74:77], v[82:85], v[0:15]
	ds_read_b128 v[64:67], v73 offset:32768
	ds_read_b128 v[74:77], v73 offset:36864
	ds_read_b128 v[78:81], v72 offset:49152
	ds_read_b128 v[82:85], v72 offset:53248
	v_add_u32_e32 v72, v69, v71
	v_add_u32_e32 v71, v68, v71
	v_add_u32_e32 v69, v69, v70
	s_waitcnt lgkmcnt(1)
	v_mfma_f32_32x32x16_bf16 v[48:63], v[64:67], v[78:81], v[48:63]
	s_waitcnt lgkmcnt(0)
	v_mfma_f32_32x32x16_bf16 v[32:47], v[64:67], v[82:85], v[32:47]
	v_mfma_f32_32x32x16_bf16 v[16:31], v[74:77], v[78:81], v[16:31]
	v_mfma_f32_32x32x16_bf16 v[0:15], v[74:77], v[82:85], v[0:15]
	ds_read_b128 v[64:67], v72 offset:32768
	ds_read_b128 v[72:75], v72 offset:36864
	ds_read_b128 v[76:79], v71 offset:49152
	ds_read_b128 v[80:83], v71 offset:53248
	s_waitcnt lgkmcnt(1)
	v_mfma_f32_32x32x16_bf16 v[48:63], v[64:67], v[76:79], v[48:63]
	s_waitcnt lgkmcnt(0)
	v_mfma_f32_32x32x16_bf16 v[32:47], v[64:67], v[80:83], v[32:47]
	v_mfma_f32_32x32x16_bf16 v[16:31], v[72:75], v[76:79], v[16:31]
	v_add_u32_e32 v76, v68, v70
	v_mfma_f32_32x32x16_bf16 v[0:15], v[72:75], v[80:83], v[0:15]
	ds_read_b128 v[64:67], v69 offset:32768
	ds_read_b128 v[72:75], v69 offset:36864
	ds_read_b128 v[68:71], v76 offset:49152
	ds_read_b128 v[76:79], v76 offset:53248
	s_waitcnt lgkmcnt(1)
	v_mfma_f32_32x32x16_bf16 v[48:63], v[64:67], v[68:71], v[48:63]
	s_waitcnt lgkmcnt(0)
	v_mfma_f32_32x32x16_bf16 v[32:47], v[64:67], v[76:79], v[32:47]
	v_mov_b32_e32 v66, v201
	v_lshl_add_u32 v67, s85, 7, v144
	v_lshl_or_b32 v65, s62, 7, v145
	v_add_lshl_u32 v66, v67, v66, 10
	v_add_u32_e32 v200, v66, v65
	v_or_b32_e32 v64, 32, v65
	v_mfma_f32_32x32x16_bf16 v[16:31], v[72:75], v[68:71], v[16:31]
	v_lshlrev_b64 v[68:69], 1, v[200:201]
	v_lshl_add_u64 v[70:71], s[40:41], 0, v[68:69]
	global_load_ushort v67, v[70:71], off
	v_lshl_add_u64 v[68:69], s[60:61], 0, v[68:69]
	s_waitcnt vmcnt(0)
	v_lshlrev_b32_e32 v67, 16, v67
	v_fma_mixlo_f16 v48, v67, s12, v48
	global_store_short v[68:69], v48, off
	v_add_u32_e32 v48, 0x400, v66
	v_add_u32_e32 v200, v48, v65
	v_lshlrev_b64 v[68:69], 1, v[200:201]
	v_lshl_add_u64 v[70:71], s[40:41], 0, v[68:69]
	global_load_ushort v67, v[70:71], off
	v_lshl_add_u64 v[68:69], s[60:61], 0, v[68:69]
	v_mfma_f32_32x32x16_bf16 v[0:15], v[72:75], v[76:79], v[0:15]
	s_waitcnt vmcnt(0)
	v_lshlrev_b32_e32 v67, 16, v67
	v_fma_mixlo_f16 v49, v67, s12, v49
	global_store_short v[68:69], v49, off
	v_add_u32_e32 v49, 0x800, v66
	v_add_u32_e32 v200, v49, v65
	v_lshlrev_b64 v[68:69], 1, v[200:201]
	v_lshl_add_u64 v[70:71], s[40:41], 0, v[68:69]
	global_load_ushort v67, v[70:71], off
	v_lshl_add_u64 v[68:69], s[60:61], 0, v[68:69]
	s_waitcnt vmcnt(0)
	v_lshlrev_b32_e32 v67, 16, v67
	v_fma_mixlo_f16 v50, v67, s12, v50
	global_store_short v[68:69], v50, off
	v_add_u32_e32 v50, 0xc00, v66
	v_add_u32_e32 v200, v50, v65
	v_lshlrev_b64 v[68:69], 1, v[200:201]
	v_lshl_add_u64 v[70:71], s[40:41], 0, v[68:69]
	global_load_ushort v67, v[70:71], off
	v_lshl_add_u64 v[68:69], s[60:61], 0, v[68:69]
	s_waitcnt vmcnt(0)
; __device__ __forceinline__ float bf2f(u16 v) { return __uint_as_float(((unsigned)v) << 16); }
; __device__ __forceinline__ void phase_ffn_down(const P& p, int layer, char* lds) {
;     ...
;         for (int r = 0; r < 16; ++r) {
;           const unsigned row = rb + mi * 32 + (r & 3) + 8 * (r >> 2); const unsigned col = tn * 128 + wc * 64 + ni * 32 + r32;
;           ((_Float16*)(p.ws + OFF_PRE2))[row * DM + col] = (_Float16)(ALPHA * bf2f(xb[row * DM + col]) + acc[mi][ni][r]);
	v_lshlrev_b32_e32 v67, 16, v67
	v_fma_mixlo_f16 v51, v67, s12, v51
	global_store_short v[68:69], v51, off
	v_add_u32_e32 v51, 0x2000, v66
	v_add_u32_e32 v200, v51, v65
	v_lshlrev_b64 v[68:69], 1, v[200:201]
	v_lshl_add_u64 v[70:71], s[40:41], 0, v[68:69]
	global_load_ushort v67, v[70:71], off
	v_lshl_add_u64 v[68:69], s[60:61], 0, v[68:69]
	s_waitcnt vmcnt(0)
	v_lshlrev_b32_e32 v67, 16, v67
	v_fma_mixlo_f16 v52, v67, s12, v52
	global_store_short v[68:69], v52, off
	v_add_u32_e32 v52, 0x2400, v66
	v_add_u32_e32 v200, v52, v65
	v_lshlrev_b64 v[68:69], 1, v[200:201]
	v_lshl_add_u64 v[70:71], s[40:41], 0, v[68:69]
	global_load_ushort v67, v[70:71], off
	v_lshl_add_u64 v[68:69], s[60:61], 0, v[68:69]
	s_waitcnt vmcnt(0)
	v_lshlrev_b32_e32 v67, 16, v67
	v_fma_mixlo_f16 v53, v67, s12, v53
	global_store_short v[68:69], v53, off
	v_add_u32_e32 v53, 0x2800, v66
	v_add_u32_e32 v200, v53, v65
	v_lshlrev_b64 v[68:69], 1, v[200:201]
	v_lshl_add_u64 v[70:71], s[40:41], 0, v[68:69]
	global_load_ushort v67, v[70:71], off
	v_lshl_add_u64 v[68:69], s[60:61], 0, v[68:69]
	s_waitcnt vmcnt(0)
	v_lshlrev_b32_e32 v67, 16, v67
	v_fma_mixlo_f16 v54, v67, s12, v54
	global_store_short v[68:69], v54, off
	v_add_u32_e32 v54, 0x2c00, v66
	v_add_u32_e32 v200, v54, v65
	v_lshlrev_b64 v[68:69], 1, v[200:201]
	v_lshl_add_u64 v[70:71], s[40:41], 0, v[68:69]
	global_load_ushort v67, v[70:71], off
	v_lshl_add_u64 v[68:69], s[60:61], 0, v[68:69]
	s_waitcnt vmcnt(0)
	v_lshlrev_b32_e32 v67, 16, v67
	v_fma_mixlo_f16 v55, v67, s12, v55
	global_store_short v[68:69], v55, off
	v_add_u32_e32 v55, 0x4000, v66
	v_add_u32_e32 v200, v55, v65
	v_lshlrev_b64 v[68:69], 1, v[200:201]
	v_lshl_add_u64 v[70:71], s[40:41], 0, v[68:69]
	global_load_ushort v67, v[70:71], off
	v_lshl_add_u64 v[68:69], s[60:61], 0, v[68:69]
	s_waitcnt vmcnt(0)
	v_lshlrev_b32_e32 v67, 16, v67
	v_fma_mixlo_f16 v56, v67, s12, v56
	global_store_short v[68:69], v56, off
	v_add_u32_e32 v56, 0x4400, v66
	v_add_u32_e32 v200, v56, v65
	v_lshlrev_b64 v[68:69], 1, v[200:201]
	v_lshl_add_u64 v[70:71], s[40:41], 0, v[68:69]
	global_load_ushort v67, v[70:71], off
	v_lshl_add_u64 v[68:69], s[60:61], 0, v[68:69]
	s_waitcnt vmcnt(0)
	v_lshlrev_b32_e32 v67, 16, v67
	v_fma_mixlo_f16 v57, v67, s12, v57
	global_store_short v[68:69], v57, off
	v_add_u32_e32 v57, 0x4800, v66
	v_add_u32_e32 v200, v57, v65
	v_lshlrev_b64 v[68:69], 1, v[200:201]
	v_lshl_add_u64 v[70:71], s[40:41], 0, v[68:69]
	global_load_ushort v67, v[70:71], off
	v_lshl_add_u64 v[68:69], s[60:61], 0, v[68:69]
	s_waitcnt vmcnt(0)
	v_lshlrev_b32_e32 v67, 16, v67
	v_fma_mixlo_f16 v58, v67, s12, v58
	global_store_short v[68:69], v58, off
	v_add_u32_e32 v58, 0x4c00, v66
	v_add_u32_e32 v200, v58, v65
	v_lshlrev_b64 v[68:69], 1, v[200:201]
	v_lshl_add_u64 v[70:71], s[40:41], 0, v[68:69]
	global_load_ushort v67, v[70:71], off
	v_lshl_add_u64 v[68:69], s[60:61], 0, v[68:69]
	s_waitcnt vmcnt(0)
	v_lshlrev_b32_e32 v67, 16, v67
	v_fma_mixlo_f16 v59, v67, s12, v59
	global_store_short v[68:69], v59, off
	v_add_u32_e32 v59, 0x6000, v66
	v_add_u32_e32 v200, v59, v65
	v_lshlrev_b64 v[68:69], 1, v[200:201]
	v_lshl_add_u64 v[70:71], s[40:41], 0, v[68:69]
	global_load_ushort v67, v[70:71], off
	v_lshl_add_u64 v[68:69], s[60:61], 0, v[68:69]
	s_waitcnt vmcnt(0)
	v_lshlrev_b32_e32 v67, 16, v67
	v_fma_mixlo_f16 v60, v67, s12, v60
	v_add_u32_e32 v67, 0x6400, v66
	v_add_u32_e32 v200, v67, v65
	global_store_short v[68:69], v60, off
	v_lshlrev_b64 v[68:69], 1, v[200:201]
	v_lshl_add_u64 v[70:71], s[40:41], 0, v[68:69]
	global_load_ushort v60, v[70:71], off
	v_add_u32_e32 v71, 0x6c00, v66
	s_waitcnt vmcnt(0)
	v_lshlrev_b32_e32 v60, 16, v60
	v_fma_mixlo_f16 v70, v60, s12, v61
	v_lshl_add_u64 v[60:61], s[60:61], 0, v[68:69]
	global_store_short v[60:61], v70, off
	v_add_u32_e32 v70, 0x6800, v66
	v_add_u32_e32 v200, v70, v65
	v_lshlrev_b64 v[60:61], 1, v[200:201]
	v_lshl_add_u64 v[68:69], s[40:41], 0, v[60:61]
	global_load_ushort v68, v[68:69], off
	v_lshl_add_u64 v[60:61], s[60:61], 0, v[60:61]
	v_add_u32_e32 v200, v71, v65
	s_waitcnt vmcnt(0)
	v_lshlrev_b32_e32 v68, 16, v68
	v_fma_mixlo_f16 v62, v68, s12, v62
	global_store_short v[60:61], v62, off
	v_lshlrev_b64 v[60:61], 1, v[200:201]
	v_lshl_add_u64 v[68:69], s[40:41], 0, v[60:61]
	global_load_ushort v62, v[68:69], off
	v_lshl_add_u64 v[60:61], s[60:61], 0, v[60:61]
	v_add_u32_e32 v200, v66, v64
	s_waitcnt vmcnt(0)
	v_lshlrev_b32_e32 v62, 16, v62
	v_fma_mixlo_f16 v62, v62, s12, v63
	global_store_short v[60:61], v62, off
	v_lshlrev_b64 v[60:61], 1, v[200:201]
	v_lshl_add_u64 v[62:63], s[40:41], 0, v[60:61]
	global_load_ushort v62, v[62:63], off
	v_lshl_add_u64 v[60:61], s[60:61], 0, v[60:61]
	v_add_u32_e32 v200, v48, v64
	s_waitcnt vmcnt(0)
	v_lshlrev_b32_e32 v62, 16, v62
	v_fma_mixlo_f16 v32, v62, s12, v32
	global_store_short v[60:61], v32, off
	v_lshlrev_b64 v[60:61], 1, v[200:201]
	v_lshl_add_u64 v[62:63], s[40:41], 0, v[60:61]
	global_load_ushort v32, v[62:63], off
	v_add_u32_e32 v200, v49, v64
	s_waitcnt vmcnt(0)
	v_lshlrev_b32_e32 v32, 16, v32
	v_fma_mixlo_f16 v48, v32, s12, v33
	v_lshl_add_u64 v[32:33], s[60:61], 0, v[60:61]
	global_store_short v[32:33], v48, off
	v_lshlrev_b64 v[32:33], 1, v[200:201]
	v_lshl_add_u64 v[48:49], s[40:41], 0, v[32:33]
	global_load_ushort v48, v[48:49], off
	v_lshl_add_u64 v[32:33], s[60:61], 0, v[32:33]
	v_add_u32_e32 v200, v50, v64
	s_waitcnt vmcnt(0)
	v_lshlrev_b32_e32 v48, 16, v48
	v_fma_mixlo_f16 v34, v48, s12, v34
	global_store_short v[32:33], v34, off
	v_lshlrev_b64 v[32:33], 1, v[200:201]
	v_lshl_add_u64 v[48:49], s[40:41], 0, v[32:33]
	global_load_ushort v34, v[48:49], off
	v_lshl_add_u64 v[32:33], s[60:61], 0, v[32:33]
	v_add_u32_e32 v200, v51, v64
	s_waitcnt vmcnt(0)
; __device__ __forceinline__ float bf2f(u16 v) { return __uint_as_float(((unsigned)v) << 16); }
; __device__ __forceinline__ void phase_ffn_down(const P& p, int layer, char* lds) {
;     ...
;         for (int r = 0; r < 16; ++r) {
;           const unsigned row = rb + mi * 32 + (r & 3) + 8 * (r >> 2); const unsigned col = tn * 128 + wc * 64 + ni * 32 + r32;
;           ((_Float16*)(p.ws + OFF_PRE2))[row * DM + col] = (_Float16)(ALPHA * bf2f(xb[row * DM + col]) + acc[mi][ni][r]);
	v_lshlrev_b32_e32 v34, 16, v34
	v_fma_mixlo_f16 v34, v34, s12, v35
	global_store_short v[32:33], v34, off
	v_lshlrev_b64 v[32:33], 1, v[200:201]
	v_lshl_add_u64 v[34:35], s[40:41], 0, v[32:33]
	global_load_ushort v34, v[34:35], off
	v_lshl_add_u64 v[32:33], s[60:61], 0, v[32:33]
	v_add_u32_e32 v200, v52, v64
	s_waitcnt vmcnt(0)
	v_lshlrev_b32_e32 v34, 16, v34
	v_fma_mixlo_f16 v34, v34, s12, v36
	global_store_short v[32:33], v34, off
	v_lshlrev_b64 v[32:33], 1, v[200:201]
	v_lshl_add_u64 v[34:35], s[40:41], 0, v[32:33]
	global_load_ushort v34, v[34:35], off
	v_lshl_add_u64 v[32:33], s[60:61], 0, v[32:33]
	v_add_u32_e32 v200, v53, v64
	s_waitcnt vmcnt(0)
	v_lshlrev_b32_e32 v34, 16, v34
	v_fma_mixlo_f16 v34, v34, s12, v37
	global_store_short v[32:33], v34, off
	v_lshlrev_b64 v[32:33], 1, v[200:201]
	v_lshl_add_u64 v[34:35], s[40:41], 0, v[32:33]
	global_load_ushort v34, v[34:35], off
	v_lshl_add_u64 v[32:33], s[60:61], 0, v[32:33]
	v_add_u32_e32 v200, v54, v64
	s_waitcnt vmcnt(0)
	v_lshlrev_b32_e32 v34, 16, v34
	v_fma_mixlo_f16 v34, v34, s12, v38
	global_store_short v[32:33], v34, off
	v_lshlrev_b64 v[32:33], 1, v[200:201]
	v_lshl_add_u64 v[34:35], s[40:41], 0, v[32:33]
	global_load_ushort v34, v[34:35], off
	v_lshl_add_u64 v[32:33], s[60:61], 0, v[32:33]
	v_add_u32_e32 v200, v55, v64
	s_waitcnt vmcnt(0)
	v_lshlrev_b32_e32 v34, 16, v34
	v_fma_mixlo_f16 v34, v34, s12, v39
	global_store_short v[32:33], v34, off
	v_lshlrev_b64 v[32:33], 1, v[200:201]
	v_lshl_add_u64 v[34:35], s[40:41], 0, v[32:33]
	global_load_ushort v34, v[34:35], off
	v_lshl_add_u64 v[32:33], s[60:61], 0, v[32:33]
	v_add_u32_e32 v200, v56, v64
	s_waitcnt vmcnt(0)
	v_lshlrev_b32_e32 v34, 16, v34
	v_fma_mixlo_f16 v34, v34, s12, v40
	global_store_short v[32:33], v34, off
	v_lshlrev_b64 v[32:33], 1, v[200:201]
	v_lshl_add_u64 v[34:35], s[40:41], 0, v[32:33]
	global_load_ushort v34, v[34:35], off
	v_lshl_add_u64 v[32:33], s[60:61], 0, v[32:33]
	v_add_u32_e32 v200, v57, v64
	s_waitcnt vmcnt(0)
	v_lshlrev_b32_e32 v34, 16, v34
	v_fma_mixlo_f16 v34, v34, s12, v41
	global_store_short v[32:33], v34, off
	v_lshlrev_b64 v[32:33], 1, v[200:201]
	v_lshl_add_u64 v[34:35], s[40:41], 0, v[32:33]
	global_load_ushort v34, v[34:35], off
	v_lshl_add_u64 v[32:33], s[60:61], 0, v[32:33]
	v_add_u32_e32 v200, v58, v64
	s_waitcnt vmcnt(0)
	v_lshlrev_b32_e32 v34, 16, v34
	v_fma_mixlo_f16 v34, v34, s12, v42
	global_store_short v[32:33], v34, off
	v_lshlrev_b64 v[32:33], 1, v[200:201]
	v_lshl_add_u64 v[34:35], s[40:41], 0, v[32:33]
	global_load_ushort v34, v[34:35], off
	v_lshl_add_u64 v[32:33], s[60:61], 0, v[32:33]
	v_add_u32_e32 v200, v59, v64
	s_waitcnt vmcnt(0)
	v_lshlrev_b32_e32 v34, 16, v34
	v_fma_mixlo_f16 v34, v34, s12, v43
	global_store_short v[32:33], v34, off
	v_lshlrev_b64 v[32:33], 1, v[200:201]
	v_lshl_add_u64 v[34:35], s[40:41], 0, v[32:33]
	global_load_ushort v34, v[34:35], off
	v_lshl_add_u64 v[32:33], s[60:61], 0, v[32:33]
	v_add_u32_e32 v200, v67, v64
	s_waitcnt vmcnt(0)
	v_lshlrev_b32_e32 v34, 16, v34
	v_fma_mixlo_f16 v34, v34, s12, v44
	global_store_short v[32:33], v34, off
	v_lshlrev_b64 v[32:33], 1, v[200:201]
	v_lshl_add_u64 v[34:35], s[40:41], 0, v[32:33]
	global_load_ushort v34, v[34:35], off
	v_lshl_add_u64 v[32:33], s[60:61], 0, v[32:33]
	v_add_u32_e32 v200, v70, v64
	s_waitcnt vmcnt(0)
	v_lshlrev_b32_e32 v34, 16, v34
	v_fma_mixlo_f16 v34, v34, s12, v45
	global_store_short v[32:33], v34, off
	v_lshlrev_b64 v[32:33], 1, v[200:201]
	v_lshl_add_u64 v[34:35], s[40:41], 0, v[32:33]
	global_load_ushort v34, v[34:35], off
	v_lshl_add_u64 v[32:33], s[60:61], 0, v[32:33]
	v_add_u32_e32 v200, v71, v64
	s_waitcnt vmcnt(0)
	v_lshlrev_b32_e32 v34, 16, v34
	v_fma_mixlo_f16 v34, v34, s12, v46
	global_store_short v[32:33], v34, off
	v_lshlrev_b64 v[32:33], 1, v[200:201]
	v_lshl_add_u64 v[34:35], s[40:41], 0, v[32:33]
	global_load_ushort v34, v[34:35], off
	v_lshl_add_u64 v[32:33], s[60:61], 0, v[32:33]
	s_waitcnt vmcnt(0)
	v_lshlrev_b32_e32 v34, 16, v34
	v_fma_mixlo_f16 v34, v34, s12, v47
	global_store_short v[32:33], v34, off
	v_add_u32_e32 v32, 0x8000, v66
	v_add_u32_e32 v200, v32, v65
	v_lshlrev_b64 v[34:35], 1, v[200:201]
	v_lshl_add_u64 v[36:37], s[40:41], 0, v[34:35]
	global_load_ushort v33, v[36:37], off
	v_lshl_add_u64 v[34:35], s[60:61], 0, v[34:35]
	s_waitcnt vmcnt(0)
	v_lshlrev_b32_e32 v33, 16, v33
	v_fma_mixlo_f16 v16, v33, s12, v16
	global_store_short v[34:35], v16, off
	v_add_u32_e32 v16, 0x8400, v66
	v_add_u32_e32 v200, v16, v65
	v_lshlrev_b64 v[34:35], 1, v[200:201]
	v_lshl_add_u64 v[36:37], s[40:41], 0, v[34:35]
	global_load_ushort v33, v[36:37], off
	v_lshl_add_u64 v[34:35], s[60:61], 0, v[34:35]
	s_waitcnt vmcnt(0)
	v_lshlrev_b32_e32 v33, 16, v33
	v_fma_mixlo_f16 v17, v33, s12, v17
	global_store_short v[34:35], v17, off
	v_add_u32_e32 v17, 0x8800, v66
	v_add_u32_e32 v200, v17, v65
	v_lshlrev_b64 v[34:35], 1, v[200:201]
	v_lshl_add_u64 v[36:37], s[40:41], 0, v[34:35]
	global_load_ushort v33, v[36:37], off
	v_lshl_add_u64 v[34:35], s[60:61], 0, v[34:35]
	s_waitcnt vmcnt(0)
	v_lshlrev_b32_e32 v33, 16, v33
	v_fma_mixlo_f16 v18, v33, s12, v18
	global_store_short v[34:35], v18, off
	v_add_u32_e32 v18, 0x8c00, v66
	v_add_u32_e32 v200, v18, v65
	v_lshlrev_b64 v[34:35], 1, v[200:201]
	v_lshl_add_u64 v[36:37], s[40:41], 0, v[34:35]
	global_load_ushort v33, v[36:37], off
	v_lshl_add_u64 v[34:35], s[60:61], 0, v[34:35]
	s_waitcnt vmcnt(0)
	v_lshlrev_b32_e32 v33, 16, v33
	v_fma_mixlo_f16 v19, v33, s12, v19
	global_store_short v[34:35], v19, off
	v_add_u32_e32 v19, 0xa000, v66
	v_add_u32_e32 v200, v19, v65
	v_lshlrev_b64 v[34:35], 1, v[200:201]
	v_lshl_add_u64 v[36:37], s[40:41], 0, v[34:35]
	global_load_ushort v33, v[36:37], off
	v_lshl_add_u64 v[34:35], s[60:61], 0, v[34:35]
	s_waitcnt vmcnt(0)
; __device__ __forceinline__ float bf2f(u16 v) { return __uint_as_float(((unsigned)v) << 16); }
; __device__ __forceinline__ void phase_ffn_down(const P& p, int layer, char* lds) {
;     ...
;         for (int r = 0; r < 16; ++r) {
;           const unsigned row = rb + mi * 32 + (r & 3) + 8 * (r >> 2); const unsigned col = tn * 128 + wc * 64 + ni * 32 + r32;
;           ((_Float16*)(p.ws + OFF_PRE2))[row * DM + col] = (_Float16)(ALPHA * bf2f(xb[row * DM + col]) + acc[mi][ni][r]);
	v_lshlrev_b32_e32 v33, 16, v33
	v_fma_mixlo_f16 v20, v33, s12, v20
	global_store_short v[34:35], v20, off
	v_add_u32_e32 v20, 0xa400, v66
	v_add_u32_e32 v200, v20, v65
	v_lshlrev_b64 v[34:35], 1, v[200:201]
	v_lshl_add_u64 v[36:37], s[40:41], 0, v[34:35]
	global_load_ushort v33, v[36:37], off
	v_lshl_add_u64 v[34:35], s[60:61], 0, v[34:35]
	s_waitcnt vmcnt(0)
	v_lshlrev_b32_e32 v33, 16, v33
	v_fma_mixlo_f16 v21, v33, s12, v21
	global_store_short v[34:35], v21, off
	v_add_u32_e32 v21, 0xa800, v66
	v_add_u32_e32 v200, v21, v65
	v_lshlrev_b64 v[34:35], 1, v[200:201]
	v_lshl_add_u64 v[36:37], s[40:41], 0, v[34:35]
	global_load_ushort v33, v[36:37], off
	v_lshl_add_u64 v[34:35], s[60:61], 0, v[34:35]
	s_waitcnt vmcnt(0)
	v_lshlrev_b32_e32 v33, 16, v33
	v_fma_mixlo_f16 v22, v33, s12, v22
	global_store_short v[34:35], v22, off
	v_add_u32_e32 v22, 0xac00, v66
	v_add_u32_e32 v200, v22, v65
	v_lshlrev_b64 v[34:35], 1, v[200:201]
	v_lshl_add_u64 v[36:37], s[40:41], 0, v[34:35]
	global_load_ushort v33, v[36:37], off
	v_lshl_add_u64 v[34:35], s[60:61], 0, v[34:35]
	s_waitcnt vmcnt(0)
	v_lshlrev_b32_e32 v33, 16, v33
	v_fma_mixlo_f16 v23, v33, s12, v23
	global_store_short v[34:35], v23, off
	v_add_u32_e32 v23, 0xc000, v66
	v_add_u32_e32 v200, v23, v65
	v_lshlrev_b64 v[34:35], 1, v[200:201]
	v_lshl_add_u64 v[36:37], s[40:41], 0, v[34:35]
	global_load_ushort v33, v[36:37], off
	v_lshl_add_u64 v[34:35], s[60:61], 0, v[34:35]
	s_waitcnt vmcnt(0)
	v_lshlrev_b32_e32 v33, 16, v33
	v_fma_mixlo_f16 v24, v33, s12, v24
	global_store_short v[34:35], v24, off
	v_add_u32_e32 v24, 0xc400, v66
	v_add_u32_e32 v200, v24, v65
	v_lshlrev_b64 v[34:35], 1, v[200:201]
	v_lshl_add_u64 v[36:37], s[40:41], 0, v[34:35]
	global_load_ushort v33, v[36:37], off
	v_lshl_add_u64 v[34:35], s[60:61], 0, v[34:35]
	s_waitcnt vmcnt(0)
	v_lshlrev_b32_e32 v33, 16, v33
	v_fma_mixlo_f16 v25, v33, s12, v25
	global_store_short v[34:35], v25, off
	v_add_u32_e32 v25, 0xc800, v66
	v_add_u32_e32 v200, v25, v65
	v_lshlrev_b64 v[34:35], 1, v[200:201]
	v_lshl_add_u64 v[36:37], s[40:41], 0, v[34:35]
	global_load_ushort v33, v[36:37], off
	v_lshl_add_u64 v[34:35], s[60:61], 0, v[34:35]
	s_waitcnt vmcnt(0)
	v_lshlrev_b32_e32 v33, 16, v33
	v_fma_mixlo_f16 v26, v33, s12, v26
	global_store_short v[34:35], v26, off
	v_add_u32_e32 v26, 0xcc00, v66
	v_add_u32_e32 v200, v26, v65
	v_lshlrev_b64 v[34:35], 1, v[200:201]
	v_lshl_add_u64 v[36:37], s[40:41], 0, v[34:35]
	global_load_ushort v33, v[36:37], off
	v_lshl_add_u64 v[34:35], s[60:61], 0, v[34:35]
	s_waitcnt vmcnt(0)
	v_lshlrev_b32_e32 v33, 16, v33
	v_fma_mixlo_f16 v27, v33, s12, v27
	global_store_short v[34:35], v27, off
	v_add_u32_e32 v27, 0xe000, v66
	v_add_u32_e32 v200, v27, v65
	v_lshlrev_b64 v[34:35], 1, v[200:201]
	v_lshl_add_u64 v[36:37], s[40:41], 0, v[34:35]
	global_load_ushort v33, v[36:37], off
	v_lshl_add_u64 v[34:35], s[60:61], 0, v[34:35]
	s_waitcnt vmcnt(0)
	v_lshlrev_b32_e32 v33, 16, v33
	v_fma_mixlo_f16 v28, v33, s12, v28
	v_add_u32_e32 v33, 0xe400, v66
	v_add_u32_e32 v200, v33, v65
	global_store_short v[34:35], v28, off
	v_lshlrev_b64 v[34:35], 1, v[200:201]
	v_lshl_add_u64 v[36:37], s[40:41], 0, v[34:35]
	global_load_ushort v28, v[36:37], off
	v_add_u32_e32 v37, 0xec00, v66
	s_waitcnt vmcnt(0)
	v_lshlrev_b32_e32 v28, 16, v28
	v_fma_mixlo_f16 v36, v28, s12, v29
	v_lshl_add_u64 v[28:29], s[60:61], 0, v[34:35]
	global_store_short v[28:29], v36, off
	v_add_u32_e32 v36, 0xe800, v66
	v_add_u32_e32 v200, v36, v65
	v_lshlrev_b64 v[28:29], 1, v[200:201]
	v_lshl_add_u64 v[34:35], s[40:41], 0, v[28:29]
	global_load_ushort v34, v[34:35], off
	v_lshl_add_u64 v[28:29], s[60:61], 0, v[28:29]
	v_add_u32_e32 v200, v37, v65
	s_waitcnt vmcnt(0)
	v_lshlrev_b32_e32 v34, 16, v34
	v_fma_mixlo_f16 v30, v34, s12, v30
	global_store_short v[28:29], v30, off
	v_lshlrev_b64 v[28:29], 1, v[200:201]
	v_lshl_add_u64 v[34:35], s[40:41], 0, v[28:29]
	global_load_ushort v30, v[34:35], off
	v_lshl_add_u64 v[28:29], s[60:61], 0, v[28:29]
	v_add_u32_e32 v200, v32, v64
	s_waitcnt vmcnt(0)
	v_lshlrev_b32_e32 v30, 16, v30
	v_fma_mixlo_f16 v30, v30, s12, v31
	global_store_short v[28:29], v30, off
	v_lshlrev_b64 v[28:29], 1, v[200:201]
	v_lshl_add_u64 v[30:31], s[40:41], 0, v[28:29]
	global_load_ushort v30, v[30:31], off
	v_lshl_add_u64 v[28:29], s[60:61], 0, v[28:29]
	v_add_u32_e32 v200, v16, v64
	s_waitcnt vmcnt(0)
	v_lshlrev_b32_e32 v30, 16, v30
	v_fma_mixlo_f16 v0, v30, s12, v0
	global_store_short v[28:29], v0, off
	v_lshlrev_b64 v[28:29], 1, v[200:201]
	v_lshl_add_u64 v[30:31], s[40:41], 0, v[28:29]
	global_load_ushort v0, v[30:31], off
	v_add_u32_e32 v200, v17, v64
	s_waitcnt vmcnt(0)
; __device__ __forceinline__ float bf2f(u16 v) { return __uint_as_float(((unsigned)v) << 16); }
; __device__ __forceinline__ bool tile_at(int it, int nM, int nN, int& tm, int& tn) {
;   const int total = nM * nN, per = (total + 7) / 8, x = blockIdx.x & 7, lb = blockIdx.x >> 3, nlb = gridDim.x >> 3;
;   const int i = lb + it * nlb; if (i >= per) return false;
;   const int idx = x * per + i; if (idx >= total) return false;
;   const int grp = idx / (8 * nN), rem = idx - grp * 8 * nN;
;   tm = grp * 8 + (rem & 7); tn = rem >> 3; return true;
; __device__ __forceinline__ void phase_ffn_down(const P& p, int layer, char* lds) {
;     ...
;   for (int it = 0; tile_at(it, 256, 8, tm, tn); ++it) {
;     ...
;         for (int r = 0; r < 16; ++r) {
;           const unsigned row = rb + mi * 32 + (r & 3) + 8 * (r >> 2); const unsigned col = tn * 128 + wc * 64 + ni * 32 + r32;
;           ((_Float16*)(p.ws + OFF_PRE2))[row * DM + col] = (_Float16)(ALPHA * bf2f(xb[row * DM + col]) + acc[mi][ni][r]);
	v_lshlrev_b32_e32 v0, 16, v0
	v_fma_mixlo_f16 v16, v0, s12, v1
	v_lshl_add_u64 v[0:1], s[60:61], 0, v[28:29]
	global_store_short v[0:1], v16, off
	v_lshlrev_b64 v[0:1], 1, v[200:201]
	v_lshl_add_u64 v[16:17], s[40:41], 0, v[0:1]
	global_load_ushort v16, v[16:17], off
	v_lshl_add_u64 v[0:1], s[60:61], 0, v[0:1]
	v_add_u32_e32 v200, v18, v64
	s_waitcnt vmcnt(0)
	v_lshlrev_b32_e32 v16, 16, v16
	v_fma_mixlo_f16 v2, v16, s12, v2
	global_store_short v[0:1], v2, off
	v_lshlrev_b64 v[0:1], 1, v[200:201]
	v_lshl_add_u64 v[16:17], s[40:41], 0, v[0:1]
	global_load_ushort v2, v[16:17], off
	v_lshl_add_u64 v[0:1], s[60:61], 0, v[0:1]
	v_add_u32_e32 v200, v19, v64
	s_waitcnt vmcnt(0)
	v_lshlrev_b32_e32 v2, 16, v2
	v_fma_mixlo_f16 v2, v2, s12, v3
	global_store_short v[0:1], v2, off
	v_lshlrev_b64 v[0:1], 1, v[200:201]
	v_lshl_add_u64 v[2:3], s[40:41], 0, v[0:1]
	global_load_ushort v2, v[2:3], off
	v_lshl_add_u64 v[0:1], s[60:61], 0, v[0:1]
	v_add_u32_e32 v200, v20, v64
	s_waitcnt vmcnt(0)
	v_lshlrev_b32_e32 v2, 16, v2
	v_fma_mixlo_f16 v2, v2, s12, v4
	global_store_short v[0:1], v2, off
	v_lshlrev_b64 v[0:1], 1, v[200:201]
	v_lshl_add_u64 v[2:3], s[40:41], 0, v[0:1]
	global_load_ushort v2, v[2:3], off
	v_lshl_add_u64 v[0:1], s[60:61], 0, v[0:1]
	v_add_u32_e32 v200, v21, v64
	s_waitcnt vmcnt(0)
	v_lshlrev_b32_e32 v2, 16, v2
	v_fma_mixlo_f16 v2, v2, s12, v5
	global_store_short v[0:1], v2, off
	v_lshlrev_b64 v[0:1], 1, v[200:201]
	v_lshl_add_u64 v[2:3], s[40:41], 0, v[0:1]
	global_load_ushort v2, v[2:3], off
	v_lshl_add_u64 v[0:1], s[60:61], 0, v[0:1]
	v_add_u32_e32 v200, v22, v64
	s_waitcnt vmcnt(0)
	v_lshlrev_b32_e32 v2, 16, v2
	v_fma_mixlo_f16 v2, v2, s12, v6
	global_store_short v[0:1], v2, off
	v_lshlrev_b64 v[0:1], 1, v[200:201]
	v_lshl_add_u64 v[2:3], s[40:41], 0, v[0:1]
	global_load_ushort v2, v[2:3], off
	v_lshl_add_u64 v[0:1], s[60:61], 0, v[0:1]
	v_add_u32_e32 v200, v23, v64
	s_waitcnt vmcnt(0)
	v_lshlrev_b32_e32 v2, 16, v2
	v_fma_mixlo_f16 v2, v2, s12, v7
	global_store_short v[0:1], v2, off
	v_lshlrev_b64 v[0:1], 1, v[200:201]
	v_lshl_add_u64 v[2:3], s[40:41], 0, v[0:1]
	global_load_ushort v2, v[2:3], off
	v_lshl_add_u64 v[0:1], s[60:61], 0, v[0:1]
	v_add_u32_e32 v200, v24, v64
	s_waitcnt vmcnt(0)
	v_lshlrev_b32_e32 v2, 16, v2
	v_fma_mixlo_f16 v2, v2, s12, v8
	global_store_short v[0:1], v2, off
	v_lshlrev_b64 v[0:1], 1, v[200:201]
	v_lshl_add_u64 v[2:3], s[40:41], 0, v[0:1]
	global_load_ushort v2, v[2:3], off
	v_lshl_add_u64 v[0:1], s[60:61], 0, v[0:1]
	v_add_u32_e32 v200, v25, v64
	s_waitcnt vmcnt(0)
	v_lshlrev_b32_e32 v2, 16, v2
	v_fma_mixlo_f16 v2, v2, s12, v9
	global_store_short v[0:1], v2, off
	v_lshlrev_b64 v[0:1], 1, v[200:201]
	v_lshl_add_u64 v[2:3], s[40:41], 0, v[0:1]
	global_load_ushort v2, v[2:3], off
	v_lshl_add_u64 v[0:1], s[60:61], 0, v[0:1]
	v_add_u32_e32 v200, v26, v64
	s_waitcnt vmcnt(0)
	v_lshlrev_b32_e32 v2, 16, v2
	v_fma_mixlo_f16 v2, v2, s12, v10
	global_store_short v[0:1], v2, off
	v_lshlrev_b64 v[0:1], 1, v[200:201]
	v_lshl_add_u64 v[2:3], s[40:41], 0, v[0:1]
	global_load_ushort v2, v[2:3], off
	v_lshl_add_u64 v[0:1], s[60:61], 0, v[0:1]
	v_add_u32_e32 v200, v27, v64
	s_waitcnt vmcnt(0)
	v_lshlrev_b32_e32 v2, 16, v2
	v_fma_mixlo_f16 v2, v2, s12, v11
	global_store_short v[0:1], v2, off
	v_lshlrev_b64 v[0:1], 1, v[200:201]
	v_lshl_add_u64 v[2:3], s[40:41], 0, v[0:1]
	global_load_ushort v2, v[2:3], off
	v_lshl_add_u64 v[0:1], s[60:61], 0, v[0:1]
	v_add_u32_e32 v200, v33, v64
	s_waitcnt vmcnt(0)
	v_lshlrev_b32_e32 v2, 16, v2
	v_fma_mixlo_f16 v2, v2, s12, v12
	global_store_short v[0:1], v2, off
	v_lshlrev_b64 v[0:1], 1, v[200:201]
	v_lshl_add_u64 v[2:3], s[40:41], 0, v[0:1]
	global_load_ushort v2, v[2:3], off
	v_lshl_add_u64 v[0:1], s[60:61], 0, v[0:1]
	v_add_u32_e32 v200, v36, v64
	s_waitcnt vmcnt(0)
	v_lshlrev_b32_e32 v2, 16, v2
	v_fma_mixlo_f16 v2, v2, s12, v13
	global_store_short v[0:1], v2, off
	v_lshlrev_b64 v[0:1], 1, v[200:201]
	v_lshl_add_u64 v[2:3], s[40:41], 0, v[0:1]
	global_load_ushort v2, v[2:3], off
	v_lshl_add_u64 v[0:1], s[60:61], 0, v[0:1]
	v_add_u32_e32 v200, v37, v64
	s_waitcnt vmcnt(0)
	v_lshlrev_b32_e32 v2, 16, v2
	v_fma_mixlo_f16 v2, v2, s12, v14
	global_store_short v[0:1], v2, off
	v_lshlrev_b64 v[0:1], 1, v[200:201]
	v_lshl_add_u64 v[2:3], s[40:41], 0, v[0:1]
	global_load_ushort v2, v[2:3], off
	v_lshl_add_u64 v[0:1], s[60:61], 0, v[0:1]
	s_waitcnt vmcnt(0)
	v_lshlrev_b32_e32 v2, 16, v2
	v_fma_mixlo_f16 v2, v2, s12, v15
	global_store_short v[0:1], v2, off
	s_add_i32 s84, s84, 1
	v_readlane_b32 s3, v255, 25
	s_mul_i32 s3, s84, s3
	s_add_i32 s80, s3, s13
	s_cmpk_gt_u32 s80, 0xff
	s_cbranch_scc0 .LBB0_155

; __device__ __forceinline__ int ltid() { int t = (int)threadIdx.x; asm volatile("" : "+v"(t)); return t; }
; #define ISSUE(k0, bf) do { char* A_ = lw + (bf) * BUF; \
;     _Pragma("unroll") for (int i_ = 0; i_ < 4; ++i_) { glds16(al.ptr(lrow + 32 * i_, (k0) + cg), A_ + i_ * 4096); glds16(bl.ptr(lrow + 32 * i_, (k0) + cg), A_ + ABYTES + i_ * 4096); } \
;     if (HALO) { if (wid == 0) glds16(gh + (k0), A_ + 16384); } } while (0)
; template <bool HALO, class AL, class BL>
; __device__ __forceinline__ void gemm_core(f32x16 (&acc)[2][2], f32x16& hacc, const AL& al, const BL& bl, int K, char* lds,
;                                           const u16* halo0, const u16* halo1, int brow0, int brow1) {
;     ...
;   const int tid = ltid(), lane = tid & 63, wid = tid >> 6, wr = wid >> 1, r32 = lane & 31, hi = lane >> 5;
;   const int lrow = tid >> 3, cg = ((tid & 7) ^ ((lrow >> 1) & 7)) * 8;
;   const u16* gh = nullptr;
;   if (HALO) { const int c = ((lane & 7) ^ ((lane >> 4) & 7)) * 8; gh = ((lane < 8) ? halo0 : halo1) + c; }
;   char* lw = lds + tid * 16;
;     ...
;   const int sa = ((wr * 64 + r32) >> 1) & 7, sb0 = ((brow0 + r32) >> 1) & 7, sb1 = ((brow1 + r32) >> 1) & 7, sh = (r32 >> 1) & 7;
;   const int oa = (wr * 64 + r32) * 128, ob0 = ABYTES + (brow0 + r32) * 128, ob1 = ABYTES + (brow1 + r32) * 128, oh = (128 + r32) * 128;
;   __syncthreads();
;   ISSUE(0, 0);
;   const int nk = K >> 6;
;   for (int kt = 0; kt < nk; ++kt) {
;     asm volatile("s_waitcnt vmcnt(0)" ::: "memory");
;     __syncthreads();
;     if (kt + 1 < nk) ISSUE((kt + 1) * 64, (kt + 1) & 1);
; __device__ __forceinline__ void phase_ffn_up(const P& p, int layer, char* lds) {
;     ...
;   for (int it = 0; tile_at(it, 256, 44, tm, tn); ++it) {
;     f32x16 acc[2][2] = {}; f32x16 hacc = {};
;     const long r0 = (long)tm * 128;
;     const bool top0 = (r0 % SEQ) == 0, bot0 = ((r0 + 128) % SEQ) == 0;
;     LdBf al{xb + r0 * DM, DM}; LdBsplit bl{wt, DM, tn * 64};
;     const u16* zr = (const u16*)(p.ws + OFF_ZERO);
;     const u16* h0 = top0 ? zr : xb + (r0 - 1) * DM; const u16* h1 = bot0 ? zr : xb + (r0 + 128) * DM;
;     gemm_core<true>(acc, hacc, al, bl, DM, lds, h0, h1, wc * 32, 64 + wc * 32);
.LBB0_166:
	v_readlane_b32 s7, v254, 55
	s_add_i32 s7, s6, s7
	s_mul_hi_u32 s8, s7, 0xba2e8ba3
	s_lshr_b32 s8, s8, 8
	s_lshl_b32 s42, s8, 3
	s_and_b32 s6, s6, 7
	s_mulk_i32 s8, 0xfea0
	s_or_b32 s92, s42, s6
	s_add_i32 s8, s8, s7
	s_lshl_b64 s[6:7], s[92:93], 7
	s_and_b32 s64, s92, 63
	v_mov_b32_e32 v0, v229
	s_add_u32 s84, s6, 0x80
	s_addc_u32 s85, s7, 0
	v_lshrrev_b32_e32 v1, 4, v0
	s_and_b32 s72, s84, 0x1f80
	s_lshl_b64 s[6:7], s[92:93], 18
	v_xor_b32_e32 v1, v1, v0
	v_lshl_add_u32 v102, v0, 4, 0
	s_add_u32 s6, s69, s6
	v_ashrrev_i32_e32 v2, 3, v0
	v_lshlrev_b32_e32 v1, 4, v1
	v_readfirstlane_b32 s42, v102
	s_addc_u32 s7, s3, s7
	s_lshl_b32 s8, s8, 3
	v_and_b32_e32 v200, 0x70, v1
	v_ashrrev_i32_e32 v3, 31, v2
	s_mov_b32 m0, s42
	v_add_u32_e32 v1, 0xac0, v2
	v_cmp_gt_i32_e64 s[42:43], 64, v2
	s_andn2_b32 s8, s8, 63
	v_lshl_add_u64 v[4:5], s[6:7], 0, v[200:201]
	v_lshlrev_b64 v[6:7], 11, v[2:3]
	v_cndmask_b32_e64 v1, v1, v2, s[42:43]
	v_lshl_add_u64 v[82:83], v[4:5], 0, v[6:7]
	v_add_u32_e32 v6, s8, v1
	v_ashrrev_i32_e32 v7, 31, v6
	v_add_u32_e32 v123, 0x4400, v102
	v_lshlrev_b64 v[6:7], 11, v[6:7]
	v_lshl_add_u64 v[6:7], s[80:81], 0, v[6:7]
	v_readfirstlane_b32 s42, v123
	v_add_u32_e32 v124, 0x1000, v102
	s_waitcnt lgkmcnt(0)
	s_barrier
	global_load_lds_dwordx4 v[82:83], off
	v_lshl_add_u64 v[84:85], v[6:7], 0, v[200:201]
	s_mov_b32 m0, s42
	v_readfirstlane_b32 s42, v124
	global_load_lds_dwordx4 v[84:85], off sc1
	v_add_u32_e32 v6, 32, v2
	s_mov_b32 m0, s42
	v_add_u32_e32 v1, 0xae0, v2
	v_cmp_gt_i32_e64 s[42:43], 32, v2
	v_ashrrev_i32_e32 v7, 31, v6
	s_waitcnt vmcnt(0)
	v_lshlrev_b64 v[8:9], 11, v[6:7]
	v_cndmask_b32_e64 v1, v1, v6, s[42:43]
	v_add_u32_e32 v6, s8, v1
	v_ashrrev_i32_e32 v7, 31, v6
	v_lshlrev_b64 v[6:7], 11, v[6:7]
	v_add_u32_e32 v125, 0x5400, v102
	v_lshl_add_u64 v[86:87], v[4:5], 0, v[8:9]
	v_lshl_add_u64 v[6:7], s[80:81], 0, v[6:7]
	v_readfirstlane_b32 s42, v125
	v_add_u32_e32 v126, 0x2000, v102
	global_load_lds_dwordx4 v[86:87], off
	v_lshl_add_u64 v[88:89], v[6:7], 0, v[200:201]
	s_mov_b32 m0, s42
	v_readfirstlane_b32 s42, v126
	global_load_lds_dwordx4 v[88:89], off sc1
	v_add_u32_e32 v6, 64, v2
	s_mov_b32 m0, s42
	v_add_u32_e32 v1, 0xb00, v2
	v_cmp_gt_i32_e64 s[42:43], 0, v2
	v_ashrrev_i32_e32 v7, 31, v6
	v_lshlrev_b64 v[8:9], 11, v[6:7]
	v_cndmask_b32_e64 v1, v1, v6, s[42:43]
	v_add_u32_e32 v6, s8, v1
	v_ashrrev_i32_e32 v7, 31, v6
	v_lshlrev_b64 v[6:7], 11, v[6:7]
	v_add_u32_e32 v127, 0x6400, v102
	v_lshl_add_u64 v[90:91], v[4:5], 0, v[8:9]
	v_lshl_add_u64 v[6:7], s[80:81], 0, v[6:7]
	v_readfirstlane_b32 s42, v127
	v_add_u32_e32 v128, 0x3000, v102
	global_load_lds_dwordx4 v[90:91], off
	v_lshl_add_u64 v[92:93], v[6:7], 0, v[200:201]
	s_mov_b32 m0, s42
	v_readfirstlane_b32 s42, v128
	global_load_lds_dwordx4 v[92:93], off sc1
	s_mov_b32 m0, s42
	s_movk_i32 s42, 0xffe0
	v_add_u32_e32 v6, 0x60, v2
	v_add_u32_e32 v1, 0xb20, v2
	v_cmp_gt_i32_e64 s[42:43], s42, v2
	v_ashrrev_i32_e32 v7, 31, v6
	v_lshlrev_b64 v[8:9], 11, v[6:7]
	v_cndmask_b32_e64 v1, v1, v6, s[42:43]
	v_add_u32_e32 v2, s8, v1
	v_ashrrev_i32_e32 v3, 31, v2
	v_lshlrev_b64 v[2:3], 11, v[2:3]
	v_add_u32_e32 v129, 0x7400, v102
	v_lshl_add_u64 v[94:95], v[4:5], 0, v[8:9]
	v_lshl_add_u64 v[2:3], s[80:81], 0, v[2:3]
	v_readfirstlane_b32 s42, v129
	global_load_lds_dwordx4 v[94:95], off
	v_lshl_add_u64 v[96:97], v[2:3], 0, v[200:201]
	s_mov_b32 m0, s42
	s_add_u32 s6, s6, 0xfffff800
	global_load_lds_dwordx4 v[96:97], off sc1
	s_addc_u32 s7, s7, -1
	s_cmp_eq_u32 s64, 0
	s_cselect_b32 s64, s40, s6
	s_cselect_b32 s42, s41, s7
	s_lshl_b64 s[6:7], s[84:85], 11
	s_add_u32 s6, s69, s6
	s_mov_b32 s73, s93
	s_addc_u32 s7, s3, s7
	s_cmp_eq_u64 s[72:73], 0
	s_cselect_b32 s7, s41, s7
	v_and_b32_e32 v1, 63, v0
	v_bfe_u32 v2, v0, 4, 2
	s_cselect_b32 s6, s40, s6
	v_bitop3_b32 v4, v2, v0, 7 bitop3:0x78
	v_mov_b32_e32 v2, s7
	v_mov_b32_e32 v3, s42
	v_cmp_gt_u32_e64 s[42:43], 8, v1
	v_mov_b32_e32 v5, s64
	v_lshlrev_b32_e32 v200, 4, v4
	v_cndmask_b32_e64 v3, v2, v3, s[42:43]
	v_mov_b32_e32 v2, s6
	v_cndmask_b32_e64 v2, v2, v5, s[42:43]
	v_lshl_add_u64 v[98:99], v[2:3], 0, v[200:201]
	v_cmp_gt_u32_e64 s[42:43], 64, v0
	s_and_saveexec_b64 s[6:7], s[42:43]
	s_cbranch_execz .LBB0_168
	v_add_u32_e32 v2, 0x4000, v102
	s_nop 0
	v_readfirstlane_b32 s64, v2
	s_mov_b32 m0, s64
	s_nop 0
	global_load_lds_dwordx4 v[98:99], off
.LBB0_168:
	s_or_b64 exec, exec, s[6:7]
	v_add_u32_e32 v119, 0x8400, v102
	v_add_u32_e32 v115, 0xc800, v102
	v_readfirstlane_b32 s6, v119
	v_lshl_add_u64 v[2:3], v[82:83], 0, s[78:79]
	s_mov_b32 m0, s6
	v_readfirstlane_b32 s6, v115
	v_add_u32_e32 v117, 0x9400, v102
	s_waitcnt vmcnt(0)
	s_waitcnt vmcnt(0) lgkmcnt(0)
	s_barrier
	global_load_lds_dwordx4 v[2:3], off
	v_lshl_add_u64 v[2:3], v[84:85], 0, s[78:79]
	s_mov_b32 m0, s6
	v_readfirstlane_b32 s6, v117
	v_add_u32_e32 v118, 0xd800, v102
	global_load_lds_dwordx4 v[2:3], off sc1
	v_lshl_add_u64 v[2:3], v[86:87], 0, s[78:79]
	s_mov_b32 m0, s6
	v_readfirstlane_b32 s6, v118
	v_add_u32_e32 v116, 0xa400, v102
	global_load_lds_dwordx4 v[2:3], off
	v_lshl_add_u64 v[2:3], v[88:89], 0, s[78:79]
	s_mov_b32 m0, s6
	v_readfirstlane_b32 s6, v116
	v_add_u32_e32 v113, 0xe800, v102
	global_load_lds_dwordx4 v[2:3], off sc1
	v_lshl_add_u64 v[2:3], v[90:91], 0, s[78:79]
	s_mov_b32 m0, s6
	v_readfirstlane_b32 s6, v113
	v_add_u32_e32 v114, 0xb400, v102
	global_load_lds_dwordx4 v[2:3], off
	v_lshl_add_u64 v[2:3], v[92:93], 0, s[78:79]
	s_mov_b32 m0, s6
	v_readfirstlane_b32 s6, v114
	v_add_u32_e32 v112, 0xf800, v102
	global_load_lds_dwordx4 v[2:3], off sc1
	v_lshl_add_u64 v[2:3], v[94:95], 0, s[78:79]
	s_mov_b32 m0, s6
	v_readfirstlane_b32 s6, v112
	global_load_lds_dwordx4 v[2:3], off
	v_lshl_add_u64 v[2:3], v[96:97], 0, s[78:79]
	s_mov_b32 m0, s6
	s_nop 0
	global_load_lds_dwordx4 v[2:3], off sc1
	s_and_saveexec_b64 s[6:7], s[42:43]
	s_cbranch_execz .LBB0_170
	v_add_u32_e32 v4, 0xc400, v102
	v_lshl_add_u64 v[2:3], v[98:99], 0, s[78:79]
	v_readfirstlane_b32 s64, v4
	s_mov_b32 m0, s64
	s_nop 0
	global_load_lds_dwordx4 v[2:3], off
; #define MFMA(a, b, c) __builtin_amdgcn_mfma_f32_32x32x16_bf16(a, b, c, 0, 0, 0)
; #define ISSUE(k0, bf) do { char* A_ = lw + (bf) * BUF; \
;     _Pragma("unroll") for (int i_ = 0; i_ < 4; ++i_) { glds16(al.ptr(lrow + 32 * i_, (k0) + cg), A_ + i_ * 4096); glds16(bl.ptr(lrow + 32 * i_, (k0) + cg), A_ + ABYTES + i_ * 4096); } \
;     if (HALO) { if (wid == 0) glds16(gh + (k0), A_ + 16384); } } while (0)
; template <bool HALO, class AL, class BL>
; __device__ __forceinline__ void gemm_core(f32x16 (&acc)[2][2], f32x16& hacc, const AL& al, const BL& bl, int K, char* lds,
;                                           const u16* halo0, const u16* halo1, int brow0, int brow1) {
;     ...
;   for (int kt = 0; kt < nk; ++kt) {
;     asm volatile("s_waitcnt vmcnt(0)" ::: "memory");
;     __syncthreads();
;     if (kt + 1 < nk) ISSUE((kt + 1) * 64, (kt + 1) & 1);
;     const char* T = lds + (kt & 1) * BUF;
; #pragma unroll
;     for (int kk = 0; kk < 4; ++kk) {
;       const int c = kk * 2 + hi;
;       bf16x8 a0 = *(const bf16x8*)(T + oa + ((c ^ sa) << 4));
;       bf16x8 a1 = *(const bf16x8*)(T + oa + 4096 + ((c ^ sa) << 4));
;       bf16x8 b0 = *(const bf16x8*)(T + ob0 + ((c ^ sb0) << 4));
;       bf16x8 b1 = *(const bf16x8*)(T + ob1 + ((c ^ sb1) << 4));
;       acc[0][0] = MFMA(a0, b0, acc[0][0]); acc[0][1] = MFMA(a0, b1, acc[0][1]);
;       acc[1][0] = MFMA(a1, b0, acc[1][0]); acc[1][1] = MFMA(a1, b1, acc[1][1]);
;       if (HALO) { bf16x8 ah = *(const bf16x8*)(T + oh + ((c ^ sh) << 4)); hacc = MFMA(ah, b0, hacc); }
;     }
.LBB0_170:
	s_or_b64 exec, exec, s[6:7]
	v_lshrrev_b32_e32 v2, 1, v0
	v_lshrrev_b32_e32 v1, 5, v1
	v_bfe_u32 v3, v0, 1, 3
	v_bitop3_b32 v4, v1, v2, 7 bitop3:0x78
	v_lshlrev_b32_e32 v68, 4, v4
	v_bitop3_b32 v4, v1, v3, 2 bitop3:0x36
	v_lshlrev_b32_e32 v105, 4, v4
	v_bitop3_b32 v4, v1, v3, 4 bitop3:0x36
	v_bitop3_b32 v1, v1, v3, 6 bitop3:0x36
	v_and_b32_e32 v0, 31, v0
	v_lshlrev_b32_e32 v122, 4, v1
	v_and_or_b32 v1, v2, s94, v0
	v_or_b32_e32 v2, v0, v81
	v_lshl_add_u32 v121, v1, 7, 0
	v_lshl_add_u32 v146, v2, 7, 0
	v_add_u32_e32 v104, v121, v68
	v_add_u32_e32 v107, v146, v68
	v_lshlrev_b32_e32 v120, 4, v4
	v_lshl_add_u32 v147, v0, 7, 0
	ds_read_b128 v[0:3], v104
	ds_read_b128 v[4:7], v104 offset:4096
	ds_read_b128 v[64:67], v107 offset:17408
	ds_read_b128 v[8:11], v107 offset:25600
	v_add_u32_e32 v103, v147, v68
	s_waitcnt lgkmcnt(0)
	v_mfma_f32_32x32x16_bf16 v[48:63], v[0:3], v[64:67], 0
	ds_read_b128 v[68:71], v103 offset:16384
	v_add_u32_e32 v106, v121, v105
	v_add_u32_e32 v108, v146, v105
	ds_read_b128 v[130:133], v106
	ds_read_b128 v[134:137], v106 offset:4096
	ds_read_b128 v[138:141], v108 offset:17408
	ds_read_b128 v[142:145], v108 offset:25600
	v_add_u32_e32 v109, v147, v105
	v_add_u32_e32 v110, v121, v120
	v_mfma_f32_32x32x16_bf16 v[32:47], v[0:3], v[8:11], 0
	v_add_u32_e32 v111, v146, v120
	v_add_u32_e32 v105, v147, v120
	v_add_u32_e32 v120, v121, v122
	v_add_u32_e32 v121, v146, v122
	v_add_u32_e32 v122, v147, v122
	v_readfirstlane_b32 s6, v102
	s_mov_b32 m0, s6
	s_waitcnt lgkmcnt(0)
	v_mfma_f32_32x32x16_bf16 v[48:63], v[130:133], v[138:141], v[48:63]
	v_readfirstlane_b32 s6, v123
	v_mfma_f32_32x32x16_bf16 v[32:47], v[130:133], v[142:145], v[32:47]
	ds_read_b128 v[130:133], v109 offset:16384
	v_mfma_f32_32x32x16_bf16 v[16:31], v[4:7], v[64:67], 0
	v_mfma_f32_32x32x16_bf16 v[0:15], v[4:7], v[8:11], 0
	v_mfma_f32_32x32x16_bf16 v[64:79], v[68:71], v[64:67], 0
	v_mfma_f32_32x32x16_bf16 v[16:31], v[134:137], v[138:141], v[16:31]
	v_mfma_f32_32x32x16_bf16 v[0:15], v[134:137], v[142:145], v[0:15]
	s_waitcnt lgkmcnt(0)
	v_mfma_f32_32x32x16_bf16 v[64:79], v[130:133], v[138:141], v[64:79]
	ds_read_b128 v[130:133], v110
	ds_read_b128 v[134:137], v110 offset:4096
	ds_read_b128 v[138:141], v111 offset:17408
	ds_read_b128 v[142:145], v111 offset:25600
	s_waitcnt lgkmcnt(0)
	v_mfma_f32_32x32x16_bf16 v[48:63], v[130:133], v[138:141], v[48:63]
	v_mfma_f32_32x32x16_bf16 v[32:47], v[130:133], v[142:145], v[32:47]
	ds_read_b128 v[130:133], v105 offset:16384
	v_mfma_f32_32x32x16_bf16 v[16:31], v[134:137], v[138:141], v[16:31]
	v_mfma_f32_32x32x16_bf16 v[0:15], v[134:137], v[142:145], v[0:15]
	s_waitcnt lgkmcnt(0)
	v_mfma_f32_32x32x16_bf16 v[64:79], v[130:133], v[138:141], v[64:79]
	ds_read_b128 v[130:133], v120
	ds_read_b128 v[134:137], v120 offset:4096
	ds_read_b128 v[138:141], v121 offset:17408
	ds_read_b128 v[142:145], v121 offset:25600
	s_waitcnt lgkmcnt(0)
	v_mfma_f32_32x32x16_bf16 v[48:63], v[130:133], v[138:141], v[48:63]
	v_mfma_f32_32x32x16_bf16 v[32:47], v[130:133], v[142:145], v[32:47]
	ds_read_b128 v[130:133], v122 offset:16384
	s_waitcnt vmcnt(0)
	s_waitcnt vmcnt(0) lgkmcnt(0)
	s_barrier
	v_mfma_f32_32x32x16_bf16 v[64:79], v[130:133], v[138:141], v[64:79]
	v_lshl_add_u64 v[130:131], v[82:83], 0, s[24:25]
	global_load_lds_dwordx4 v[130:131], off
	v_lshl_add_u64 v[130:131], v[84:85], 0, s[24:25]
	s_mov_b32 m0, s6
	v_readfirstlane_b32 s6, v124
	global_load_lds_dwordx4 v[130:131], off sc1
	v_lshl_add_u64 v[130:131], v[86:87], 0, s[24:25]
	s_mov_b32 m0, s6
	v_readfirstlane_b32 s6, v125
	global_load_lds_dwordx4 v[130:131], off
	v_lshl_add_u64 v[130:131], v[88:89], 0, s[24:25]
	s_mov_b32 m0, s6
	v_readfirstlane_b32 s6, v126
	global_load_lds_dwordx4 v[130:131], off sc1
	v_lshl_add_u64 v[130:131], v[90:91], 0, s[24:25]
	s_mov_b32 m0, s6
	v_readfirstlane_b32 s6, v127
	global_load_lds_dwordx4 v[130:131], off
	v_lshl_add_u64 v[130:131], v[92:93], 0, s[24:25]
	s_mov_b32 m0, s6
	v_readfirstlane_b32 s6, v128
	global_load_lds_dwordx4 v[130:131], off sc1
	v_lshl_add_u64 v[130:131], v[94:95], 0, s[24:25]
	s_mov_b32 m0, s6
	v_readfirstlane_b32 s6, v129
	global_load_lds_dwordx4 v[130:131], off
	v_lshl_add_u64 v[130:131], v[96:97], 0, s[24:25]
	s_mov_b32 m0, s6
	v_mfma_f32_32x32x16_bf16 v[16:31], v[134:137], v[138:141], v[16:31]
	global_load_lds_dwordx4 v[130:131], off sc1
	v_mfma_f32_32x32x16_bf16 v[0:15], v[134:137], v[142:145], v[0:15]
	s_and_saveexec_b64 s[6:7], s[42:43]
	s_cbranch_execz .LBB0_172
	v_add_u32_e32 v132, 0x4000, v102
	v_lshl_add_u64 v[130:131], v[98:99], 0, s[24:25]
	v_readfirstlane_b32 s64, v132
	s_mov_b32 m0, s64
	s_nop 0
	global_load_lds_dwordx4 v[130:131], off
; #define MFMA(a, b, c) __builtin_amdgcn_mfma_f32_32x32x16_bf16(a, b, c, 0, 0, 0)
; #define ISSUE(k0, bf) do { char* A_ = lw + (bf) * BUF; \
;     _Pragma("unroll") for (int i_ = 0; i_ < 4; ++i_) { glds16(al.ptr(lrow + 32 * i_, (k0) + cg), A_ + i_ * 4096); glds16(bl.ptr(lrow + 32 * i_, (k0) + cg), A_ + ABYTES + i_ * 4096); } \
;     if (HALO) { if (wid == 0) glds16(gh + (k0), A_ + 16384); } } while (0)
; template <bool HALO, class AL, class BL>
; __device__ __forceinline__ void gemm_core(f32x16 (&acc)[2][2], f32x16& hacc, const AL& al, const BL& bl, int K, char* lds,
;                                           const u16* halo0, const u16* halo1, int brow0, int brow1) {
;     ...
;   for (int kt = 0; kt < nk; ++kt) {
;     asm volatile("s_waitcnt vmcnt(0)" ::: "memory");
;     __syncthreads();
;     if (kt + 1 < nk) ISSUE((kt + 1) * 64, (kt + 1) & 1);
;     const char* T = lds + (kt & 1) * BUF;
; #pragma unroll
;     for (int kk = 0; kk < 4; ++kk) {
;       const int c = kk * 2 + hi;
;       bf16x8 a0 = *(const bf16x8*)(T + oa + ((c ^ sa) << 4));
;       bf16x8 a1 = *(const bf16x8*)(T + oa + 4096 + ((c ^ sa) << 4));
;       bf16x8 b0 = *(const bf16x8*)(T + ob0 + ((c ^ sb0) << 4));
;       bf16x8 b1 = *(const bf16x8*)(T + ob1 + ((c ^ sb1) << 4));
;       acc[0][0] = MFMA(a0, b0, acc[0][0]); acc[0][1] = MFMA(a0, b1, acc[0][1]);
;       acc[1][0] = MFMA(a1, b0, acc[1][0]); acc[1][1] = MFMA(a1, b1, acc[1][1]);
;       if (HALO) { bf16x8 ah = *(const bf16x8*)(T + oh + ((c ^ sh) << 4)); hacc = MFMA(ah, b0, hacc); }
;     }
.LBB0_172:
	s_or_b64 exec, exec, s[6:7]
	ds_read_b128 v[130:133], v104 offset:33792
	ds_read_b128 v[134:137], v104 offset:37888
	ds_read_b128 v[138:141], v107 offset:51200
	ds_read_b128 v[142:145], v107 offset:59392
	v_readfirstlane_b32 s6, v119
	s_mov_b32 m0, s6
	v_readfirstlane_b32 s6, v115
	s_waitcnt lgkmcnt(0)
	v_mfma_f32_32x32x16_bf16 v[48:63], v[130:133], v[138:141], v[48:63]
	v_mfma_f32_32x32x16_bf16 v[32:47], v[130:133], v[142:145], v[32:47]
	ds_read_b128 v[130:133], v103 offset:50176
	v_mfma_f32_32x32x16_bf16 v[16:31], v[134:137], v[138:141], v[16:31]
	v_mfma_f32_32x32x16_bf16 v[0:15], v[134:137], v[142:145], v[0:15]
	s_waitcnt lgkmcnt(0)
	v_mfma_f32_32x32x16_bf16 v[64:79], v[130:133], v[138:141], v[64:79]
	ds_read_b128 v[130:133], v106 offset:33792
	ds_read_b128 v[134:137], v106 offset:37888
	ds_read_b128 v[138:141], v108 offset:51200
	ds_read_b128 v[142:145], v108 offset:59392
	s_waitcnt lgkmcnt(0)
	v_mfma_f32_32x32x16_bf16 v[48:63], v[130:133], v[138:141], v[48:63]
	v_mfma_f32_32x32x16_bf16 v[32:47], v[130:133], v[142:145], v[32:47]
	ds_read_b128 v[130:133], v109 offset:50176
	v_mfma_f32_32x32x16_bf16 v[16:31], v[134:137], v[138:141], v[16:31]
	v_mfma_f32_32x32x16_bf16 v[0:15], v[134:137], v[142:145], v[0:15]
	s_waitcnt lgkmcnt(0)
	v_mfma_f32_32x32x16_bf16 v[64:79], v[130:133], v[138:141], v[64:79]
	ds_read_b128 v[130:133], v110 offset:33792
	ds_read_b128 v[134:137], v110 offset:37888
	ds_read_b128 v[138:141], v111 offset:51200
	ds_read_b128 v[142:145], v111 offset:59392
	s_waitcnt lgkmcnt(0)
	v_mfma_f32_32x32x16_bf16 v[48:63], v[130:133], v[138:141], v[48:63]
	v_mfma_f32_32x32x16_bf16 v[32:47], v[130:133], v[142:145], v[32:47]
	ds_read_b128 v[130:133], v105 offset:50176
	v_mfma_f32_32x32x16_bf16 v[16:31], v[134:137], v[138:141], v[16:31]
	v_mfma_f32_32x32x16_bf16 v[0:15], v[134:137], v[142:145], v[0:15]
	s_waitcnt lgkmcnt(0)
	v_mfma_f32_32x32x16_bf16 v[64:79], v[130:133], v[138:141], v[64:79]
	ds_read_b128 v[130:133], v120 offset:33792
	ds_read_b128 v[134:137], v120 offset:37888
	ds_read_b128 v[138:141], v121 offset:51200
	ds_read_b128 v[142:145], v121 offset:59392
	s_waitcnt lgkmcnt(0)
	v_mfma_f32_32x32x16_bf16 v[48:63], v[130:133], v[138:141], v[48:63]
	v_mfma_f32_32x32x16_bf16 v[32:47], v[130:133], v[142:145], v[32:47]
	ds_read_b128 v[130:133], v122 offset:50176
	s_waitcnt vmcnt(0)
	s_waitcnt vmcnt(0) lgkmcnt(0)
	s_barrier
	v_mfma_f32_32x32x16_bf16 v[64:79], v[130:133], v[138:141], v[64:79]
	v_lshl_add_u64 v[130:131], v[82:83], 0, s[74:75]
	global_load_lds_dwordx4 v[130:131], off
	v_lshl_add_u64 v[130:131], v[84:85], 0, s[74:75]
	s_mov_b32 m0, s6
	v_readfirstlane_b32 s6, v117
	global_load_lds_dwordx4 v[130:131], off sc1
	v_lshl_add_u64 v[130:131], v[86:87], 0, s[74:75]
	s_mov_b32 m0, s6
	v_readfirstlane_b32 s6, v118
	global_load_lds_dwordx4 v[130:131], off
	v_lshl_add_u64 v[130:131], v[88:89], 0, s[74:75]
	s_mov_b32 m0, s6
	v_readfirstlane_b32 s6, v116
	global_load_lds_dwordx4 v[130:131], off sc1
	v_lshl_add_u64 v[130:131], v[90:91], 0, s[74:75]
	s_mov_b32 m0, s6
	v_readfirstlane_b32 s6, v113
	global_load_lds_dwordx4 v[130:131], off
	v_lshl_add_u64 v[130:131], v[92:93], 0, s[74:75]
	s_mov_b32 m0, s6
	v_readfirstlane_b32 s6, v114
	global_load_lds_dwordx4 v[130:131], off sc1
	v_lshl_add_u64 v[130:131], v[94:95], 0, s[74:75]
	s_mov_b32 m0, s6
	v_readfirstlane_b32 s6, v112
	global_load_lds_dwordx4 v[130:131], off
	v_lshl_add_u64 v[130:131], v[96:97], 0, s[74:75]
	s_mov_b32 m0, s6
	v_mfma_f32_32x32x16_bf16 v[16:31], v[134:137], v[138:141], v[16:31]
	global_load_lds_dwordx4 v[130:131], off sc1
	v_mfma_f32_32x32x16_bf16 v[0:15], v[134:137], v[142:145], v[0:15]
	s_and_saveexec_b64 s[6:7], s[42:43]
	s_cbranch_execz .LBB0_174
	v_add_u32_e32 v132, 0xc400, v102
	v_lshl_add_u64 v[130:131], v[98:99], 0, s[74:75]
	v_readfirstlane_b32 s64, v132
	s_mov_b32 m0, s64
	s_nop 0
	global_load_lds_dwordx4 v[130:131], off
.LBB0_174:
	s_or_b64 exec, exec, s[6:7]
	ds_read_b128 v[130:133], v104
	ds_read_b128 v[134:137], v104 offset:4096
	ds_read_b128 v[138:141], v107 offset:17408
	ds_read_b128 v[142:145], v107 offset:25600
	v_readfirstlane_b32 s6, v102
	s_mov_b32 m0, s6
	v_readfirstlane_b32 s6, v123
	s_waitcnt lgkmcnt(0)
	v_mfma_f32_32x32x16_bf16 v[48:63], v[130:133], v[138:141], v[48:63]
	v_mfma_f32_32x32x16_bf16 v[32:47], v[130:133], v[142:145], v[32:47]
	ds_read_b128 v[130:133], v103 offset:16384
	v_mfma_f32_32x32x16_bf16 v[16:31], v[134:137], v[138:141], v[16:31]
	v_mfma_f32_32x32x16_bf16 v[0:15], v[134:137], v[142:145], v[0:15]
	s_waitcnt lgkmcnt(0)
	v_mfma_f32_32x32x16_bf16 v[64:79], v[130:133], v[138:141], v[64:79]
	ds_read_b128 v[130:133], v106
	ds_read_b128 v[134:137], v106 offset:4096
	ds_read_b128 v[138:141], v108 offset:17408
	ds_read_b128 v[142:145], v108 offset:25600
	s_waitcnt lgkmcnt(0)
	v_mfma_f32_32x32x16_bf16 v[48:63], v[130:133], v[138:141], v[48:63]
	v_mfma_f32_32x32x16_bf16 v[32:47], v[130:133], v[142:145], v[32:47]
	ds_read_b128 v[130:133], v109 offset:16384
	v_mfma_f32_32x32x16_bf16 v[16:31], v[134:137], v[138:141], v[16:31]
	v_mfma_f32_32x32x16_bf16 v[0:15], v[134:137], v[142:145], v[0:15]
	s_waitcnt lgkmcnt(0)
	v_mfma_f32_32x32x16_bf16 v[64:79], v[130:133], v[138:141], v[64:79]
	ds_read_b128 v[130:133], v110
	ds_read_b128 v[134:137], v110 offset:4096
	ds_read_b128 v[138:141], v111 offset:17408
	ds_read_b128 v[142:145], v111 offset:25600
	s_waitcnt lgkmcnt(0)
	v_mfma_f32_32x32x16_bf16 v[48:63], v[130:133], v[138:141], v[48:63]
	v_mfma_f32_32x32x16_bf16 v[32:47], v[130:133], v[142:145], v[32:47]
	ds_read_b128 v[130:133], v105 offset:16384
	v_mfma_f32_32x32x16_bf16 v[16:31], v[134:137], v[138:141], v[16:31]
	v_mfma_f32_32x32x16_bf16 v[0:15], v[134:137], v[142:145], v[0:15]
	s_waitcnt lgkmcnt(0)
	v_mfma_f32_32x32x16_bf16 v[64:79], v[130:133], v[138:141], v[64:79]
	ds_read_b128 v[130:133], v120
	ds_read_b128 v[134:137], v120 offset:4096
	ds_read_b128 v[138:141], v121 offset:17408
	ds_read_b128 v[142:145], v121 offset:25600
	s_waitcnt lgkmcnt(0)
	v_mfma_f32_32x32x16_bf16 v[48:63], v[130:133], v[138:141], v[48:63]
	v_mfma_f32_32x32x16_bf16 v[32:47], v[130:133], v[142:145], v[32:47]
	ds_read_b128 v[130:133], v122 offset:16384
	s_waitcnt vmcnt(0)
	s_waitcnt vmcnt(0) lgkmcnt(0)
	s_barrier
; #define MFMA(a, b, c) __builtin_amdgcn_mfma_f32_32x32x16_bf16(a, b, c, 0, 0, 0)
; #define ISSUE(k0, bf) do { char* A_ = lw + (bf) * BUF; \
;     _Pragma("unroll") for (int i_ = 0; i_ < 4; ++i_) { glds16(al.ptr(lrow + 32 * i_, (k0) + cg), A_ + i_ * 4096); glds16(bl.ptr(lrow + 32 * i_, (k0) + cg), A_ + ABYTES + i_ * 4096); } \
;     if (HALO) { if (wid == 0) glds16(gh + (k0), A_ + 16384); } } while (0)
; template <bool HALO, class AL, class BL>
; __device__ __forceinline__ void gemm_core(f32x16 (&acc)[2][2], f32x16& hacc, const AL& al, const BL& bl, int K, char* lds,
;                                           const u16* halo0, const u16* halo1, int brow0, int brow1) {
;     ...
;   for (int kt = 0; kt < nk; ++kt) {
;     asm volatile("s_waitcnt vmcnt(0)" ::: "memory");
;     __syncthreads();
;     if (kt + 1 < nk) ISSUE((kt + 1) * 64, (kt + 1) & 1);
;     const char* T = lds + (kt & 1) * BUF;
; #pragma unroll
;     for (int kk = 0; kk < 4; ++kk) {
;       const int c = kk * 2 + hi;
;       bf16x8 a0 = *(const bf16x8*)(T + oa + ((c ^ sa) << 4));
;       bf16x8 a1 = *(const bf16x8*)(T + oa + 4096 + ((c ^ sa) << 4));
;       bf16x8 b0 = *(const bf16x8*)(T + ob0 + ((c ^ sb0) << 4));
;       bf16x8 b1 = *(const bf16x8*)(T + ob1 + ((c ^ sb1) << 4));
;       acc[0][0] = MFMA(a0, b0, acc[0][0]); acc[0][1] = MFMA(a0, b1, acc[0][1]);
;       acc[1][0] = MFMA(a1, b0, acc[1][0]); acc[1][1] = MFMA(a1, b1, acc[1][1]);
;       if (HALO) { bf16x8 ah = *(const bf16x8*)(T + oh + ((c ^ sh) << 4)); hacc = MFMA(ah, b0, hacc); }
;     }
	v_mfma_f32_32x32x16_bf16 v[64:79], v[130:133], v[138:141], v[64:79]
	v_lshl_add_u64 v[130:131], v[82:83], 0, s[20:21]
	global_load_lds_dwordx4 v[130:131], off
	v_lshl_add_u64 v[130:131], v[84:85], 0, s[20:21]
	s_mov_b32 m0, s6
	v_readfirstlane_b32 s6, v124
	global_load_lds_dwordx4 v[130:131], off sc1
	v_lshl_add_u64 v[130:131], v[86:87], 0, s[20:21]
	s_mov_b32 m0, s6
	v_readfirstlane_b32 s6, v125
	global_load_lds_dwordx4 v[130:131], off
	v_lshl_add_u64 v[130:131], v[88:89], 0, s[20:21]
	s_mov_b32 m0, s6
	v_readfirstlane_b32 s6, v126
	global_load_lds_dwordx4 v[130:131], off sc1
	v_lshl_add_u64 v[130:131], v[90:91], 0, s[20:21]
	s_mov_b32 m0, s6
	v_readfirstlane_b32 s6, v127
	global_load_lds_dwordx4 v[130:131], off
	v_lshl_add_u64 v[130:131], v[92:93], 0, s[20:21]
	s_mov_b32 m0, s6
	v_readfirstlane_b32 s6, v128
	global_load_lds_dwordx4 v[130:131], off sc1
	v_lshl_add_u64 v[130:131], v[94:95], 0, s[20:21]
	s_mov_b32 m0, s6
	v_readfirstlane_b32 s6, v129
	global_load_lds_dwordx4 v[130:131], off
	v_lshl_add_u64 v[130:131], v[96:97], 0, s[20:21]
	s_mov_b32 m0, s6
	v_mfma_f32_32x32x16_bf16 v[16:31], v[134:137], v[138:141], v[16:31]
	global_load_lds_dwordx4 v[130:131], off sc1
	v_mfma_f32_32x32x16_bf16 v[0:15], v[134:137], v[142:145], v[0:15]
	s_and_saveexec_b64 s[6:7], s[42:43]
	s_cbranch_execz .LBB0_176
	v_add_u32_e32 v132, 0x4000, v102
	v_lshl_add_u64 v[130:131], v[98:99], 0, s[20:21]
	v_readfirstlane_b32 s64, v132
	s_mov_b32 m0, s64
	s_nop 0
	global_load_lds_dwordx4 v[130:131], off
.LBB0_176:
	s_or_b64 exec, exec, s[6:7]
	ds_read_b128 v[130:133], v104 offset:33792
	ds_read_b128 v[134:137], v104 offset:37888
	ds_read_b128 v[138:141], v107 offset:51200
	ds_read_b128 v[142:145], v107 offset:59392
	v_readfirstlane_b32 s6, v119
	s_mov_b32 m0, s6
	v_readfirstlane_b32 s6, v115
	s_waitcnt lgkmcnt(0)
	v_mfma_f32_32x32x16_bf16 v[48:63], v[130:133], v[138:141], v[48:63]
	v_mfma_f32_32x32x16_bf16 v[32:47], v[130:133], v[142:145], v[32:47]
	ds_read_b128 v[130:133], v103 offset:50176
	v_mfma_f32_32x32x16_bf16 v[16:31], v[134:137], v[138:141], v[16:31]
	v_mfma_f32_32x32x16_bf16 v[0:15], v[134:137], v[142:145], v[0:15]
	s_waitcnt lgkmcnt(0)
	v_mfma_f32_32x32x16_bf16 v[64:79], v[130:133], v[138:141], v[64:79]
	ds_read_b128 v[130:133], v106 offset:33792
	ds_read_b128 v[134:137], v106 offset:37888
	ds_read_b128 v[138:141], v108 offset:51200
	ds_read_b128 v[142:145], v108 offset:59392
	s_waitcnt lgkmcnt(0)
	v_mfma_f32_32x32x16_bf16 v[48:63], v[130:133], v[138:141], v[48:63]
	v_mfma_f32_32x32x16_bf16 v[32:47], v[130:133], v[142:145], v[32:47]
	ds_read_b128 v[130:133], v109 offset:50176
	v_mfma_f32_32x32x16_bf16 v[16:31], v[134:137], v[138:141], v[16:31]
	v_mfma_f32_32x32x16_bf16 v[0:15], v[134:137], v[142:145], v[0:15]
	s_waitcnt lgkmcnt(0)
	v_mfma_f32_32x32x16_bf16 v[64:79], v[130:133], v[138:141], v[64:79]
	ds_read_b128 v[130:133], v110 offset:33792
	ds_read_b128 v[134:137], v110 offset:37888
	ds_read_b128 v[138:141], v111 offset:51200
	ds_read_b128 v[142:145], v111 offset:59392
	s_waitcnt lgkmcnt(0)
	v_mfma_f32_32x32x16_bf16 v[48:63], v[130:133], v[138:141], v[48:63]
	v_mfma_f32_32x32x16_bf16 v[32:47], v[130:133], v[142:145], v[32:47]
	ds_read_b128 v[130:133], v105 offset:50176
	v_mfma_f32_32x32x16_bf16 v[16:31], v[134:137], v[138:141], v[16:31]
	v_mfma_f32_32x32x16_bf16 v[0:15], v[134:137], v[142:145], v[0:15]
	s_waitcnt lgkmcnt(0)
	v_mfma_f32_32x32x16_bf16 v[64:79], v[130:133], v[138:141], v[64:79]
	ds_read_b128 v[130:133], v120 offset:33792
	ds_read_b128 v[134:137], v120 offset:37888
	ds_read_b128 v[138:141], v121 offset:51200
	ds_read_b128 v[142:145], v121 offset:59392
	s_waitcnt lgkmcnt(0)
	v_mfma_f32_32x32x16_bf16 v[48:63], v[130:133], v[138:141], v[48:63]
	v_mfma_f32_32x32x16_bf16 v[32:47], v[130:133], v[142:145], v[32:47]
	ds_read_b128 v[130:133], v122 offset:50176
	s_waitcnt vmcnt(0)
	s_waitcnt vmcnt(0) lgkmcnt(0)
	s_barrier
	v_mfma_f32_32x32x16_bf16 v[64:79], v[130:133], v[138:141], v[64:79]
	v_lshl_add_u64 v[130:131], v[82:83], 0, s[86:87]
	global_load_lds_dwordx4 v[130:131], off
	v_lshl_add_u64 v[130:131], v[84:85], 0, s[86:87]
	s_mov_b32 m0, s6
	v_readfirstlane_b32 s6, v117
	global_load_lds_dwordx4 v[130:131], off sc1
	v_lshl_add_u64 v[130:131], v[86:87], 0, s[86:87]
	s_mov_b32 m0, s6
	v_readfirstlane_b32 s6, v118
	global_load_lds_dwordx4 v[130:131], off
	v_lshl_add_u64 v[130:131], v[88:89], 0, s[86:87]
	s_mov_b32 m0, s6
	v_readfirstlane_b32 s6, v116
	global_load_lds_dwordx4 v[130:131], off sc1
	v_lshl_add_u64 v[130:131], v[90:91], 0, s[86:87]
	s_mov_b32 m0, s6
	v_readfirstlane_b32 s6, v113
	global_load_lds_dwordx4 v[130:131], off
	v_lshl_add_u64 v[130:131], v[92:93], 0, s[86:87]
	s_mov_b32 m0, s6
	v_readfirstlane_b32 s6, v114
	global_load_lds_dwordx4 v[130:131], off sc1
	v_lshl_add_u64 v[130:131], v[94:95], 0, s[86:87]
	s_mov_b32 m0, s6
	v_readfirstlane_b32 s6, v112
	global_load_lds_dwordx4 v[130:131], off
	v_lshl_add_u64 v[130:131], v[96:97], 0, s[86:87]
	s_mov_b32 m0, s6
	v_mfma_f32_32x32x16_bf16 v[16:31], v[134:137], v[138:141], v[16:31]
	global_load_lds_dwordx4 v[130:131], off sc1
	v_mfma_f32_32x32x16_bf16 v[0:15], v[134:137], v[142:145], v[0:15]
	s_and_saveexec_b64 s[6:7], s[42:43]
	s_cbranch_execz .LBB0_178
	v_add_u32_e32 v132, 0xc400, v102
	v_lshl_add_u64 v[130:131], v[98:99], 0, s[86:87]
	v_readfirstlane_b32 s64, v132
	s_mov_b32 m0, s64
	s_nop 0
	global_load_lds_dwordx4 v[130:131], off
; #define MFMA(a, b, c) __builtin_amdgcn_mfma_f32_32x32x16_bf16(a, b, c, 0, 0, 0)
; #define ISSUE(k0, bf) do { char* A_ = lw + (bf) * BUF; \
;     _Pragma("unroll") for (int i_ = 0; i_ < 4; ++i_) { glds16(al.ptr(lrow + 32 * i_, (k0) + cg), A_ + i_ * 4096); glds16(bl.ptr(lrow + 32 * i_, (k0) + cg), A_ + ABYTES + i_ * 4096); } \
;     if (HALO) { if (wid == 0) glds16(gh + (k0), A_ + 16384); } } while (0)
; template <bool HALO, class AL, class BL>
; __device__ __forceinline__ void gemm_core(f32x16 (&acc)[2][2], f32x16& hacc, const AL& al, const BL& bl, int K, char* lds,
;                                           const u16* halo0, const u16* halo1, int brow0, int brow1) {
;     ...
;   for (int kt = 0; kt < nk; ++kt) {
;     asm volatile("s_waitcnt vmcnt(0)" ::: "memory");
;     __syncthreads();
;     if (kt + 1 < nk) ISSUE((kt + 1) * 64, (kt + 1) & 1);
;     const char* T = lds + (kt & 1) * BUF;
; #pragma unroll
;     for (int kk = 0; kk < 4; ++kk) {
;       const int c = kk * 2 + hi;
;       bf16x8 a0 = *(const bf16x8*)(T + oa + ((c ^ sa) << 4));
;       bf16x8 a1 = *(const bf16x8*)(T + oa + 4096 + ((c ^ sa) << 4));
;       bf16x8 b0 = *(const bf16x8*)(T + ob0 + ((c ^ sb0) << 4));
;       bf16x8 b1 = *(const bf16x8*)(T + ob1 + ((c ^ sb1) << 4));
;       acc[0][0] = MFMA(a0, b0, acc[0][0]); acc[0][1] = MFMA(a0, b1, acc[0][1]);
;       acc[1][0] = MFMA(a1, b0, acc[1][0]); acc[1][1] = MFMA(a1, b1, acc[1][1]);
;       if (HALO) { bf16x8 ah = *(const bf16x8*)(T + oh + ((c ^ sh) << 4)); hacc = MFMA(ah, b0, hacc); }
;     }
.LBB0_178:
	s_or_b64 exec, exec, s[6:7]
	ds_read_b128 v[130:133], v104
	ds_read_b128 v[134:137], v104 offset:4096
	ds_read_b128 v[138:141], v107 offset:17408
	ds_read_b128 v[142:145], v107 offset:25600
	v_readfirstlane_b32 s6, v102
	s_mov_b32 m0, s6
	v_readfirstlane_b32 s6, v123
	s_waitcnt lgkmcnt(0)
	v_mfma_f32_32x32x16_bf16 v[48:63], v[130:133], v[138:141], v[48:63]
	v_mfma_f32_32x32x16_bf16 v[32:47], v[130:133], v[142:145], v[32:47]
	ds_read_b128 v[130:133], v103 offset:16384
	v_mfma_f32_32x32x16_bf16 v[16:31], v[134:137], v[138:141], v[16:31]
	v_mfma_f32_32x32x16_bf16 v[0:15], v[134:137], v[142:145], v[0:15]
	s_waitcnt lgkmcnt(0)
	v_mfma_f32_32x32x16_bf16 v[64:79], v[130:133], v[138:141], v[64:79]
	ds_read_b128 v[130:133], v106
	ds_read_b128 v[134:137], v106 offset:4096
	ds_read_b128 v[138:141], v108 offset:17408
	ds_read_b128 v[142:145], v108 offset:25600
	s_waitcnt lgkmcnt(0)
	v_mfma_f32_32x32x16_bf16 v[48:63], v[130:133], v[138:141], v[48:63]
	v_mfma_f32_32x32x16_bf16 v[32:47], v[130:133], v[142:145], v[32:47]
	ds_read_b128 v[130:133], v109 offset:16384
	v_mfma_f32_32x32x16_bf16 v[16:31], v[134:137], v[138:141], v[16:31]
	v_mfma_f32_32x32x16_bf16 v[0:15], v[134:137], v[142:145], v[0:15]
	s_waitcnt lgkmcnt(0)
	v_mfma_f32_32x32x16_bf16 v[64:79], v[130:133], v[138:141], v[64:79]
	ds_read_b128 v[130:133], v110
	ds_read_b128 v[134:137], v110 offset:4096
	ds_read_b128 v[138:141], v111 offset:17408
	ds_read_b128 v[142:145], v111 offset:25600
	s_waitcnt lgkmcnt(0)
	v_mfma_f32_32x32x16_bf16 v[48:63], v[130:133], v[138:141], v[48:63]
	v_mfma_f32_32x32x16_bf16 v[32:47], v[130:133], v[142:145], v[32:47]
	ds_read_b128 v[130:133], v105 offset:16384
	v_mfma_f32_32x32x16_bf16 v[16:31], v[134:137], v[138:141], v[16:31]
	v_mfma_f32_32x32x16_bf16 v[0:15], v[134:137], v[142:145], v[0:15]
	s_waitcnt lgkmcnt(0)
	v_mfma_f32_32x32x16_bf16 v[64:79], v[130:133], v[138:141], v[64:79]
	ds_read_b128 v[130:133], v120
	ds_read_b128 v[134:137], v120 offset:4096
	ds_read_b128 v[138:141], v121 offset:17408
	ds_read_b128 v[142:145], v121 offset:25600
	s_waitcnt lgkmcnt(0)
	v_mfma_f32_32x32x16_bf16 v[48:63], v[130:133], v[138:141], v[48:63]
	v_mfma_f32_32x32x16_bf16 v[32:47], v[130:133], v[142:145], v[32:47]
	ds_read_b128 v[130:133], v122 offset:16384
	s_waitcnt vmcnt(0)
	s_waitcnt vmcnt(0) lgkmcnt(0)
	s_barrier
	v_mfma_f32_32x32x16_bf16 v[64:79], v[130:133], v[138:141], v[64:79]
	v_lshl_add_u64 v[130:131], v[82:83], 0, s[30:31]
	global_load_lds_dwordx4 v[130:131], off
	v_lshl_add_u64 v[130:131], v[84:85], 0, s[30:31]
	s_mov_b32 m0, s6
	v_readfirstlane_b32 s6, v124
	global_load_lds_dwordx4 v[130:131], off sc1
	v_lshl_add_u64 v[130:131], v[86:87], 0, s[30:31]
	s_mov_b32 m0, s6
	v_readfirstlane_b32 s6, v125
	global_load_lds_dwordx4 v[130:131], off
	v_lshl_add_u64 v[130:131], v[88:89], 0, s[30:31]
	s_mov_b32 m0, s6
	v_readfirstlane_b32 s6, v126
	global_load_lds_dwordx4 v[130:131], off sc1
	v_lshl_add_u64 v[130:131], v[90:91], 0, s[30:31]
	s_mov_b32 m0, s6
	v_readfirstlane_b32 s6, v127
	global_load_lds_dwordx4 v[130:131], off
	v_lshl_add_u64 v[130:131], v[92:93], 0, s[30:31]
	s_mov_b32 m0, s6
	v_readfirstlane_b32 s6, v128
	global_load_lds_dwordx4 v[130:131], off sc1
	v_lshl_add_u64 v[130:131], v[94:95], 0, s[30:31]
	s_mov_b32 m0, s6
	v_readfirstlane_b32 s6, v129
	global_load_lds_dwordx4 v[130:131], off
	v_lshl_add_u64 v[130:131], v[96:97], 0, s[30:31]
	s_mov_b32 m0, s6
	v_mfma_f32_32x32x16_bf16 v[16:31], v[134:137], v[138:141], v[16:31]
	global_load_lds_dwordx4 v[130:131], off sc1
	v_mfma_f32_32x32x16_bf16 v[0:15], v[134:137], v[142:145], v[0:15]
	s_and_saveexec_b64 s[6:7], s[42:43]
	s_cbranch_execz .LBB0_180
	v_add_u32_e32 v132, 0x4000, v102
	v_lshl_add_u64 v[130:131], v[98:99], 0, s[30:31]
	v_readfirstlane_b32 s64, v132
	s_mov_b32 m0, s64
	s_nop 0
	global_load_lds_dwordx4 v[130:131], off
.LBB0_180:
	s_or_b64 exec, exec, s[6:7]
	ds_read_b128 v[130:133], v104 offset:33792
	ds_read_b128 v[134:137], v104 offset:37888
	ds_read_b128 v[138:141], v107 offset:51200
	ds_read_b128 v[142:145], v107 offset:59392
	v_readfirstlane_b32 s6, v119
	s_mov_b32 m0, s6
	v_readfirstlane_b32 s6, v115
	s_waitcnt lgkmcnt(0)
	v_mfma_f32_32x32x16_bf16 v[48:63], v[130:133], v[138:141], v[48:63]
	v_mfma_f32_32x32x16_bf16 v[32:47], v[130:133], v[142:145], v[32:47]
	ds_read_b128 v[130:133], v103 offset:50176
	v_mfma_f32_32x32x16_bf16 v[16:31], v[134:137], v[138:141], v[16:31]
	v_mfma_f32_32x32x16_bf16 v[0:15], v[134:137], v[142:145], v[0:15]
	s_waitcnt lgkmcnt(0)
	v_mfma_f32_32x32x16_bf16 v[64:79], v[130:133], v[138:141], v[64:79]
	ds_read_b128 v[130:133], v106 offset:33792
	ds_read_b128 v[134:137], v106 offset:37888
	ds_read_b128 v[138:141], v108 offset:51200
	ds_read_b128 v[142:145], v108 offset:59392
	s_waitcnt lgkmcnt(0)
	v_mfma_f32_32x32x16_bf16 v[48:63], v[130:133], v[138:141], v[48:63]
	v_mfma_f32_32x32x16_bf16 v[32:47], v[130:133], v[142:145], v[32:47]
	ds_read_b128 v[130:133], v109 offset:50176
	v_mfma_f32_32x32x16_bf16 v[16:31], v[134:137], v[138:141], v[16:31]
	v_mfma_f32_32x32x16_bf16 v[0:15], v[134:137], v[142:145], v[0:15]
	s_waitcnt lgkmcnt(0)
	v_mfma_f32_32x32x16_bf16 v[64:79], v[130:133], v[138:141], v[64:79]
	ds_read_b128 v[130:133], v110 offset:33792
	ds_read_b128 v[134:137], v110 offset:37888
	ds_read_b128 v[138:141], v111 offset:51200
	ds_read_b128 v[142:145], v111 offset:59392
	s_waitcnt lgkmcnt(0)
	v_mfma_f32_32x32x16_bf16 v[48:63], v[130:133], v[138:141], v[48:63]
	v_mfma_f32_32x32x16_bf16 v[32:47], v[130:133], v[142:145], v[32:47]
	ds_read_b128 v[130:133], v105 offset:50176
	v_mfma_f32_32x32x16_bf16 v[16:31], v[134:137], v[138:141], v[16:31]
	v_mfma_f32_32x32x16_bf16 v[0:15], v[134:137], v[142:145], v[0:15]
	s_waitcnt lgkmcnt(0)
	v_mfma_f32_32x32x16_bf16 v[64:79], v[130:133], v[138:141], v[64:79]
	ds_read_b128 v[130:133], v120 offset:33792
	ds_read_b128 v[134:137], v120 offset:37888
	ds_read_b128 v[138:141], v121 offset:51200
	ds_read_b128 v[142:145], v121 offset:59392
	s_waitcnt lgkmcnt(0)
	v_mfma_f32_32x32x16_bf16 v[48:63], v[130:133], v[138:141], v[48:63]
	v_mfma_f32_32x32x16_bf16 v[32:47], v[130:133], v[142:145], v[32:47]
	ds_read_b128 v[130:133], v122 offset:50176
	s_waitcnt vmcnt(0)
	s_waitcnt vmcnt(0) lgkmcnt(0)
	s_barrier
; #define MFMA(a, b, c) __builtin_amdgcn_mfma_f32_32x32x16_bf16(a, b, c, 0, 0, 0)
; #define ISSUE(k0, bf) do { char* A_ = lw + (bf) * BUF; \
;     _Pragma("unroll") for (int i_ = 0; i_ < 4; ++i_) { glds16(al.ptr(lrow + 32 * i_, (k0) + cg), A_ + i_ * 4096); glds16(bl.ptr(lrow + 32 * i_, (k0) + cg), A_ + ABYTES + i_ * 4096); } \
;     if (HALO) { if (wid == 0) glds16(gh + (k0), A_ + 16384); } } while (0)
; template <bool HALO, class AL, class BL>
; __device__ __forceinline__ void gemm_core(f32x16 (&acc)[2][2], f32x16& hacc, const AL& al, const BL& bl, int K, char* lds,
;                                           const u16* halo0, const u16* halo1, int brow0, int brow1) {
;     ...
;   for (int kt = 0; kt < nk; ++kt) {
;     asm volatile("s_waitcnt vmcnt(0)" ::: "memory");
;     __syncthreads();
;     if (kt + 1 < nk) ISSUE((kt + 1) * 64, (kt + 1) & 1);
;     const char* T = lds + (kt & 1) * BUF;
; #pragma unroll
;     for (int kk = 0; kk < 4; ++kk) {
;       const int c = kk * 2 + hi;
;       bf16x8 a0 = *(const bf16x8*)(T + oa + ((c ^ sa) << 4));
;       bf16x8 a1 = *(const bf16x8*)(T + oa + 4096 + ((c ^ sa) << 4));
;       bf16x8 b0 = *(const bf16x8*)(T + ob0 + ((c ^ sb0) << 4));
;       bf16x8 b1 = *(const bf16x8*)(T + ob1 + ((c ^ sb1) << 4));
;       acc[0][0] = MFMA(a0, b0, acc[0][0]); acc[0][1] = MFMA(a0, b1, acc[0][1]);
;       acc[1][0] = MFMA(a1, b0, acc[1][0]); acc[1][1] = MFMA(a1, b1, acc[1][1]);
;       if (HALO) { bf16x8 ah = *(const bf16x8*)(T + oh + ((c ^ sh) << 4)); hacc = MFMA(ah, b0, hacc); }
;     }
	v_mfma_f32_32x32x16_bf16 v[64:79], v[130:133], v[138:141], v[64:79]
	v_lshl_add_u64 v[130:131], v[82:83], 0, s[4:5]
	global_load_lds_dwordx4 v[130:131], off
	v_lshl_add_u64 v[130:131], v[84:85], 0, s[4:5]
	s_mov_b32 m0, s6
	v_readfirstlane_b32 s6, v117
	global_load_lds_dwordx4 v[130:131], off sc1
	v_lshl_add_u64 v[130:131], v[86:87], 0, s[4:5]
	s_mov_b32 m0, s6
	v_readfirstlane_b32 s6, v118
	global_load_lds_dwordx4 v[130:131], off
	v_lshl_add_u64 v[130:131], v[88:89], 0, s[4:5]
	s_mov_b32 m0, s6
	v_readfirstlane_b32 s6, v116
	global_load_lds_dwordx4 v[130:131], off sc1
	v_lshl_add_u64 v[130:131], v[90:91], 0, s[4:5]
	s_mov_b32 m0, s6
	v_readfirstlane_b32 s6, v113
	global_load_lds_dwordx4 v[130:131], off
	v_lshl_add_u64 v[130:131], v[92:93], 0, s[4:5]
	s_mov_b32 m0, s6
	v_readfirstlane_b32 s6, v114
	global_load_lds_dwordx4 v[130:131], off sc1
	v_lshl_add_u64 v[130:131], v[94:95], 0, s[4:5]
	s_mov_b32 m0, s6
	v_readfirstlane_b32 s6, v112
	global_load_lds_dwordx4 v[130:131], off
	v_lshl_add_u64 v[130:131], v[96:97], 0, s[4:5]
	s_mov_b32 m0, s6
	v_mfma_f32_32x32x16_bf16 v[16:31], v[134:137], v[138:141], v[16:31]
	global_load_lds_dwordx4 v[130:131], off sc1
	v_mfma_f32_32x32x16_bf16 v[0:15], v[134:137], v[142:145], v[0:15]
	s_and_saveexec_b64 s[6:7], s[42:43]
	s_cbranch_execz .LBB0_182
	v_add_u32_e32 v132, 0xc400, v102
	v_lshl_add_u64 v[130:131], v[98:99], 0, s[4:5]
	v_readfirstlane_b32 s64, v132
	s_mov_b32 m0, s64
	s_nop 0
	global_load_lds_dwordx4 v[130:131], off
.LBB0_182:
	s_or_b64 exec, exec, s[6:7]
	ds_read_b128 v[130:133], v104
	ds_read_b128 v[134:137], v104 offset:4096
	ds_read_b128 v[138:141], v107 offset:17408
	ds_read_b128 v[142:145], v107 offset:25600
	v_readfirstlane_b32 s6, v102
	s_mov_b32 m0, s6
	v_readfirstlane_b32 s6, v123
	s_waitcnt lgkmcnt(0)
	v_mfma_f32_32x32x16_bf16 v[48:63], v[130:133], v[138:141], v[48:63]
	v_mfma_f32_32x32x16_bf16 v[32:47], v[130:133], v[142:145], v[32:47]
	ds_read_b128 v[130:133], v103 offset:16384
	v_mfma_f32_32x32x16_bf16 v[16:31], v[134:137], v[138:141], v[16:31]
	v_mfma_f32_32x32x16_bf16 v[0:15], v[134:137], v[142:145], v[0:15]
	s_waitcnt lgkmcnt(0)
	v_mfma_f32_32x32x16_bf16 v[64:79], v[130:133], v[138:141], v[64:79]
	ds_read_b128 v[130:133], v106
	ds_read_b128 v[134:137], v106 offset:4096
	ds_read_b128 v[138:141], v108 offset:17408
	ds_read_b128 v[142:145], v108 offset:25600
	s_waitcnt lgkmcnt(0)
	v_mfma_f32_32x32x16_bf16 v[48:63], v[130:133], v[138:141], v[48:63]
	v_mfma_f32_32x32x16_bf16 v[32:47], v[130:133], v[142:145], v[32:47]
	ds_read_b128 v[130:133], v109 offset:16384
	v_mfma_f32_32x32x16_bf16 v[16:31], v[134:137], v[138:141], v[16:31]
	v_mfma_f32_32x32x16_bf16 v[0:15], v[134:137], v[142:145], v[0:15]
	s_waitcnt lgkmcnt(0)
	v_mfma_f32_32x32x16_bf16 v[64:79], v[130:133], v[138:141], v[64:79]
	ds_read_b128 v[130:133], v110
	ds_read_b128 v[134:137], v110 offset:4096
	ds_read_b128 v[138:141], v111 offset:17408
	ds_read_b128 v[142:145], v111 offset:25600
	s_waitcnt lgkmcnt(0)
	v_mfma_f32_32x32x16_bf16 v[48:63], v[130:133], v[138:141], v[48:63]
	v_mfma_f32_32x32x16_bf16 v[32:47], v[130:133], v[142:145], v[32:47]
	ds_read_b128 v[130:133], v105 offset:16384
	v_mfma_f32_32x32x16_bf16 v[16:31], v[134:137], v[138:141], v[16:31]
	v_mfma_f32_32x32x16_bf16 v[0:15], v[134:137], v[142:145], v[0:15]
	s_waitcnt lgkmcnt(0)
	v_mfma_f32_32x32x16_bf16 v[64:79], v[130:133], v[138:141], v[64:79]
	ds_read_b128 v[130:133], v120
	ds_read_b128 v[134:137], v120 offset:4096
	ds_read_b128 v[138:141], v121 offset:17408
	ds_read_b128 v[142:145], v121 offset:25600
	s_waitcnt lgkmcnt(0)
	v_mfma_f32_32x32x16_bf16 v[48:63], v[130:133], v[138:141], v[48:63]
	v_mfma_f32_32x32x16_bf16 v[32:47], v[130:133], v[142:145], v[32:47]
	ds_read_b128 v[130:133], v122 offset:16384
	s_waitcnt vmcnt(0)
	s_waitcnt vmcnt(0) lgkmcnt(0)
	s_barrier
	v_mfma_f32_32x32x16_bf16 v[64:79], v[130:133], v[138:141], v[64:79]
	v_lshl_add_u64 v[130:131], v[82:83], 0, s[66:67]
	global_load_lds_dwordx4 v[130:131], off
	v_lshl_add_u64 v[130:131], v[84:85], 0, s[66:67]
	s_mov_b32 m0, s6
	v_readfirstlane_b32 s6, v124
	global_load_lds_dwordx4 v[130:131], off sc1
	v_lshl_add_u64 v[130:131], v[86:87], 0, s[66:67]
	s_mov_b32 m0, s6
	v_readfirstlane_b32 s6, v125
	global_load_lds_dwordx4 v[130:131], off
	v_lshl_add_u64 v[130:131], v[88:89], 0, s[66:67]
	s_mov_b32 m0, s6
	v_readfirstlane_b32 s6, v126
	global_load_lds_dwordx4 v[130:131], off sc1
	v_lshl_add_u64 v[130:131], v[90:91], 0, s[66:67]
	s_mov_b32 m0, s6
	v_readfirstlane_b32 s6, v127
	global_load_lds_dwordx4 v[130:131], off
	v_lshl_add_u64 v[130:131], v[92:93], 0, s[66:67]
	s_mov_b32 m0, s6
	v_readfirstlane_b32 s6, v128
	global_load_lds_dwordx4 v[130:131], off sc1
	v_lshl_add_u64 v[130:131], v[94:95], 0, s[66:67]
	s_mov_b32 m0, s6
	v_readfirstlane_b32 s6, v129
	global_load_lds_dwordx4 v[130:131], off
	v_lshl_add_u64 v[130:131], v[96:97], 0, s[66:67]
	s_mov_b32 m0, s6
	v_mfma_f32_32x32x16_bf16 v[16:31], v[134:137], v[138:141], v[16:31]
	global_load_lds_dwordx4 v[130:131], off sc1
	v_mfma_f32_32x32x16_bf16 v[0:15], v[134:137], v[142:145], v[0:15]
	s_and_saveexec_b64 s[6:7], s[42:43]
	s_cbranch_execz .LBB0_184
	v_add_u32_e32 v132, 0x4000, v102
	v_lshl_add_u64 v[130:131], v[98:99], 0, s[66:67]
	v_readfirstlane_b32 s64, v132
	s_mov_b32 m0, s64
	s_nop 0
	global_load_lds_dwordx4 v[130:131], off
; #define MFMA(a, b, c) __builtin_amdgcn_mfma_f32_32x32x16_bf16(a, b, c, 0, 0, 0)
; #define ISSUE(k0, bf) do { char* A_ = lw + (bf) * BUF; \
;     _Pragma("unroll") for (int i_ = 0; i_ < 4; ++i_) { glds16(al.ptr(lrow + 32 * i_, (k0) + cg), A_ + i_ * 4096); glds16(bl.ptr(lrow + 32 * i_, (k0) + cg), A_ + ABYTES + i_ * 4096); } \
;     if (HALO) { if (wid == 0) glds16(gh + (k0), A_ + 16384); } } while (0)
; template <bool HALO, class AL, class BL>
; __device__ __forceinline__ void gemm_core(f32x16 (&acc)[2][2], f32x16& hacc, const AL& al, const BL& bl, int K, char* lds,
;                                           const u16* halo0, const u16* halo1, int brow0, int brow1) {
;     ...
;   for (int kt = 0; kt < nk; ++kt) {
;     asm volatile("s_waitcnt vmcnt(0)" ::: "memory");
;     __syncthreads();
;     if (kt + 1 < nk) ISSUE((kt + 1) * 64, (kt + 1) & 1);
;     const char* T = lds + (kt & 1) * BUF;
; #pragma unroll
;     for (int kk = 0; kk < 4; ++kk) {
;       const int c = kk * 2 + hi;
;       bf16x8 a0 = *(const bf16x8*)(T + oa + ((c ^ sa) << 4));
;       bf16x8 a1 = *(const bf16x8*)(T + oa + 4096 + ((c ^ sa) << 4));
;       bf16x8 b0 = *(const bf16x8*)(T + ob0 + ((c ^ sb0) << 4));
;       bf16x8 b1 = *(const bf16x8*)(T + ob1 + ((c ^ sb1) << 4));
;       acc[0][0] = MFMA(a0, b0, acc[0][0]); acc[0][1] = MFMA(a0, b1, acc[0][1]);
;       acc[1][0] = MFMA(a1, b0, acc[1][0]); acc[1][1] = MFMA(a1, b1, acc[1][1]);
;       if (HALO) { bf16x8 ah = *(const bf16x8*)(T + oh + ((c ^ sh) << 4)); hacc = MFMA(ah, b0, hacc); }
;     }
.LBB0_184:
	s_or_b64 exec, exec, s[6:7]
	ds_read_b128 v[130:133], v104 offset:33792
	ds_read_b128 v[134:137], v104 offset:37888
	ds_read_b128 v[138:141], v107 offset:51200
	ds_read_b128 v[142:145], v107 offset:59392
	v_readfirstlane_b32 s6, v119
	s_mov_b32 m0, s6
	v_readfirstlane_b32 s6, v115
	s_waitcnt lgkmcnt(0)
	v_mfma_f32_32x32x16_bf16 v[48:63], v[130:133], v[138:141], v[48:63]
	v_mfma_f32_32x32x16_bf16 v[32:47], v[130:133], v[142:145], v[32:47]
	ds_read_b128 v[130:133], v103 offset:50176
	v_mfma_f32_32x32x16_bf16 v[16:31], v[134:137], v[138:141], v[16:31]
	v_mfma_f32_32x32x16_bf16 v[0:15], v[134:137], v[142:145], v[0:15]
	s_waitcnt lgkmcnt(0)
	v_mfma_f32_32x32x16_bf16 v[64:79], v[130:133], v[138:141], v[64:79]
	ds_read_b128 v[130:133], v106 offset:33792
	ds_read_b128 v[134:137], v106 offset:37888
	ds_read_b128 v[138:141], v108 offset:51200
	ds_read_b128 v[142:145], v108 offset:59392
	s_waitcnt lgkmcnt(0)
	v_mfma_f32_32x32x16_bf16 v[48:63], v[130:133], v[138:141], v[48:63]
	v_mfma_f32_32x32x16_bf16 v[32:47], v[130:133], v[142:145], v[32:47]
	ds_read_b128 v[130:133], v109 offset:50176
	v_mfma_f32_32x32x16_bf16 v[16:31], v[134:137], v[138:141], v[16:31]
	v_mfma_f32_32x32x16_bf16 v[0:15], v[134:137], v[142:145], v[0:15]
	s_waitcnt lgkmcnt(0)
	v_mfma_f32_32x32x16_bf16 v[64:79], v[130:133], v[138:141], v[64:79]
	ds_read_b128 v[130:133], v110 offset:33792
	ds_read_b128 v[134:137], v110 offset:37888
	ds_read_b128 v[138:141], v111 offset:51200
	ds_read_b128 v[142:145], v111 offset:59392
	s_waitcnt lgkmcnt(0)
	v_mfma_f32_32x32x16_bf16 v[48:63], v[130:133], v[138:141], v[48:63]
	v_mfma_f32_32x32x16_bf16 v[32:47], v[130:133], v[142:145], v[32:47]
	ds_read_b128 v[130:133], v105 offset:50176
	v_mfma_f32_32x32x16_bf16 v[16:31], v[134:137], v[138:141], v[16:31]
	v_mfma_f32_32x32x16_bf16 v[0:15], v[134:137], v[142:145], v[0:15]
	s_waitcnt lgkmcnt(0)
	v_mfma_f32_32x32x16_bf16 v[64:79], v[130:133], v[138:141], v[64:79]
	ds_read_b128 v[130:133], v120 offset:33792
	ds_read_b128 v[134:137], v120 offset:37888
	ds_read_b128 v[138:141], v121 offset:51200
	ds_read_b128 v[142:145], v121 offset:59392
	s_waitcnt lgkmcnt(0)
	v_mfma_f32_32x32x16_bf16 v[48:63], v[130:133], v[138:141], v[48:63]
	v_mfma_f32_32x32x16_bf16 v[32:47], v[130:133], v[142:145], v[32:47]
	ds_read_b128 v[130:133], v122 offset:50176
	s_waitcnt vmcnt(0)
	s_waitcnt vmcnt(0) lgkmcnt(0)
	s_barrier
	v_mfma_f32_32x32x16_bf16 v[64:79], v[130:133], v[138:141], v[64:79]
	v_lshl_add_u64 v[130:131], v[82:83], 0, s[26:27]
	global_load_lds_dwordx4 v[130:131], off
	v_lshl_add_u64 v[130:131], v[84:85], 0, s[26:27]
	s_mov_b32 m0, s6
	v_readfirstlane_b32 s6, v117
	global_load_lds_dwordx4 v[130:131], off sc1
	v_lshl_add_u64 v[130:131], v[86:87], 0, s[26:27]
	s_mov_b32 m0, s6
	v_readfirstlane_b32 s6, v118
	global_load_lds_dwordx4 v[130:131], off
	v_lshl_add_u64 v[130:131], v[88:89], 0, s[26:27]
	s_mov_b32 m0, s6
	v_readfirstlane_b32 s6, v116
	global_load_lds_dwordx4 v[130:131], off sc1
	v_lshl_add_u64 v[130:131], v[90:91], 0, s[26:27]
	s_mov_b32 m0, s6
	v_readfirstlane_b32 s6, v113
	global_load_lds_dwordx4 v[130:131], off
	v_lshl_add_u64 v[130:131], v[92:93], 0, s[26:27]
	s_mov_b32 m0, s6
	v_readfirstlane_b32 s6, v114
	global_load_lds_dwordx4 v[130:131], off sc1
	v_lshl_add_u64 v[130:131], v[94:95], 0, s[26:27]
	s_mov_b32 m0, s6
	v_readfirstlane_b32 s6, v112
	global_load_lds_dwordx4 v[130:131], off
	v_lshl_add_u64 v[130:131], v[96:97], 0, s[26:27]
	s_mov_b32 m0, s6
	v_mfma_f32_32x32x16_bf16 v[16:31], v[134:137], v[138:141], v[16:31]
	global_load_lds_dwordx4 v[130:131], off sc1
	v_mfma_f32_32x32x16_bf16 v[0:15], v[134:137], v[142:145], v[0:15]
	s_and_saveexec_b64 s[6:7], s[42:43]
	s_cbranch_execz .LBB0_186
	v_add_u32_e32 v132, 0xc400, v102
	v_lshl_add_u64 v[130:131], v[98:99], 0, s[26:27]
	v_readfirstlane_b32 s64, v132
	s_mov_b32 m0, s64
	s_nop 0
	global_load_lds_dwordx4 v[130:131], off
.LBB0_186:
	s_or_b64 exec, exec, s[6:7]
	ds_read_b128 v[130:133], v104
	ds_read_b128 v[134:137], v104 offset:4096
	ds_read_b128 v[138:141], v107 offset:17408
	ds_read_b128 v[142:145], v107 offset:25600
	v_readfirstlane_b32 s6, v102
	s_mov_b32 m0, s6
	v_readfirstlane_b32 s6, v123
	s_waitcnt lgkmcnt(0)
	v_mfma_f32_32x32x16_bf16 v[48:63], v[130:133], v[138:141], v[48:63]
	v_mfma_f32_32x32x16_bf16 v[32:47], v[130:133], v[142:145], v[32:47]
	ds_read_b128 v[130:133], v103 offset:16384
	v_mfma_f32_32x32x16_bf16 v[16:31], v[134:137], v[138:141], v[16:31]
	v_mfma_f32_32x32x16_bf16 v[0:15], v[134:137], v[142:145], v[0:15]
	s_waitcnt lgkmcnt(0)
	v_mfma_f32_32x32x16_bf16 v[64:79], v[130:133], v[138:141], v[64:79]
	ds_read_b128 v[130:133], v106
	ds_read_b128 v[134:137], v106 offset:4096
	ds_read_b128 v[138:141], v108 offset:17408
	ds_read_b128 v[142:145], v108 offset:25600
	s_waitcnt lgkmcnt(0)
	v_mfma_f32_32x32x16_bf16 v[48:63], v[130:133], v[138:141], v[48:63]
	v_mfma_f32_32x32x16_bf16 v[32:47], v[130:133], v[142:145], v[32:47]
	ds_read_b128 v[130:133], v109 offset:16384
	v_mfma_f32_32x32x16_bf16 v[16:31], v[134:137], v[138:141], v[16:31]
	v_mfma_f32_32x32x16_bf16 v[0:15], v[134:137], v[142:145], v[0:15]
	s_waitcnt lgkmcnt(0)
	v_mfma_f32_32x32x16_bf16 v[64:79], v[130:133], v[138:141], v[64:79]
	ds_read_b128 v[130:133], v110
	ds_read_b128 v[134:137], v110 offset:4096
	ds_read_b128 v[138:141], v111 offset:17408
	ds_read_b128 v[142:145], v111 offset:25600
	s_waitcnt lgkmcnt(0)
	v_mfma_f32_32x32x16_bf16 v[48:63], v[130:133], v[138:141], v[48:63]
	v_mfma_f32_32x32x16_bf16 v[32:47], v[130:133], v[142:145], v[32:47]
	ds_read_b128 v[130:133], v105 offset:16384
	v_mfma_f32_32x32x16_bf16 v[16:31], v[134:137], v[138:141], v[16:31]
	v_mfma_f32_32x32x16_bf16 v[0:15], v[134:137], v[142:145], v[0:15]
	s_waitcnt lgkmcnt(0)
	v_mfma_f32_32x32x16_bf16 v[64:79], v[130:133], v[138:141], v[64:79]
	ds_read_b128 v[130:133], v120
	ds_read_b128 v[134:137], v120 offset:4096
	ds_read_b128 v[138:141], v121 offset:17408
	ds_read_b128 v[142:145], v121 offset:25600
	s_waitcnt lgkmcnt(0)
	v_mfma_f32_32x32x16_bf16 v[48:63], v[130:133], v[138:141], v[48:63]
	v_mfma_f32_32x32x16_bf16 v[32:47], v[130:133], v[142:145], v[32:47]
	ds_read_b128 v[130:133], v122 offset:16384
	s_waitcnt vmcnt(0)
	s_waitcnt vmcnt(0) lgkmcnt(0)
	s_barrier
; #define MFMA(a, b, c) __builtin_amdgcn_mfma_f32_32x32x16_bf16(a, b, c, 0, 0, 0)
; #define ISSUE(k0, bf) do { char* A_ = lw + (bf) * BUF; \
;     _Pragma("unroll") for (int i_ = 0; i_ < 4; ++i_) { glds16(al.ptr(lrow + 32 * i_, (k0) + cg), A_ + i_ * 4096); glds16(bl.ptr(lrow + 32 * i_, (k0) + cg), A_ + ABYTES + i_ * 4096); } \
;     if (HALO) { if (wid == 0) glds16(gh + (k0), A_ + 16384); } } while (0)
; template <bool HALO, class AL, class BL>
; __device__ __forceinline__ void gemm_core(f32x16 (&acc)[2][2], f32x16& hacc, const AL& al, const BL& bl, int K, char* lds,
;                                           const u16* halo0, const u16* halo1, int brow0, int brow1) {
;     ...
;   for (int kt = 0; kt < nk; ++kt) {
;     asm volatile("s_waitcnt vmcnt(0)" ::: "memory");
;     __syncthreads();
;     if (kt + 1 < nk) ISSUE((kt + 1) * 64, (kt + 1) & 1);
;     const char* T = lds + (kt & 1) * BUF;
; #pragma unroll
;     for (int kk = 0; kk < 4; ++kk) {
;       const int c = kk * 2 + hi;
;       bf16x8 a0 = *(const bf16x8*)(T + oa + ((c ^ sa) << 4));
;       bf16x8 a1 = *(const bf16x8*)(T + oa + 4096 + ((c ^ sa) << 4));
;       bf16x8 b0 = *(const bf16x8*)(T + ob0 + ((c ^ sb0) << 4));
;       bf16x8 b1 = *(const bf16x8*)(T + ob1 + ((c ^ sb1) << 4));
;       acc[0][0] = MFMA(a0, b0, acc[0][0]); acc[0][1] = MFMA(a0, b1, acc[0][1]);
;       acc[1][0] = MFMA(a1, b0, acc[1][0]); acc[1][1] = MFMA(a1, b1, acc[1][1]);
;       if (HALO) { bf16x8 ah = *(const bf16x8*)(T + oh + ((c ^ sh) << 4)); hacc = MFMA(ah, b0, hacc); }
;     }
	v_mfma_f32_32x32x16_bf16 v[64:79], v[130:133], v[138:141], v[64:79]
	v_lshl_add_u64 v[130:131], v[82:83], 0, s[88:89]
	global_load_lds_dwordx4 v[130:131], off
	v_lshl_add_u64 v[130:131], v[84:85], 0, s[88:89]
	s_mov_b32 m0, s6
	v_readfirstlane_b32 s6, v124
	global_load_lds_dwordx4 v[130:131], off sc1
	v_lshl_add_u64 v[130:131], v[86:87], 0, s[88:89]
	s_mov_b32 m0, s6
	v_readfirstlane_b32 s6, v125
	global_load_lds_dwordx4 v[130:131], off
	v_lshl_add_u64 v[130:131], v[88:89], 0, s[88:89]
	s_mov_b32 m0, s6
	v_readfirstlane_b32 s6, v126
	global_load_lds_dwordx4 v[130:131], off sc1
	v_lshl_add_u64 v[130:131], v[90:91], 0, s[88:89]
	s_mov_b32 m0, s6
	v_readfirstlane_b32 s6, v127
	global_load_lds_dwordx4 v[130:131], off
	v_lshl_add_u64 v[130:131], v[92:93], 0, s[88:89]
	s_mov_b32 m0, s6
	v_readfirstlane_b32 s6, v128
	global_load_lds_dwordx4 v[130:131], off sc1
	v_lshl_add_u64 v[130:131], v[94:95], 0, s[88:89]
	s_mov_b32 m0, s6
	v_readfirstlane_b32 s6, v129
	global_load_lds_dwordx4 v[130:131], off
	v_lshl_add_u64 v[130:131], v[96:97], 0, s[88:89]
	s_mov_b32 m0, s6
	v_mfma_f32_32x32x16_bf16 v[16:31], v[134:137], v[138:141], v[16:31]
	global_load_lds_dwordx4 v[130:131], off sc1
	v_mfma_f32_32x32x16_bf16 v[0:15], v[134:137], v[142:145], v[0:15]
	s_and_saveexec_b64 s[6:7], s[42:43]
	s_cbranch_execz .LBB0_188
	v_add_u32_e32 v132, 0x4000, v102
	v_lshl_add_u64 v[130:131], v[98:99], 0, s[88:89]
	v_readfirstlane_b32 s64, v132
	s_mov_b32 m0, s64
	s_nop 0
	global_load_lds_dwordx4 v[130:131], off
.LBB0_188:
	s_or_b64 exec, exec, s[6:7]
	ds_read_b128 v[130:133], v104 offset:33792
	ds_read_b128 v[134:137], v104 offset:37888
	ds_read_b128 v[138:141], v107 offset:51200
	ds_read_b128 v[142:145], v107 offset:59392
	v_readfirstlane_b32 s6, v119
	s_mov_b32 m0, s6
	v_readfirstlane_b32 s6, v115
	s_waitcnt lgkmcnt(0)
	v_mfma_f32_32x32x16_bf16 v[48:63], v[130:133], v[138:141], v[48:63]
	v_mfma_f32_32x32x16_bf16 v[32:47], v[130:133], v[142:145], v[32:47]
	ds_read_b128 v[130:133], v103 offset:50176
	v_mfma_f32_32x32x16_bf16 v[16:31], v[134:137], v[138:141], v[16:31]
	v_mfma_f32_32x32x16_bf16 v[0:15], v[134:137], v[142:145], v[0:15]
	s_waitcnt lgkmcnt(0)
	v_mfma_f32_32x32x16_bf16 v[64:79], v[130:133], v[138:141], v[64:79]
	ds_read_b128 v[130:133], v106 offset:33792
	ds_read_b128 v[134:137], v106 offset:37888
	ds_read_b128 v[138:141], v108 offset:51200
	ds_read_b128 v[142:145], v108 offset:59392
	s_waitcnt lgkmcnt(0)
	v_mfma_f32_32x32x16_bf16 v[48:63], v[130:133], v[138:141], v[48:63]
	v_mfma_f32_32x32x16_bf16 v[32:47], v[130:133], v[142:145], v[32:47]
	ds_read_b128 v[130:133], v109 offset:50176
	v_mfma_f32_32x32x16_bf16 v[16:31], v[134:137], v[138:141], v[16:31]
	v_mfma_f32_32x32x16_bf16 v[0:15], v[134:137], v[142:145], v[0:15]
	s_waitcnt lgkmcnt(0)
	v_mfma_f32_32x32x16_bf16 v[64:79], v[130:133], v[138:141], v[64:79]
	ds_read_b128 v[130:133], v110 offset:33792
	ds_read_b128 v[134:137], v110 offset:37888
	ds_read_b128 v[138:141], v111 offset:51200
	ds_read_b128 v[142:145], v111 offset:59392
	s_waitcnt lgkmcnt(0)
	v_mfma_f32_32x32x16_bf16 v[48:63], v[130:133], v[138:141], v[48:63]
	v_mfma_f32_32x32x16_bf16 v[32:47], v[130:133], v[142:145], v[32:47]
	ds_read_b128 v[130:133], v105 offset:50176
	v_mfma_f32_32x32x16_bf16 v[16:31], v[134:137], v[138:141], v[16:31]
	v_mfma_f32_32x32x16_bf16 v[0:15], v[134:137], v[142:145], v[0:15]
	s_waitcnt lgkmcnt(0)
	v_mfma_f32_32x32x16_bf16 v[64:79], v[130:133], v[138:141], v[64:79]
	ds_read_b128 v[130:133], v120 offset:33792
	ds_read_b128 v[134:137], v120 offset:37888
	ds_read_b128 v[138:141], v121 offset:51200
	ds_read_b128 v[142:145], v121 offset:59392
	s_waitcnt lgkmcnt(0)
	v_mfma_f32_32x32x16_bf16 v[48:63], v[130:133], v[138:141], v[48:63]
	v_mfma_f32_32x32x16_bf16 v[32:47], v[130:133], v[142:145], v[32:47]
	ds_read_b128 v[130:133], v122 offset:50176
	s_waitcnt vmcnt(0)
	s_waitcnt vmcnt(0) lgkmcnt(0)
	s_barrier
	v_mfma_f32_32x32x16_bf16 v[64:79], v[130:133], v[138:141], v[64:79]
	v_lshl_add_u64 v[130:131], v[82:83], 0, s[22:23]
	global_load_lds_dwordx4 v[130:131], off
	v_lshl_add_u64 v[130:131], v[84:85], 0, s[22:23]
	s_mov_b32 m0, s6
	v_readfirstlane_b32 s6, v117
	global_load_lds_dwordx4 v[130:131], off sc1
	v_lshl_add_u64 v[130:131], v[86:87], 0, s[22:23]
	s_mov_b32 m0, s6
	v_readfirstlane_b32 s6, v118
	global_load_lds_dwordx4 v[130:131], off
	v_lshl_add_u64 v[130:131], v[88:89], 0, s[22:23]
	s_mov_b32 m0, s6
	v_readfirstlane_b32 s6, v116
	global_load_lds_dwordx4 v[130:131], off sc1
	v_lshl_add_u64 v[130:131], v[90:91], 0, s[22:23]
	s_mov_b32 m0, s6
	v_readfirstlane_b32 s6, v113
	global_load_lds_dwordx4 v[130:131], off
	v_lshl_add_u64 v[130:131], v[92:93], 0, s[22:23]
	s_mov_b32 m0, s6
	v_readfirstlane_b32 s6, v114
	global_load_lds_dwordx4 v[130:131], off sc1
	v_lshl_add_u64 v[130:131], v[94:95], 0, s[22:23]
	s_mov_b32 m0, s6
	v_readfirstlane_b32 s6, v112
	global_load_lds_dwordx4 v[130:131], off
	v_lshl_add_u64 v[130:131], v[96:97], 0, s[22:23]
	s_mov_b32 m0, s6
	v_mfma_f32_32x32x16_bf16 v[16:31], v[134:137], v[138:141], v[16:31]
	global_load_lds_dwordx4 v[130:131], off sc1
	v_mfma_f32_32x32x16_bf16 v[0:15], v[134:137], v[142:145], v[0:15]
	s_and_saveexec_b64 s[6:7], s[42:43]
	s_cbranch_execz .LBB0_190
	v_add_u32_e32 v132, 0xc400, v102
	v_lshl_add_u64 v[130:131], v[98:99], 0, s[22:23]
	v_readfirstlane_b32 s64, v132
	s_mov_b32 m0, s64
	s_nop 0
	global_load_lds_dwordx4 v[130:131], off
; #define MFMA(a, b, c) __builtin_amdgcn_mfma_f32_32x32x16_bf16(a, b, c, 0, 0, 0)
; #define ISSUE(k0, bf) do { char* A_ = lw + (bf) * BUF; \
;     _Pragma("unroll") for (int i_ = 0; i_ < 4; ++i_) { glds16(al.ptr(lrow + 32 * i_, (k0) + cg), A_ + i_ * 4096); glds16(bl.ptr(lrow + 32 * i_, (k0) + cg), A_ + ABYTES + i_ * 4096); } \
;     if (HALO) { if (wid == 0) glds16(gh + (k0), A_ + 16384); } } while (0)
; template <bool HALO, class AL, class BL>
; __device__ __forceinline__ void gemm_core(f32x16 (&acc)[2][2], f32x16& hacc, const AL& al, const BL& bl, int K, char* lds,
;                                           const u16* halo0, const u16* halo1, int brow0, int brow1) {
;     ...
;   for (int kt = 0; kt < nk; ++kt) {
;     asm volatile("s_waitcnt vmcnt(0)" ::: "memory");
;     __syncthreads();
;     if (kt + 1 < nk) ISSUE((kt + 1) * 64, (kt + 1) & 1);
;     const char* T = lds + (kt & 1) * BUF;
; #pragma unroll
;     for (int kk = 0; kk < 4; ++kk) {
;       const int c = kk * 2 + hi;
;       bf16x8 a0 = *(const bf16x8*)(T + oa + ((c ^ sa) << 4));
;       bf16x8 a1 = *(const bf16x8*)(T + oa + 4096 + ((c ^ sa) << 4));
;       bf16x8 b0 = *(const bf16x8*)(T + ob0 + ((c ^ sb0) << 4));
;       bf16x8 b1 = *(const bf16x8*)(T + ob1 + ((c ^ sb1) << 4));
;       acc[0][0] = MFMA(a0, b0, acc[0][0]); acc[0][1] = MFMA(a0, b1, acc[0][1]);
;       acc[1][0] = MFMA(a1, b0, acc[1][0]); acc[1][1] = MFMA(a1, b1, acc[1][1]);
;       if (HALO) { bf16x8 ah = *(const bf16x8*)(T + oh + ((c ^ sh) << 4)); hacc = MFMA(ah, b0, hacc); }
;     }
.LBB0_190:
	s_or_b64 exec, exec, s[6:7]
	ds_read_b128 v[130:133], v104
	ds_read_b128 v[134:137], v104 offset:4096
	ds_read_b128 v[138:141], v107 offset:17408
	ds_read_b128 v[142:145], v107 offset:25600
	v_readfirstlane_b32 s6, v102
	s_mov_b32 m0, s6
	v_readfirstlane_b32 s6, v123
	s_waitcnt lgkmcnt(0)
	v_mfma_f32_32x32x16_bf16 v[48:63], v[130:133], v[138:141], v[48:63]
	v_mfma_f32_32x32x16_bf16 v[32:47], v[130:133], v[142:145], v[32:47]
	ds_read_b128 v[130:133], v103 offset:16384
	v_mfma_f32_32x32x16_bf16 v[16:31], v[134:137], v[138:141], v[16:31]
	v_mfma_f32_32x32x16_bf16 v[0:15], v[134:137], v[142:145], v[0:15]
	s_waitcnt lgkmcnt(0)
	v_mfma_f32_32x32x16_bf16 v[64:79], v[130:133], v[138:141], v[64:79]
	ds_read_b128 v[130:133], v106
	ds_read_b128 v[134:137], v106 offset:4096
	ds_read_b128 v[138:141], v108 offset:17408
	ds_read_b128 v[142:145], v108 offset:25600
	s_waitcnt lgkmcnt(0)
	v_mfma_f32_32x32x16_bf16 v[48:63], v[130:133], v[138:141], v[48:63]
	v_mfma_f32_32x32x16_bf16 v[32:47], v[130:133], v[142:145], v[32:47]
	ds_read_b128 v[130:133], v109 offset:16384
	v_mfma_f32_32x32x16_bf16 v[16:31], v[134:137], v[138:141], v[16:31]
	v_mfma_f32_32x32x16_bf16 v[0:15], v[134:137], v[142:145], v[0:15]
	s_waitcnt lgkmcnt(0)
	v_mfma_f32_32x32x16_bf16 v[64:79], v[130:133], v[138:141], v[64:79]
	ds_read_b128 v[130:133], v110
	ds_read_b128 v[134:137], v110 offset:4096
	ds_read_b128 v[138:141], v111 offset:17408
	ds_read_b128 v[142:145], v111 offset:25600
	s_waitcnt lgkmcnt(0)
	v_mfma_f32_32x32x16_bf16 v[48:63], v[130:133], v[138:141], v[48:63]
	v_mfma_f32_32x32x16_bf16 v[32:47], v[130:133], v[142:145], v[32:47]
	ds_read_b128 v[130:133], v105 offset:16384
	v_mfma_f32_32x32x16_bf16 v[16:31], v[134:137], v[138:141], v[16:31]
	v_mfma_f32_32x32x16_bf16 v[0:15], v[134:137], v[142:145], v[0:15]
	s_waitcnt lgkmcnt(0)
	v_mfma_f32_32x32x16_bf16 v[64:79], v[130:133], v[138:141], v[64:79]
	ds_read_b128 v[130:133], v120
	ds_read_b128 v[134:137], v120 offset:4096
	ds_read_b128 v[138:141], v121 offset:17408
	ds_read_b128 v[142:145], v121 offset:25600
	s_waitcnt lgkmcnt(0)
	v_mfma_f32_32x32x16_bf16 v[48:63], v[130:133], v[138:141], v[48:63]
	v_mfma_f32_32x32x16_bf16 v[32:47], v[130:133], v[142:145], v[32:47]
	ds_read_b128 v[130:133], v122 offset:16384
	s_waitcnt vmcnt(0)
	s_waitcnt vmcnt(0) lgkmcnt(0)
	s_barrier
	v_mfma_f32_32x32x16_bf16 v[64:79], v[130:133], v[138:141], v[64:79]
	v_lshl_add_u64 v[130:131], v[82:83], 0, s[90:91]
	global_load_lds_dwordx4 v[130:131], off
	v_lshl_add_u64 v[130:131], v[84:85], 0, s[90:91]
	s_mov_b32 m0, s6
	v_readfirstlane_b32 s6, v124
	global_load_lds_dwordx4 v[130:131], off sc1
	v_lshl_add_u64 v[130:131], v[86:87], 0, s[90:91]
	s_mov_b32 m0, s6
	v_readfirstlane_b32 s6, v125
	global_load_lds_dwordx4 v[130:131], off
	v_lshl_add_u64 v[130:131], v[88:89], 0, s[90:91]
	s_mov_b32 m0, s6
	v_readfirstlane_b32 s6, v126
	global_load_lds_dwordx4 v[130:131], off sc1
	v_lshl_add_u64 v[130:131], v[90:91], 0, s[90:91]
	s_mov_b32 m0, s6
	v_readfirstlane_b32 s6, v127
	global_load_lds_dwordx4 v[130:131], off
	v_lshl_add_u64 v[130:131], v[92:93], 0, s[90:91]
	s_mov_b32 m0, s6
	v_readfirstlane_b32 s6, v128
	global_load_lds_dwordx4 v[130:131], off sc1
	v_lshl_add_u64 v[130:131], v[94:95], 0, s[90:91]
	s_mov_b32 m0, s6
	v_readfirstlane_b32 s6, v129
	global_load_lds_dwordx4 v[130:131], off
	v_lshl_add_u64 v[130:131], v[96:97], 0, s[90:91]
	s_mov_b32 m0, s6
	v_mfma_f32_32x32x16_bf16 v[16:31], v[134:137], v[138:141], v[16:31]
	global_load_lds_dwordx4 v[130:131], off sc1
	v_mfma_f32_32x32x16_bf16 v[0:15], v[134:137], v[142:145], v[0:15]
	s_and_saveexec_b64 s[6:7], s[42:43]
	s_cbranch_execz .LBB0_192
	v_add_u32_e32 v132, 0x4000, v102
	v_lshl_add_u64 v[130:131], v[98:99], 0, s[90:91]
	v_readfirstlane_b32 s64, v132
	s_mov_b32 m0, s64
	s_nop 0
	global_load_lds_dwordx4 v[130:131], off
.LBB0_192:
	s_or_b64 exec, exec, s[6:7]
	ds_read_b128 v[130:133], v104 offset:33792
	ds_read_b128 v[134:137], v104 offset:37888
	ds_read_b128 v[138:141], v107 offset:51200
	ds_read_b128 v[142:145], v107 offset:59392
	v_readfirstlane_b32 s6, v119
	s_mov_b32 m0, s6
	v_readfirstlane_b32 s6, v115
	s_waitcnt lgkmcnt(0)
	v_mfma_f32_32x32x16_bf16 v[48:63], v[130:133], v[138:141], v[48:63]
	v_mfma_f32_32x32x16_bf16 v[32:47], v[130:133], v[142:145], v[32:47]
	ds_read_b128 v[130:133], v103 offset:50176
	v_mfma_f32_32x32x16_bf16 v[16:31], v[134:137], v[138:141], v[16:31]
	v_mfma_f32_32x32x16_bf16 v[0:15], v[134:137], v[142:145], v[0:15]
	s_waitcnt lgkmcnt(0)
	v_mfma_f32_32x32x16_bf16 v[64:79], v[130:133], v[138:141], v[64:79]
	ds_read_b128 v[130:133], v106 offset:33792
	ds_read_b128 v[134:137], v106 offset:37888
	ds_read_b128 v[138:141], v108 offset:51200
	ds_read_b128 v[142:145], v108 offset:59392
	s_waitcnt lgkmcnt(0)
	v_mfma_f32_32x32x16_bf16 v[48:63], v[130:133], v[138:141], v[48:63]
	v_mfma_f32_32x32x16_bf16 v[32:47], v[130:133], v[142:145], v[32:47]
	ds_read_b128 v[130:133], v109 offset:50176
	v_mfma_f32_32x32x16_bf16 v[16:31], v[134:137], v[138:141], v[16:31]
	v_mfma_f32_32x32x16_bf16 v[0:15], v[134:137], v[142:145], v[0:15]
	s_waitcnt lgkmcnt(0)
	v_mfma_f32_32x32x16_bf16 v[64:79], v[130:133], v[138:141], v[64:79]
	ds_read_b128 v[130:133], v110 offset:33792
	ds_read_b128 v[134:137], v110 offset:37888
	ds_read_b128 v[138:141], v111 offset:51200
	ds_read_b128 v[142:145], v111 offset:59392
	s_waitcnt lgkmcnt(0)
	v_mfma_f32_32x32x16_bf16 v[48:63], v[130:133], v[138:141], v[48:63]
	v_mfma_f32_32x32x16_bf16 v[32:47], v[130:133], v[142:145], v[32:47]
	ds_read_b128 v[130:133], v105 offset:50176
	v_mfma_f32_32x32x16_bf16 v[16:31], v[134:137], v[138:141], v[16:31]
	v_mfma_f32_32x32x16_bf16 v[0:15], v[134:137], v[142:145], v[0:15]
	s_waitcnt lgkmcnt(0)
	v_mfma_f32_32x32x16_bf16 v[64:79], v[130:133], v[138:141], v[64:79]
	ds_read_b128 v[130:133], v120 offset:33792
	ds_read_b128 v[134:137], v120 offset:37888
	ds_read_b128 v[138:141], v121 offset:51200
	ds_read_b128 v[142:145], v121 offset:59392
	s_waitcnt lgkmcnt(0)
	v_mfma_f32_32x32x16_bf16 v[48:63], v[130:133], v[138:141], v[48:63]
	v_mfma_f32_32x32x16_bf16 v[32:47], v[130:133], v[142:145], v[32:47]
	ds_read_b128 v[130:133], v122 offset:50176
	s_waitcnt vmcnt(0)
	s_waitcnt vmcnt(0) lgkmcnt(0)
	s_barrier
; #define MFMA(a, b, c) __builtin_amdgcn_mfma_f32_32x32x16_bf16(a, b, c, 0, 0, 0)
; #define ISSUE(k0, bf) do { char* A_ = lw + (bf) * BUF; \
;     _Pragma("unroll") for (int i_ = 0; i_ < 4; ++i_) { glds16(al.ptr(lrow + 32 * i_, (k0) + cg), A_ + i_ * 4096); glds16(bl.ptr(lrow + 32 * i_, (k0) + cg), A_ + ABYTES + i_ * 4096); } \
;     if (HALO) { if (wid == 0) glds16(gh + (k0), A_ + 16384); } } while (0)
; template <bool HALO, class AL, class BL>
; __device__ __forceinline__ void gemm_core(f32x16 (&acc)[2][2], f32x16& hacc, const AL& al, const BL& bl, int K, char* lds,
;                                           const u16* halo0, const u16* halo1, int brow0, int brow1) {
;     ...
;   for (int kt = 0; kt < nk; ++kt) {
;     asm volatile("s_waitcnt vmcnt(0)" ::: "memory");
;     __syncthreads();
;     if (kt + 1 < nk) ISSUE((kt + 1) * 64, (kt + 1) & 1);
;     const char* T = lds + (kt & 1) * BUF;
; #pragma unroll
;     for (int kk = 0; kk < 4; ++kk) {
;       const int c = kk * 2 + hi;
;       bf16x8 a0 = *(const bf16x8*)(T + oa + ((c ^ sa) << 4));
;       bf16x8 a1 = *(const bf16x8*)(T + oa + 4096 + ((c ^ sa) << 4));
;       bf16x8 b0 = *(const bf16x8*)(T + ob0 + ((c ^ sb0) << 4));
;       bf16x8 b1 = *(const bf16x8*)(T + ob1 + ((c ^ sb1) << 4));
;       acc[0][0] = MFMA(a0, b0, acc[0][0]); acc[0][1] = MFMA(a0, b1, acc[0][1]);
;       acc[1][0] = MFMA(a1, b0, acc[1][0]); acc[1][1] = MFMA(a1, b1, acc[1][1]);
;       if (HALO) { bf16x8 ah = *(const bf16x8*)(T + oh + ((c ^ sh) << 4)); hacc = MFMA(ah, b0, hacc); }
;     }
	v_mfma_f32_32x32x16_bf16 v[64:79], v[130:133], v[138:141], v[64:79]
	v_lshl_add_u64 v[130:131], v[82:83], 0, s[0:1]
	global_load_lds_dwordx4 v[130:131], off
	v_lshl_add_u64 v[130:131], v[84:85], 0, s[0:1]
	s_mov_b32 m0, s6
	v_readfirstlane_b32 s6, v117
	global_load_lds_dwordx4 v[130:131], off sc1
	v_lshl_add_u64 v[130:131], v[86:87], 0, s[0:1]
	s_mov_b32 m0, s6
	v_readfirstlane_b32 s6, v118
	global_load_lds_dwordx4 v[130:131], off
	v_lshl_add_u64 v[130:131], v[88:89], 0, s[0:1]
	s_mov_b32 m0, s6
	v_readfirstlane_b32 s6, v116
	global_load_lds_dwordx4 v[130:131], off sc1
	v_lshl_add_u64 v[130:131], v[90:91], 0, s[0:1]
	s_mov_b32 m0, s6
	v_readfirstlane_b32 s6, v113
	global_load_lds_dwordx4 v[130:131], off
	v_lshl_add_u64 v[130:131], v[92:93], 0, s[0:1]
	s_mov_b32 m0, s6
	v_readfirstlane_b32 s6, v114
	global_load_lds_dwordx4 v[130:131], off sc1
	v_lshl_add_u64 v[130:131], v[94:95], 0, s[0:1]
	s_mov_b32 m0, s6
	v_readfirstlane_b32 s6, v112
	global_load_lds_dwordx4 v[130:131], off
	v_lshl_add_u64 v[130:131], v[96:97], 0, s[0:1]
	s_mov_b32 m0, s6
	v_mfma_f32_32x32x16_bf16 v[16:31], v[134:137], v[138:141], v[16:31]
	global_load_lds_dwordx4 v[130:131], off sc1
	v_mfma_f32_32x32x16_bf16 v[0:15], v[134:137], v[142:145], v[0:15]
	s_and_saveexec_b64 s[6:7], s[42:43]
	s_cbranch_execz .LBB0_194
	v_add_u32_e32 v132, 0xc400, v102
	v_lshl_add_u64 v[130:131], v[98:99], 0, s[0:1]
	v_readfirstlane_b32 s64, v132
	s_mov_b32 m0, s64
	s_nop 0
	global_load_lds_dwordx4 v[130:131], off
.LBB0_194:
	s_or_b64 exec, exec, s[6:7]
	ds_read_b128 v[130:133], v104
	ds_read_b128 v[134:137], v104 offset:4096
	ds_read_b128 v[138:141], v107 offset:17408
	ds_read_b128 v[142:145], v107 offset:25600
	v_readfirstlane_b32 s6, v102
	s_mov_b32 m0, s6
	v_readfirstlane_b32 s6, v123
	s_waitcnt lgkmcnt(0)
	v_mfma_f32_32x32x16_bf16 v[48:63], v[130:133], v[138:141], v[48:63]
	v_mfma_f32_32x32x16_bf16 v[32:47], v[130:133], v[142:145], v[32:47]
	ds_read_b128 v[130:133], v103 offset:16384
	v_mfma_f32_32x32x16_bf16 v[16:31], v[134:137], v[138:141], v[16:31]
	v_mfma_f32_32x32x16_bf16 v[0:15], v[134:137], v[142:145], v[0:15]
	s_waitcnt lgkmcnt(0)
	v_mfma_f32_32x32x16_bf16 v[64:79], v[130:133], v[138:141], v[64:79]
	ds_read_b128 v[130:133], v106
	ds_read_b128 v[134:137], v106 offset:4096
	ds_read_b128 v[138:141], v108 offset:17408
	ds_read_b128 v[142:145], v108 offset:25600
	s_waitcnt lgkmcnt(0)
	v_mfma_f32_32x32x16_bf16 v[48:63], v[130:133], v[138:141], v[48:63]
	v_mfma_f32_32x32x16_bf16 v[32:47], v[130:133], v[142:145], v[32:47]
	ds_read_b128 v[130:133], v109 offset:16384
	v_mfma_f32_32x32x16_bf16 v[16:31], v[134:137], v[138:141], v[16:31]
	v_mfma_f32_32x32x16_bf16 v[0:15], v[134:137], v[142:145], v[0:15]
	s_waitcnt lgkmcnt(0)
	v_mfma_f32_32x32x16_bf16 v[64:79], v[130:133], v[138:141], v[64:79]
	ds_read_b128 v[130:133], v110
	ds_read_b128 v[134:137], v110 offset:4096
	ds_read_b128 v[138:141], v111 offset:17408
	ds_read_b128 v[142:145], v111 offset:25600
	s_waitcnt lgkmcnt(0)
	v_mfma_f32_32x32x16_bf16 v[48:63], v[130:133], v[138:141], v[48:63]
	v_mfma_f32_32x32x16_bf16 v[32:47], v[130:133], v[142:145], v[32:47]
	ds_read_b128 v[130:133], v105 offset:16384
	v_mfma_f32_32x32x16_bf16 v[16:31], v[134:137], v[138:141], v[16:31]
	v_mfma_f32_32x32x16_bf16 v[0:15], v[134:137], v[142:145], v[0:15]
	s_waitcnt lgkmcnt(0)
	v_mfma_f32_32x32x16_bf16 v[64:79], v[130:133], v[138:141], v[64:79]
	ds_read_b128 v[130:133], v120
	ds_read_b128 v[134:137], v120 offset:4096
	ds_read_b128 v[138:141], v121 offset:17408
	ds_read_b128 v[142:145], v121 offset:25600
	s_waitcnt lgkmcnt(0)
	v_mfma_f32_32x32x16_bf16 v[48:63], v[130:133], v[138:141], v[48:63]
	v_mfma_f32_32x32x16_bf16 v[32:47], v[130:133], v[142:145], v[32:47]
	ds_read_b128 v[130:133], v122 offset:16384
	s_waitcnt vmcnt(0)
	s_waitcnt vmcnt(0) lgkmcnt(0)
	s_barrier
	v_mfma_f32_32x32x16_bf16 v[64:79], v[130:133], v[138:141], v[64:79]
	v_lshl_add_u64 v[130:131], v[82:83], 0, s[34:35]
	global_load_lds_dwordx4 v[130:131], off
	v_lshl_add_u64 v[130:131], v[84:85], 0, s[34:35]
	s_mov_b32 m0, s6
	v_readfirstlane_b32 s6, v124
	global_load_lds_dwordx4 v[130:131], off sc1
	v_lshl_add_u64 v[130:131], v[86:87], 0, s[34:35]
	s_mov_b32 m0, s6
	v_readfirstlane_b32 s6, v125
	global_load_lds_dwordx4 v[130:131], off
	v_lshl_add_u64 v[130:131], v[88:89], 0, s[34:35]
	s_mov_b32 m0, s6
	v_readfirstlane_b32 s6, v126
	global_load_lds_dwordx4 v[130:131], off sc1
	v_lshl_add_u64 v[124:125], v[90:91], 0, s[34:35]
	s_mov_b32 m0, s6
	v_readfirstlane_b32 s6, v127
	global_load_lds_dwordx4 v[124:125], off
	v_lshl_add_u64 v[124:125], v[92:93], 0, s[34:35]
	s_mov_b32 m0, s6
	v_readfirstlane_b32 s6, v128
	global_load_lds_dwordx4 v[124:125], off sc1
	v_lshl_add_u64 v[124:125], v[94:95], 0, s[34:35]
	s_mov_b32 m0, s6
	v_readfirstlane_b32 s6, v129
	global_load_lds_dwordx4 v[124:125], off
	v_lshl_add_u64 v[124:125], v[96:97], 0, s[34:35]
	s_mov_b32 m0, s6
	v_mfma_f32_32x32x16_bf16 v[16:31], v[134:137], v[138:141], v[16:31]
	global_load_lds_dwordx4 v[124:125], off sc1
	v_mfma_f32_32x32x16_bf16 v[0:15], v[134:137], v[142:145], v[0:15]
	s_and_saveexec_b64 s[6:7], s[42:43]
	s_cbranch_execz .LBB0_196
	v_add_u32_e32 v123, 0x4000, v102
	v_lshl_add_u64 v[124:125], v[98:99], 0, s[34:35]
	v_readfirstlane_b32 s64, v123
	s_mov_b32 m0, s64
	s_nop 0
	global_load_lds_dwordx4 v[124:125], off
; #define MFMA(a, b, c) __builtin_amdgcn_mfma_f32_32x32x16_bf16(a, b, c, 0, 0, 0)
; #define ISSUE(k0, bf) do { char* A_ = lw + (bf) * BUF; \
;     _Pragma("unroll") for (int i_ = 0; i_ < 4; ++i_) { glds16(al.ptr(lrow + 32 * i_, (k0) + cg), A_ + i_ * 4096); glds16(bl.ptr(lrow + 32 * i_, (k0) + cg), A_ + ABYTES + i_ * 4096); } \
;     if (HALO) { if (wid == 0) glds16(gh + (k0), A_ + 16384); } } while (0)
; template <bool HALO, class AL, class BL>
; __device__ __forceinline__ void gemm_core(f32x16 (&acc)[2][2], f32x16& hacc, const AL& al, const BL& bl, int K, char* lds,
;                                           const u16* halo0, const u16* halo1, int brow0, int brow1) {
;     ...
;   for (int kt = 0; kt < nk; ++kt) {
;     asm volatile("s_waitcnt vmcnt(0)" ::: "memory");
;     __syncthreads();
;     if (kt + 1 < nk) ISSUE((kt + 1) * 64, (kt + 1) & 1);
;     const char* T = lds + (kt & 1) * BUF;
; #pragma unroll
;     for (int kk = 0; kk < 4; ++kk) {
;       const int c = kk * 2 + hi;
;       bf16x8 a0 = *(const bf16x8*)(T + oa + ((c ^ sa) << 4));
;       bf16x8 a1 = *(const bf16x8*)(T + oa + 4096 + ((c ^ sa) << 4));
;       bf16x8 b0 = *(const bf16x8*)(T + ob0 + ((c ^ sb0) << 4));
;       bf16x8 b1 = *(const bf16x8*)(T + ob1 + ((c ^ sb1) << 4));
;       acc[0][0] = MFMA(a0, b0, acc[0][0]); acc[0][1] = MFMA(a0, b1, acc[0][1]);
;       acc[1][0] = MFMA(a1, b0, acc[1][0]); acc[1][1] = MFMA(a1, b1, acc[1][1]);
;       if (HALO) { bf16x8 ah = *(const bf16x8*)(T + oh + ((c ^ sh) << 4)); hacc = MFMA(ah, b0, hacc); }
;     }
.LBB0_196:
	s_or_b64 exec, exec, s[6:7]
	ds_read_b128 v[124:127], v104 offset:33792
	ds_read_b128 v[128:131], v104 offset:37888
	ds_read_b128 v[132:135], v107 offset:51200
	ds_read_b128 v[136:139], v107 offset:59392
	v_readfirstlane_b32 s6, v119
	v_lshl_add_u64 v[82:83], v[82:83], 0, s[38:39]
	s_mov_b32 m0, s6
	s_waitcnt lgkmcnt(0)
	v_mfma_f32_32x32x16_bf16 v[48:63], v[124:127], v[132:135], v[48:63]
	v_readfirstlane_b32 s6, v115
	v_mfma_f32_32x32x16_bf16 v[32:47], v[124:127], v[136:139], v[32:47]
	ds_read_b128 v[124:127], v103 offset:50176
	v_mfma_f32_32x32x16_bf16 v[16:31], v[128:131], v[132:135], v[16:31]
	v_mfma_f32_32x32x16_bf16 v[0:15], v[128:131], v[136:139], v[0:15]
	s_waitcnt lgkmcnt(0)
	v_mfma_f32_32x32x16_bf16 v[64:79], v[124:127], v[132:135], v[64:79]
	ds_read_b128 v[124:127], v106 offset:33792
	ds_read_b128 v[128:131], v106 offset:37888
	ds_read_b128 v[132:135], v108 offset:51200
	ds_read_b128 v[136:139], v108 offset:59392
	s_waitcnt lgkmcnt(0)
	v_mfma_f32_32x32x16_bf16 v[48:63], v[124:127], v[132:135], v[48:63]
	v_mfma_f32_32x32x16_bf16 v[32:47], v[124:127], v[136:139], v[32:47]
	ds_read_b128 v[124:127], v109 offset:50176
	v_mfma_f32_32x32x16_bf16 v[16:31], v[128:131], v[132:135], v[16:31]
	v_mfma_f32_32x32x16_bf16 v[0:15], v[128:131], v[136:139], v[0:15]
	s_waitcnt lgkmcnt(0)
	v_mfma_f32_32x32x16_bf16 v[64:79], v[124:127], v[132:135], v[64:79]
	ds_read_b128 v[124:127], v110 offset:33792
	ds_read_b128 v[128:131], v110 offset:37888
	ds_read_b128 v[132:135], v111 offset:51200
	ds_read_b128 v[136:139], v111 offset:59392
	s_waitcnt lgkmcnt(0)
	v_mfma_f32_32x32x16_bf16 v[48:63], v[124:127], v[132:135], v[48:63]
	v_mfma_f32_32x32x16_bf16 v[32:47], v[124:127], v[136:139], v[32:47]
	ds_read_b128 v[124:127], v105 offset:50176
	v_mfma_f32_32x32x16_bf16 v[16:31], v[128:131], v[132:135], v[16:31]
	v_mfma_f32_32x32x16_bf16 v[0:15], v[128:131], v[136:139], v[0:15]
	s_waitcnt lgkmcnt(0)
	v_mfma_f32_32x32x16_bf16 v[64:79], v[124:127], v[132:135], v[64:79]
	ds_read_b128 v[124:127], v120 offset:33792
	ds_read_b128 v[128:131], v120 offset:37888
	ds_read_b128 v[132:135], v121 offset:51200
	ds_read_b128 v[136:139], v121 offset:59392
	s_waitcnt lgkmcnt(0)
	v_mfma_f32_32x32x16_bf16 v[48:63], v[124:127], v[132:135], v[48:63]
	v_mfma_f32_32x32x16_bf16 v[32:47], v[124:127], v[136:139], v[32:47]
	ds_read_b128 v[124:127], v122 offset:50176
	s_waitcnt vmcnt(0)
	s_waitcnt vmcnt(0) lgkmcnt(0)
	s_barrier
	global_load_lds_dwordx4 v[82:83], off
	v_lshl_add_u64 v[82:83], v[84:85], 0, s[38:39]
	s_mov_b32 m0, s6
	v_readfirstlane_b32 s6, v117
	global_load_lds_dwordx4 v[82:83], off sc1
	v_lshl_add_u64 v[82:83], v[86:87], 0, s[38:39]
	s_mov_b32 m0, s6
	v_readfirstlane_b32 s6, v118
	global_load_lds_dwordx4 v[82:83], off
	v_lshl_add_u64 v[82:83], v[88:89], 0, s[38:39]
	s_mov_b32 m0, s6
	v_readfirstlane_b32 s6, v116
	global_load_lds_dwordx4 v[82:83], off sc1
	v_lshl_add_u64 v[82:83], v[90:91], 0, s[38:39]
	s_mov_b32 m0, s6
	v_readfirstlane_b32 s6, v113
	global_load_lds_dwordx4 v[82:83], off
	v_lshl_add_u64 v[82:83], v[92:93], 0, s[38:39]
	s_mov_b32 m0, s6
	v_readfirstlane_b32 s6, v114
	global_load_lds_dwordx4 v[82:83], off sc1
	v_lshl_add_u64 v[82:83], v[94:95], 0, s[38:39]
	s_mov_b32 m0, s6
	v_readfirstlane_b32 s6, v112
	global_load_lds_dwordx4 v[82:83], off
	v_lshl_add_u64 v[82:83], v[96:97], 0, s[38:39]
	s_mov_b32 m0, s6
	v_mfma_f32_32x32x16_bf16 v[16:31], v[128:131], v[132:135], v[16:31]
	global_load_lds_dwordx4 v[82:83], off sc1
	v_mfma_f32_32x32x16_bf16 v[0:15], v[128:131], v[136:139], v[0:15]
	v_mfma_f32_32x32x16_bf16 v[64:79], v[124:127], v[132:135], v[64:79]
	s_and_saveexec_b64 s[6:7], s[42:43]
	s_cbranch_execz .LBB0_198
	v_add_u32_e32 v84, 0xc400, v102
	v_lshl_add_u64 v[82:83], v[98:99], 0, s[38:39]
	v_readfirstlane_b32 s42, v84
	s_mov_b32 m0, s42
	s_nop 0
	global_load_lds_dwordx4 v[82:83], off

; __device__ __forceinline__ int ltid() { int t = (int)threadIdx.x; asm volatile("" : "+v"(t)); return t; }
; template <bool HALO, class AL, class BL>
; __device__ __forceinline__ void gemm_core(f32x16 (&acc)[2][2], f32x16& hacc, const AL& al, const BL& bl, int K, char* lds,
;                                           const u16* halo0, const u16* halo1, int brow0, int brow1) {
;     ...
;   const int tid = ltid(), lane = tid & 63, wid = tid >> 6, wr = wid >> 1, r32 = lane & 31, hi = lane >> 5;
;   const int lrow = tid >> 3, cg = ((tid & 7) ^ ((lrow >> 1) & 7)) * 8;
;   const u16* gh = nullptr;
;   if (HALO) { const int c = ((lane & 7) ^ ((lane >> 4) & 7)) * 8; gh = ((lane < 8) ? halo0 : halo1) + c; }
;   char* lw = lds + tid * 16;
;     ...
;   const int sa = ((wr * 64 + r32) >> 1) & 7, sb0 = ((brow0 + r32) >> 1) & 7, sb1 = ((brow1 + r32) >> 1) & 7, sh = (r32 >> 1) & 7;
;   const int oa = (wr * 64 + r32) * 128, ob0 = ABYTES + (brow0 + r32) * 128, ob1 = ABYTES + (brow1 + r32) * 128, oh = (128 + r32) * 128;
;   __syncthreads();
;   ISSUE(0, 0);
;   const int nk = K >> 6;
;   for (int kt = 0; kt < nk; ++kt) {
;     asm volatile("s_waitcnt vmcnt(0)" ::: "memory");
;     __syncthreads();
;     if (kt + 1 < nk) ISSUE((kt + 1) * 64, (kt + 1) & 1);
;     const char* T = lds + (kt & 1) * BUF;
; #pragma unroll
;     for (int kk = 0; kk < 4; ++kk) {
;       const int c = kk * 2 + hi;
;       bf16x8 a0 = *(const bf16x8*)(T + oa + ((c ^ sa) << 4));
;       bf16x8 a1 = *(const bf16x8*)(T + oa + 4096 + ((c ^ sa) << 4));
;       bf16x8 b0 = *(const bf16x8*)(T + ob0 + ((c ^ sb0) << 4));
;       bf16x8 b1 = *(const bf16x8*)(T + ob1 + ((c ^ sb1) << 4));
;       acc[0][0] = MFMA(a0, b0, acc[0][0]); acc[0][1] = MFMA(a0, b1, acc[0][1]);
;       acc[1][0] = MFMA(a1, b0, acc[1][0]); acc[1][1] = MFMA(a1, b1, acc[1][1]);
;       if (HALO) { bf16x8 ah = *(const bf16x8*)(T + oh + ((c ^ sh) << 4)); hacc = MFMA(ah, b0, hacc); }
;     }
; __device__ __forceinline__ bool tile_at(int it, int nM, int nN, int& tm, int& tn) {
;   const int total = nM * nN, per = (total + 7) / 8, x = blockIdx.x & 7, lb = blockIdx.x >> 3, nlb = gridDim.x >> 3;
;   const int i = lb + it * nlb; if (i >= per) return false;
;   const int idx = x * per + i; if (idx >= total) return false;
;   const int grp = idx / (8 * nN), rem = idx - grp * 8 * nN;
;   tm = grp * 8 + (rem & 7); tn = rem >> 3; return true;
.LBB0_240:
	v_readlane_b32 s40, v253, 21
	s_or_b32 s40, s8, s40
	s_lshr_b32 s41, s40, 3
	s_and_b32 s41, s41, 0xf8
	s_lshl_b32 s60, s41, 3
	s_and_b32 s8, s8, 7
	s_sub_i32 s40, s40, s60
	s_or_b32 s8, s41, s8
	s_ashr_i32 s40, s40, 3
	s_lshl_b32 s41, s8, 18
	s_add_u32 s64, s3, s41
	v_mov_b32_e32 v1, v229
	s_waitcnt vmcnt(6)
	v_mov_b32_e32 v6, v229
	s_addc_u32 s65, s6, 0
	s_ashr_i32 s41, s40, 31
	s_lshl_b64 s[60:61], s[40:41], 18
	v_and_b32_e32 v7, 31, v6
	v_ashrrev_i32_e32 v0, 3, v6
	v_lshrrev_b32_e32 v2, 4, v6
	v_xor_b32_e32 v4, v2, v6
	s_waitcnt vmcnt(5)
	v_and_or_b32 v10, v1, 64, v7
	v_ashrrev_i32_e32 v1, 31, v0
	s_add_u32 s72, s7, s60
	v_lshlrev_b64 v[0:1], 11, v[0:1]
	v_lshlrev_b32_e32 v4, 4, v4
	s_addc_u32 s73, s18, s61
	v_lshl_add_u64 v[2:3], s[64:65], 0, v[0:1]
	v_and_b32_e32 v200, 0x70, v4
	s_waitcnt vmcnt(0)
	v_lshl_add_u64 v[64:65], v[2:3], 0, v[200:201]
	v_lshl_add_u64 v[2:3], s[72:73], 0, v[0:1]
	s_mov_b64 s[60:61], 0x10000
	v_lshl_add_u32 v95, v6, 4, 0
	s_waitcnt vmcnt(0)
	v_lshl_add_u64 v[66:67], v[2:3], 0, v[200:201]
	v_lshl_add_u64 v[2:3], v[0:1], 0, s[60:61]
	v_add_u32_e32 v99, 0x4000, v95
	v_readfirstlane_b32 s85, v95
	v_lshl_add_u64 v[4:5], s[64:65], 0, v[2:3]
	v_lshl_add_u64 v[2:3], s[72:73], 0, v[2:3]
	s_mov_b64 s[60:61], 0x20000
	s_mov_b32 m0, s85
	v_readfirstlane_b32 s92, v99
	v_add_u32_e32 v100, 0x1000, v95
	v_lshl_add_u64 v[70:71], v[2:3], 0, v[200:201]
	v_lshl_add_u64 v[2:3], v[0:1], 0, s[60:61]
	s_barrier
	global_load_lds_dwordx4 v[64:65], off
	s_mov_b32 m0, s92
	v_lshl_add_u64 v[68:69], v[4:5], 0, v[200:201]
	v_readfirstlane_b32 s70, v100
	v_add_u32_e32 v101, 0x5000, v95
	v_lshl_add_u64 v[4:5], s[64:65], 0, v[2:3]
	global_load_lds_dwordx4 v[66:67], off sc1
	s_mov_b32 m0, s70
	v_readfirstlane_b32 s71, v101
	v_lshl_add_u64 v[72:73], v[4:5], 0, v[200:201]
	v_add_u32_e32 v4, 0x2000, v95
	v_lshl_add_u64 v[2:3], s[72:73], 0, v[2:3]
	s_mov_b64 s[80:81], 0x30000
	global_load_lds_dwordx4 v[68:69], off
	s_mov_b32 m0, s71
	v_readfirstlane_b32 s41, v4
	v_lshl_add_u64 v[74:75], v[2:3], 0, v[200:201]
	v_add_u32_e32 v2, 0x6000, v95
	v_lshl_add_u64 v[0:1], v[0:1], 0, s[80:81]
	v_lshrrev_b32_e32 v8, 5, v6
	v_bfe_u32 v11, v6, 1, 3
	global_load_lds_dwordx4 v[70:71], off sc1
	s_mov_b32 m0, s41
	v_readfirstlane_b32 s60, v2
	v_lshl_add_u64 v[2:3], s[64:65], 0, v[0:1]
	v_add_u32_e32 v88, 0x3000, v95
	v_lshl_add_u64 v[0:1], s[72:73], 0, v[0:1]
	global_load_lds_dwordx4 v[72:73], off
	s_mov_b32 m0, s60
	v_readfirstlane_b32 s61, v88
	v_lshl_add_u64 v[78:79], v[0:1], 0, v[200:201]
	v_add_u32_e32 v89, 0x7000, v95
	v_bfe_u32 v0, v6, 5, 1
	v_bitop3_b32 v1, v8, v11, 1 bitop3:0x6c
	global_load_lds_dwordx4 v[74:75], off sc1
	v_lshl_add_u64 v[76:77], v[2:3], 0, v[200:201]
	s_mov_b32 m0, s61
	v_readfirstlane_b32 s63, v89
	v_lshlrev_b32_e32 v8, 4, v1
	v_bitop3_b32 v1, v0, v11, 2 bitop3:0x36
	v_add_u32_e32 v91, 0x8000, v95
	global_load_lds_dwordx4 v[76:77], off
	s_mov_b32 m0, s63
	v_lshlrev_b32_e32 v82, 4, v1
	v_bitop3_b32 v1, v0, v11, 4 bitop3:0x36
	v_bitop3_b32 v0, v0, v11, 6 bitop3:0x36
	v_add_u32_e32 v90, 0xc000, v95
	v_readfirstlane_b32 s69, v91
	global_load_lds_dwordx4 v[78:79], off sc1
	v_lshlrev_b32_e32 v114, 4, v1
	v_lshlrev_b32_e32 v118, 4, v0
	v_lshl_add_u64 v[0:1], v[64:65], 0, s[78:79]
	s_mov_b32 m0, s69
	v_readfirstlane_b32 s72, v90
	v_add_u32_e32 v92, 0x9000, v95
	s_waitcnt vmcnt(0)
	s_waitcnt vmcnt(0) lgkmcnt(0)
	s_barrier
	global_load_lds_dwordx4 v[0:1], off
	v_lshl_add_u64 v[0:1], v[66:67], 0, s[78:79]
	s_mov_b32 m0, s72
	v_readfirstlane_b32 s73, v92
	v_add_u32_e32 v93, 0xd000, v95
	global_load_lds_dwordx4 v[0:1], off sc1
	v_lshl_add_u64 v[0:1], v[68:69], 0, s[78:79]
	s_mov_b32 m0, s73
	v_readfirstlane_b32 s80, v93
	v_add_u32_e32 v94, 0xa000, v95
	global_load_lds_dwordx4 v[0:1], off
	v_lshl_add_u64 v[0:1], v[70:71], 0, s[78:79]
	s_mov_b32 m0, s80
	v_readfirstlane_b32 s81, v94
	v_add_u32_e32 v96, 0xe000, v95
	global_load_lds_dwordx4 v[0:1], off sc1
	v_lshl_add_u64 v[0:1], v[72:73], 0, s[78:79]
	s_mov_b32 m0, s81
	v_readfirstlane_b32 s82, v96
	v_add_u32_e32 v97, 0xb000, v95
	v_lshrrev_b32_e32 v9, 1, v6
	global_load_lds_dwordx4 v[0:1], off
	v_lshl_add_u64 v[0:1], v[74:75], 0, s[78:79]
	s_mov_b32 m0, s82
	v_readfirstlane_b32 s83, v97
	v_add_u32_e32 v98, 0xf000, v95
	v_and_or_b32 v2, v9, s52, v7
	global_load_lds_dwordx4 v[0:1], off sc1
	v_lshl_add_u64 v[0:1], v[76:77], 0, s[78:79]
	s_mov_b32 m0, s83
	v_readfirstlane_b32 s84, v98
	global_load_lds_dwordx4 v[0:1], off
	v_lshl_add_u64 v[0:1], v[78:79], 0, s[78:79]
	s_mov_b32 m0, s84
	v_lshl_add_u32 v119, v2, 7, 0
	v_lshl_add_u32 v120, v10, 7, 0
	global_load_lds_dwordx4 v[0:1], off sc1
	v_add_u32_e32 v80, v119, v8
	v_add_u32_e32 v81, v120, v8
	ds_read_b128 v[0:3], v80
	ds_read_b128 v[4:7], v80 offset:4096
	ds_read_b128 v[8:11], v81 offset:16384
	ds_read_b128 v[12:15], v81 offset:20480
	s_waitcnt lgkmcnt(0)
	v_mfma_f32_32x32x16_bf16 v[48:63], v[0:3], v[8:11], 0
	v_add_u32_e32 v83, v119, v82
	v_add_u32_e32 v82, v120, v82
	ds_read_b128 v[84:87], v83
	ds_read_b128 v[102:105], v83 offset:4096
	ds_read_b128 v[106:109], v82 offset:16384
	ds_read_b128 v[110:113], v82 offset:20480
	s_mov_b32 m0, s85
	v_readfirstlane_b32 s64, v88
	v_readfirstlane_b32 s65, v89
	v_mfma_f32_32x32x16_bf16 v[32:47], v[0:3], v[12:15], 0
	v_lshl_or_b32 v128, s40, 7, v127
	s_andn2_b64 vcc, exec, s[76:77]
	v_or_b32_e32 v136, 32, v128
	v_mfma_f32_32x32x16_bf16 v[16:31], v[4:7], v[8:11], 0
	v_mfma_f32_32x32x16_bf16 v[0:15], v[4:7], v[12:15], 0
	s_waitcnt lgkmcnt(0)
	v_mfma_f32_32x32x16_bf16 v[48:63], v[84:87], v[106:109], v[48:63]
	v_mfma_f32_32x32x16_bf16 v[32:47], v[84:87], v[110:113], v[32:47]
	v_add_u32_e32 v87, v119, v114
	v_add_u32_e32 v85, v120, v114
	v_add_u32_e32 v84, v119, v118
	v_add_u32_e32 v86, v120, v118
	v_mfma_f32_32x32x16_bf16 v[16:31], v[102:105], v[106:109], v[16:31]
	v_mfma_f32_32x32x16_bf16 v[0:15], v[102:105], v[110:113], v[0:15]
	ds_read_b128 v[102:105], v87
	ds_read_b128 v[106:109], v87 offset:4096
	ds_read_b128 v[110:113], v85 offset:16384
	ds_read_b128 v[114:117], v85 offset:20480
	s_waitcnt lgkmcnt(0)
	v_mfma_f32_32x32x16_bf16 v[48:63], v[102:105], v[110:113], v[48:63]
	v_mfma_f32_32x32x16_bf16 v[32:47], v[102:105], v[114:117], v[32:47]
	v_mfma_f32_32x32x16_bf16 v[16:31], v[106:109], v[110:113], v[16:31]
	v_mfma_f32_32x32x16_bf16 v[0:15], v[106:109], v[114:117], v[0:15]
	ds_read_b128 v[102:105], v84
	ds_read_b128 v[106:109], v84 offset:4096
	ds_read_b128 v[110:113], v86 offset:16384
	ds_read_b128 v[114:117], v86 offset:20480
	s_waitcnt vmcnt(0)
	s_waitcnt vmcnt(0) lgkmcnt(0)
	s_barrier
; #define MFMA(a, b, c) __builtin_amdgcn_mfma_f32_32x32x16_bf16(a, b, c, 0, 0, 0)
; #define ISSUE(k0, bf) do { char* A_ = lw + (bf) * BUF; \
;     _Pragma("unroll") for (int i_ = 0; i_ < 4; ++i_) { glds16(al.ptr(lrow + 32 * i_, (k0) + cg), A_ + i_ * 4096); glds16(bl.ptr(lrow + 32 * i_, (k0) + cg), A_ + ABYTES + i_ * 4096); } \
;     if (HALO) { if (wid == 0) glds16(gh + (k0), A_ + 16384); } } while (0)
; template <bool HALO, class AL, class BL>
; __device__ __forceinline__ void gemm_core(f32x16 (&acc)[2][2], f32x16& hacc, const AL& al, const BL& bl, int K, char* lds,
;                                           const u16* halo0, const u16* halo1, int brow0, int brow1) {
;     ...
;   for (int kt = 0; kt < nk; ++kt) {
;     asm volatile("s_waitcnt vmcnt(0)" ::: "memory");
;     __syncthreads();
;     if (kt + 1 < nk) ISSUE((kt + 1) * 64, (kt + 1) & 1);
;     const char* T = lds + (kt & 1) * BUF;
; #pragma unroll
;     for (int kk = 0; kk < 4; ++kk) {
;       const int c = kk * 2 + hi;
;       bf16x8 a0 = *(const bf16x8*)(T + oa + ((c ^ sa) << 4));
;       bf16x8 a1 = *(const bf16x8*)(T + oa + 4096 + ((c ^ sa) << 4));
;       bf16x8 b0 = *(const bf16x8*)(T + ob0 + ((c ^ sb0) << 4));
;       bf16x8 b1 = *(const bf16x8*)(T + ob1 + ((c ^ sb1) << 4));
;       acc[0][0] = MFMA(a0, b0, acc[0][0]); acc[0][1] = MFMA(a0, b1, acc[0][1]);
;       acc[1][0] = MFMA(a1, b0, acc[1][0]); acc[1][1] = MFMA(a1, b1, acc[1][1]);
;       if (HALO) { bf16x8 ah = *(const bf16x8*)(T + oh + ((c ^ sh) << 4)); hacc = MFMA(ah, b0, hacc); }
;     }
	v_mfma_f32_32x32x16_bf16 v[48:63], v[102:105], v[110:113], v[48:63]
	v_mfma_f32_32x32x16_bf16 v[32:47], v[102:105], v[114:117], v[32:47]
	v_lshl_add_u64 v[102:103], v[64:65], 0, s[24:25]
	global_load_lds_dwordx4 v[102:103], off
	v_lshl_add_u64 v[102:103], v[66:67], 0, s[24:25]
	s_mov_b32 m0, s92
	s_nop 0
	global_load_lds_dwordx4 v[102:103], off sc1
	v_lshl_add_u64 v[102:103], v[68:69], 0, s[24:25]
	s_mov_b32 m0, s70
	v_mfma_f32_32x32x16_bf16 v[16:31], v[106:109], v[110:113], v[16:31]
	global_load_lds_dwordx4 v[102:103], off
	v_lshl_add_u64 v[102:103], v[70:71], 0, s[24:25]
	s_mov_b32 m0, s71
	s_nop 0
	global_load_lds_dwordx4 v[102:103], off sc1
	v_lshl_add_u64 v[102:103], v[72:73], 0, s[24:25]
	s_mov_b32 m0, s41
	v_mfma_f32_32x32x16_bf16 v[0:15], v[106:109], v[114:117], v[0:15]
	global_load_lds_dwordx4 v[102:103], off
	v_lshl_add_u64 v[102:103], v[74:75], 0, s[24:25]
	s_mov_b32 m0, s60
	s_nop 0
	global_load_lds_dwordx4 v[102:103], off sc1
	v_lshl_add_u64 v[102:103], v[76:77], 0, s[24:25]
	s_mov_b32 m0, s61
	s_nop 0
	global_load_lds_dwordx4 v[102:103], off
	v_lshl_add_u64 v[102:103], v[78:79], 0, s[24:25]
	s_mov_b32 m0, s63
	s_nop 0
	global_load_lds_dwordx4 v[102:103], off sc1
	ds_read_b128 v[102:105], v80 offset:32768
	ds_read_b128 v[106:109], v80 offset:36864
	ds_read_b128 v[110:113], v81 offset:49152
	ds_read_b128 v[114:117], v81 offset:53248
	s_waitcnt lgkmcnt(0)
	v_mfma_f32_32x32x16_bf16 v[48:63], v[102:105], v[110:113], v[48:63]
	s_mov_b32 m0, s69
	v_mfma_f32_32x32x16_bf16 v[32:47], v[102:105], v[114:117], v[32:47]
	v_mfma_f32_32x32x16_bf16 v[16:31], v[106:109], v[110:113], v[16:31]
	v_mfma_f32_32x32x16_bf16 v[0:15], v[106:109], v[114:117], v[0:15]
	ds_read_b128 v[102:105], v83 offset:32768
	ds_read_b128 v[106:109], v83 offset:36864
	ds_read_b128 v[110:113], v82 offset:49152
	ds_read_b128 v[114:117], v82 offset:53248
	s_waitcnt lgkmcnt(0)
	v_mfma_f32_32x32x16_bf16 v[48:63], v[102:105], v[110:113], v[48:63]
	v_mfma_f32_32x32x16_bf16 v[32:47], v[102:105], v[114:117], v[32:47]
	v_mfma_f32_32x32x16_bf16 v[16:31], v[106:109], v[110:113], v[16:31]
	v_mfma_f32_32x32x16_bf16 v[0:15], v[106:109], v[114:117], v[0:15]
	ds_read_b128 v[102:105], v87 offset:32768
	ds_read_b128 v[106:109], v87 offset:36864
	ds_read_b128 v[110:113], v85 offset:49152
	ds_read_b128 v[114:117], v85 offset:53248
	s_waitcnt lgkmcnt(0)
	v_mfma_f32_32x32x16_bf16 v[48:63], v[102:105], v[110:113], v[48:63]
	v_mfma_f32_32x32x16_bf16 v[32:47], v[102:105], v[114:117], v[32:47]
	v_mfma_f32_32x32x16_bf16 v[16:31], v[106:109], v[110:113], v[16:31]
	v_mfma_f32_32x32x16_bf16 v[0:15], v[106:109], v[114:117], v[0:15]
	ds_read_b128 v[102:105], v84 offset:32768
	ds_read_b128 v[106:109], v84 offset:36864
	ds_read_b128 v[110:113], v86 offset:49152
	ds_read_b128 v[114:117], v86 offset:53248
	s_waitcnt vmcnt(0)
	s_waitcnt vmcnt(0) lgkmcnt(0)
	s_barrier
	v_mfma_f32_32x32x16_bf16 v[48:63], v[102:105], v[110:113], v[48:63]
	v_mfma_f32_32x32x16_bf16 v[32:47], v[102:105], v[114:117], v[32:47]
	v_lshl_add_u64 v[102:103], v[64:65], 0, s[74:75]
	global_load_lds_dwordx4 v[102:103], off
	v_lshl_add_u64 v[102:103], v[66:67], 0, s[74:75]
	s_mov_b32 m0, s72
	s_nop 0
	global_load_lds_dwordx4 v[102:103], off sc1
	v_lshl_add_u64 v[102:103], v[68:69], 0, s[74:75]
	s_mov_b32 m0, s73
	v_mfma_f32_32x32x16_bf16 v[16:31], v[106:109], v[110:113], v[16:31]
	global_load_lds_dwordx4 v[102:103], off
	v_lshl_add_u64 v[102:103], v[70:71], 0, s[74:75]
	s_mov_b32 m0, s80
	s_nop 0
	global_load_lds_dwordx4 v[102:103], off sc1
	v_lshl_add_u64 v[102:103], v[72:73], 0, s[74:75]
	s_mov_b32 m0, s81
	v_mfma_f32_32x32x16_bf16 v[0:15], v[106:109], v[114:117], v[0:15]
	global_load_lds_dwordx4 v[102:103], off
	v_lshl_add_u64 v[102:103], v[74:75], 0, s[74:75]
	s_mov_b32 m0, s82
	s_nop 0
	global_load_lds_dwordx4 v[102:103], off sc1
	v_lshl_add_u64 v[102:103], v[76:77], 0, s[74:75]
	s_mov_b32 m0, s83
	s_nop 0
	global_load_lds_dwordx4 v[102:103], off
	v_lshl_add_u64 v[102:103], v[78:79], 0, s[74:75]
	s_mov_b32 m0, s84
	s_nop 0
	global_load_lds_dwordx4 v[102:103], off sc1
	ds_read_b128 v[102:105], v80
	ds_read_b128 v[106:109], v80 offset:4096
	ds_read_b128 v[110:113], v81 offset:16384
	ds_read_b128 v[114:117], v81 offset:20480
	s_waitcnt lgkmcnt(0)
	v_mfma_f32_32x32x16_bf16 v[48:63], v[102:105], v[110:113], v[48:63]
	s_mov_b32 m0, s85
	v_mfma_f32_32x32x16_bf16 v[32:47], v[102:105], v[114:117], v[32:47]
	v_mfma_f32_32x32x16_bf16 v[16:31], v[106:109], v[110:113], v[16:31]
	v_mfma_f32_32x32x16_bf16 v[0:15], v[106:109], v[114:117], v[0:15]
	ds_read_b128 v[102:105], v83
	ds_read_b128 v[106:109], v83 offset:4096
	ds_read_b128 v[110:113], v82 offset:16384
	ds_read_b128 v[114:117], v82 offset:20480
	s_waitcnt lgkmcnt(0)
	v_mfma_f32_32x32x16_bf16 v[48:63], v[102:105], v[110:113], v[48:63]
	v_mfma_f32_32x32x16_bf16 v[32:47], v[102:105], v[114:117], v[32:47]
	v_mfma_f32_32x32x16_bf16 v[16:31], v[106:109], v[110:113], v[16:31]
	v_mfma_f32_32x32x16_bf16 v[0:15], v[106:109], v[114:117], v[0:15]
	ds_read_b128 v[102:105], v87
	ds_read_b128 v[106:109], v87 offset:4096
	ds_read_b128 v[110:113], v85 offset:16384
	ds_read_b128 v[114:117], v85 offset:20480
	s_waitcnt lgkmcnt(0)
	v_mfma_f32_32x32x16_bf16 v[48:63], v[102:105], v[110:113], v[48:63]
	v_mfma_f32_32x32x16_bf16 v[32:47], v[102:105], v[114:117], v[32:47]
	v_mfma_f32_32x32x16_bf16 v[16:31], v[106:109], v[110:113], v[16:31]
	v_mfma_f32_32x32x16_bf16 v[0:15], v[106:109], v[114:117], v[0:15]
	ds_read_b128 v[102:105], v84
	ds_read_b128 v[106:109], v84 offset:4096
	ds_read_b128 v[110:113], v86 offset:16384
	ds_read_b128 v[114:117], v86 offset:20480
	s_waitcnt vmcnt(0)
	s_waitcnt vmcnt(0) lgkmcnt(0)
	s_barrier
; #define MFMA(a, b, c) __builtin_amdgcn_mfma_f32_32x32x16_bf16(a, b, c, 0, 0, 0)
; #define ISSUE(k0, bf) do { char* A_ = lw + (bf) * BUF; \
;     _Pragma("unroll") for (int i_ = 0; i_ < 4; ++i_) { glds16(al.ptr(lrow + 32 * i_, (k0) + cg), A_ + i_ * 4096); glds16(bl.ptr(lrow + 32 * i_, (k0) + cg), A_ + ABYTES + i_ * 4096); } \
;     if (HALO) { if (wid == 0) glds16(gh + (k0), A_ + 16384); } } while (0)
; template <bool HALO, class AL, class BL>
; __device__ __forceinline__ void gemm_core(f32x16 (&acc)[2][2], f32x16& hacc, const AL& al, const BL& bl, int K, char* lds,
;                                           const u16* halo0, const u16* halo1, int brow0, int brow1) {
;     ...
;   for (int kt = 0; kt < nk; ++kt) {
;     asm volatile("s_waitcnt vmcnt(0)" ::: "memory");
;     __syncthreads();
;     if (kt + 1 < nk) ISSUE((kt + 1) * 64, (kt + 1) & 1);
;     const char* T = lds + (kt & 1) * BUF;
; #pragma unroll
;     for (int kk = 0; kk < 4; ++kk) {
;       const int c = kk * 2 + hi;
;       bf16x8 a0 = *(const bf16x8*)(T + oa + ((c ^ sa) << 4));
;       bf16x8 a1 = *(const bf16x8*)(T + oa + 4096 + ((c ^ sa) << 4));
;       bf16x8 b0 = *(const bf16x8*)(T + ob0 + ((c ^ sb0) << 4));
;       bf16x8 b1 = *(const bf16x8*)(T + ob1 + ((c ^ sb1) << 4));
;       acc[0][0] = MFMA(a0, b0, acc[0][0]); acc[0][1] = MFMA(a0, b1, acc[0][1]);
;       acc[1][0] = MFMA(a1, b0, acc[1][0]); acc[1][1] = MFMA(a1, b1, acc[1][1]);
;       if (HALO) { bf16x8 ah = *(const bf16x8*)(T + oh + ((c ^ sh) << 4)); hacc = MFMA(ah, b0, hacc); }
;     }
	v_mfma_f32_32x32x16_bf16 v[48:63], v[102:105], v[110:113], v[48:63]
	v_mfma_f32_32x32x16_bf16 v[32:47], v[102:105], v[114:117], v[32:47]
	v_lshl_add_u64 v[102:103], v[64:65], 0, s[20:21]
	global_load_lds_dwordx4 v[102:103], off
	v_lshl_add_u64 v[102:103], v[66:67], 0, s[20:21]
	s_mov_b32 m0, s92
	s_nop 0
	global_load_lds_dwordx4 v[102:103], off sc1
	v_lshl_add_u64 v[102:103], v[68:69], 0, s[20:21]
	s_mov_b32 m0, s70
	v_mfma_f32_32x32x16_bf16 v[16:31], v[106:109], v[110:113], v[16:31]
	global_load_lds_dwordx4 v[102:103], off
	v_lshl_add_u64 v[102:103], v[70:71], 0, s[20:21]
	s_mov_b32 m0, s71
	s_nop 0
	global_load_lds_dwordx4 v[102:103], off sc1
	v_lshl_add_u64 v[102:103], v[72:73], 0, s[20:21]
	s_mov_b32 m0, s41
	v_mfma_f32_32x32x16_bf16 v[0:15], v[106:109], v[114:117], v[0:15]
	global_load_lds_dwordx4 v[102:103], off
	v_lshl_add_u64 v[102:103], v[74:75], 0, s[20:21]
	s_mov_b32 m0, s60
	s_nop 0
	global_load_lds_dwordx4 v[102:103], off sc1
	v_lshl_add_u64 v[102:103], v[76:77], 0, s[20:21]
	s_mov_b32 m0, s61
	s_nop 0
	global_load_lds_dwordx4 v[102:103], off
	v_lshl_add_u64 v[102:103], v[78:79], 0, s[20:21]
	s_mov_b32 m0, s63
	s_nop 0
	global_load_lds_dwordx4 v[102:103], off sc1
	ds_read_b128 v[102:105], v80 offset:32768
	ds_read_b128 v[106:109], v80 offset:36864
	ds_read_b128 v[110:113], v81 offset:49152
	ds_read_b128 v[114:117], v81 offset:53248
	s_waitcnt lgkmcnt(0)
	v_mfma_f32_32x32x16_bf16 v[48:63], v[102:105], v[110:113], v[48:63]
	s_mov_b32 m0, s69
	v_mfma_f32_32x32x16_bf16 v[32:47], v[102:105], v[114:117], v[32:47]
	v_mfma_f32_32x32x16_bf16 v[16:31], v[106:109], v[110:113], v[16:31]
	v_mfma_f32_32x32x16_bf16 v[0:15], v[106:109], v[114:117], v[0:15]
	ds_read_b128 v[102:105], v83 offset:32768
	ds_read_b128 v[106:109], v83 offset:36864
	ds_read_b128 v[110:113], v82 offset:49152
	ds_read_b128 v[114:117], v82 offset:53248
	s_waitcnt lgkmcnt(0)
	v_mfma_f32_32x32x16_bf16 v[48:63], v[102:105], v[110:113], v[48:63]
	v_mfma_f32_32x32x16_bf16 v[32:47], v[102:105], v[114:117], v[32:47]
	v_mfma_f32_32x32x16_bf16 v[16:31], v[106:109], v[110:113], v[16:31]
	v_mfma_f32_32x32x16_bf16 v[0:15], v[106:109], v[114:117], v[0:15]
	ds_read_b128 v[102:105], v87 offset:32768
	ds_read_b128 v[106:109], v87 offset:36864
	ds_read_b128 v[110:113], v85 offset:49152
	ds_read_b128 v[114:117], v85 offset:53248
	s_waitcnt lgkmcnt(0)
	v_mfma_f32_32x32x16_bf16 v[48:63], v[102:105], v[110:113], v[48:63]
	v_mfma_f32_32x32x16_bf16 v[32:47], v[102:105], v[114:117], v[32:47]
	v_mfma_f32_32x32x16_bf16 v[16:31], v[106:109], v[110:113], v[16:31]
	v_mfma_f32_32x32x16_bf16 v[0:15], v[106:109], v[114:117], v[0:15]
	ds_read_b128 v[102:105], v84 offset:32768
	ds_read_b128 v[106:109], v84 offset:36864
	ds_read_b128 v[110:113], v86 offset:49152
	ds_read_b128 v[114:117], v86 offset:53248
	s_waitcnt vmcnt(0)
	s_waitcnt vmcnt(0) lgkmcnt(0)
	s_barrier
	v_mfma_f32_32x32x16_bf16 v[48:63], v[102:105], v[110:113], v[48:63]
	v_mfma_f32_32x32x16_bf16 v[32:47], v[102:105], v[114:117], v[32:47]
	v_lshl_add_u64 v[102:103], v[64:65], 0, s[86:87]
	global_load_lds_dwordx4 v[102:103], off
	v_lshl_add_u64 v[102:103], v[66:67], 0, s[86:87]
	s_mov_b32 m0, s72
	s_nop 0
	global_load_lds_dwordx4 v[102:103], off sc1
	v_lshl_add_u64 v[102:103], v[68:69], 0, s[86:87]
	s_mov_b32 m0, s73
	v_mfma_f32_32x32x16_bf16 v[16:31], v[106:109], v[110:113], v[16:31]
	global_load_lds_dwordx4 v[102:103], off
	v_lshl_add_u64 v[102:103], v[70:71], 0, s[86:87]
	s_mov_b32 m0, s80
	s_nop 0
	global_load_lds_dwordx4 v[102:103], off sc1
	v_lshl_add_u64 v[102:103], v[72:73], 0, s[86:87]
	s_mov_b32 m0, s81
	v_mfma_f32_32x32x16_bf16 v[0:15], v[106:109], v[114:117], v[0:15]
	global_load_lds_dwordx4 v[102:103], off
	v_lshl_add_u64 v[102:103], v[74:75], 0, s[86:87]
	s_mov_b32 m0, s82
	s_nop 0
	global_load_lds_dwordx4 v[102:103], off sc1
	v_lshl_add_u64 v[102:103], v[76:77], 0, s[86:87]
	s_mov_b32 m0, s83
	s_nop 0
	global_load_lds_dwordx4 v[102:103], off
	v_lshl_add_u64 v[102:103], v[78:79], 0, s[86:87]
	s_mov_b32 m0, s84
	s_nop 0
	global_load_lds_dwordx4 v[102:103], off sc1
	ds_read_b128 v[102:105], v80
	ds_read_b128 v[106:109], v80 offset:4096
	ds_read_b128 v[110:113], v81 offset:16384
	ds_read_b128 v[114:117], v81 offset:20480
	s_waitcnt lgkmcnt(0)
	v_mfma_f32_32x32x16_bf16 v[48:63], v[102:105], v[110:113], v[48:63]
	s_mov_b32 m0, s85
	v_mfma_f32_32x32x16_bf16 v[32:47], v[102:105], v[114:117], v[32:47]
	v_mfma_f32_32x32x16_bf16 v[16:31], v[106:109], v[110:113], v[16:31]
	v_mfma_f32_32x32x16_bf16 v[0:15], v[106:109], v[114:117], v[0:15]
	ds_read_b128 v[102:105], v83
	ds_read_b128 v[106:109], v83 offset:4096
	ds_read_b128 v[110:113], v82 offset:16384
	ds_read_b128 v[114:117], v82 offset:20480
	s_waitcnt lgkmcnt(0)
	v_mfma_f32_32x32x16_bf16 v[48:63], v[102:105], v[110:113], v[48:63]
	v_mfma_f32_32x32x16_bf16 v[32:47], v[102:105], v[114:117], v[32:47]
	v_mfma_f32_32x32x16_bf16 v[16:31], v[106:109], v[110:113], v[16:31]
	v_mfma_f32_32x32x16_bf16 v[0:15], v[106:109], v[114:117], v[0:15]
	ds_read_b128 v[102:105], v87
	ds_read_b128 v[106:109], v87 offset:4096
	ds_read_b128 v[110:113], v85 offset:16384
	ds_read_b128 v[114:117], v85 offset:20480
	s_waitcnt lgkmcnt(0)
	v_mfma_f32_32x32x16_bf16 v[48:63], v[102:105], v[110:113], v[48:63]
	v_mfma_f32_32x32x16_bf16 v[32:47], v[102:105], v[114:117], v[32:47]
	v_mfma_f32_32x32x16_bf16 v[16:31], v[106:109], v[110:113], v[16:31]
	v_mfma_f32_32x32x16_bf16 v[0:15], v[106:109], v[114:117], v[0:15]
	ds_read_b128 v[102:105], v84
	ds_read_b128 v[106:109], v84 offset:4096
	ds_read_b128 v[110:113], v86 offset:16384
	ds_read_b128 v[114:117], v86 offset:20480
	s_waitcnt vmcnt(0)
	s_waitcnt vmcnt(0) lgkmcnt(0)
	s_barrier
; #define MFMA(a, b, c) __builtin_amdgcn_mfma_f32_32x32x16_bf16(a, b, c, 0, 0, 0)
; #define ISSUE(k0, bf) do { char* A_ = lw + (bf) * BUF; \
;     _Pragma("unroll") for (int i_ = 0; i_ < 4; ++i_) { glds16(al.ptr(lrow + 32 * i_, (k0) + cg), A_ + i_ * 4096); glds16(bl.ptr(lrow + 32 * i_, (k0) + cg), A_ + ABYTES + i_ * 4096); } \
;     if (HALO) { if (wid == 0) glds16(gh + (k0), A_ + 16384); } } while (0)
; template <bool HALO, class AL, class BL>
; __device__ __forceinline__ void gemm_core(f32x16 (&acc)[2][2], f32x16& hacc, const AL& al, const BL& bl, int K, char* lds,
;                                           const u16* halo0, const u16* halo1, int brow0, int brow1) {
;     ...
;   for (int kt = 0; kt < nk; ++kt) {
;     asm volatile("s_waitcnt vmcnt(0)" ::: "memory");
;     __syncthreads();
;     if (kt + 1 < nk) ISSUE((kt + 1) * 64, (kt + 1) & 1);
;     const char* T = lds + (kt & 1) * BUF;
; #pragma unroll
;     for (int kk = 0; kk < 4; ++kk) {
;       const int c = kk * 2 + hi;
;       bf16x8 a0 = *(const bf16x8*)(T + oa + ((c ^ sa) << 4));
;       bf16x8 a1 = *(const bf16x8*)(T + oa + 4096 + ((c ^ sa) << 4));
;       bf16x8 b0 = *(const bf16x8*)(T + ob0 + ((c ^ sb0) << 4));
;       bf16x8 b1 = *(const bf16x8*)(T + ob1 + ((c ^ sb1) << 4));
;       acc[0][0] = MFMA(a0, b0, acc[0][0]); acc[0][1] = MFMA(a0, b1, acc[0][1]);
;       acc[1][0] = MFMA(a1, b0, acc[1][0]); acc[1][1] = MFMA(a1, b1, acc[1][1]);
;       if (HALO) { bf16x8 ah = *(const bf16x8*)(T + oh + ((c ^ sh) << 4)); hacc = MFMA(ah, b0, hacc); }
;     }
	v_mfma_f32_32x32x16_bf16 v[48:63], v[102:105], v[110:113], v[48:63]
	v_mfma_f32_32x32x16_bf16 v[32:47], v[102:105], v[114:117], v[32:47]
	v_lshl_add_u64 v[102:103], v[64:65], 0, s[30:31]
	global_load_lds_dwordx4 v[102:103], off
	v_lshl_add_u64 v[102:103], v[66:67], 0, s[30:31]
	s_mov_b32 m0, s92
	s_nop 0
	global_load_lds_dwordx4 v[102:103], off sc1
	v_lshl_add_u64 v[102:103], v[68:69], 0, s[30:31]
	s_mov_b32 m0, s70
	v_mfma_f32_32x32x16_bf16 v[16:31], v[106:109], v[110:113], v[16:31]
	global_load_lds_dwordx4 v[102:103], off
	v_lshl_add_u64 v[102:103], v[70:71], 0, s[30:31]
	s_mov_b32 m0, s71
	v_readfirstlane_b32 s70, v99
	global_load_lds_dwordx4 v[102:103], off sc1
	v_lshl_add_u64 v[102:103], v[72:73], 0, s[30:31]
	s_mov_b32 m0, s41
	v_mfma_f32_32x32x16_bf16 v[0:15], v[106:109], v[114:117], v[0:15]
	global_load_lds_dwordx4 v[102:103], off
	v_lshl_add_u64 v[102:103], v[74:75], 0, s[30:31]
	s_mov_b32 m0, s60
	v_readfirstlane_b32 s71, v100
	global_load_lds_dwordx4 v[102:103], off sc1
	v_lshl_add_u64 v[102:103], v[76:77], 0, s[30:31]
	s_mov_b32 m0, s61
	s_nop 0
	global_load_lds_dwordx4 v[102:103], off
	v_lshl_add_u64 v[102:103], v[78:79], 0, s[30:31]
	s_mov_b32 m0, s63
	s_nop 0
	global_load_lds_dwordx4 v[102:103], off sc1
	ds_read_b128 v[102:105], v80 offset:32768
	ds_read_b128 v[106:109], v80 offset:36864
	ds_read_b128 v[110:113], v81 offset:49152
	ds_read_b128 v[114:117], v81 offset:53248
	s_waitcnt lgkmcnt(0)
	v_mfma_f32_32x32x16_bf16 v[48:63], v[102:105], v[110:113], v[48:63]
	s_mov_b32 m0, s69
	v_readfirstlane_b32 s69, v95
	v_mfma_f32_32x32x16_bf16 v[32:47], v[102:105], v[114:117], v[32:47]
	v_mfma_f32_32x32x16_bf16 v[16:31], v[106:109], v[110:113], v[16:31]
	v_mfma_f32_32x32x16_bf16 v[0:15], v[106:109], v[114:117], v[0:15]
	ds_read_b128 v[102:105], v83 offset:32768
	ds_read_b128 v[106:109], v83 offset:36864
	ds_read_b128 v[110:113], v82 offset:49152
	ds_read_b128 v[114:117], v82 offset:53248
	s_waitcnt lgkmcnt(0)
	v_mfma_f32_32x32x16_bf16 v[48:63], v[102:105], v[110:113], v[48:63]
	v_mfma_f32_32x32x16_bf16 v[32:47], v[102:105], v[114:117], v[32:47]
	v_mfma_f32_32x32x16_bf16 v[16:31], v[106:109], v[110:113], v[16:31]
	v_mfma_f32_32x32x16_bf16 v[0:15], v[106:109], v[114:117], v[0:15]
	ds_read_b128 v[102:105], v87 offset:32768
	ds_read_b128 v[106:109], v87 offset:36864
	ds_read_b128 v[110:113], v85 offset:49152
	ds_read_b128 v[114:117], v85 offset:53248
	s_waitcnt lgkmcnt(0)
	v_mfma_f32_32x32x16_bf16 v[48:63], v[102:105], v[110:113], v[48:63]
	v_mfma_f32_32x32x16_bf16 v[32:47], v[102:105], v[114:117], v[32:47]
	v_mfma_f32_32x32x16_bf16 v[16:31], v[106:109], v[110:113], v[16:31]
	v_mfma_f32_32x32x16_bf16 v[0:15], v[106:109], v[114:117], v[0:15]
	ds_read_b128 v[102:105], v84 offset:32768
	ds_read_b128 v[106:109], v84 offset:36864
	ds_read_b128 v[110:113], v86 offset:49152
	ds_read_b128 v[114:117], v86 offset:53248
	s_waitcnt vmcnt(0)
	s_waitcnt vmcnt(0) lgkmcnt(0)
	s_barrier
	v_mfma_f32_32x32x16_bf16 v[48:63], v[102:105], v[110:113], v[48:63]
	v_mfma_f32_32x32x16_bf16 v[32:47], v[102:105], v[114:117], v[32:47]
	v_lshl_add_u64 v[102:103], v[64:65], 0, s[4:5]
	global_load_lds_dwordx4 v[102:103], off
	v_lshl_add_u64 v[102:103], v[66:67], 0, s[4:5]
	s_mov_b32 m0, s72
	v_readfirstlane_b32 s72, v101
	global_load_lds_dwordx4 v[102:103], off sc1
	v_lshl_add_u64 v[102:103], v[68:69], 0, s[4:5]
	s_mov_b32 m0, s73
	v_mfma_f32_32x32x16_bf16 v[16:31], v[106:109], v[110:113], v[16:31]
	global_load_lds_dwordx4 v[102:103], off
	v_lshl_add_u64 v[102:103], v[70:71], 0, s[4:5]
	s_mov_b32 m0, s80
	v_lshl_add_u64 v[100:101], v[72:73], 0, s[66:67]
	global_load_lds_dwordx4 v[102:103], off sc1
	v_lshl_add_u64 v[102:103], v[72:73], 0, s[4:5]
	s_mov_b32 m0, s81
	v_mfma_f32_32x32x16_bf16 v[0:15], v[106:109], v[114:117], v[0:15]
	global_load_lds_dwordx4 v[102:103], off
	v_lshl_add_u64 v[102:103], v[74:75], 0, s[4:5]
	s_mov_b32 m0, s82
	v_readfirstlane_b32 s73, v92
	global_load_lds_dwordx4 v[102:103], off sc1
	v_lshl_add_u64 v[102:103], v[76:77], 0, s[4:5]
	s_mov_b32 m0, s83
	v_readfirstlane_b32 s80, v93
	global_load_lds_dwordx4 v[102:103], off
	v_lshl_add_u64 v[102:103], v[78:79], 0, s[4:5]
	s_mov_b32 m0, s84
	v_readfirstlane_b32 s81, v94
	global_load_lds_dwordx4 v[102:103], off sc1
	ds_read_b128 v[102:105], v80
	ds_read_b128 v[106:109], v80 offset:4096
	ds_read_b128 v[110:113], v81 offset:16384
	ds_read_b128 v[114:117], v81 offset:20480
	s_waitcnt lgkmcnt(0)
	v_mfma_f32_32x32x16_bf16 v[48:63], v[102:105], v[110:113], v[48:63]
	s_mov_b32 m0, s69
	v_readfirstlane_b32 s82, v96
	v_readfirstlane_b32 s83, v97
	v_readfirstlane_b32 s84, v98
	v_mfma_f32_32x32x16_bf16 v[32:47], v[102:105], v[114:117], v[32:47]
	v_mfma_f32_32x32x16_bf16 v[16:31], v[106:109], v[110:113], v[16:31]
	v_mfma_f32_32x32x16_bf16 v[0:15], v[106:109], v[114:117], v[0:15]
	ds_read_b128 v[102:105], v83
	ds_read_b128 v[106:109], v83 offset:4096
	ds_read_b128 v[110:113], v82 offset:16384
	ds_read_b128 v[114:117], v82 offset:20480
	s_waitcnt lgkmcnt(0)
	v_mfma_f32_32x32x16_bf16 v[48:63], v[102:105], v[110:113], v[48:63]
	v_mfma_f32_32x32x16_bf16 v[32:47], v[102:105], v[114:117], v[32:47]
	v_mfma_f32_32x32x16_bf16 v[16:31], v[106:109], v[110:113], v[16:31]
	v_mfma_f32_32x32x16_bf16 v[0:15], v[106:109], v[114:117], v[0:15]
	ds_read_b128 v[102:105], v87
	ds_read_b128 v[106:109], v87 offset:4096
	ds_read_b128 v[110:113], v85 offset:16384
	ds_read_b128 v[114:117], v85 offset:20480
	s_waitcnt lgkmcnt(0)
	v_mfma_f32_32x32x16_bf16 v[48:63], v[102:105], v[110:113], v[48:63]
	v_mfma_f32_32x32x16_bf16 v[32:47], v[102:105], v[114:117], v[32:47]
	v_mfma_f32_32x32x16_bf16 v[16:31], v[106:109], v[110:113], v[16:31]
	v_mfma_f32_32x32x16_bf16 v[0:15], v[106:109], v[114:117], v[0:15]
	ds_read_b128 v[102:105], v84
	ds_read_b128 v[106:109], v84 offset:4096
	ds_read_b128 v[110:113], v86 offset:16384
	ds_read_b128 v[114:117], v86 offset:20480
	s_waitcnt vmcnt(0)
	s_waitcnt vmcnt(0) lgkmcnt(0)
	s_barrier
; #define MFMA(a, b, c) __builtin_amdgcn_mfma_f32_32x32x16_bf16(a, b, c, 0, 0, 0)
; #define ISSUE(k0, bf) do { char* A_ = lw + (bf) * BUF; \
;     _Pragma("unroll") for (int i_ = 0; i_ < 4; ++i_) { glds16(al.ptr(lrow + 32 * i_, (k0) + cg), A_ + i_ * 4096); glds16(bl.ptr(lrow + 32 * i_, (k0) + cg), A_ + ABYTES + i_ * 4096); } \
;     if (HALO) { if (wid == 0) glds16(gh + (k0), A_ + 16384); } } while (0)
; template <bool HALO, class AL, class BL>
; __device__ __forceinline__ void gemm_core(f32x16 (&acc)[2][2], f32x16& hacc, const AL& al, const BL& bl, int K, char* lds,
;                                           const u16* halo0, const u16* halo1, int brow0, int brow1) {
;     ...
;   for (int kt = 0; kt < nk; ++kt) {
;     asm volatile("s_waitcnt vmcnt(0)" ::: "memory");
;     __syncthreads();
;     if (kt + 1 < nk) ISSUE((kt + 1) * 64, (kt + 1) & 1);
;     const char* T = lds + (kt & 1) * BUF;
; #pragma unroll
;     for (int kk = 0; kk < 4; ++kk) {
;       const int c = kk * 2 + hi;
;       bf16x8 a0 = *(const bf16x8*)(T + oa + ((c ^ sa) << 4));
;       bf16x8 a1 = *(const bf16x8*)(T + oa + 4096 + ((c ^ sa) << 4));
;       bf16x8 b0 = *(const bf16x8*)(T + ob0 + ((c ^ sb0) << 4));
;       bf16x8 b1 = *(const bf16x8*)(T + ob1 + ((c ^ sb1) << 4));
;       acc[0][0] = MFMA(a0, b0, acc[0][0]); acc[0][1] = MFMA(a0, b1, acc[0][1]);
;       acc[1][0] = MFMA(a1, b0, acc[1][0]); acc[1][1] = MFMA(a1, b1, acc[1][1]);
;       if (HALO) { bf16x8 ah = *(const bf16x8*)(T + oh + ((c ^ sh) << 4)); hacc = MFMA(ah, b0, hacc); }
;     }
	v_mfma_f32_32x32x16_bf16 v[48:63], v[102:105], v[110:113], v[48:63]
	v_mfma_f32_32x32x16_bf16 v[32:47], v[102:105], v[114:117], v[32:47]
	v_lshl_add_u64 v[102:103], v[64:65], 0, s[66:67]
	global_load_lds_dwordx4 v[102:103], off
	v_lshl_add_u64 v[102:103], v[66:67], 0, s[66:67]
	s_mov_b32 m0, s70
	s_nop 0
	global_load_lds_dwordx4 v[102:103], off sc1
	v_lshl_add_u64 v[102:103], v[68:69], 0, s[66:67]
	s_mov_b32 m0, s71
	v_mfma_f32_32x32x16_bf16 v[16:31], v[106:109], v[110:113], v[16:31]
	global_load_lds_dwordx4 v[102:103], off
	v_lshl_add_u64 v[102:103], v[70:71], 0, s[66:67]
	s_mov_b32 m0, s72
	s_nop 0
	global_load_lds_dwordx4 v[102:103], off sc1
	s_mov_b32 m0, s41
	v_mfma_f32_32x32x16_bf16 v[0:15], v[106:109], v[114:117], v[0:15]
	global_load_lds_dwordx4 v[100:101], off
	v_lshl_add_u64 v[100:101], v[74:75], 0, s[66:67]
	s_mov_b32 m0, s60
	s_nop 0
	global_load_lds_dwordx4 v[100:101], off sc1
	v_lshl_add_u64 v[100:101], v[76:77], 0, s[66:67]
	s_mov_b32 m0, s61
	v_readfirstlane_b32 s61, v91
	global_load_lds_dwordx4 v[100:101], off
	v_lshl_add_u64 v[100:101], v[78:79], 0, s[66:67]
	s_mov_b32 m0, s63
	v_readfirstlane_b32 s63, v90
	global_load_lds_dwordx4 v[100:101], off sc1
	ds_read_b128 v[100:103], v80 offset:32768
	ds_read_b128 v[104:107], v80 offset:36864
	ds_read_b128 v[108:111], v81 offset:49152
	ds_read_b128 v[112:115], v81 offset:53248
	s_waitcnt lgkmcnt(0)
	v_mfma_f32_32x32x16_bf16 v[48:63], v[100:103], v[108:111], v[48:63]
	s_mov_b32 m0, s61
	v_lshl_add_u64 v[90:91], v[68:69], 0, s[26:27]
	v_mfma_f32_32x32x16_bf16 v[32:47], v[100:103], v[112:115], v[32:47]
	v_mfma_f32_32x32x16_bf16 v[16:31], v[104:107], v[108:111], v[16:31]
	v_mfma_f32_32x32x16_bf16 v[0:15], v[104:107], v[112:115], v[0:15]
	ds_read_b128 v[100:103], v83 offset:32768
	ds_read_b128 v[104:107], v83 offset:36864
	ds_read_b128 v[108:111], v82 offset:49152
	ds_read_b128 v[112:115], v82 offset:53248
	s_waitcnt lgkmcnt(0)
	v_mfma_f32_32x32x16_bf16 v[48:63], v[100:103], v[108:111], v[48:63]
	v_mfma_f32_32x32x16_bf16 v[32:47], v[100:103], v[112:115], v[32:47]
	v_mfma_f32_32x32x16_bf16 v[16:31], v[104:107], v[108:111], v[16:31]
	v_mfma_f32_32x32x16_bf16 v[0:15], v[104:107], v[112:115], v[0:15]
	ds_read_b128 v[100:103], v87 offset:32768
	ds_read_b128 v[104:107], v87 offset:36864
	ds_read_b128 v[108:111], v85 offset:49152
	ds_read_b128 v[112:115], v85 offset:53248
	s_waitcnt lgkmcnt(0)
	v_mfma_f32_32x32x16_bf16 v[48:63], v[100:103], v[108:111], v[48:63]
	v_mfma_f32_32x32x16_bf16 v[32:47], v[100:103], v[112:115], v[32:47]
	v_mfma_f32_32x32x16_bf16 v[16:31], v[104:107], v[108:111], v[16:31]
	v_mfma_f32_32x32x16_bf16 v[0:15], v[104:107], v[112:115], v[0:15]
	ds_read_b128 v[100:103], v84 offset:32768
	ds_read_b128 v[104:107], v84 offset:36864
	ds_read_b128 v[108:111], v86 offset:49152
	ds_read_b128 v[112:115], v86 offset:53248
	s_waitcnt vmcnt(0)
	s_waitcnt vmcnt(0) lgkmcnt(0)
	s_barrier
	v_mfma_f32_32x32x16_bf16 v[48:63], v[100:103], v[108:111], v[48:63]
	v_mfma_f32_32x32x16_bf16 v[32:47], v[100:103], v[112:115], v[32:47]
	v_lshl_add_u64 v[100:101], v[64:65], 0, s[26:27]
	global_load_lds_dwordx4 v[100:101], off
	v_lshl_add_u64 v[100:101], v[66:67], 0, s[26:27]
	s_mov_b32 m0, s63
	s_nop 0
	global_load_lds_dwordx4 v[100:101], off sc1
	s_mov_b32 m0, s73
	v_mfma_f32_32x32x16_bf16 v[16:31], v[104:107], v[108:111], v[16:31]
	global_load_lds_dwordx4 v[90:91], off
	v_lshl_add_u64 v[90:91], v[70:71], 0, s[26:27]
	s_mov_b32 m0, s80
	s_nop 0
	global_load_lds_dwordx4 v[90:91], off sc1
	v_lshl_add_u64 v[90:91], v[72:73], 0, s[26:27]
	s_mov_b32 m0, s81
	v_mfma_f32_32x32x16_bf16 v[0:15], v[104:107], v[112:115], v[0:15]
	global_load_lds_dwordx4 v[90:91], off
	v_lshl_add_u64 v[90:91], v[74:75], 0, s[26:27]
	s_mov_b32 m0, s82
	s_nop 0
	global_load_lds_dwordx4 v[90:91], off sc1
	v_lshl_add_u64 v[90:91], v[76:77], 0, s[26:27]
	s_mov_b32 m0, s83
	s_nop 0
	global_load_lds_dwordx4 v[90:91], off
	v_lshl_add_u64 v[90:91], v[78:79], 0, s[26:27]
	s_mov_b32 m0, s84
	s_nop 0
	global_load_lds_dwordx4 v[90:91], off sc1
	ds_read_b128 v[90:93], v80
	ds_read_b128 v[94:97], v80 offset:4096
	ds_read_b128 v[98:101], v81 offset:16384
	ds_read_b128 v[102:105], v81 offset:20480
	s_waitcnt lgkmcnt(0)
	v_mfma_f32_32x32x16_bf16 v[48:63], v[90:93], v[98:101], v[48:63]
	s_mov_b32 m0, s69
	v_mfma_f32_32x32x16_bf16 v[32:47], v[90:93], v[102:105], v[32:47]
	v_mfma_f32_32x32x16_bf16 v[16:31], v[94:97], v[98:101], v[16:31]
	v_mfma_f32_32x32x16_bf16 v[0:15], v[94:97], v[102:105], v[0:15]
	ds_read_b128 v[90:93], v83
	ds_read_b128 v[94:97], v83 offset:4096
	ds_read_b128 v[98:101], v82 offset:16384
	ds_read_b128 v[102:105], v82 offset:20480
	s_waitcnt lgkmcnt(0)
	v_mfma_f32_32x32x16_bf16 v[48:63], v[90:93], v[98:101], v[48:63]
	v_mfma_f32_32x32x16_bf16 v[32:47], v[90:93], v[102:105], v[32:47]
	v_mfma_f32_32x32x16_bf16 v[16:31], v[94:97], v[98:101], v[16:31]
	v_mfma_f32_32x32x16_bf16 v[0:15], v[94:97], v[102:105], v[0:15]
	ds_read_b128 v[90:93], v87
	ds_read_b128 v[94:97], v87 offset:4096
	ds_read_b128 v[98:101], v85 offset:16384
	ds_read_b128 v[102:105], v85 offset:20480
	s_waitcnt lgkmcnt(0)
	v_mfma_f32_32x32x16_bf16 v[48:63], v[90:93], v[98:101], v[48:63]
	v_mfma_f32_32x32x16_bf16 v[32:47], v[90:93], v[102:105], v[32:47]
	v_mfma_f32_32x32x16_bf16 v[16:31], v[94:97], v[98:101], v[16:31]
	v_mfma_f32_32x32x16_bf16 v[0:15], v[94:97], v[102:105], v[0:15]
	ds_read_b128 v[90:93], v84
	ds_read_b128 v[94:97], v84 offset:4096
	ds_read_b128 v[98:101], v86 offset:16384
	ds_read_b128 v[102:105], v86 offset:20480
	s_waitcnt vmcnt(0)
	s_waitcnt vmcnt(0) lgkmcnt(0)
	s_barrier
; #define MFMA(a, b, c) __builtin_amdgcn_mfma_f32_32x32x16_bf16(a, b, c, 0, 0, 0)
; #define ISSUE(k0, bf) do { char* A_ = lw + (bf) * BUF; \
;     _Pragma("unroll") for (int i_ = 0; i_ < 4; ++i_) { glds16(al.ptr(lrow + 32 * i_, (k0) + cg), A_ + i_ * 4096); glds16(bl.ptr(lrow + 32 * i_, (k0) + cg), A_ + ABYTES + i_ * 4096); } \
;     if (HALO) { if (wid == 0) glds16(gh + (k0), A_ + 16384); } } while (0)
; template <bool HALO, class AL, class BL>
; __device__ __forceinline__ void gemm_core(f32x16 (&acc)[2][2], f32x16& hacc, const AL& al, const BL& bl, int K, char* lds,
;                                           const u16* halo0, const u16* halo1, int brow0, int brow1) {
;     ...
;   for (int kt = 0; kt < nk; ++kt) {
;     asm volatile("s_waitcnt vmcnt(0)" ::: "memory");
;     __syncthreads();
;     if (kt + 1 < nk) ISSUE((kt + 1) * 64, (kt + 1) & 1);
;     const char* T = lds + (kt & 1) * BUF;
; #pragma unroll
;     for (int kk = 0; kk < 4; ++kk) {
;       const int c = kk * 2 + hi;
;       bf16x8 a0 = *(const bf16x8*)(T + oa + ((c ^ sa) << 4));
;       bf16x8 a1 = *(const bf16x8*)(T + oa + 4096 + ((c ^ sa) << 4));
;       bf16x8 b0 = *(const bf16x8*)(T + ob0 + ((c ^ sb0) << 4));
;       bf16x8 b1 = *(const bf16x8*)(T + ob1 + ((c ^ sb1) << 4));
;       acc[0][0] = MFMA(a0, b0, acc[0][0]); acc[0][1] = MFMA(a0, b1, acc[0][1]);
;       acc[1][0] = MFMA(a1, b0, acc[1][0]); acc[1][1] = MFMA(a1, b1, acc[1][1]);
;       if (HALO) { bf16x8 ah = *(const bf16x8*)(T + oh + ((c ^ sh) << 4)); hacc = MFMA(ah, b0, hacc); }
;     }
	v_mfma_f32_32x32x16_bf16 v[48:63], v[90:93], v[98:101], v[48:63]
	v_mfma_f32_32x32x16_bf16 v[32:47], v[90:93], v[102:105], v[32:47]
	v_lshl_add_u64 v[90:91], v[64:65], 0, s[88:89]
	global_load_lds_dwordx4 v[90:91], off
	v_lshl_add_u64 v[90:91], v[66:67], 0, s[88:89]
	s_mov_b32 m0, s70
	s_nop 0
	global_load_lds_dwordx4 v[90:91], off sc1
	v_lshl_add_u64 v[90:91], v[68:69], 0, s[88:89]
	s_mov_b32 m0, s71
	v_mfma_f32_32x32x16_bf16 v[16:31], v[94:97], v[98:101], v[16:31]
	global_load_lds_dwordx4 v[90:91], off
	v_lshl_add_u64 v[90:91], v[70:71], 0, s[88:89]
	s_mov_b32 m0, s72
	s_nop 0
	global_load_lds_dwordx4 v[90:91], off sc1
	v_lshl_add_u64 v[90:91], v[72:73], 0, s[88:89]
	s_mov_b32 m0, s41
	v_mfma_f32_32x32x16_bf16 v[0:15], v[94:97], v[102:105], v[0:15]
	global_load_lds_dwordx4 v[90:91], off
	v_lshl_add_u64 v[90:91], v[74:75], 0, s[88:89]
	s_mov_b32 m0, s60
	s_nop 0
	global_load_lds_dwordx4 v[90:91], off sc1
	v_lshl_add_u64 v[90:91], v[76:77], 0, s[88:89]
	s_mov_b32 m0, s64
	s_nop 0
	global_load_lds_dwordx4 v[90:91], off
	v_lshl_add_u64 v[90:91], v[78:79], 0, s[88:89]
	s_mov_b32 m0, s65
	s_nop 0
	global_load_lds_dwordx4 v[90:91], off sc1
	ds_read_b128 v[88:91], v80 offset:32768
	ds_read_b128 v[92:95], v80 offset:36864
	ds_read_b128 v[96:99], v81 offset:49152
	ds_read_b128 v[100:103], v81 offset:53248
	s_waitcnt lgkmcnt(0)
	v_mfma_f32_32x32x16_bf16 v[48:63], v[88:91], v[96:99], v[48:63]
	s_mov_b32 m0, s61
	v_mfma_f32_32x32x16_bf16 v[32:47], v[88:91], v[100:103], v[32:47]
	v_mfma_f32_32x32x16_bf16 v[16:31], v[92:95], v[96:99], v[16:31]
	v_mfma_f32_32x32x16_bf16 v[0:15], v[92:95], v[100:103], v[0:15]
	ds_read_b128 v[88:91], v83 offset:32768
	ds_read_b128 v[92:95], v83 offset:36864
	ds_read_b128 v[96:99], v82 offset:49152
	ds_read_b128 v[100:103], v82 offset:53248
	s_waitcnt lgkmcnt(0)
	v_mfma_f32_32x32x16_bf16 v[48:63], v[88:91], v[96:99], v[48:63]
	v_mfma_f32_32x32x16_bf16 v[32:47], v[88:91], v[100:103], v[32:47]
	v_mfma_f32_32x32x16_bf16 v[16:31], v[92:95], v[96:99], v[16:31]
	v_mfma_f32_32x32x16_bf16 v[0:15], v[92:95], v[100:103], v[0:15]
	ds_read_b128 v[88:91], v87 offset:32768
	ds_read_b128 v[92:95], v87 offset:36864
	ds_read_b128 v[96:99], v85 offset:49152
	ds_read_b128 v[100:103], v85 offset:53248
	s_waitcnt lgkmcnt(0)
	v_mfma_f32_32x32x16_bf16 v[48:63], v[88:91], v[96:99], v[48:63]
	v_mfma_f32_32x32x16_bf16 v[32:47], v[88:91], v[100:103], v[32:47]
	v_mfma_f32_32x32x16_bf16 v[16:31], v[92:95], v[96:99], v[16:31]
	v_mfma_f32_32x32x16_bf16 v[0:15], v[92:95], v[100:103], v[0:15]
	ds_read_b128 v[88:91], v84 offset:32768
	ds_read_b128 v[92:95], v84 offset:36864
	ds_read_b128 v[96:99], v86 offset:49152
	ds_read_b128 v[100:103], v86 offset:53248
	s_waitcnt vmcnt(0)
	s_waitcnt vmcnt(0) lgkmcnt(0)
	s_barrier
	v_mfma_f32_32x32x16_bf16 v[48:63], v[88:91], v[96:99], v[48:63]
	v_mfma_f32_32x32x16_bf16 v[32:47], v[88:91], v[100:103], v[32:47]
	v_lshl_add_u64 v[88:89], v[64:65], 0, s[22:23]
	global_load_lds_dwordx4 v[88:89], off
	v_lshl_add_u64 v[88:89], v[66:67], 0, s[22:23]
	s_mov_b32 m0, s63
	s_nop 0
	global_load_lds_dwordx4 v[88:89], off sc1
	v_lshl_add_u64 v[88:89], v[68:69], 0, s[22:23]
	s_mov_b32 m0, s73
	v_mfma_f32_32x32x16_bf16 v[16:31], v[92:95], v[96:99], v[16:31]
	global_load_lds_dwordx4 v[88:89], off
	v_lshl_add_u64 v[88:89], v[70:71], 0, s[22:23]
	s_mov_b32 m0, s80
	s_nop 0
	global_load_lds_dwordx4 v[88:89], off sc1
	v_lshl_add_u64 v[88:89], v[72:73], 0, s[22:23]
	s_mov_b32 m0, s81
	v_mfma_f32_32x32x16_bf16 v[0:15], v[92:95], v[100:103], v[0:15]
	global_load_lds_dwordx4 v[88:89], off
	v_lshl_add_u64 v[88:89], v[74:75], 0, s[22:23]
	s_mov_b32 m0, s82
	s_nop 0
	global_load_lds_dwordx4 v[88:89], off sc1
	v_lshl_add_u64 v[88:89], v[76:77], 0, s[22:23]
	s_mov_b32 m0, s83
	s_nop 0
	global_load_lds_dwordx4 v[88:89], off
	v_lshl_add_u64 v[88:89], v[78:79], 0, s[22:23]
	s_mov_b32 m0, s84
	s_nop 0
	global_load_lds_dwordx4 v[88:89], off sc1
	ds_read_b128 v[88:91], v80
	ds_read_b128 v[92:95], v80 offset:4096
	ds_read_b128 v[96:99], v81 offset:16384
	ds_read_b128 v[100:103], v81 offset:20480
	s_waitcnt lgkmcnt(0)
	v_mfma_f32_32x32x16_bf16 v[48:63], v[88:91], v[96:99], v[48:63]
	s_mov_b32 m0, s69
	v_mfma_f32_32x32x16_bf16 v[32:47], v[88:91], v[100:103], v[32:47]
	v_mfma_f32_32x32x16_bf16 v[16:31], v[92:95], v[96:99], v[16:31]
	v_mfma_f32_32x32x16_bf16 v[0:15], v[92:95], v[100:103], v[0:15]
	ds_read_b128 v[88:91], v83
	ds_read_b128 v[92:95], v83 offset:4096
	ds_read_b128 v[96:99], v82 offset:16384
	ds_read_b128 v[100:103], v82 offset:20480
	s_waitcnt lgkmcnt(0)
	v_mfma_f32_32x32x16_bf16 v[48:63], v[88:91], v[96:99], v[48:63]
	v_mfma_f32_32x32x16_bf16 v[32:47], v[88:91], v[100:103], v[32:47]
	v_mfma_f32_32x32x16_bf16 v[16:31], v[92:95], v[96:99], v[16:31]
	v_mfma_f32_32x32x16_bf16 v[0:15], v[92:95], v[100:103], v[0:15]
	ds_read_b128 v[88:91], v87
	ds_read_b128 v[92:95], v87 offset:4096
	ds_read_b128 v[96:99], v85 offset:16384
	ds_read_b128 v[100:103], v85 offset:20480
	s_waitcnt lgkmcnt(0)
	v_mfma_f32_32x32x16_bf16 v[48:63], v[88:91], v[96:99], v[48:63]
	v_mfma_f32_32x32x16_bf16 v[32:47], v[88:91], v[100:103], v[32:47]
	v_mfma_f32_32x32x16_bf16 v[16:31], v[92:95], v[96:99], v[16:31]
	v_mfma_f32_32x32x16_bf16 v[0:15], v[92:95], v[100:103], v[0:15]
	ds_read_b128 v[88:91], v84
	ds_read_b128 v[92:95], v84 offset:4096
	ds_read_b128 v[96:99], v86 offset:16384
	ds_read_b128 v[100:103], v86 offset:20480
	s_waitcnt vmcnt(0)
	s_waitcnt vmcnt(0) lgkmcnt(0)
	s_barrier
; #define MFMA(a, b, c) __builtin_amdgcn_mfma_f32_32x32x16_bf16(a, b, c, 0, 0, 0)
; #define ISSUE(k0, bf) do { char* A_ = lw + (bf) * BUF; \
;     _Pragma("unroll") for (int i_ = 0; i_ < 4; ++i_) { glds16(al.ptr(lrow + 32 * i_, (k0) + cg), A_ + i_ * 4096); glds16(bl.ptr(lrow + 32 * i_, (k0) + cg), A_ + ABYTES + i_ * 4096); } \
;     if (HALO) { if (wid == 0) glds16(gh + (k0), A_ + 16384); } } while (0)
; template <bool HALO, class AL, class BL>
; __device__ __forceinline__ void gemm_core(f32x16 (&acc)[2][2], f32x16& hacc, const AL& al, const BL& bl, int K, char* lds,
;                                           const u16* halo0, const u16* halo1, int brow0, int brow1) {
;     ...
;   for (int kt = 0; kt < nk; ++kt) {
;     asm volatile("s_waitcnt vmcnt(0)" ::: "memory");
;     __syncthreads();
;     if (kt + 1 < nk) ISSUE((kt + 1) * 64, (kt + 1) & 1);
;     const char* T = lds + (kt & 1) * BUF;
; #pragma unroll
;     for (int kk = 0; kk < 4; ++kk) {
;       const int c = kk * 2 + hi;
;       bf16x8 a0 = *(const bf16x8*)(T + oa + ((c ^ sa) << 4));
;       bf16x8 a1 = *(const bf16x8*)(T + oa + 4096 + ((c ^ sa) << 4));
;       bf16x8 b0 = *(const bf16x8*)(T + ob0 + ((c ^ sb0) << 4));
;       bf16x8 b1 = *(const bf16x8*)(T + ob1 + ((c ^ sb1) << 4));
;       acc[0][0] = MFMA(a0, b0, acc[0][0]); acc[0][1] = MFMA(a0, b1, acc[0][1]);
;       acc[1][0] = MFMA(a1, b0, acc[1][0]); acc[1][1] = MFMA(a1, b1, acc[1][1]);
;       if (HALO) { bf16x8 ah = *(const bf16x8*)(T + oh + ((c ^ sh) << 4)); hacc = MFMA(ah, b0, hacc); }
;     }
	v_mfma_f32_32x32x16_bf16 v[48:63], v[88:91], v[96:99], v[48:63]
	v_mfma_f32_32x32x16_bf16 v[32:47], v[88:91], v[100:103], v[32:47]
	v_lshl_add_u64 v[88:89], v[64:65], 0, s[90:91]
	global_load_lds_dwordx4 v[88:89], off
	v_lshl_add_u64 v[88:89], v[66:67], 0, s[90:91]
	s_mov_b32 m0, s70
	s_nop 0
	global_load_lds_dwordx4 v[88:89], off sc1
	v_lshl_add_u64 v[88:89], v[68:69], 0, s[90:91]
	s_mov_b32 m0, s71
	v_mfma_f32_32x32x16_bf16 v[16:31], v[92:95], v[96:99], v[16:31]
	global_load_lds_dwordx4 v[88:89], off
	v_lshl_add_u64 v[88:89], v[70:71], 0, s[90:91]
	s_mov_b32 m0, s72
	s_nop 0
	global_load_lds_dwordx4 v[88:89], off sc1
	v_lshl_add_u64 v[88:89], v[72:73], 0, s[90:91]
	s_mov_b32 m0, s41
	v_mfma_f32_32x32x16_bf16 v[0:15], v[92:95], v[100:103], v[0:15]
	global_load_lds_dwordx4 v[88:89], off
	v_lshl_add_u64 v[88:89], v[74:75], 0, s[90:91]
	s_mov_b32 m0, s60
	s_nop 0
	global_load_lds_dwordx4 v[88:89], off sc1
	v_lshl_add_u64 v[88:89], v[76:77], 0, s[90:91]
	s_mov_b32 m0, s64
	s_nop 0
	global_load_lds_dwordx4 v[88:89], off
	v_lshl_add_u64 v[88:89], v[78:79], 0, s[90:91]
	s_mov_b32 m0, s65
	s_nop 0
	global_load_lds_dwordx4 v[88:89], off sc1
	ds_read_b128 v[88:91], v80 offset:32768
	ds_read_b128 v[92:95], v80 offset:36864
	ds_read_b128 v[96:99], v81 offset:49152
	ds_read_b128 v[100:103], v81 offset:53248
	s_waitcnt lgkmcnt(0)
	v_mfma_f32_32x32x16_bf16 v[48:63], v[88:91], v[96:99], v[48:63]
	s_mov_b32 m0, s61
	v_mfma_f32_32x32x16_bf16 v[32:47], v[88:91], v[100:103], v[32:47]
	v_mfma_f32_32x32x16_bf16 v[16:31], v[92:95], v[96:99], v[16:31]
	v_mfma_f32_32x32x16_bf16 v[0:15], v[92:95], v[100:103], v[0:15]
	ds_read_b128 v[88:91], v83 offset:32768
	ds_read_b128 v[92:95], v83 offset:36864
	ds_read_b128 v[96:99], v82 offset:49152
	ds_read_b128 v[100:103], v82 offset:53248
	s_waitcnt lgkmcnt(0)
	v_mfma_f32_32x32x16_bf16 v[48:63], v[88:91], v[96:99], v[48:63]
	v_mfma_f32_32x32x16_bf16 v[32:47], v[88:91], v[100:103], v[32:47]
	v_mfma_f32_32x32x16_bf16 v[16:31], v[92:95], v[96:99], v[16:31]
	v_mfma_f32_32x32x16_bf16 v[0:15], v[92:95], v[100:103], v[0:15]
	ds_read_b128 v[88:91], v87 offset:32768
	ds_read_b128 v[92:95], v87 offset:36864
	ds_read_b128 v[96:99], v85 offset:49152
	ds_read_b128 v[100:103], v85 offset:53248
	s_waitcnt lgkmcnt(0)
	v_mfma_f32_32x32x16_bf16 v[48:63], v[88:91], v[96:99], v[48:63]
	v_mfma_f32_32x32x16_bf16 v[32:47], v[88:91], v[100:103], v[32:47]
	v_mfma_f32_32x32x16_bf16 v[16:31], v[92:95], v[96:99], v[16:31]
	v_mfma_f32_32x32x16_bf16 v[0:15], v[92:95], v[100:103], v[0:15]
	ds_read_b128 v[88:91], v84 offset:32768
	ds_read_b128 v[92:95], v84 offset:36864
	ds_read_b128 v[96:99], v86 offset:49152
	ds_read_b128 v[100:103], v86 offset:53248
	s_waitcnt vmcnt(0)
	s_waitcnt vmcnt(0) lgkmcnt(0)
	s_barrier
	v_mfma_f32_32x32x16_bf16 v[48:63], v[88:91], v[96:99], v[48:63]
	v_mfma_f32_32x32x16_bf16 v[32:47], v[88:91], v[100:103], v[32:47]
	v_lshl_add_u64 v[88:89], v[64:65], 0, s[0:1]
	global_load_lds_dwordx4 v[88:89], off
	v_lshl_add_u64 v[88:89], v[66:67], 0, s[0:1]
	s_mov_b32 m0, s63
	s_nop 0
	global_load_lds_dwordx4 v[88:89], off sc1
	v_lshl_add_u64 v[88:89], v[68:69], 0, s[0:1]
	s_mov_b32 m0, s73
	v_mfma_f32_32x32x16_bf16 v[16:31], v[92:95], v[96:99], v[16:31]
	global_load_lds_dwordx4 v[88:89], off
	v_lshl_add_u64 v[88:89], v[70:71], 0, s[0:1]
	s_mov_b32 m0, s80
	s_nop 0
	global_load_lds_dwordx4 v[88:89], off sc1
	v_lshl_add_u64 v[88:89], v[72:73], 0, s[0:1]
	s_mov_b32 m0, s81
	v_mfma_f32_32x32x16_bf16 v[0:15], v[92:95], v[100:103], v[0:15]
	global_load_lds_dwordx4 v[88:89], off
	v_lshl_add_u64 v[88:89], v[74:75], 0, s[0:1]
	s_mov_b32 m0, s82
	s_nop 0
	global_load_lds_dwordx4 v[88:89], off sc1
	v_lshl_add_u64 v[88:89], v[76:77], 0, s[0:1]
	s_mov_b32 m0, s83
	s_nop 0
	global_load_lds_dwordx4 v[88:89], off
	v_lshl_add_u64 v[88:89], v[78:79], 0, s[0:1]
	s_mov_b32 m0, s84
	s_nop 0
	global_load_lds_dwordx4 v[88:89], off sc1
	ds_read_b128 v[88:91], v80
	ds_read_b128 v[92:95], v80 offset:4096
	ds_read_b128 v[96:99], v81 offset:16384
	ds_read_b128 v[100:103], v81 offset:20480
	s_waitcnt lgkmcnt(0)
	v_mfma_f32_32x32x16_bf16 v[48:63], v[88:91], v[96:99], v[48:63]
	s_mov_b32 m0, s69
	v_mfma_f32_32x32x16_bf16 v[32:47], v[88:91], v[100:103], v[32:47]
	v_mfma_f32_32x32x16_bf16 v[16:31], v[92:95], v[96:99], v[16:31]
	v_mfma_f32_32x32x16_bf16 v[0:15], v[92:95], v[100:103], v[0:15]
	ds_read_b128 v[88:91], v83
	ds_read_b128 v[92:95], v83 offset:4096
	ds_read_b128 v[96:99], v82 offset:16384
	ds_read_b128 v[100:103], v82 offset:20480
	s_waitcnt lgkmcnt(0)
	v_mfma_f32_32x32x16_bf16 v[48:63], v[88:91], v[96:99], v[48:63]
	v_mfma_f32_32x32x16_bf16 v[32:47], v[88:91], v[100:103], v[32:47]
	v_mfma_f32_32x32x16_bf16 v[16:31], v[92:95], v[96:99], v[16:31]
	v_mfma_f32_32x32x16_bf16 v[0:15], v[92:95], v[100:103], v[0:15]
	ds_read_b128 v[88:91], v87
	ds_read_b128 v[92:95], v87 offset:4096
	ds_read_b128 v[96:99], v85 offset:16384
	ds_read_b128 v[100:103], v85 offset:20480
	s_waitcnt lgkmcnt(0)
	v_mfma_f32_32x32x16_bf16 v[48:63], v[88:91], v[96:99], v[48:63]
	v_mfma_f32_32x32x16_bf16 v[32:47], v[88:91], v[100:103], v[32:47]
	v_mfma_f32_32x32x16_bf16 v[16:31], v[92:95], v[96:99], v[16:31]
	v_mfma_f32_32x32x16_bf16 v[0:15], v[92:95], v[100:103], v[0:15]
	ds_read_b128 v[88:91], v84
	ds_read_b128 v[92:95], v84 offset:4096
	ds_read_b128 v[96:99], v86 offset:16384
	ds_read_b128 v[100:103], v86 offset:20480
	s_waitcnt vmcnt(0)
	s_waitcnt vmcnt(0) lgkmcnt(0)
	s_barrier
; #define MFMA(a, b, c) __builtin_amdgcn_mfma_f32_32x32x16_bf16(a, b, c, 0, 0, 0)
; #define ISSUE(k0, bf) do { char* A_ = lw + (bf) * BUF; \
;     _Pragma("unroll") for (int i_ = 0; i_ < 4; ++i_) { glds16(al.ptr(lrow + 32 * i_, (k0) + cg), A_ + i_ * 4096); glds16(bl.ptr(lrow + 32 * i_, (k0) + cg), A_ + ABYTES + i_ * 4096); } \
;     if (HALO) { if (wid == 0) glds16(gh + (k0), A_ + 16384); } } while (0)
; template <bool HALO, class AL, class BL>
; __device__ __forceinline__ void gemm_core(f32x16 (&acc)[2][2], f32x16& hacc, const AL& al, const BL& bl, int K, char* lds,
;                                           const u16* halo0, const u16* halo1, int brow0, int brow1) {
;     ...
;   for (int kt = 0; kt < nk; ++kt) {
;     asm volatile("s_waitcnt vmcnt(0)" ::: "memory");
;     __syncthreads();
;     if (kt + 1 < nk) ISSUE((kt + 1) * 64, (kt + 1) & 1);
;     const char* T = lds + (kt & 1) * BUF;
; #pragma unroll
;     for (int kk = 0; kk < 4; ++kk) {
;       const int c = kk * 2 + hi;
;       bf16x8 a0 = *(const bf16x8*)(T + oa + ((c ^ sa) << 4));
;       bf16x8 a1 = *(const bf16x8*)(T + oa + 4096 + ((c ^ sa) << 4));
;       bf16x8 b0 = *(const bf16x8*)(T + ob0 + ((c ^ sb0) << 4));
;       bf16x8 b1 = *(const bf16x8*)(T + ob1 + ((c ^ sb1) << 4));
;       acc[0][0] = MFMA(a0, b0, acc[0][0]); acc[0][1] = MFMA(a0, b1, acc[0][1]);
;       acc[1][0] = MFMA(a1, b0, acc[1][0]); acc[1][1] = MFMA(a1, b1, acc[1][1]);
;       if (HALO) { bf16x8 ah = *(const bf16x8*)(T + oh + ((c ^ sh) << 4)); hacc = MFMA(ah, b0, hacc); }
;     }
	v_mfma_f32_32x32x16_bf16 v[48:63], v[88:91], v[96:99], v[48:63]
	v_mfma_f32_32x32x16_bf16 v[32:47], v[88:91], v[100:103], v[32:47]
	v_lshl_add_u64 v[88:89], v[64:65], 0, s[34:35]
	global_load_lds_dwordx4 v[88:89], off
	v_lshl_add_u64 v[88:89], v[66:67], 0, s[34:35]
	s_mov_b32 m0, s70
	v_lshl_add_u64 v[64:65], v[64:65], 0, s[38:39]
	global_load_lds_dwordx4 v[88:89], off sc1
	v_lshl_add_u64 v[88:89], v[68:69], 0, s[34:35]
	s_mov_b32 m0, s71
	v_mfma_f32_32x32x16_bf16 v[16:31], v[92:95], v[96:99], v[16:31]
	global_load_lds_dwordx4 v[88:89], off
	v_lshl_add_u64 v[88:89], v[70:71], 0, s[34:35]
	s_mov_b32 m0, s72
	s_nop 0
	global_load_lds_dwordx4 v[88:89], off sc1
	v_lshl_add_u64 v[88:89], v[72:73], 0, s[34:35]
	s_mov_b32 m0, s41
	v_mfma_f32_32x32x16_bf16 v[0:15], v[92:95], v[100:103], v[0:15]
	global_load_lds_dwordx4 v[88:89], off
	v_lshl_add_u64 v[88:89], v[74:75], 0, s[34:35]
	s_mov_b32 m0, s60
	s_nop 0
	global_load_lds_dwordx4 v[88:89], off sc1
	v_lshl_add_u64 v[88:89], v[76:77], 0, s[34:35]
	s_mov_b32 m0, s64
	s_nop 0
	global_load_lds_dwordx4 v[88:89], off
	v_lshl_add_u64 v[88:89], v[78:79], 0, s[34:35]
	s_mov_b32 m0, s65
	s_nop 0
	global_load_lds_dwordx4 v[88:89], off sc1
	ds_read_b128 v[88:91], v80 offset:32768
	ds_read_b128 v[92:95], v80 offset:36864
	ds_read_b128 v[96:99], v81 offset:49152
	ds_read_b128 v[100:103], v81 offset:53248
	s_waitcnt lgkmcnt(0)
	v_mfma_f32_32x32x16_bf16 v[48:63], v[88:91], v[96:99], v[48:63]
	s_mov_b32 m0, s61
	s_mov_b64 s[60:61], -1
	v_mfma_f32_32x32x16_bf16 v[32:47], v[88:91], v[100:103], v[32:47]
	v_mfma_f32_32x32x16_bf16 v[16:31], v[92:95], v[96:99], v[16:31]
	v_mfma_f32_32x32x16_bf16 v[0:15], v[92:95], v[100:103], v[0:15]
	ds_read_b128 v[88:91], v83 offset:32768
	ds_read_b128 v[92:95], v83 offset:36864
	ds_read_b128 v[96:99], v82 offset:49152
	ds_read_b128 v[100:103], v82 offset:53248
	s_waitcnt lgkmcnt(0)
	v_mfma_f32_32x32x16_bf16 v[48:63], v[88:91], v[96:99], v[48:63]
	v_mfma_f32_32x32x16_bf16 v[32:47], v[88:91], v[100:103], v[32:47]
	v_mfma_f32_32x32x16_bf16 v[16:31], v[92:95], v[96:99], v[16:31]
	v_mfma_f32_32x32x16_bf16 v[0:15], v[92:95], v[100:103], v[0:15]
	ds_read_b128 v[88:91], v87 offset:32768
	ds_read_b128 v[92:95], v87 offset:36864
	ds_read_b128 v[96:99], v85 offset:49152
	ds_read_b128 v[100:103], v85 offset:53248
	s_waitcnt lgkmcnt(0)
	v_mfma_f32_32x32x16_bf16 v[48:63], v[88:91], v[96:99], v[48:63]
	v_mfma_f32_32x32x16_bf16 v[32:47], v[88:91], v[100:103], v[32:47]
	v_mfma_f32_32x32x16_bf16 v[16:31], v[92:95], v[96:99], v[16:31]
	v_mfma_f32_32x32x16_bf16 v[0:15], v[92:95], v[100:103], v[0:15]
	ds_read_b128 v[88:91], v84 offset:32768
	ds_read_b128 v[92:95], v84 offset:36864
	ds_read_b128 v[96:99], v86 offset:49152
	ds_read_b128 v[100:103], v86 offset:53248
	s_waitcnt vmcnt(0)
	s_waitcnt vmcnt(0) lgkmcnt(0)
	s_barrier
	global_load_lds_dwordx4 v[64:65], off
	v_lshl_add_u64 v[64:65], v[66:67], 0, s[38:39]
	s_mov_b32 m0, s63
	v_mfma_f32_32x32x16_bf16 v[48:63], v[88:91], v[96:99], v[48:63]
	global_load_lds_dwordx4 v[64:65], off sc1
	v_lshl_add_u64 v[64:65], v[68:69], 0, s[38:39]
	s_mov_b32 m0, s73
	s_nop 0
	global_load_lds_dwordx4 v[64:65], off
	v_lshl_add_u64 v[64:65], v[70:71], 0, s[38:39]
	s_mov_b32 m0, s80
	v_mfma_f32_32x32x16_bf16 v[32:47], v[88:91], v[100:103], v[32:47]
	global_load_lds_dwordx4 v[64:65], off sc1
	v_lshl_add_u64 v[64:65], v[72:73], 0, s[38:39]
	s_mov_b32 m0, s81
	s_nop 0
	global_load_lds_dwordx4 v[64:65], off
	v_lshl_add_u64 v[64:65], v[74:75], 0, s[38:39]
	s_mov_b32 m0, s82
	v_mfma_f32_32x32x16_bf16 v[16:31], v[92:95], v[96:99], v[16:31]
	global_load_lds_dwordx4 v[64:65], off sc1
	v_lshl_add_u64 v[64:65], v[76:77], 0, s[38:39]
	s_mov_b32 m0, s83
	s_nop 0
	global_load_lds_dwordx4 v[64:65], off
	v_lshl_add_u64 v[64:65], v[78:79], 0, s[38:39]
	s_mov_b32 m0, s84
	v_mfma_f32_32x32x16_bf16 v[0:15], v[92:95], v[100:103], v[0:15]
	global_load_lds_dwordx4 v[64:65], off sc1
	ds_read_b128 v[64:67], v80
	ds_read_b128 v[68:71], v80 offset:4096
	ds_read_b128 v[72:75], v81 offset:16384
	ds_read_b128 v[76:79], v81 offset:20480
	s_waitcnt lgkmcnt(0)
	v_mfma_f32_32x32x16_bf16 v[48:63], v[64:67], v[72:75], v[48:63]
	v_mfma_f32_32x32x16_bf16 v[32:47], v[64:67], v[76:79], v[32:47]
	v_mfma_f32_32x32x16_bf16 v[16:31], v[68:71], v[72:75], v[16:31]
	v_mfma_f32_32x32x16_bf16 v[0:15], v[68:71], v[76:79], v[0:15]
	ds_read_b128 v[64:67], v83
	ds_read_b128 v[68:71], v83 offset:4096
	ds_read_b128 v[72:75], v82 offset:16384
	ds_read_b128 v[76:79], v82 offset:20480
	s_waitcnt lgkmcnt(0)
	v_mfma_f32_32x32x16_bf16 v[48:63], v[64:67], v[72:75], v[48:63]
	v_mfma_f32_32x32x16_bf16 v[32:47], v[64:67], v[76:79], v[32:47]
	v_mfma_f32_32x32x16_bf16 v[16:31], v[68:71], v[72:75], v[16:31]
	v_mfma_f32_32x32x16_bf16 v[0:15], v[68:71], v[76:79], v[0:15]
	ds_read_b128 v[64:67], v87
	ds_read_b128 v[68:71], v87 offset:4096
	ds_read_b128 v[72:75], v85 offset:16384
	ds_read_b128 v[76:79], v85 offset:20480
	s_waitcnt lgkmcnt(0)
	v_mfma_f32_32x32x16_bf16 v[48:63], v[64:67], v[72:75], v[48:63]
	v_mfma_f32_32x32x16_bf16 v[32:47], v[64:67], v[76:79], v[32:47]
	v_mfma_f32_32x32x16_bf16 v[16:31], v[68:71], v[72:75], v[16:31]
	v_mfma_f32_32x32x16_bf16 v[0:15], v[68:71], v[76:79], v[0:15]
	ds_read_b128 v[64:67], v84
	ds_read_b128 v[68:71], v84 offset:4096
	ds_read_b128 v[72:75], v86 offset:16384
	ds_read_b128 v[76:79], v86 offset:20480
	s_waitcnt vmcnt(0)
	s_waitcnt vmcnt(0) lgkmcnt(0)
	s_barrier
; __device__ __forceinline__ float bf2f(u16 v) { return __uint_as_float(((unsigned)v) << 16); }
; __device__ __forceinline__ int opq() { int z = 0; asm volatile("" : "+v"(z)); return z; }
; #define MFMA(a, b, c) __builtin_amdgcn_mfma_f32_32x32x16_bf16(a, b, c, 0, 0, 0)
; template <bool HALO, class AL, class BL>
; __device__ __forceinline__ void gemm_core(f32x16 (&acc)[2][2], f32x16& hacc, const AL& al, const BL& bl, int K, char* lds,
;                                           const u16* halo0, const u16* halo1, int brow0, int brow1) {
;     ...
;   for (int kt = 0; kt < nk; ++kt) {
;     asm volatile("s_waitcnt vmcnt(0)" ::: "memory");
;     __syncthreads();
;     if (kt + 1 < nk) ISSUE((kt + 1) * 64, (kt + 1) & 1);
;     const char* T = lds + (kt & 1) * BUF;
; #pragma unroll
;     for (int kk = 0; kk < 4; ++kk) {
;       const int c = kk * 2 + hi;
;       bf16x8 a0 = *(const bf16x8*)(T + oa + ((c ^ sa) << 4));
;       bf16x8 a1 = *(const bf16x8*)(T + oa + 4096 + ((c ^ sa) << 4));
;       bf16x8 b0 = *(const bf16x8*)(T + ob0 + ((c ^ sb0) << 4));
;       bf16x8 b1 = *(const bf16x8*)(T + ob1 + ((c ^ sb1) << 4));
;       acc[0][0] = MFMA(a0, b0, acc[0][0]); acc[0][1] = MFMA(a0, b1, acc[0][1]);
;       acc[1][0] = MFMA(a1, b0, acc[1][0]); acc[1][1] = MFMA(a1, b1, acc[1][1]);
;       if (HALO) { bf16x8 ah = *(const bf16x8*)(T + oh + ((c ^ sh) << 4)); hacc = MFMA(ah, b0, hacc); }
;     }
; __device__ __forceinline__ void phase_wout(const P& p, int layer, char* lds) {
;     ...
;     const unsigned rb = (unsigned)(tm * 128 + wr * 64 + 4 * hi + opq());
;     _Float16* pre1 = (_Float16*)(p.ws + OFF_PRE1);
; #pragma unroll
;     for (int mi = 0; mi < 2; ++mi) {
;       float xr[2][16];
;       if (layer == 0) {
; #pragma unroll
;         for (int ni = 0; ni < 2; ++ni)
; #pragma unroll
;           for (int r = 0; r < 16; ++r) xr[ni][r] = p.x[(rb + mi * 32 + (r & 3) + 8 * (r >> 2)) * DM + tn * 128 + wc * 64 + ni * 32 + r32];
;       } else {
; #pragma unroll
;         for (int ni = 0; ni < 2; ++ni)
; #pragma unroll
;           for (int r = 0; r < 16; ++r) xr[ni][r] = bf2f(xbr[(rb + mi * 32 + (r & 3) + 8 * (r >> 2)) * DM + tn * 128 + wc * 64 + ni * 32 + r32]);
	v_mfma_f32_32x32x16_bf16 v[48:63], v[64:67], v[72:75], v[48:63]
	v_mfma_f32_32x32x16_bf16 v[32:47], v[64:67], v[76:79], v[32:47]
	v_mfma_f32_32x32x16_bf16 v[16:31], v[68:71], v[72:75], v[16:31]
	v_mfma_f32_32x32x16_bf16 v[0:15], v[68:71], v[76:79], v[0:15]
	ds_read_b128 v[64:67], v80 offset:32768
	ds_read_b128 v[68:71], v80 offset:36864
	ds_read_b128 v[72:75], v81 offset:49152
	ds_read_b128 v[76:79], v81 offset:53248
	s_waitcnt lgkmcnt(1)
	v_mfma_f32_32x32x16_bf16 v[48:63], v[64:67], v[72:75], v[48:63]
	s_waitcnt lgkmcnt(0)
	v_mfma_f32_32x32x16_bf16 v[32:47], v[64:67], v[76:79], v[32:47]
	v_mfma_f32_32x32x16_bf16 v[16:31], v[68:71], v[72:75], v[16:31]
	v_mfma_f32_32x32x16_bf16 v[0:15], v[68:71], v[76:79], v[0:15]
	ds_read_b128 v[64:67], v83 offset:32768
	ds_read_b128 v[68:71], v83 offset:36864
	ds_read_b128 v[72:75], v82 offset:49152
	ds_read_b128 v[76:79], v82 offset:53248
	s_waitcnt lgkmcnt(1)
	v_mfma_f32_32x32x16_bf16 v[48:63], v[64:67], v[72:75], v[48:63]
	s_waitcnt lgkmcnt(0)
	v_mfma_f32_32x32x16_bf16 v[32:47], v[64:67], v[76:79], v[32:47]
	v_mfma_f32_32x32x16_bf16 v[16:31], v[68:71], v[72:75], v[16:31]
	v_mfma_f32_32x32x16_bf16 v[0:15], v[68:71], v[76:79], v[0:15]
	ds_read_b128 v[64:67], v87 offset:32768
	ds_read_b128 v[68:71], v87 offset:36864
	ds_read_b128 v[72:75], v85 offset:49152
	ds_read_b128 v[76:79], v85 offset:53248
	s_waitcnt lgkmcnt(1)
	v_mfma_f32_32x32x16_bf16 v[48:63], v[64:67], v[72:75], v[48:63]
	s_waitcnt lgkmcnt(0)
	v_mfma_f32_32x32x16_bf16 v[32:47], v[64:67], v[76:79], v[32:47]
	v_mfma_f32_32x32x16_bf16 v[16:31], v[68:71], v[72:75], v[16:31]
	v_mfma_f32_32x32x16_bf16 v[0:15], v[68:71], v[76:79], v[0:15]
	ds_read_b128 v[64:67], v84 offset:32768
	ds_read_b128 v[68:71], v84 offset:36864
	ds_read_b128 v[72:75], v86 offset:49152
	ds_read_b128 v[76:79], v86 offset:53248
	s_waitcnt lgkmcnt(1)
	v_mfma_f32_32x32x16_bf16 v[48:63], v[64:67], v[72:75], v[48:63]
	s_waitcnt lgkmcnt(0)
	v_mfma_f32_32x32x16_bf16 v[32:47], v[64:67], v[76:79], v[32:47]
	v_mov_b32_e32 v64, v201
	v_lshl_add_u32 v65, s8, 7, v126
	s_nop 0
	v_add_lshl_u32 v129, v65, v64, 10
	v_cndmask_b32_e64 v64, 0, 1, s[76:77]
	v_add_u32_e32 v157, 0x400, v129
	v_mfma_f32_32x32x16_bf16 v[16:31], v[68:71], v[72:75], v[16:31]
	v_add_u32_e32 v156, 0x800, v129
	v_add_u32_e32 v155, 0xc00, v129
	v_add_u32_e32 v153, 0x2000, v129
	v_add_u32_e32 v151, 0x2400, v129
	v_add_u32_e32 v150, 0x2800, v129
	v_add_u32_e32 v149, 0x2c00, v129
	v_add_u32_e32 v146, 0x4000, v129
	v_mfma_f32_32x32x16_bf16 v[0:15], v[68:71], v[76:79], v[0:15]
	v_add_u32_e32 v145, 0x4400, v129
	v_add_u32_e32 v144, 0x4800, v129
	v_add_u32_e32 v142, 0x4c00, v129
	v_add_u32_e32 v141, 0x6000, v129
	v_add_u32_e32 v140, 0x6400, v129
	v_add_u32_e32 v138, 0x6800, v129
	v_add_u32_e32 v137, 0x6c00, v129
	v_add_u32_e32 v200, v129, v128
	v_cmp_ne_u32_e64 s[40:41], 1, v64
	v_add_u32_e32 v90, v157, v128
	v_add_u32_e32 v92, v156, v128
	v_add_u32_e32 v88, v155, v128
	v_add_u32_e32 v86, v153, v128
	v_add_u32_e32 v84, v151, v128
	v_add_u32_e32 v82, v150, v128
	v_add_u32_e32 v80, v149, v128
	v_add_u32_e32 v76, v146, v128
	v_add_u32_e32 v78, v145, v128
	v_add_u32_e32 v74, v144, v128
	v_add_u32_e32 v72, v142, v128
	v_add_u32_e32 v70, v141, v128
	v_add_u32_e32 v68, v140, v128
	v_add_u32_e32 v66, v138, v128
	v_add_u32_e32 v64, v137, v128
	s_cbranch_vccnz .LBB0_242
; __device__ __forceinline__ float bf2f(u16 v) { return __uint_as_float(((unsigned)v) << 16); }
; __device__ __forceinline__ void phase_wout(const P& p, int layer, char* lds) {
;     ...
; #pragma unroll
;         for (int ni = 0; ni < 2; ++ni)
; #pragma unroll
;           for (int r = 0; r < 16; ++r) xr[ni][r] = bf2f(xbr[(rb + mi * 32 + (r & 3) + 8 * (r >> 2)) * DM + tn * 128 + wc * 64 + ni * 32 + r32]);
;       }
	v_lshl_add_u64 v[94:95], v[200:201], 1, s[42:43]
	v_mov_b32_e32 v91, v201
	v_lshl_add_u64 v[96:97], v[90:91], 1, s[42:43]
	global_load_ushort v65, v[94:95], off
	global_load_ushort v67, v[96:97], off
	v_mov_b32_e32 v93, v201
	v_lshl_add_u64 v[94:95], v[92:93], 1, s[42:43]
	v_mov_b32_e32 v89, v201
	v_lshl_add_u64 v[96:97], v[88:89], 1, s[42:43]
	v_mov_b32_e32 v87, v201
	v_mov_b32_e32 v85, v201
	v_mov_b32_e32 v83, v201
	v_mov_b32_e32 v81, v201
	v_mov_b32_e32 v77, v201
	v_mov_b32_e32 v79, v201
	v_mov_b32_e32 v75, v201
	v_mov_b32_e32 v73, v201
	v_mov_b32_e32 v71, v201
	v_mov_b32_e32 v69, v201
	v_or_b32_e32 v168, 32, v128
	v_mov_b32_e32 v205, v179
	v_mov_b32_e32 v217, v181
	s_mov_b64 s[60:61], 0
	s_waitcnt vmcnt(1)
	v_lshlrev_b32_e32 v130, 16, v65
	s_waitcnt vmcnt(0)
	v_lshlrev_b32_e32 v131, 16, v67
	global_load_ushort v65, v[94:95], off
	global_load_ushort v67, v[96:97], off
	v_lshl_add_u64 v[94:95], v[86:87], 1, s[42:43]
	v_lshl_add_u64 v[96:97], v[84:85], 1, s[42:43]
	s_waitcnt vmcnt(1)
	v_lshlrev_b32_e32 v132, 16, v65
	s_waitcnt vmcnt(0)
	v_lshlrev_b32_e32 v133, 16, v67
	global_load_ushort v65, v[94:95], off
	global_load_ushort v67, v[96:97], off
	v_lshl_add_u64 v[94:95], v[82:83], 1, s[42:43]
	v_lshl_add_u64 v[96:97], v[80:81], 1, s[42:43]
	s_waitcnt vmcnt(1)
	v_lshlrev_b32_e32 v134, 16, v65
	s_waitcnt vmcnt(0)
	v_lshlrev_b32_e32 v135, 16, v67
	global_load_ushort v65, v[94:95], off
	global_load_ushort v67, v[96:97], off
	v_lshl_add_u64 v[94:95], v[76:77], 1, s[42:43]
	v_lshl_add_u64 v[96:97], v[78:79], 1, s[42:43]
	s_waitcnt vmcnt(1)
	v_lshlrev_b32_e32 v139, 16, v65
	s_waitcnt vmcnt(0)
	v_lshlrev_b32_e32 v143, 16, v67
	global_load_ushort v65, v[94:95], off
	global_load_ushort v67, v[96:97], off
	v_lshl_add_u64 v[94:95], v[74:75], 1, s[42:43]
	v_lshl_add_u64 v[96:97], v[72:73], 1, s[42:43]
	s_waitcnt vmcnt(1)
	v_lshlrev_b32_e32 v147, 16, v65
	s_waitcnt vmcnt(0)
	v_lshlrev_b32_e32 v148, 16, v67
	global_load_ushort v65, v[94:95], off
	global_load_ushort v67, v[96:97], off
	v_lshl_add_u64 v[94:95], v[70:71], 1, s[42:43]
	v_lshl_add_u64 v[96:97], v[68:69], 1, s[42:43]
	s_waitcnt vmcnt(1)
	v_lshlrev_b32_e32 v152, 16, v65
	s_waitcnt vmcnt(0)
	v_lshlrev_b32_e32 v154, 16, v67
	global_load_ushort v65, v[94:95], off
	global_load_ushort v67, v[96:97], off
	s_waitcnt vmcnt(1)
	v_lshlrev_b32_e32 v158, 16, v65
	s_waitcnt vmcnt(0)
	v_lshlrev_b32_e32 v159, 16, v67
	v_mov_b32_e32 v67, v201
	v_lshl_add_u64 v[94:95], v[66:67], 1, s[42:43]
	v_mov_b32_e32 v65, v201
	v_lshl_add_u64 v[96:97], v[64:65], 1, s[42:43]
	global_load_ushort v94, v[94:95], off
	s_nop 0
	global_load_ushort v95, v[96:97], off
	v_add_u32_e32 v96, v157, v168
	v_mov_b32_e32 v97, v201
	v_lshl_add_u64 v[100:101], v[96:97], 1, s[42:43]
	s_waitcnt vmcnt(1)
	v_lshlrev_b32_e32 v160, 16, v94
	s_waitcnt vmcnt(0)
	v_lshlrev_b32_e32 v161, 16, v95
	v_add_u32_e32 v94, v129, v168
	v_mov_b32_e32 v95, v201
	v_lshl_add_u64 v[98:99], v[94:95], 1, s[42:43]
	global_load_ushort v100, v[100:101], off
	s_nop 0
	global_load_ushort v98, v[98:99], off
	v_mov_b32_e32 v99, v201
	v_mov_b32_e32 v101, v201
	s_waitcnt vmcnt(1)
	v_lshlrev_b32_e32 v163, 16, v100
	s_waitcnt vmcnt(0)
	v_lshlrev_b32_e32 v162, 16, v98
	v_add_u32_e32 v98, v156, v168
	v_lshl_add_u64 v[102:103], v[98:99], 1, s[42:43]
	v_add_u32_e32 v100, v155, v168
	v_lshl_add_u64 v[104:105], v[100:101], 1, s[42:43]
	global_load_ushort v102, v[102:103], off
	s_nop 0
	global_load_ushort v103, v[104:105], off
	v_add_u32_e32 v104, v151, v168
	v_mov_b32_e32 v105, v201
	v_lshl_add_u64 v[108:109], v[104:105], 1, s[42:43]
	s_waitcnt vmcnt(1)
	v_lshlrev_b32_e32 v164, 16, v102
	s_waitcnt vmcnt(0)
	v_lshlrev_b32_e32 v165, 16, v103
	v_add_u32_e32 v102, v153, v168
	v_mov_b32_e32 v103, v201
	v_lshl_add_u64 v[106:107], v[102:103], 1, s[42:43]
	global_load_ushort v106, v[106:107], off
	s_nop 0
	global_load_ushort v107, v[108:109], off
	v_add_u32_e32 v108, v149, v168
	v_mov_b32_e32 v109, v201
	v_lshl_add_u64 v[112:113], v[108:109], 1, s[42:43]
	s_waitcnt vmcnt(1)
	v_lshlrev_b32_e32 v166, 16, v106
	s_waitcnt vmcnt(0)
	v_lshlrev_b32_e32 v167, 16, v107
	v_add_u32_e32 v106, v150, v168
	v_mov_b32_e32 v107, v201
	v_lshl_add_u64 v[110:111], v[106:107], 1, s[42:43]
	global_load_ushort v110, v[110:111], off
	s_nop 0
	global_load_ushort v111, v[112:113], off
	v_add_u32_e32 v112, v145, v168
	v_mov_b32_e32 v113, v201
	v_lshl_add_u64 v[116:117], v[112:113], 1, s[42:43]
	s_waitcnt vmcnt(1)
	v_lshlrev_b32_e32 v169, 16, v110
	s_waitcnt vmcnt(0)
	v_lshlrev_b32_e32 v170, 16, v111
	v_add_u32_e32 v110, v146, v168
	v_mov_b32_e32 v111, v201
	v_lshl_add_u64 v[114:115], v[110:111], 1, s[42:43]
	global_load_ushort v114, v[114:115], off
	s_nop 0
	global_load_ushort v115, v[116:117], off
	v_add_u32_e32 v116, v142, v168
	v_mov_b32_e32 v117, v201
	v_lshl_add_u64 v[120:121], v[116:117], 1, s[42:43]
	s_waitcnt vmcnt(1)
	v_lshlrev_b32_e32 v171, 16, v114
	s_waitcnt vmcnt(0)
	v_lshlrev_b32_e32 v172, 16, v115
	v_add_u32_e32 v114, v144, v168
	v_mov_b32_e32 v115, v201
	v_lshl_add_u64 v[118:119], v[114:115], 1, s[42:43]
	global_load_ushort v118, v[118:119], off
	s_nop 0
	global_load_ushort v119, v[120:121], off
	v_add_u32_e32 v120, v140, v168
	v_mov_b32_e32 v121, v201
	v_lshl_add_u64 v[124:125], v[120:121], 1, s[42:43]
	s_waitcnt vmcnt(1)
	v_lshlrev_b32_e32 v173, 16, v118
	s_waitcnt vmcnt(0)
	v_lshlrev_b32_e32 v174, 16, v119
	v_add_u32_e32 v118, v141, v168
	v_mov_b32_e32 v119, v201
	v_lshl_add_u64 v[122:123], v[118:119], 1, s[42:43]
	global_load_ushort v122, v[122:123], off
	s_nop 0
	global_load_ushort v123, v[124:125], off
	v_add_u32_e32 v124, v137, v168
	v_mov_b32_e32 v125, v201
	v_lshl_add_u64 v[180:181], v[124:125], 1, s[42:43]
	s_waitcnt vmcnt(1)
	v_lshlrev_b32_e32 v175, 16, v122
	s_waitcnt vmcnt(0)
	v_lshlrev_b32_e32 v176, 16, v123
	v_add_u32_e32 v122, v138, v168
	v_mov_b32_e32 v123, v201
	v_lshl_add_u64 v[178:179], v[122:123], 1, s[42:43]
	global_load_ushort v177, v[178:179], off
	v_mov_b32_e32 v179, v205
	global_load_ushort v178, v[180:181], off
	v_mov_b32_e32 v181, v217
	s_waitcnt vmcnt(1)
	v_lshlrev_b32_e32 v177, 16, v177
	s_waitcnt vmcnt(0)
	v_lshlrev_b32_e32 v178, 16, v178

; __device__ __forceinline__ int ltid() { int t = (int)threadIdx.x; asm volatile("" : "+v"(t)); return t; }
; template <bool HALO, class AL, class BL>
; __device__ __forceinline__ void gemm_core(f32x16 (&acc)[2][2], f32x16& hacc, const AL& al, const BL& bl, int K, char* lds,
;                                           const u16* halo0, const u16* halo1, int brow0, int brow1) {
;     ...
;   const int tid = ltid(), lane = tid & 63, wid = tid >> 6, wr = wid >> 1, r32 = lane & 31, hi = lane >> 5;
;   const int lrow = tid >> 3, cg = ((tid & 7) ^ ((lrow >> 1) & 7)) * 8;
;   const u16* gh = nullptr;
;   if (HALO) { const int c = ((lane & 7) ^ ((lane >> 4) & 7)) * 8; gh = ((lane < 8) ? halo0 : halo1) + c; }
;   char* lw = lds + tid * 16;
;     ...
;   const int sa = ((wr * 64 + r32) >> 1) & 7, sb0 = ((brow0 + r32) >> 1) & 7, sb1 = ((brow1 + r32) >> 1) & 7, sh = (r32 >> 1) & 7;
;   const int oa = (wr * 64 + r32) * 128, ob0 = ABYTES + (brow0 + r32) * 128, ob1 = ABYTES + (brow1 + r32) * 128, oh = (128 + r32) * 128;
;   __syncthreads();
;   ISSUE(0, 0);
;   const int nk = K >> 6;
;   for (int kt = 0; kt < nk; ++kt) {
;     asm volatile("s_waitcnt vmcnt(0)" ::: "memory");
;     __syncthreads();
;     if (kt + 1 < nk) ISSUE((kt + 1) * 64, (kt + 1) & 1);
;     const char* T = lds + (kt & 1) * BUF;
; #pragma unroll
;     for (int kk = 0; kk < 4; ++kk) {
;       const int c = kk * 2 + hi;
;       bf16x8 a0 = *(const bf16x8*)(T + oa + ((c ^ sa) << 4));
;       bf16x8 a1 = *(const bf16x8*)(T + oa + 4096 + ((c ^ sa) << 4));
;       bf16x8 b0 = *(const bf16x8*)(T + ob0 + ((c ^ sb0) << 4));
;       bf16x8 b1 = *(const bf16x8*)(T + ob1 + ((c ^ sb1) << 4));
;       acc[0][0] = MFMA(a0, b0, acc[0][0]); acc[0][1] = MFMA(a0, b1, acc[0][1]);
;       acc[1][0] = MFMA(a1, b0, acc[1][0]); acc[1][1] = MFMA(a1, b1, acc[1][1]);
;       if (HALO) { bf16x8 ah = *(const bf16x8*)(T + oh + ((c ^ sh) << 4)); hacc = MFMA(ah, b0, hacc); }
;     }
; __device__ __forceinline__ bool tile_at(int it, int nM, int nN, int& tm, int& tn) {
;   const int total = nM * nN, per = (total + 7) / 8, x = blockIdx.x & 7, lb = blockIdx.x >> 3, nlb = gridDim.x >> 3;
;   const int i = lb + it * nlb; if (i >= per) return false;
;   const int idx = x * per + i; if (idx >= total) return false;
;   const int grp = idx / (8 * nN), rem = idx - grp * 8 * nN;
;   tm = grp * 8 + (rem & 7); tn = rem >> 3; return true;
.LBB0_345:
	v_readlane_b32 s47, v253, 6
	s_add_i32 s47, s46, s47
	s_mul_hi_u32 s48, s47, 0xba2e8ba3
	s_lshr_b32 s48, s48, 7
	s_lshl_b32 s49, s48, 3
	s_mulk_i32 s48, 0xff50
	s_and_b32 s46, s46, 7
	s_add_i32 s47, s48, s47
	s_or_b32 s48, s49, s46
	s_ashr_i32 s46, s47, 3
	s_lshl_b32 s47, s48, 18
	s_add_u32 s56, s3, s47
	s_waitcnt vmcnt(6)
	v_mov_b32_e32 v6, v229
	s_waitcnt vmcnt(1)
	v_mov_b32_e32 v24, v229
	s_addc_u32 s57, s6, 0
	s_ashr_i32 s47, s46, 31
	s_lshl_b64 s[58:59], s[46:47], 18
	v_ashrrev_i32_e32 v0, 3, v24
	v_lshrrev_b32_e32 v1, 4, v24
	v_xor_b32_e32 v4, v1, v24
	v_ashrrev_i32_e32 v1, 31, v0
	s_add_u32 s58, s7, s58
	v_lshlrev_b64 v[0:1], 11, v[0:1]
	v_lshlrev_b32_e32 v4, 4, v4
	s_addc_u32 s59, s8, s59
	v_lshl_add_u64 v[2:3], s[56:57], 0, v[0:1]
	v_and_b32_e32 v200, 0x70, v4
	s_waitcnt vmcnt(0)
	v_lshl_add_u64 v[64:65], v[2:3], 0, v[200:201]
	v_lshl_add_u64 v[2:3], s[58:59], 0, v[0:1]
	s_mov_b64 s[60:61], 0x10000
	v_lshl_add_u32 v101, v24, 4, 0
	v_lshl_add_u64 v[66:67], v[2:3], 0, v[200:201]
	v_lshl_add_u64 v[2:3], v[0:1], 0, s[60:61]
	v_add_u32_e32 v102, 0x4000, v101
	v_readfirstlane_b32 s71, v101
	v_lshl_add_u64 v[4:5], s[56:57], 0, v[2:3]
	v_lshl_add_u64 v[2:3], s[58:59], 0, v[2:3]
	s_mov_b64 s[60:61], 0x20000
	s_mov_b32 m0, s71
	v_readfirstlane_b32 s72, v102
	v_add_u32_e32 v103, 0x1000, v101
	v_lshl_add_u64 v[70:71], v[2:3], 0, v[200:201]
	v_lshl_add_u64 v[2:3], v[0:1], 0, s[60:61]
	s_barrier
	global_load_lds_dwordx4 v[64:65], off
	s_mov_b32 m0, s72
	v_lshl_add_u64 v[68:69], v[4:5], 0, v[200:201]
	v_readfirstlane_b32 s73, v103
	v_add_u32_e32 v104, 0x5000, v101
	v_lshl_add_u64 v[4:5], s[56:57], 0, v[2:3]
	global_load_lds_dwordx4 v[66:67], off sc1
	s_mov_b32 m0, s73
	v_readfirstlane_b32 s76, v104
	v_lshl_add_u64 v[72:73], v[4:5], 0, v[200:201]
	v_add_u32_e32 v4, 0x2000, v101
	v_lshl_add_u64 v[2:3], s[58:59], 0, v[2:3]
	global_load_lds_dwordx4 v[68:69], off
	s_mov_b32 m0, s76
	v_readfirstlane_b32 s47, v4
	v_lshl_add_u64 v[74:75], v[2:3], 0, v[200:201]
	v_add_u32_e32 v2, 0x6000, v101
	s_mov_b64 s[60:61], 0x30000
	global_load_lds_dwordx4 v[70:71], off sc1
	s_mov_b32 m0, s47
	v_readfirstlane_b32 s49, v2
	v_lshl_add_u64 v[0:1], v[0:1], 0, s[60:61]
	v_add_u32_e32 v91, 0x3000, v101
	global_load_lds_dwordx4 v[72:73], off
	s_mov_b32 m0, s49
	v_lshl_add_u64 v[2:3], s[56:57], 0, v[0:1]
	v_readfirstlane_b32 s56, v91
	v_add_u32_e32 v92, 0x7000, v101
	v_lshrrev_b32_e32 v8, 5, v24
	v_bfe_u32 v89, v24, 1, 3
	global_load_lds_dwordx4 v[74:75], off sc1
	v_lshl_add_u64 v[76:77], v[2:3], 0, v[200:201]
	s_mov_b32 m0, s56
	v_lshl_add_u64 v[0:1], s[58:59], 0, v[0:1]
	v_readfirstlane_b32 s57, v92
	v_add_u32_e32 v94, 0x8000, v101
	global_load_lds_dwordx4 v[76:77], off
	v_lshl_add_u64 v[78:79], v[0:1], 0, v[200:201]
	s_mov_b32 m0, s57
	v_bitop3_b32 v0, v8, v89, 1 bitop3:0x6c
	v_add_u32_e32 v93, 0xc000, v101
	v_readfirstlane_b32 s58, v94
	global_load_lds_dwordx4 v[78:79], off sc1
	v_lshlrev_b32_e32 v4, 4, v0
	v_lshl_add_u64 v[0:1], v[64:65], 0, s[78:79]
	s_mov_b32 m0, s58
	v_readfirstlane_b32 s59, v93
	v_add_u32_e32 v95, 0x9000, v101
	s_waitcnt vmcnt(0)
	s_waitcnt vmcnt(0) lgkmcnt(0)
	s_barrier
	global_load_lds_dwordx4 v[0:1], off
	v_lshl_add_u64 v[0:1], v[66:67], 0, s[78:79]
	s_mov_b32 m0, s59
	v_readfirstlane_b32 s60, v95
	v_add_u32_e32 v96, 0xd000, v101
	global_load_lds_dwordx4 v[0:1], off sc1
	v_lshl_add_u64 v[0:1], v[68:69], 0, s[78:79]
	s_mov_b32 m0, s60
	v_readfirstlane_b32 s61, v96
	v_add_u32_e32 v97, 0xa000, v101
	global_load_lds_dwordx4 v[0:1], off
	v_lshl_add_u64 v[0:1], v[70:71], 0, s[78:79]
	s_mov_b32 m0, s61
	v_readfirstlane_b32 s62, v97
	v_add_u32_e32 v98, 0xe000, v101
	global_load_lds_dwordx4 v[0:1], off sc1
	v_lshl_add_u64 v[0:1], v[72:73], 0, s[78:79]
	s_mov_b32 m0, s62
	v_readfirstlane_b32 s63, v98
	v_add_u32_e32 v99, 0xb000, v101
	v_and_b32_e32 v7, 31, v24
	v_lshrrev_b32_e32 v9, 1, v24
	global_load_lds_dwordx4 v[0:1], off
	v_lshl_add_u64 v[0:1], v[74:75], 0, s[78:79]
	s_mov_b32 m0, s63
	v_readfirstlane_b32 s69, v99
	v_add_u32_e32 v100, 0xf000, v101
	v_and_or_b32 v2, v9, s94, v7
	global_load_lds_dwordx4 v[0:1], off sc1
	v_lshl_add_u64 v[0:1], v[76:77], 0, s[78:79]
	s_mov_b32 m0, s69
	v_readfirstlane_b32 s70, v100
	global_load_lds_dwordx4 v[0:1], off
	v_lshl_add_u64 v[0:1], v[78:79], 0, s[78:79]
	s_mov_b32 m0, s70
	v_lshl_add_u32 v90, v2, 7, 0
	global_load_lds_dwordx4 v[0:1], off sc1
	v_add_u32_e32 v83, v90, v4
	ds_read_b128 v[0:3], v83
	ds_read_b128 v[20:23], v83 offset:4096
	v_and_or_b32 v5, v6, 64, v7
	v_lshl_add_u32 v105, v5, 7, 0
	v_add_u32_e32 v85, v105, v4
	ds_read_b128 v[4:7], v85 offset:16384
	ds_read_b128 v[16:19], v85 offset:20480
	v_bfe_u32 v118, v24, 5, 1
	v_bitop3_b32 v24, v118, v89, 2 bitop3:0x36
	v_lshlrev_b32_e32 v86, 4, v24
	v_add_u32_e32 v84, v90, v86
	ds_read_b128 v[106:109], v84
	v_add_u32_e32 v87, v105, v86
	s_waitcnt lgkmcnt(0)
	v_mfma_f32_32x32x16_bf16 v[32:47], v[0:3], v[4:7], 0
	ds_read_b128 v[110:113], v87 offset:16384
	ds_read_b128 v[114:117], v87 offset:20480
	v_bitop3_b32 v86, v118, v89, 4 bitop3:0x36
	v_lshlrev_b32_e32 v88, 4, v86
	v_add_u32_e32 v86, v90, v88
	v_add_u32_e32 v88, v105, v88
	v_bitop3_b32 v89, v118, v89, 6 bitop3:0x36
	v_mfma_f32_32x32x16_bf16 v[48:63], v[0:3], v[16:19], 0
	s_mov_b32 m0, s71
	v_readfirstlane_b32 s64, v91
	v_readfirstlane_b32 s65, v92
	s_waitcnt lgkmcnt(0)
	v_mfma_f32_32x32x16_bf16 v[32:47], v[106:109], v[110:113], v[32:47]
	v_mfma_f32_32x32x16_bf16 v[48:63], v[106:109], v[114:117], v[48:63]
	ds_read_b128 v[106:109], v84 offset:4096
	v_mfma_f32_32x32x16_bf16 v[0:15], v[20:23], v[4:7], 0
	v_mfma_f32_32x32x16_bf16 v[16:31], v[20:23], v[16:19], 0
	s_waitcnt lgkmcnt(0)
	v_mfma_f32_32x32x16_bf16 v[0:15], v[106:109], v[110:113], v[0:15]
	ds_read_b128 v[110:113], v88 offset:16384
	v_mfma_f32_32x32x16_bf16 v[16:31], v[106:109], v[114:117], v[16:31]
	ds_read_b128 v[106:109], v86
	ds_read_b128 v[114:117], v88 offset:20480
	s_waitcnt lgkmcnt(0)
	v_mfma_f32_32x32x16_bf16 v[32:47], v[106:109], v[110:113], v[32:47]
	v_mfma_f32_32x32x16_bf16 v[48:63], v[106:109], v[114:117], v[48:63]
	ds_read_b128 v[106:109], v86 offset:4096
	s_waitcnt lgkmcnt(0)
	v_mfma_f32_32x32x16_bf16 v[0:15], v[106:109], v[110:113], v[0:15]
	v_lshlrev_b32_e32 v110, 4, v89
	v_add_u32_e32 v89, v90, v110
	v_add_u32_e32 v90, v105, v110
	ds_read_b128 v[110:113], v90 offset:16384
	v_mfma_f32_32x32x16_bf16 v[16:31], v[106:109], v[114:117], v[16:31]
	ds_read_b128 v[106:109], v89
	ds_read_b128 v[114:117], v90 offset:20480
	s_waitcnt lgkmcnt(0)
	v_mfma_f32_32x32x16_bf16 v[32:47], v[106:109], v[110:113], v[32:47]
	v_mfma_f32_32x32x16_bf16 v[48:63], v[106:109], v[114:117], v[48:63]
	ds_read_b128 v[106:109], v89 offset:4096
	s_waitcnt vmcnt(0)
	s_waitcnt vmcnt(0) lgkmcnt(0)
	s_barrier
; #define MFMA(a, b, c) __builtin_amdgcn_mfma_f32_32x32x16_bf16(a, b, c, 0, 0, 0)
; #define ISSUE(k0, bf) do { char* A_ = lw + (bf) * BUF; \
;     _Pragma("unroll") for (int i_ = 0; i_ < 4; ++i_) { glds16(al.ptr(lrow + 32 * i_, (k0) + cg), A_ + i_ * 4096); glds16(bl.ptr(lrow + 32 * i_, (k0) + cg), A_ + ABYTES + i_ * 4096); } \
;     if (HALO) { if (wid == 0) glds16(gh + (k0), A_ + 16384); } } while (0)
; template <bool HALO, class AL, class BL>
; __device__ __forceinline__ void gemm_core(f32x16 (&acc)[2][2], f32x16& hacc, const AL& al, const BL& bl, int K, char* lds,
;                                           const u16* halo0, const u16* halo1, int brow0, int brow1) {
;     ...
;   for (int kt = 0; kt < nk; ++kt) {
;     asm volatile("s_waitcnt vmcnt(0)" ::: "memory");
;     __syncthreads();
;     if (kt + 1 < nk) ISSUE((kt + 1) * 64, (kt + 1) & 1);
;     const char* T = lds + (kt & 1) * BUF;
; #pragma unroll
;     for (int kk = 0; kk < 4; ++kk) {
;       const int c = kk * 2 + hi;
;       bf16x8 a0 = *(const bf16x8*)(T + oa + ((c ^ sa) << 4));
;       bf16x8 a1 = *(const bf16x8*)(T + oa + 4096 + ((c ^ sa) << 4));
;       bf16x8 b0 = *(const bf16x8*)(T + ob0 + ((c ^ sb0) << 4));
;       bf16x8 b1 = *(const bf16x8*)(T + ob1 + ((c ^ sb1) << 4));
;       acc[0][0] = MFMA(a0, b0, acc[0][0]); acc[0][1] = MFMA(a0, b1, acc[0][1]);
;       acc[1][0] = MFMA(a1, b0, acc[1][0]); acc[1][1] = MFMA(a1, b1, acc[1][1]);
;       if (HALO) { bf16x8 ah = *(const bf16x8*)(T + oh + ((c ^ sh) << 4)); hacc = MFMA(ah, b0, hacc); }
;     }
	v_mfma_f32_32x32x16_bf16 v[0:15], v[106:109], v[110:113], v[0:15]
	v_mfma_f32_32x32x16_bf16 v[16:31], v[106:109], v[114:117], v[16:31]
	v_lshl_add_u64 v[106:107], v[64:65], 0, s[24:25]
	global_load_lds_dwordx4 v[106:107], off
	v_lshl_add_u64 v[106:107], v[66:67], 0, s[24:25]
	s_mov_b32 m0, s72
	s_nop 0
	global_load_lds_dwordx4 v[106:107], off sc1
	v_lshl_add_u64 v[106:107], v[68:69], 0, s[24:25]
	s_mov_b32 m0, s73
	s_nop 0
	global_load_lds_dwordx4 v[106:107], off
	v_lshl_add_u64 v[106:107], v[70:71], 0, s[24:25]
	s_mov_b32 m0, s76
	s_nop 0
	global_load_lds_dwordx4 v[106:107], off sc1
	v_lshl_add_u64 v[106:107], v[72:73], 0, s[24:25]
	s_mov_b32 m0, s47
	s_nop 0
	global_load_lds_dwordx4 v[106:107], off
	v_lshl_add_u64 v[106:107], v[74:75], 0, s[24:25]
	s_mov_b32 m0, s49
	s_nop 0
	global_load_lds_dwordx4 v[106:107], off sc1
	v_lshl_add_u64 v[106:107], v[76:77], 0, s[24:25]
	s_mov_b32 m0, s56
	s_nop 0
	global_load_lds_dwordx4 v[106:107], off
	v_lshl_add_u64 v[106:107], v[78:79], 0, s[24:25]
	s_mov_b32 m0, s57
	s_nop 0
	global_load_lds_dwordx4 v[106:107], off sc1
	ds_read_b128 v[106:109], v83 offset:32768
	ds_read_b128 v[110:113], v85 offset:49152
	ds_read_b128 v[114:117], v85 offset:53248
	s_waitcnt lgkmcnt(0)
	v_mfma_f32_32x32x16_bf16 v[32:47], v[106:109], v[110:113], v[32:47]
	s_mov_b32 m0, s58
	v_mfma_f32_32x32x16_bf16 v[48:63], v[106:109], v[114:117], v[48:63]
	ds_read_b128 v[106:109], v83 offset:36864
	s_waitcnt lgkmcnt(0)
	v_mfma_f32_32x32x16_bf16 v[0:15], v[106:109], v[110:113], v[0:15]
	v_mfma_f32_32x32x16_bf16 v[16:31], v[106:109], v[114:117], v[16:31]
	ds_read_b128 v[106:109], v84 offset:32768
	ds_read_b128 v[110:113], v87 offset:49152
	ds_read_b128 v[114:117], v87 offset:53248
	s_waitcnt lgkmcnt(0)
	v_mfma_f32_32x32x16_bf16 v[32:47], v[106:109], v[110:113], v[32:47]
	v_mfma_f32_32x32x16_bf16 v[48:63], v[106:109], v[114:117], v[48:63]
	ds_read_b128 v[106:109], v84 offset:36864
	s_waitcnt lgkmcnt(0)
	v_mfma_f32_32x32x16_bf16 v[0:15], v[106:109], v[110:113], v[0:15]
	v_mfma_f32_32x32x16_bf16 v[16:31], v[106:109], v[114:117], v[16:31]
	ds_read_b128 v[106:109], v86 offset:32768
	ds_read_b128 v[110:113], v88 offset:49152
	ds_read_b128 v[114:117], v88 offset:53248
	s_waitcnt lgkmcnt(0)
	v_mfma_f32_32x32x16_bf16 v[32:47], v[106:109], v[110:113], v[32:47]
	v_mfma_f32_32x32x16_bf16 v[48:63], v[106:109], v[114:117], v[48:63]
	ds_read_b128 v[106:109], v86 offset:36864
	s_waitcnt lgkmcnt(0)
	v_mfma_f32_32x32x16_bf16 v[0:15], v[106:109], v[110:113], v[0:15]
	v_mfma_f32_32x32x16_bf16 v[16:31], v[106:109], v[114:117], v[16:31]
	ds_read_b128 v[106:109], v89 offset:32768
	ds_read_b128 v[110:113], v90 offset:49152
	ds_read_b128 v[114:117], v90 offset:53248
	s_waitcnt lgkmcnt(0)
	v_mfma_f32_32x32x16_bf16 v[32:47], v[106:109], v[110:113], v[32:47]
	v_mfma_f32_32x32x16_bf16 v[48:63], v[106:109], v[114:117], v[48:63]
	ds_read_b128 v[106:109], v89 offset:36864
	s_waitcnt vmcnt(0)
	s_waitcnt vmcnt(0) lgkmcnt(0)
	s_barrier
	v_mfma_f32_32x32x16_bf16 v[0:15], v[106:109], v[110:113], v[0:15]
	v_mfma_f32_32x32x16_bf16 v[16:31], v[106:109], v[114:117], v[16:31]
	v_lshl_add_u64 v[106:107], v[64:65], 0, s[74:75]
	global_load_lds_dwordx4 v[106:107], off
	v_lshl_add_u64 v[106:107], v[66:67], 0, s[74:75]
	s_mov_b32 m0, s59
	s_nop 0
	global_load_lds_dwordx4 v[106:107], off sc1
	v_lshl_add_u64 v[106:107], v[68:69], 0, s[74:75]
	s_mov_b32 m0, s60
	s_nop 0
	global_load_lds_dwordx4 v[106:107], off
	v_lshl_add_u64 v[106:107], v[70:71], 0, s[74:75]
	s_mov_b32 m0, s61
	s_nop 0
	global_load_lds_dwordx4 v[106:107], off sc1
	v_lshl_add_u64 v[106:107], v[72:73], 0, s[74:75]
	s_mov_b32 m0, s62
	s_nop 0
	global_load_lds_dwordx4 v[106:107], off
	v_lshl_add_u64 v[106:107], v[74:75], 0, s[74:75]
	s_mov_b32 m0, s63
	s_nop 0
	global_load_lds_dwordx4 v[106:107], off sc1
	v_lshl_add_u64 v[106:107], v[76:77], 0, s[74:75]
	s_mov_b32 m0, s69
	s_nop 0
	global_load_lds_dwordx4 v[106:107], off
	v_lshl_add_u64 v[106:107], v[78:79], 0, s[74:75]
	s_mov_b32 m0, s70
	s_nop 0
	global_load_lds_dwordx4 v[106:107], off sc1
	ds_read_b128 v[106:109], v83
	ds_read_b128 v[110:113], v85 offset:16384
	ds_read_b128 v[114:117], v85 offset:20480
	s_waitcnt lgkmcnt(0)
	v_mfma_f32_32x32x16_bf16 v[32:47], v[106:109], v[110:113], v[32:47]
	s_mov_b32 m0, s71
	v_mfma_f32_32x32x16_bf16 v[48:63], v[106:109], v[114:117], v[48:63]
	ds_read_b128 v[106:109], v83 offset:4096
	s_waitcnt lgkmcnt(0)
	v_mfma_f32_32x32x16_bf16 v[0:15], v[106:109], v[110:113], v[0:15]
	v_mfma_f32_32x32x16_bf16 v[16:31], v[106:109], v[114:117], v[16:31]
	ds_read_b128 v[106:109], v84
	ds_read_b128 v[110:113], v87 offset:16384
	ds_read_b128 v[114:117], v87 offset:20480
	s_waitcnt lgkmcnt(0)
	v_mfma_f32_32x32x16_bf16 v[32:47], v[106:109], v[110:113], v[32:47]
	v_mfma_f32_32x32x16_bf16 v[48:63], v[106:109], v[114:117], v[48:63]
	ds_read_b128 v[106:109], v84 offset:4096
	s_waitcnt lgkmcnt(0)
	v_mfma_f32_32x32x16_bf16 v[0:15], v[106:109], v[110:113], v[0:15]
	v_mfma_f32_32x32x16_bf16 v[16:31], v[106:109], v[114:117], v[16:31]
	ds_read_b128 v[106:109], v86
	ds_read_b128 v[110:113], v88 offset:16384
	ds_read_b128 v[114:117], v88 offset:20480
	s_waitcnt lgkmcnt(0)
	v_mfma_f32_32x32x16_bf16 v[32:47], v[106:109], v[110:113], v[32:47]
	v_mfma_f32_32x32x16_bf16 v[48:63], v[106:109], v[114:117], v[48:63]
	ds_read_b128 v[106:109], v86 offset:4096
	s_waitcnt lgkmcnt(0)
	v_mfma_f32_32x32x16_bf16 v[0:15], v[106:109], v[110:113], v[0:15]
	v_mfma_f32_32x32x16_bf16 v[16:31], v[106:109], v[114:117], v[16:31]
	ds_read_b128 v[106:109], v89
	ds_read_b128 v[110:113], v90 offset:16384
	ds_read_b128 v[114:117], v90 offset:20480
	s_waitcnt lgkmcnt(0)
	v_mfma_f32_32x32x16_bf16 v[32:47], v[106:109], v[110:113], v[32:47]
	v_mfma_f32_32x32x16_bf16 v[48:63], v[106:109], v[114:117], v[48:63]
	ds_read_b128 v[106:109], v89 offset:4096
	s_waitcnt vmcnt(0)
	s_waitcnt vmcnt(0) lgkmcnt(0)
	s_barrier
; #define MFMA(a, b, c) __builtin_amdgcn_mfma_f32_32x32x16_bf16(a, b, c, 0, 0, 0)
; #define ISSUE(k0, bf) do { char* A_ = lw + (bf) * BUF; \
;     _Pragma("unroll") for (int i_ = 0; i_ < 4; ++i_) { glds16(al.ptr(lrow + 32 * i_, (k0) + cg), A_ + i_ * 4096); glds16(bl.ptr(lrow + 32 * i_, (k0) + cg), A_ + ABYTES + i_ * 4096); } \
;     if (HALO) { if (wid == 0) glds16(gh + (k0), A_ + 16384); } } while (0)
; template <bool HALO, class AL, class BL>
; __device__ __forceinline__ void gemm_core(f32x16 (&acc)[2][2], f32x16& hacc, const AL& al, const BL& bl, int K, char* lds,
;                                           const u16* halo0, const u16* halo1, int brow0, int brow1) {
;     ...
;   for (int kt = 0; kt < nk; ++kt) {
;     asm volatile("s_waitcnt vmcnt(0)" ::: "memory");
;     __syncthreads();
;     if (kt + 1 < nk) ISSUE((kt + 1) * 64, (kt + 1) & 1);
;     const char* T = lds + (kt & 1) * BUF;
; #pragma unroll
;     for (int kk = 0; kk < 4; ++kk) {
;       const int c = kk * 2 + hi;
;       bf16x8 a0 = *(const bf16x8*)(T + oa + ((c ^ sa) << 4));
;       bf16x8 a1 = *(const bf16x8*)(T + oa + 4096 + ((c ^ sa) << 4));
;       bf16x8 b0 = *(const bf16x8*)(T + ob0 + ((c ^ sb0) << 4));
;       bf16x8 b1 = *(const bf16x8*)(T + ob1 + ((c ^ sb1) << 4));
;       acc[0][0] = MFMA(a0, b0, acc[0][0]); acc[0][1] = MFMA(a0, b1, acc[0][1]);
;       acc[1][0] = MFMA(a1, b0, acc[1][0]); acc[1][1] = MFMA(a1, b1, acc[1][1]);
;       if (HALO) { bf16x8 ah = *(const bf16x8*)(T + oh + ((c ^ sh) << 4)); hacc = MFMA(ah, b0, hacc); }
;     }
	v_mfma_f32_32x32x16_bf16 v[0:15], v[106:109], v[110:113], v[0:15]
	v_mfma_f32_32x32x16_bf16 v[16:31], v[106:109], v[114:117], v[16:31]
	v_lshl_add_u64 v[106:107], v[64:65], 0, s[20:21]
	global_load_lds_dwordx4 v[106:107], off
	v_lshl_add_u64 v[106:107], v[66:67], 0, s[20:21]
	s_mov_b32 m0, s72
	s_nop 0
	global_load_lds_dwordx4 v[106:107], off sc1
	v_lshl_add_u64 v[106:107], v[68:69], 0, s[20:21]
	s_mov_b32 m0, s73
	s_nop 0
	global_load_lds_dwordx4 v[106:107], off
	v_lshl_add_u64 v[106:107], v[70:71], 0, s[20:21]
	s_mov_b32 m0, s76
	s_nop 0
	global_load_lds_dwordx4 v[106:107], off sc1
	v_lshl_add_u64 v[106:107], v[72:73], 0, s[20:21]
	s_mov_b32 m0, s47
	s_nop 0
	global_load_lds_dwordx4 v[106:107], off
	v_lshl_add_u64 v[106:107], v[74:75], 0, s[20:21]
	s_mov_b32 m0, s49
	s_nop 0
	global_load_lds_dwordx4 v[106:107], off sc1
	v_lshl_add_u64 v[106:107], v[76:77], 0, s[20:21]
	s_mov_b32 m0, s56
	s_nop 0
	global_load_lds_dwordx4 v[106:107], off
	v_lshl_add_u64 v[106:107], v[78:79], 0, s[20:21]
	s_mov_b32 m0, s57
	s_nop 0
	global_load_lds_dwordx4 v[106:107], off sc1
	ds_read_b128 v[106:109], v83 offset:32768
	ds_read_b128 v[110:113], v85 offset:49152
	ds_read_b128 v[114:117], v85 offset:53248
	s_waitcnt lgkmcnt(0)
	v_mfma_f32_32x32x16_bf16 v[32:47], v[106:109], v[110:113], v[32:47]
	s_mov_b32 m0, s58
	v_mfma_f32_32x32x16_bf16 v[48:63], v[106:109], v[114:117], v[48:63]
	ds_read_b128 v[106:109], v83 offset:36864
	s_waitcnt lgkmcnt(0)
	v_mfma_f32_32x32x16_bf16 v[0:15], v[106:109], v[110:113], v[0:15]
	v_mfma_f32_32x32x16_bf16 v[16:31], v[106:109], v[114:117], v[16:31]
	ds_read_b128 v[106:109], v84 offset:32768
	ds_read_b128 v[110:113], v87 offset:49152
	ds_read_b128 v[114:117], v87 offset:53248
	s_waitcnt lgkmcnt(0)
	v_mfma_f32_32x32x16_bf16 v[32:47], v[106:109], v[110:113], v[32:47]
	v_mfma_f32_32x32x16_bf16 v[48:63], v[106:109], v[114:117], v[48:63]
	ds_read_b128 v[106:109], v84 offset:36864
	s_waitcnt lgkmcnt(0)
	v_mfma_f32_32x32x16_bf16 v[0:15], v[106:109], v[110:113], v[0:15]
	v_mfma_f32_32x32x16_bf16 v[16:31], v[106:109], v[114:117], v[16:31]
	ds_read_b128 v[106:109], v86 offset:32768
	ds_read_b128 v[110:113], v88 offset:49152
	ds_read_b128 v[114:117], v88 offset:53248
	s_waitcnt lgkmcnt(0)
	v_mfma_f32_32x32x16_bf16 v[32:47], v[106:109], v[110:113], v[32:47]
	v_mfma_f32_32x32x16_bf16 v[48:63], v[106:109], v[114:117], v[48:63]
	ds_read_b128 v[106:109], v86 offset:36864
	s_waitcnt lgkmcnt(0)
	v_mfma_f32_32x32x16_bf16 v[0:15], v[106:109], v[110:113], v[0:15]
	v_mfma_f32_32x32x16_bf16 v[16:31], v[106:109], v[114:117], v[16:31]
	ds_read_b128 v[106:109], v89 offset:32768
	ds_read_b128 v[110:113], v90 offset:49152
	ds_read_b128 v[114:117], v90 offset:53248
	s_waitcnt lgkmcnt(0)
	v_mfma_f32_32x32x16_bf16 v[32:47], v[106:109], v[110:113], v[32:47]
	v_mfma_f32_32x32x16_bf16 v[48:63], v[106:109], v[114:117], v[48:63]
	ds_read_b128 v[106:109], v89 offset:36864
	s_waitcnt vmcnt(0)
	s_waitcnt vmcnt(0) lgkmcnt(0)
	s_barrier
	v_mfma_f32_32x32x16_bf16 v[0:15], v[106:109], v[110:113], v[0:15]
	v_mfma_f32_32x32x16_bf16 v[16:31], v[106:109], v[114:117], v[16:31]
	v_lshl_add_u64 v[106:107], v[64:65], 0, s[86:87]
	global_load_lds_dwordx4 v[106:107], off
	v_lshl_add_u64 v[106:107], v[66:67], 0, s[86:87]
	s_mov_b32 m0, s59
	s_nop 0
	global_load_lds_dwordx4 v[106:107], off sc1
	v_lshl_add_u64 v[106:107], v[68:69], 0, s[86:87]
	s_mov_b32 m0, s60
	s_nop 0
	global_load_lds_dwordx4 v[106:107], off
	v_lshl_add_u64 v[106:107], v[70:71], 0, s[86:87]
	s_mov_b32 m0, s61
	s_nop 0
	global_load_lds_dwordx4 v[106:107], off sc1
	v_lshl_add_u64 v[106:107], v[72:73], 0, s[86:87]
	s_mov_b32 m0, s62
	s_nop 0
	global_load_lds_dwordx4 v[106:107], off
	v_lshl_add_u64 v[106:107], v[74:75], 0, s[86:87]
	s_mov_b32 m0, s63
	s_nop 0
	global_load_lds_dwordx4 v[106:107], off sc1
	v_lshl_add_u64 v[106:107], v[76:77], 0, s[86:87]
	s_mov_b32 m0, s69
	s_nop 0
	global_load_lds_dwordx4 v[106:107], off
	v_lshl_add_u64 v[106:107], v[78:79], 0, s[86:87]
	s_mov_b32 m0, s70
	s_nop 0
	global_load_lds_dwordx4 v[106:107], off sc1
	ds_read_b128 v[106:109], v83
	ds_read_b128 v[110:113], v85 offset:16384
	ds_read_b128 v[114:117], v85 offset:20480
	s_waitcnt lgkmcnt(0)
	v_mfma_f32_32x32x16_bf16 v[32:47], v[106:109], v[110:113], v[32:47]
	s_mov_b32 m0, s71
	v_readfirstlane_b32 s71, v99
	v_mfma_f32_32x32x16_bf16 v[48:63], v[106:109], v[114:117], v[48:63]
	ds_read_b128 v[106:109], v83 offset:4096
	s_waitcnt lgkmcnt(0)
	v_mfma_f32_32x32x16_bf16 v[0:15], v[106:109], v[110:113], v[0:15]
	v_mfma_f32_32x32x16_bf16 v[16:31], v[106:109], v[114:117], v[16:31]
	ds_read_b128 v[106:109], v84
	ds_read_b128 v[110:113], v87 offset:16384
	ds_read_b128 v[114:117], v87 offset:20480
	s_waitcnt lgkmcnt(0)
	v_mfma_f32_32x32x16_bf16 v[32:47], v[106:109], v[110:113], v[32:47]
	v_mfma_f32_32x32x16_bf16 v[48:63], v[106:109], v[114:117], v[48:63]
	ds_read_b128 v[106:109], v84 offset:4096
	s_waitcnt lgkmcnt(0)
	v_mfma_f32_32x32x16_bf16 v[0:15], v[106:109], v[110:113], v[0:15]
	v_mfma_f32_32x32x16_bf16 v[16:31], v[106:109], v[114:117], v[16:31]
	ds_read_b128 v[106:109], v86
	ds_read_b128 v[110:113], v88 offset:16384
	ds_read_b128 v[114:117], v88 offset:20480
	s_waitcnt lgkmcnt(0)
	v_mfma_f32_32x32x16_bf16 v[32:47], v[106:109], v[110:113], v[32:47]
	v_mfma_f32_32x32x16_bf16 v[48:63], v[106:109], v[114:117], v[48:63]
	ds_read_b128 v[106:109], v86 offset:4096
	s_waitcnt lgkmcnt(0)
	v_mfma_f32_32x32x16_bf16 v[0:15], v[106:109], v[110:113], v[0:15]
	v_mfma_f32_32x32x16_bf16 v[16:31], v[106:109], v[114:117], v[16:31]
	ds_read_b128 v[106:109], v89
	ds_read_b128 v[110:113], v90 offset:16384
	ds_read_b128 v[114:117], v90 offset:20480
	s_waitcnt lgkmcnt(0)
	v_mfma_f32_32x32x16_bf16 v[32:47], v[106:109], v[110:113], v[32:47]
	v_mfma_f32_32x32x16_bf16 v[48:63], v[106:109], v[114:117], v[48:63]
	ds_read_b128 v[106:109], v89 offset:4096
	s_waitcnt vmcnt(0)
	s_waitcnt vmcnt(0) lgkmcnt(0)
	s_barrier
; #define MFMA(a, b, c) __builtin_amdgcn_mfma_f32_32x32x16_bf16(a, b, c, 0, 0, 0)
; #define ISSUE(k0, bf) do { char* A_ = lw + (bf) * BUF; \
;     _Pragma("unroll") for (int i_ = 0; i_ < 4; ++i_) { glds16(al.ptr(lrow + 32 * i_, (k0) + cg), A_ + i_ * 4096); glds16(bl.ptr(lrow + 32 * i_, (k0) + cg), A_ + ABYTES + i_ * 4096); } \
;     if (HALO) { if (wid == 0) glds16(gh + (k0), A_ + 16384); } } while (0)
; template <bool HALO, class AL, class BL>
; __device__ __forceinline__ void gemm_core(f32x16 (&acc)[2][2], f32x16& hacc, const AL& al, const BL& bl, int K, char* lds,
;                                           const u16* halo0, const u16* halo1, int brow0, int brow1) {
;     ...
;   for (int kt = 0; kt < nk; ++kt) {
;     asm volatile("s_waitcnt vmcnt(0)" ::: "memory");
;     __syncthreads();
;     if (kt + 1 < nk) ISSUE((kt + 1) * 64, (kt + 1) & 1);
;     const char* T = lds + (kt & 1) * BUF;
; #pragma unroll
;     for (int kk = 0; kk < 4; ++kk) {
;       const int c = kk * 2 + hi;
;       bf16x8 a0 = *(const bf16x8*)(T + oa + ((c ^ sa) << 4));
;       bf16x8 a1 = *(const bf16x8*)(T + oa + 4096 + ((c ^ sa) << 4));
;       bf16x8 b0 = *(const bf16x8*)(T + ob0 + ((c ^ sb0) << 4));
;       bf16x8 b1 = *(const bf16x8*)(T + ob1 + ((c ^ sb1) << 4));
;       acc[0][0] = MFMA(a0, b0, acc[0][0]); acc[0][1] = MFMA(a0, b1, acc[0][1]);
;       acc[1][0] = MFMA(a1, b0, acc[1][0]); acc[1][1] = MFMA(a1, b1, acc[1][1]);
;       if (HALO) { bf16x8 ah = *(const bf16x8*)(T + oh + ((c ^ sh) << 4)); hacc = MFMA(ah, b0, hacc); }
;     }
	v_mfma_f32_32x32x16_bf16 v[0:15], v[106:109], v[110:113], v[0:15]
	v_mfma_f32_32x32x16_bf16 v[16:31], v[106:109], v[114:117], v[16:31]
	v_lshl_add_u64 v[106:107], v[64:65], 0, s[30:31]
	global_load_lds_dwordx4 v[106:107], off
	v_lshl_add_u64 v[106:107], v[66:67], 0, s[30:31]
	s_mov_b32 m0, s72
	v_readfirstlane_b32 s72, v100
	global_load_lds_dwordx4 v[106:107], off sc1
	v_lshl_add_u64 v[106:107], v[68:69], 0, s[30:31]
	s_mov_b32 m0, s73
	s_nop 0
	global_load_lds_dwordx4 v[106:107], off
	v_lshl_add_u64 v[106:107], v[70:71], 0, s[30:31]
	s_mov_b32 m0, s76
	s_nop 0
	global_load_lds_dwordx4 v[106:107], off sc1
	v_lshl_add_u64 v[106:107], v[72:73], 0, s[30:31]
	s_mov_b32 m0, s47
	s_nop 0
	global_load_lds_dwordx4 v[106:107], off
	v_lshl_add_u64 v[106:107], v[74:75], 0, s[30:31]
	s_mov_b32 m0, s49
	s_nop 0
	global_load_lds_dwordx4 v[106:107], off sc1
	v_lshl_add_u64 v[106:107], v[76:77], 0, s[30:31]
	s_mov_b32 m0, s56
	s_nop 0
	global_load_lds_dwordx4 v[106:107], off
	v_lshl_add_u64 v[106:107], v[78:79], 0, s[30:31]
	s_mov_b32 m0, s57
	s_nop 0
	global_load_lds_dwordx4 v[106:107], off sc1
	ds_read_b128 v[106:109], v83 offset:32768
	ds_read_b128 v[110:113], v85 offset:49152
	ds_read_b128 v[114:117], v85 offset:53248
	s_waitcnt lgkmcnt(0)
	v_mfma_f32_32x32x16_bf16 v[32:47], v[106:109], v[110:113], v[32:47]
	s_mov_b32 m0, s58
	v_readfirstlane_b32 s58, v101
	v_mfma_f32_32x32x16_bf16 v[48:63], v[106:109], v[114:117], v[48:63]
	ds_read_b128 v[106:109], v83 offset:36864
	s_waitcnt lgkmcnt(0)
	v_mfma_f32_32x32x16_bf16 v[0:15], v[106:109], v[110:113], v[0:15]
	v_mfma_f32_32x32x16_bf16 v[16:31], v[106:109], v[114:117], v[16:31]
	ds_read_b128 v[106:109], v84 offset:32768
	ds_read_b128 v[110:113], v87 offset:49152
	ds_read_b128 v[114:117], v87 offset:53248
	s_waitcnt lgkmcnt(0)
	v_mfma_f32_32x32x16_bf16 v[32:47], v[106:109], v[110:113], v[32:47]
	v_mfma_f32_32x32x16_bf16 v[48:63], v[106:109], v[114:117], v[48:63]
	ds_read_b128 v[106:109], v84 offset:36864
	s_waitcnt lgkmcnt(0)
	v_mfma_f32_32x32x16_bf16 v[0:15], v[106:109], v[110:113], v[0:15]
	v_mfma_f32_32x32x16_bf16 v[16:31], v[106:109], v[114:117], v[16:31]
	ds_read_b128 v[106:109], v86 offset:32768
	ds_read_b128 v[110:113], v88 offset:49152
	ds_read_b128 v[114:117], v88 offset:53248
	s_waitcnt lgkmcnt(0)
	v_mfma_f32_32x32x16_bf16 v[32:47], v[106:109], v[110:113], v[32:47]
	v_mfma_f32_32x32x16_bf16 v[48:63], v[106:109], v[114:117], v[48:63]
	ds_read_b128 v[106:109], v86 offset:36864
	s_waitcnt lgkmcnt(0)
	v_mfma_f32_32x32x16_bf16 v[0:15], v[106:109], v[110:113], v[0:15]
	v_mfma_f32_32x32x16_bf16 v[16:31], v[106:109], v[114:117], v[16:31]
	ds_read_b128 v[106:109], v89 offset:32768
	ds_read_b128 v[110:113], v90 offset:49152
	ds_read_b128 v[114:117], v90 offset:53248
	s_waitcnt lgkmcnt(0)
	v_mfma_f32_32x32x16_bf16 v[32:47], v[106:109], v[110:113], v[32:47]
	v_mfma_f32_32x32x16_bf16 v[48:63], v[106:109], v[114:117], v[48:63]
	ds_read_b128 v[106:109], v89 offset:36864
	s_waitcnt vmcnt(0)
	s_waitcnt vmcnt(0) lgkmcnt(0)
	s_barrier
	v_mfma_f32_32x32x16_bf16 v[0:15], v[106:109], v[110:113], v[0:15]
	v_mfma_f32_32x32x16_bf16 v[16:31], v[106:109], v[114:117], v[16:31]
	v_lshl_add_u64 v[106:107], v[64:65], 0, s[4:5]
	global_load_lds_dwordx4 v[106:107], off
	v_lshl_add_u64 v[106:107], v[66:67], 0, s[4:5]
	s_mov_b32 m0, s59
	v_readfirstlane_b32 s59, v102
	global_load_lds_dwordx4 v[106:107], off sc1
	v_lshl_add_u64 v[106:107], v[68:69], 0, s[4:5]
	s_mov_b32 m0, s60
	v_readfirstlane_b32 s60, v103
	global_load_lds_dwordx4 v[106:107], off
	v_lshl_add_u64 v[106:107], v[70:71], 0, s[4:5]
	s_mov_b32 m0, s61
	v_readfirstlane_b32 s61, v104
	global_load_lds_dwordx4 v[106:107], off sc1
	v_lshl_add_u64 v[106:107], v[72:73], 0, s[4:5]
	s_mov_b32 m0, s62
	v_lshl_add_u64 v[102:103], v[70:71], 0, s[66:67]
	global_load_lds_dwordx4 v[106:107], off
	v_lshl_add_u64 v[106:107], v[74:75], 0, s[4:5]
	s_mov_b32 m0, s63
	v_readfirstlane_b32 s62, v95
	global_load_lds_dwordx4 v[106:107], off sc1
	v_lshl_add_u64 v[106:107], v[76:77], 0, s[4:5]
	s_mov_b32 m0, s69
	v_readfirstlane_b32 s63, v96
	global_load_lds_dwordx4 v[106:107], off
	v_lshl_add_u64 v[106:107], v[78:79], 0, s[4:5]
	s_mov_b32 m0, s70
	v_readfirstlane_b32 s69, v97
	global_load_lds_dwordx4 v[106:107], off sc1
	ds_read_b128 v[106:109], v83
	ds_read_b128 v[110:113], v85 offset:16384
	ds_read_b128 v[114:117], v85 offset:20480
	s_waitcnt lgkmcnt(0)
	v_mfma_f32_32x32x16_bf16 v[32:47], v[106:109], v[110:113], v[32:47]
	s_mov_b32 m0, s58
	v_readfirstlane_b32 s70, v98
	v_mfma_f32_32x32x16_bf16 v[48:63], v[106:109], v[114:117], v[48:63]
	ds_read_b128 v[106:109], v83 offset:4096
	s_waitcnt lgkmcnt(0)
	v_mfma_f32_32x32x16_bf16 v[0:15], v[106:109], v[110:113], v[0:15]
	v_mfma_f32_32x32x16_bf16 v[16:31], v[106:109], v[114:117], v[16:31]
	ds_read_b128 v[106:109], v84
	ds_read_b128 v[110:113], v87 offset:16384
	ds_read_b128 v[114:117], v87 offset:20480
	s_waitcnt lgkmcnt(0)
	v_mfma_f32_32x32x16_bf16 v[32:47], v[106:109], v[110:113], v[32:47]
	v_mfma_f32_32x32x16_bf16 v[48:63], v[106:109], v[114:117], v[48:63]
	ds_read_b128 v[106:109], v84 offset:4096
	s_waitcnt lgkmcnt(0)
	v_mfma_f32_32x32x16_bf16 v[0:15], v[106:109], v[110:113], v[0:15]
	v_mfma_f32_32x32x16_bf16 v[16:31], v[106:109], v[114:117], v[16:31]
	ds_read_b128 v[106:109], v86
	ds_read_b128 v[110:113], v88 offset:16384
	ds_read_b128 v[114:117], v88 offset:20480
	s_waitcnt lgkmcnt(0)
	v_mfma_f32_32x32x16_bf16 v[32:47], v[106:109], v[110:113], v[32:47]
	v_mfma_f32_32x32x16_bf16 v[48:63], v[106:109], v[114:117], v[48:63]
	ds_read_b128 v[106:109], v86 offset:4096
	s_waitcnt lgkmcnt(0)
	v_mfma_f32_32x32x16_bf16 v[0:15], v[106:109], v[110:113], v[0:15]
	v_mfma_f32_32x32x16_bf16 v[16:31], v[106:109], v[114:117], v[16:31]
	ds_read_b128 v[106:109], v89
	ds_read_b128 v[110:113], v90 offset:16384
	ds_read_b128 v[114:117], v90 offset:20480
	s_waitcnt lgkmcnt(0)
	v_mfma_f32_32x32x16_bf16 v[32:47], v[106:109], v[110:113], v[32:47]
	v_mfma_f32_32x32x16_bf16 v[48:63], v[106:109], v[114:117], v[48:63]
	ds_read_b128 v[106:109], v89 offset:4096
	s_waitcnt vmcnt(0)
	s_waitcnt vmcnt(0) lgkmcnt(0)
	s_barrier
; #define MFMA(a, b, c) __builtin_amdgcn_mfma_f32_32x32x16_bf16(a, b, c, 0, 0, 0)
; #define ISSUE(k0, bf) do { char* A_ = lw + (bf) * BUF; \
;     _Pragma("unroll") for (int i_ = 0; i_ < 4; ++i_) { glds16(al.ptr(lrow + 32 * i_, (k0) + cg), A_ + i_ * 4096); glds16(bl.ptr(lrow + 32 * i_, (k0) + cg), A_ + ABYTES + i_ * 4096); } \
;     if (HALO) { if (wid == 0) glds16(gh + (k0), A_ + 16384); } } while (0)
; template <bool HALO, class AL, class BL>
; __device__ __forceinline__ void gemm_core(f32x16 (&acc)[2][2], f32x16& hacc, const AL& al, const BL& bl, int K, char* lds,
;                                           const u16* halo0, const u16* halo1, int brow0, int brow1) {
;     ...
;   for (int kt = 0; kt < nk; ++kt) {
;     asm volatile("s_waitcnt vmcnt(0)" ::: "memory");
;     __syncthreads();
;     if (kt + 1 < nk) ISSUE((kt + 1) * 64, (kt + 1) & 1);
;     const char* T = lds + (kt & 1) * BUF;
; #pragma unroll
;     for (int kk = 0; kk < 4; ++kk) {
;       const int c = kk * 2 + hi;
;       bf16x8 a0 = *(const bf16x8*)(T + oa + ((c ^ sa) << 4));
;       bf16x8 a1 = *(const bf16x8*)(T + oa + 4096 + ((c ^ sa) << 4));
;       bf16x8 b0 = *(const bf16x8*)(T + ob0 + ((c ^ sb0) << 4));
;       bf16x8 b1 = *(const bf16x8*)(T + ob1 + ((c ^ sb1) << 4));
;       acc[0][0] = MFMA(a0, b0, acc[0][0]); acc[0][1] = MFMA(a0, b1, acc[0][1]);
;       acc[1][0] = MFMA(a1, b0, acc[1][0]); acc[1][1] = MFMA(a1, b1, acc[1][1]);
;       if (HALO) { bf16x8 ah = *(const bf16x8*)(T + oh + ((c ^ sh) << 4)); hacc = MFMA(ah, b0, hacc); }
;     }
	v_mfma_f32_32x32x16_bf16 v[0:15], v[106:109], v[110:113], v[0:15]
	v_mfma_f32_32x32x16_bf16 v[16:31], v[106:109], v[114:117], v[16:31]
	v_lshl_add_u64 v[106:107], v[64:65], 0, s[66:67]
	global_load_lds_dwordx4 v[106:107], off
	v_lshl_add_u64 v[106:107], v[66:67], 0, s[66:67]
	s_mov_b32 m0, s59
	s_nop 0
	global_load_lds_dwordx4 v[106:107], off sc1
	v_lshl_add_u64 v[106:107], v[68:69], 0, s[66:67]
	s_mov_b32 m0, s60
	s_nop 0
	global_load_lds_dwordx4 v[106:107], off
	s_mov_b32 m0, s61
	s_nop 0
	global_load_lds_dwordx4 v[102:103], off sc1
	v_lshl_add_u64 v[102:103], v[72:73], 0, s[66:67]
	s_mov_b32 m0, s47
	s_nop 0
	global_load_lds_dwordx4 v[102:103], off
	v_lshl_add_u64 v[102:103], v[74:75], 0, s[66:67]
	s_mov_b32 m0, s49
	s_nop 0
	global_load_lds_dwordx4 v[102:103], off sc1
	v_lshl_add_u64 v[102:103], v[76:77], 0, s[66:67]
	s_mov_b32 m0, s56
	v_readfirstlane_b32 s56, v94
	global_load_lds_dwordx4 v[102:103], off
	v_lshl_add_u64 v[102:103], v[78:79], 0, s[66:67]
	s_mov_b32 m0, s57
	v_readfirstlane_b32 s57, v93
	global_load_lds_dwordx4 v[102:103], off sc1
	ds_read_b128 v[102:105], v83 offset:32768
	ds_read_b128 v[106:109], v85 offset:49152
	ds_read_b128 v[110:113], v85 offset:53248
	s_waitcnt lgkmcnt(0)
	v_mfma_f32_32x32x16_bf16 v[32:47], v[102:105], v[106:109], v[32:47]
	s_mov_b32 m0, s56
	v_lshl_add_u64 v[94:95], v[70:71], 0, s[26:27]
	v_mfma_f32_32x32x16_bf16 v[48:63], v[102:105], v[110:113], v[48:63]
	ds_read_b128 v[102:105], v83 offset:36864
	s_waitcnt lgkmcnt(0)
	v_mfma_f32_32x32x16_bf16 v[0:15], v[102:105], v[106:109], v[0:15]
	v_mfma_f32_32x32x16_bf16 v[16:31], v[102:105], v[110:113], v[16:31]
	ds_read_b128 v[102:105], v84 offset:32768
	ds_read_b128 v[106:109], v87 offset:49152
	ds_read_b128 v[110:113], v87 offset:53248
	s_waitcnt lgkmcnt(0)
	v_mfma_f32_32x32x16_bf16 v[32:47], v[102:105], v[106:109], v[32:47]
	v_mfma_f32_32x32x16_bf16 v[48:63], v[102:105], v[110:113], v[48:63]
	ds_read_b128 v[102:105], v84 offset:36864
	s_waitcnt lgkmcnt(0)
	v_mfma_f32_32x32x16_bf16 v[0:15], v[102:105], v[106:109], v[0:15]
	v_mfma_f32_32x32x16_bf16 v[16:31], v[102:105], v[110:113], v[16:31]
	ds_read_b128 v[102:105], v86 offset:32768
	ds_read_b128 v[106:109], v88 offset:49152
	ds_read_b128 v[110:113], v88 offset:53248
	s_waitcnt lgkmcnt(0)
	v_mfma_f32_32x32x16_bf16 v[32:47], v[102:105], v[106:109], v[32:47]
	v_mfma_f32_32x32x16_bf16 v[48:63], v[102:105], v[110:113], v[48:63]
	ds_read_b128 v[102:105], v86 offset:36864
	s_waitcnt lgkmcnt(0)
	v_mfma_f32_32x32x16_bf16 v[0:15], v[102:105], v[106:109], v[0:15]
	v_mfma_f32_32x32x16_bf16 v[16:31], v[102:105], v[110:113], v[16:31]
	ds_read_b128 v[102:105], v89 offset:32768
	ds_read_b128 v[106:109], v90 offset:49152
	ds_read_b128 v[110:113], v90 offset:53248
	s_waitcnt lgkmcnt(0)
	v_mfma_f32_32x32x16_bf16 v[32:47], v[102:105], v[106:109], v[32:47]
	v_mfma_f32_32x32x16_bf16 v[48:63], v[102:105], v[110:113], v[48:63]
	ds_read_b128 v[102:105], v89 offset:36864
	s_waitcnt vmcnt(0)
	s_waitcnt vmcnt(0) lgkmcnt(0)
	s_barrier
	v_mfma_f32_32x32x16_bf16 v[0:15], v[102:105], v[106:109], v[0:15]
	v_mfma_f32_32x32x16_bf16 v[16:31], v[102:105], v[110:113], v[16:31]
	v_lshl_add_u64 v[102:103], v[64:65], 0, s[26:27]
	global_load_lds_dwordx4 v[102:103], off
	v_lshl_add_u64 v[102:103], v[66:67], 0, s[26:27]
	s_mov_b32 m0, s57
	s_nop 0
	global_load_lds_dwordx4 v[102:103], off sc1
	v_lshl_add_u64 v[102:103], v[68:69], 0, s[26:27]
	s_mov_b32 m0, s62
	s_nop 0
	global_load_lds_dwordx4 v[102:103], off
	s_mov_b32 m0, s63
	s_nop 0
	global_load_lds_dwordx4 v[94:95], off sc1
	v_lshl_add_u64 v[94:95], v[72:73], 0, s[26:27]
	s_mov_b32 m0, s69
	s_nop 0
	global_load_lds_dwordx4 v[94:95], off
	v_lshl_add_u64 v[94:95], v[74:75], 0, s[26:27]
	s_mov_b32 m0, s70
	s_nop 0
	global_load_lds_dwordx4 v[94:95], off sc1
	v_lshl_add_u64 v[94:95], v[76:77], 0, s[26:27]
	s_mov_b32 m0, s71
	s_nop 0
	global_load_lds_dwordx4 v[94:95], off
	v_lshl_add_u64 v[94:95], v[78:79], 0, s[26:27]
	s_mov_b32 m0, s72
	s_nop 0
	global_load_lds_dwordx4 v[94:95], off sc1
	ds_read_b128 v[94:97], v83
	ds_read_b128 v[98:101], v85 offset:16384
	ds_read_b128 v[102:105], v85 offset:20480
	s_waitcnt lgkmcnt(0)
	v_mfma_f32_32x32x16_bf16 v[32:47], v[94:97], v[98:101], v[32:47]
	s_mov_b32 m0, s58
	v_mfma_f32_32x32x16_bf16 v[48:63], v[94:97], v[102:105], v[48:63]
	ds_read_b128 v[94:97], v83 offset:4096
	s_waitcnt lgkmcnt(0)
	v_mfma_f32_32x32x16_bf16 v[0:15], v[94:97], v[98:101], v[0:15]
	v_mfma_f32_32x32x16_bf16 v[16:31], v[94:97], v[102:105], v[16:31]
	ds_read_b128 v[94:97], v84
	ds_read_b128 v[98:101], v87 offset:16384
	ds_read_b128 v[102:105], v87 offset:20480
	s_waitcnt lgkmcnt(0)
	v_mfma_f32_32x32x16_bf16 v[32:47], v[94:97], v[98:101], v[32:47]
	v_mfma_f32_32x32x16_bf16 v[48:63], v[94:97], v[102:105], v[48:63]
	ds_read_b128 v[94:97], v84 offset:4096
	s_waitcnt lgkmcnt(0)
	v_mfma_f32_32x32x16_bf16 v[0:15], v[94:97], v[98:101], v[0:15]
	v_mfma_f32_32x32x16_bf16 v[16:31], v[94:97], v[102:105], v[16:31]
	ds_read_b128 v[94:97], v86
	ds_read_b128 v[98:101], v88 offset:16384
	ds_read_b128 v[102:105], v88 offset:20480
	s_waitcnt lgkmcnt(0)
	v_mfma_f32_32x32x16_bf16 v[32:47], v[94:97], v[98:101], v[32:47]
	v_mfma_f32_32x32x16_bf16 v[48:63], v[94:97], v[102:105], v[48:63]
	ds_read_b128 v[94:97], v86 offset:4096
	s_waitcnt lgkmcnt(0)
	v_mfma_f32_32x32x16_bf16 v[0:15], v[94:97], v[98:101], v[0:15]
	v_mfma_f32_32x32x16_bf16 v[16:31], v[94:97], v[102:105], v[16:31]
	ds_read_b128 v[94:97], v89
	ds_read_b128 v[98:101], v90 offset:16384
	ds_read_b128 v[102:105], v90 offset:20480
	s_waitcnt lgkmcnt(0)
	v_mfma_f32_32x32x16_bf16 v[32:47], v[94:97], v[98:101], v[32:47]
	v_mfma_f32_32x32x16_bf16 v[48:63], v[94:97], v[102:105], v[48:63]
	ds_read_b128 v[94:97], v89 offset:4096
	s_waitcnt vmcnt(0)
	s_waitcnt vmcnt(0) lgkmcnt(0)
	s_barrier
; #define MFMA(a, b, c) __builtin_amdgcn_mfma_f32_32x32x16_bf16(a, b, c, 0, 0, 0)
; #define ISSUE(k0, bf) do { char* A_ = lw + (bf) * BUF; \
;     _Pragma("unroll") for (int i_ = 0; i_ < 4; ++i_) { glds16(al.ptr(lrow + 32 * i_, (k0) + cg), A_ + i_ * 4096); glds16(bl.ptr(lrow + 32 * i_, (k0) + cg), A_ + ABYTES + i_ * 4096); } \
;     if (HALO) { if (wid == 0) glds16(gh + (k0), A_ + 16384); } } while (0)
; template <bool HALO, class AL, class BL>
; __device__ __forceinline__ void gemm_core(f32x16 (&acc)[2][2], f32x16& hacc, const AL& al, const BL& bl, int K, char* lds,
;                                           const u16* halo0, const u16* halo1, int brow0, int brow1) {
;     ...
;   for (int kt = 0; kt < nk; ++kt) {
;     asm volatile("s_waitcnt vmcnt(0)" ::: "memory");
;     __syncthreads();
;     if (kt + 1 < nk) ISSUE((kt + 1) * 64, (kt + 1) & 1);
;     const char* T = lds + (kt & 1) * BUF;
; #pragma unroll
;     for (int kk = 0; kk < 4; ++kk) {
;       const int c = kk * 2 + hi;
;       bf16x8 a0 = *(const bf16x8*)(T + oa + ((c ^ sa) << 4));
;       bf16x8 a1 = *(const bf16x8*)(T + oa + 4096 + ((c ^ sa) << 4));
;       bf16x8 b0 = *(const bf16x8*)(T + ob0 + ((c ^ sb0) << 4));
;       bf16x8 b1 = *(const bf16x8*)(T + ob1 + ((c ^ sb1) << 4));
;       acc[0][0] = MFMA(a0, b0, acc[0][0]); acc[0][1] = MFMA(a0, b1, acc[0][1]);
;       acc[1][0] = MFMA(a1, b0, acc[1][0]); acc[1][1] = MFMA(a1, b1, acc[1][1]);
;       if (HALO) { bf16x8 ah = *(const bf16x8*)(T + oh + ((c ^ sh) << 4)); hacc = MFMA(ah, b0, hacc); }
;     }
	v_mfma_f32_32x32x16_bf16 v[0:15], v[94:97], v[98:101], v[0:15]
	v_mfma_f32_32x32x16_bf16 v[16:31], v[94:97], v[102:105], v[16:31]
	v_lshl_add_u64 v[94:95], v[64:65], 0, s[88:89]
	global_load_lds_dwordx4 v[94:95], off
	v_lshl_add_u64 v[94:95], v[66:67], 0, s[88:89]
	s_mov_b32 m0, s59
	s_nop 0
	global_load_lds_dwordx4 v[94:95], off sc1
	v_lshl_add_u64 v[94:95], v[68:69], 0, s[88:89]
	s_mov_b32 m0, s60
	s_nop 0
	global_load_lds_dwordx4 v[94:95], off
	v_lshl_add_u64 v[94:95], v[70:71], 0, s[88:89]
	s_mov_b32 m0, s61
	s_nop 0
	global_load_lds_dwordx4 v[94:95], off sc1
	v_lshl_add_u64 v[94:95], v[72:73], 0, s[88:89]
	s_mov_b32 m0, s47
	s_nop 0
	global_load_lds_dwordx4 v[94:95], off
	v_lshl_add_u64 v[94:95], v[74:75], 0, s[88:89]
	s_mov_b32 m0, s49
	s_nop 0
	global_load_lds_dwordx4 v[94:95], off sc1
	v_lshl_add_u64 v[94:95], v[76:77], 0, s[88:89]
	s_mov_b32 m0, s64
	s_nop 0
	global_load_lds_dwordx4 v[94:95], off
	v_lshl_add_u64 v[94:95], v[78:79], 0, s[88:89]
	s_mov_b32 m0, s65
	s_nop 0
	global_load_lds_dwordx4 v[94:95], off sc1
	ds_read_b128 v[92:95], v83 offset:32768
	ds_read_b128 v[96:99], v85 offset:49152
	ds_read_b128 v[100:103], v85 offset:53248
	s_waitcnt lgkmcnt(0)
	v_mfma_f32_32x32x16_bf16 v[32:47], v[92:95], v[96:99], v[32:47]
	s_mov_b32 m0, s56
	v_mfma_f32_32x32x16_bf16 v[48:63], v[92:95], v[100:103], v[48:63]
	ds_read_b128 v[92:95], v83 offset:36864
	s_waitcnt lgkmcnt(0)
	v_mfma_f32_32x32x16_bf16 v[0:15], v[92:95], v[96:99], v[0:15]
	v_mfma_f32_32x32x16_bf16 v[16:31], v[92:95], v[100:103], v[16:31]
	ds_read_b128 v[92:95], v84 offset:32768
	ds_read_b128 v[96:99], v87 offset:49152
	ds_read_b128 v[100:103], v87 offset:53248
	s_waitcnt lgkmcnt(0)
	v_mfma_f32_32x32x16_bf16 v[32:47], v[92:95], v[96:99], v[32:47]
	v_mfma_f32_32x32x16_bf16 v[48:63], v[92:95], v[100:103], v[48:63]
	ds_read_b128 v[92:95], v84 offset:36864
	s_waitcnt lgkmcnt(0)
	v_mfma_f32_32x32x16_bf16 v[0:15], v[92:95], v[96:99], v[0:15]
	v_mfma_f32_32x32x16_bf16 v[16:31], v[92:95], v[100:103], v[16:31]
	ds_read_b128 v[92:95], v86 offset:32768
	ds_read_b128 v[96:99], v88 offset:49152
	ds_read_b128 v[100:103], v88 offset:53248
	s_waitcnt lgkmcnt(0)
	v_mfma_f32_32x32x16_bf16 v[32:47], v[92:95], v[96:99], v[32:47]
	v_mfma_f32_32x32x16_bf16 v[48:63], v[92:95], v[100:103], v[48:63]
	ds_read_b128 v[92:95], v86 offset:36864
	s_waitcnt lgkmcnt(0)
	v_mfma_f32_32x32x16_bf16 v[0:15], v[92:95], v[96:99], v[0:15]
	v_mfma_f32_32x32x16_bf16 v[16:31], v[92:95], v[100:103], v[16:31]
	ds_read_b128 v[92:95], v89 offset:32768
	ds_read_b128 v[96:99], v90 offset:49152
	ds_read_b128 v[100:103], v90 offset:53248
	s_waitcnt lgkmcnt(0)
	v_mfma_f32_32x32x16_bf16 v[32:47], v[92:95], v[96:99], v[32:47]
	v_mfma_f32_32x32x16_bf16 v[48:63], v[92:95], v[100:103], v[48:63]
	ds_read_b128 v[92:95], v89 offset:36864
	s_waitcnt vmcnt(0)
	s_waitcnt vmcnt(0) lgkmcnt(0)
	s_barrier
	v_mfma_f32_32x32x16_bf16 v[0:15], v[92:95], v[96:99], v[0:15]
	v_mfma_f32_32x32x16_bf16 v[16:31], v[92:95], v[100:103], v[16:31]
	v_lshl_add_u64 v[92:93], v[64:65], 0, s[22:23]
	global_load_lds_dwordx4 v[92:93], off
	v_lshl_add_u64 v[92:93], v[66:67], 0, s[22:23]
	s_mov_b32 m0, s57
	s_nop 0
	global_load_lds_dwordx4 v[92:93], off sc1
	v_lshl_add_u64 v[92:93], v[68:69], 0, s[22:23]
	s_mov_b32 m0, s62
	s_nop 0
	global_load_lds_dwordx4 v[92:93], off
	v_lshl_add_u64 v[92:93], v[70:71], 0, s[22:23]
	s_mov_b32 m0, s63
	s_nop 0
	global_load_lds_dwordx4 v[92:93], off sc1
	v_lshl_add_u64 v[92:93], v[72:73], 0, s[22:23]
	s_mov_b32 m0, s69
	s_nop 0
	global_load_lds_dwordx4 v[92:93], off
	v_lshl_add_u64 v[92:93], v[74:75], 0, s[22:23]
	s_mov_b32 m0, s70
	s_nop 0
	global_load_lds_dwordx4 v[92:93], off sc1
	v_lshl_add_u64 v[92:93], v[76:77], 0, s[22:23]
	s_mov_b32 m0, s71
	s_nop 0
	global_load_lds_dwordx4 v[92:93], off
	v_lshl_add_u64 v[92:93], v[78:79], 0, s[22:23]
	s_mov_b32 m0, s72
	s_nop 0
	global_load_lds_dwordx4 v[92:93], off sc1
	ds_read_b128 v[92:95], v83
	ds_read_b128 v[96:99], v85 offset:16384
	ds_read_b128 v[100:103], v85 offset:20480
	s_waitcnt lgkmcnt(0)
	v_mfma_f32_32x32x16_bf16 v[32:47], v[92:95], v[96:99], v[32:47]
	s_mov_b32 m0, s58
	v_mfma_f32_32x32x16_bf16 v[48:63], v[92:95], v[100:103], v[48:63]
	ds_read_b128 v[92:95], v83 offset:4096
	s_waitcnt lgkmcnt(0)
	v_mfma_f32_32x32x16_bf16 v[0:15], v[92:95], v[96:99], v[0:15]
	v_mfma_f32_32x32x16_bf16 v[16:31], v[92:95], v[100:103], v[16:31]
	ds_read_b128 v[92:95], v84
	ds_read_b128 v[96:99], v87 offset:16384
	ds_read_b128 v[100:103], v87 offset:20480
	s_waitcnt lgkmcnt(0)
	v_mfma_f32_32x32x16_bf16 v[32:47], v[92:95], v[96:99], v[32:47]
	v_mfma_f32_32x32x16_bf16 v[48:63], v[92:95], v[100:103], v[48:63]
	ds_read_b128 v[92:95], v84 offset:4096
	s_waitcnt lgkmcnt(0)
	v_mfma_f32_32x32x16_bf16 v[0:15], v[92:95], v[96:99], v[0:15]
	v_mfma_f32_32x32x16_bf16 v[16:31], v[92:95], v[100:103], v[16:31]
	ds_read_b128 v[92:95], v86
	ds_read_b128 v[96:99], v88 offset:16384
	ds_read_b128 v[100:103], v88 offset:20480
	s_waitcnt lgkmcnt(0)
	v_mfma_f32_32x32x16_bf16 v[32:47], v[92:95], v[96:99], v[32:47]
	v_mfma_f32_32x32x16_bf16 v[48:63], v[92:95], v[100:103], v[48:63]
	ds_read_b128 v[92:95], v86 offset:4096
	s_waitcnt lgkmcnt(0)
	v_mfma_f32_32x32x16_bf16 v[0:15], v[92:95], v[96:99], v[0:15]
	v_mfma_f32_32x32x16_bf16 v[16:31], v[92:95], v[100:103], v[16:31]
	ds_read_b128 v[92:95], v89
	ds_read_b128 v[96:99], v90 offset:16384
	ds_read_b128 v[100:103], v90 offset:20480
	s_waitcnt lgkmcnt(0)
	v_mfma_f32_32x32x16_bf16 v[32:47], v[92:95], v[96:99], v[32:47]
	v_mfma_f32_32x32x16_bf16 v[48:63], v[92:95], v[100:103], v[48:63]
	ds_read_b128 v[92:95], v89 offset:4096
	s_waitcnt vmcnt(0)
	s_waitcnt vmcnt(0) lgkmcnt(0)
	s_barrier
; #define MFMA(a, b, c) __builtin_amdgcn_mfma_f32_32x32x16_bf16(a, b, c, 0, 0, 0)
; #define ISSUE(k0, bf) do { char* A_ = lw + (bf) * BUF; \
;     _Pragma("unroll") for (int i_ = 0; i_ < 4; ++i_) { glds16(al.ptr(lrow + 32 * i_, (k0) + cg), A_ + i_ * 4096); glds16(bl.ptr(lrow + 32 * i_, (k0) + cg), A_ + ABYTES + i_ * 4096); } \
;     if (HALO) { if (wid == 0) glds16(gh + (k0), A_ + 16384); } } while (0)
; template <bool HALO, class AL, class BL>
; __device__ __forceinline__ void gemm_core(f32x16 (&acc)[2][2], f32x16& hacc, const AL& al, const BL& bl, int K, char* lds,
;                                           const u16* halo0, const u16* halo1, int brow0, int brow1) {
;     ...
;   for (int kt = 0; kt < nk; ++kt) {
;     asm volatile("s_waitcnt vmcnt(0)" ::: "memory");
;     __syncthreads();
;     if (kt + 1 < nk) ISSUE((kt + 1) * 64, (kt + 1) & 1);
;     const char* T = lds + (kt & 1) * BUF;
; #pragma unroll
;     for (int kk = 0; kk < 4; ++kk) {
;       const int c = kk * 2 + hi;
;       bf16x8 a0 = *(const bf16x8*)(T + oa + ((c ^ sa) << 4));
;       bf16x8 a1 = *(const bf16x8*)(T + oa + 4096 + ((c ^ sa) << 4));
;       bf16x8 b0 = *(const bf16x8*)(T + ob0 + ((c ^ sb0) << 4));
;       bf16x8 b1 = *(const bf16x8*)(T + ob1 + ((c ^ sb1) << 4));
;       acc[0][0] = MFMA(a0, b0, acc[0][0]); acc[0][1] = MFMA(a0, b1, acc[0][1]);
;       acc[1][0] = MFMA(a1, b0, acc[1][0]); acc[1][1] = MFMA(a1, b1, acc[1][1]);
;       if (HALO) { bf16x8 ah = *(const bf16x8*)(T + oh + ((c ^ sh) << 4)); hacc = MFMA(ah, b0, hacc); }
;     }
	v_mfma_f32_32x32x16_bf16 v[0:15], v[92:95], v[96:99], v[0:15]
	v_mfma_f32_32x32x16_bf16 v[16:31], v[92:95], v[100:103], v[16:31]
	v_lshl_add_u64 v[92:93], v[64:65], 0, s[90:91]
	global_load_lds_dwordx4 v[92:93], off
	v_lshl_add_u64 v[92:93], v[66:67], 0, s[90:91]
	s_mov_b32 m0, s59
	s_nop 0
	global_load_lds_dwordx4 v[92:93], off sc1
	v_lshl_add_u64 v[92:93], v[68:69], 0, s[90:91]
	s_mov_b32 m0, s60
	s_nop 0
	global_load_lds_dwordx4 v[92:93], off
	v_lshl_add_u64 v[92:93], v[70:71], 0, s[90:91]
	s_mov_b32 m0, s61
	s_nop 0
	global_load_lds_dwordx4 v[92:93], off sc1
	v_lshl_add_u64 v[92:93], v[72:73], 0, s[90:91]
	s_mov_b32 m0, s47
	s_nop 0
	global_load_lds_dwordx4 v[92:93], off
	v_lshl_add_u64 v[92:93], v[74:75], 0, s[90:91]
	s_mov_b32 m0, s49
	s_nop 0
	global_load_lds_dwordx4 v[92:93], off sc1
	v_lshl_add_u64 v[92:93], v[76:77], 0, s[90:91]
	s_mov_b32 m0, s64
	s_nop 0
	global_load_lds_dwordx4 v[92:93], off
	v_lshl_add_u64 v[92:93], v[78:79], 0, s[90:91]
	s_mov_b32 m0, s65
	s_nop 0
	global_load_lds_dwordx4 v[92:93], off sc1
	ds_read_b128 v[92:95], v83 offset:32768
	ds_read_b128 v[96:99], v85 offset:49152
	ds_read_b128 v[100:103], v85 offset:53248
	s_waitcnt lgkmcnt(0)
	v_mfma_f32_32x32x16_bf16 v[32:47], v[92:95], v[96:99], v[32:47]
	s_mov_b32 m0, s56
	v_mfma_f32_32x32x16_bf16 v[48:63], v[92:95], v[100:103], v[48:63]
	ds_read_b128 v[92:95], v83 offset:36864
	s_waitcnt lgkmcnt(0)
	v_mfma_f32_32x32x16_bf16 v[0:15], v[92:95], v[96:99], v[0:15]
	v_mfma_f32_32x32x16_bf16 v[16:31], v[92:95], v[100:103], v[16:31]
	ds_read_b128 v[92:95], v84 offset:32768
	ds_read_b128 v[96:99], v87 offset:49152
	ds_read_b128 v[100:103], v87 offset:53248
	s_waitcnt lgkmcnt(0)
	v_mfma_f32_32x32x16_bf16 v[32:47], v[92:95], v[96:99], v[32:47]
	v_mfma_f32_32x32x16_bf16 v[48:63], v[92:95], v[100:103], v[48:63]
	ds_read_b128 v[92:95], v84 offset:36864
	s_waitcnt lgkmcnt(0)
	v_mfma_f32_32x32x16_bf16 v[0:15], v[92:95], v[96:99], v[0:15]
	v_mfma_f32_32x32x16_bf16 v[16:31], v[92:95], v[100:103], v[16:31]
	ds_read_b128 v[92:95], v86 offset:32768
	ds_read_b128 v[96:99], v88 offset:49152
	ds_read_b128 v[100:103], v88 offset:53248
	s_waitcnt lgkmcnt(0)
	v_mfma_f32_32x32x16_bf16 v[32:47], v[92:95], v[96:99], v[32:47]
	v_mfma_f32_32x32x16_bf16 v[48:63], v[92:95], v[100:103], v[48:63]
	ds_read_b128 v[92:95], v86 offset:36864
	s_waitcnt lgkmcnt(0)
	v_mfma_f32_32x32x16_bf16 v[0:15], v[92:95], v[96:99], v[0:15]
	v_mfma_f32_32x32x16_bf16 v[16:31], v[92:95], v[100:103], v[16:31]
	ds_read_b128 v[92:95], v89 offset:32768
	ds_read_b128 v[96:99], v90 offset:49152
	ds_read_b128 v[100:103], v90 offset:53248
	s_waitcnt lgkmcnt(0)
	v_mfma_f32_32x32x16_bf16 v[32:47], v[92:95], v[96:99], v[32:47]
	v_mfma_f32_32x32x16_bf16 v[48:63], v[92:95], v[100:103], v[48:63]
	ds_read_b128 v[92:95], v89 offset:36864
	s_waitcnt vmcnt(0)
	s_waitcnt vmcnt(0) lgkmcnt(0)
	s_barrier
	v_mfma_f32_32x32x16_bf16 v[0:15], v[92:95], v[96:99], v[0:15]
	v_mfma_f32_32x32x16_bf16 v[16:31], v[92:95], v[100:103], v[16:31]
	v_lshl_add_u64 v[92:93], v[64:65], 0, s[0:1]
	global_load_lds_dwordx4 v[92:93], off
	v_lshl_add_u64 v[92:93], v[66:67], 0, s[0:1]
	s_mov_b32 m0, s57
	s_nop 0
	global_load_lds_dwordx4 v[92:93], off sc1
	v_lshl_add_u64 v[92:93], v[68:69], 0, s[0:1]
	s_mov_b32 m0, s62
	s_nop 0
	global_load_lds_dwordx4 v[92:93], off
	v_lshl_add_u64 v[92:93], v[70:71], 0, s[0:1]
	s_mov_b32 m0, s63
	s_nop 0
	global_load_lds_dwordx4 v[92:93], off sc1
	v_lshl_add_u64 v[92:93], v[72:73], 0, s[0:1]
	s_mov_b32 m0, s69
	s_nop 0
	global_load_lds_dwordx4 v[92:93], off
	v_lshl_add_u64 v[92:93], v[74:75], 0, s[0:1]
	s_mov_b32 m0, s70
	s_nop 0
	global_load_lds_dwordx4 v[92:93], off sc1
	v_lshl_add_u64 v[92:93], v[76:77], 0, s[0:1]
	s_mov_b32 m0, s71
	s_nop 0
	global_load_lds_dwordx4 v[92:93], off
	v_lshl_add_u64 v[92:93], v[78:79], 0, s[0:1]
	s_mov_b32 m0, s72
	s_nop 0
	global_load_lds_dwordx4 v[92:93], off sc1
	ds_read_b128 v[92:95], v83
	ds_read_b128 v[96:99], v85 offset:16384
	ds_read_b128 v[100:103], v85 offset:20480
	s_waitcnt lgkmcnt(0)
	v_mfma_f32_32x32x16_bf16 v[32:47], v[92:95], v[96:99], v[32:47]
	s_mov_b32 m0, s58
	v_mfma_f32_32x32x16_bf16 v[48:63], v[92:95], v[100:103], v[48:63]
	ds_read_b128 v[92:95], v83 offset:4096
	s_waitcnt lgkmcnt(0)
	v_mfma_f32_32x32x16_bf16 v[0:15], v[92:95], v[96:99], v[0:15]
	v_mfma_f32_32x32x16_bf16 v[16:31], v[92:95], v[100:103], v[16:31]
	ds_read_b128 v[92:95], v84
	ds_read_b128 v[96:99], v87 offset:16384
	ds_read_b128 v[100:103], v87 offset:20480
	s_waitcnt lgkmcnt(0)
	v_mfma_f32_32x32x16_bf16 v[32:47], v[92:95], v[96:99], v[32:47]
	v_mfma_f32_32x32x16_bf16 v[48:63], v[92:95], v[100:103], v[48:63]
	ds_read_b128 v[92:95], v84 offset:4096
	s_waitcnt lgkmcnt(0)
	v_mfma_f32_32x32x16_bf16 v[0:15], v[92:95], v[96:99], v[0:15]
	v_mfma_f32_32x32x16_bf16 v[16:31], v[92:95], v[100:103], v[16:31]
	ds_read_b128 v[92:95], v86
	ds_read_b128 v[96:99], v88 offset:16384
	ds_read_b128 v[100:103], v88 offset:20480
	s_waitcnt lgkmcnt(0)
	v_mfma_f32_32x32x16_bf16 v[32:47], v[92:95], v[96:99], v[32:47]
	v_mfma_f32_32x32x16_bf16 v[48:63], v[92:95], v[100:103], v[48:63]
	ds_read_b128 v[92:95], v86 offset:4096
	s_waitcnt lgkmcnt(0)
	v_mfma_f32_32x32x16_bf16 v[0:15], v[92:95], v[96:99], v[0:15]
	v_mfma_f32_32x32x16_bf16 v[16:31], v[92:95], v[100:103], v[16:31]
	ds_read_b128 v[92:95], v89
	ds_read_b128 v[96:99], v90 offset:16384
	ds_read_b128 v[100:103], v90 offset:20480
	s_waitcnt lgkmcnt(0)
	v_mfma_f32_32x32x16_bf16 v[32:47], v[92:95], v[96:99], v[32:47]
	v_mfma_f32_32x32x16_bf16 v[48:63], v[92:95], v[100:103], v[48:63]
	ds_read_b128 v[92:95], v89 offset:4096
	s_waitcnt vmcnt(0)
	s_waitcnt vmcnt(0) lgkmcnt(0)
	s_barrier
; #define MFMA(a, b, c) __builtin_amdgcn_mfma_f32_32x32x16_bf16(a, b, c, 0, 0, 0)
; #define ISSUE(k0, bf) do { char* A_ = lw + (bf) * BUF; \
;     _Pragma("unroll") for (int i_ = 0; i_ < 4; ++i_) { glds16(al.ptr(lrow + 32 * i_, (k0) + cg), A_ + i_ * 4096); glds16(bl.ptr(lrow + 32 * i_, (k0) + cg), A_ + ABYTES + i_ * 4096); } \
;     if (HALO) { if (wid == 0) glds16(gh + (k0), A_ + 16384); } } while (0)
; template <bool HALO, class AL, class BL>
; __device__ __forceinline__ void gemm_core(f32x16 (&acc)[2][2], f32x16& hacc, const AL& al, const BL& bl, int K, char* lds,
;                                           const u16* halo0, const u16* halo1, int brow0, int brow1) {
;     ...
;   for (int kt = 0; kt < nk; ++kt) {
;     asm volatile("s_waitcnt vmcnt(0)" ::: "memory");
;     __syncthreads();
;     if (kt + 1 < nk) ISSUE((kt + 1) * 64, (kt + 1) & 1);
;     const char* T = lds + (kt & 1) * BUF;
; #pragma unroll
;     for (int kk = 0; kk < 4; ++kk) {
;       const int c = kk * 2 + hi;
;       bf16x8 a0 = *(const bf16x8*)(T + oa + ((c ^ sa) << 4));
;       bf16x8 a1 = *(const bf16x8*)(T + oa + 4096 + ((c ^ sa) << 4));
;       bf16x8 b0 = *(const bf16x8*)(T + ob0 + ((c ^ sb0) << 4));
;       bf16x8 b1 = *(const bf16x8*)(T + ob1 + ((c ^ sb1) << 4));
;       acc[0][0] = MFMA(a0, b0, acc[0][0]); acc[0][1] = MFMA(a0, b1, acc[0][1]);
;       acc[1][0] = MFMA(a1, b0, acc[1][0]); acc[1][1] = MFMA(a1, b1, acc[1][1]);
;       if (HALO) { bf16x8 ah = *(const bf16x8*)(T + oh + ((c ^ sh) << 4)); hacc = MFMA(ah, b0, hacc); }
;     }
	v_mfma_f32_32x32x16_bf16 v[0:15], v[92:95], v[96:99], v[0:15]
	v_mfma_f32_32x32x16_bf16 v[16:31], v[92:95], v[100:103], v[16:31]
	v_lshl_add_u64 v[92:93], v[64:65], 0, s[34:35]
	global_load_lds_dwordx4 v[92:93], off
	v_lshl_add_u64 v[92:93], v[66:67], 0, s[34:35]
	s_mov_b32 m0, s59
	v_lshl_add_u64 v[64:65], v[64:65], 0, s[38:39]
	global_load_lds_dwordx4 v[92:93], off sc1
	v_lshl_add_u64 v[92:93], v[68:69], 0, s[34:35]
	s_mov_b32 m0, s60
	s_nop 0
	global_load_lds_dwordx4 v[92:93], off
	v_lshl_add_u64 v[92:93], v[70:71], 0, s[34:35]
	s_mov_b32 m0, s61
	s_nop 0
	global_load_lds_dwordx4 v[92:93], off sc1
	v_lshl_add_u64 v[92:93], v[72:73], 0, s[34:35]
	s_mov_b32 m0, s47
	s_and_b32 s47, s46, 0x7ffffffc
	global_load_lds_dwordx4 v[92:93], off
	v_lshl_add_u64 v[92:93], v[74:75], 0, s[34:35]
	s_mov_b32 m0, s49
	s_cmp_lg_u32 s47, 12
	global_load_lds_dwordx4 v[92:93], off sc1
	v_lshl_add_u64 v[92:93], v[76:77], 0, s[34:35]
	s_mov_b32 m0, s64
	s_nop 0
	global_load_lds_dwordx4 v[92:93], off
	v_lshl_add_u64 v[92:93], v[78:79], 0, s[34:35]
	s_mov_b32 m0, s65
	s_nop 0
	global_load_lds_dwordx4 v[92:93], off sc1
	ds_read_b128 v[92:95], v83 offset:32768
	ds_read_b128 v[96:99], v85 offset:49152
	ds_read_b128 v[100:103], v85 offset:53248
	s_waitcnt lgkmcnt(0)
	v_mfma_f32_32x32x16_bf16 v[32:47], v[92:95], v[96:99], v[32:47]
	s_mov_b32 m0, s56
	v_mfma_f32_32x32x16_bf16 v[48:63], v[92:95], v[100:103], v[48:63]
	ds_read_b128 v[92:95], v83 offset:36864
	s_waitcnt lgkmcnt(0)
	v_mfma_f32_32x32x16_bf16 v[0:15], v[92:95], v[96:99], v[0:15]
	v_mfma_f32_32x32x16_bf16 v[16:31], v[92:95], v[100:103], v[16:31]
	ds_read_b128 v[92:95], v84 offset:32768
	ds_read_b128 v[96:99], v87 offset:49152
	ds_read_b128 v[100:103], v87 offset:53248
	s_waitcnt lgkmcnt(0)
	v_mfma_f32_32x32x16_bf16 v[32:47], v[92:95], v[96:99], v[32:47]
	v_mfma_f32_32x32x16_bf16 v[48:63], v[92:95], v[100:103], v[48:63]
	ds_read_b128 v[92:95], v84 offset:36864
	s_waitcnt lgkmcnt(0)
	v_mfma_f32_32x32x16_bf16 v[0:15], v[92:95], v[96:99], v[0:15]
	v_mfma_f32_32x32x16_bf16 v[16:31], v[92:95], v[100:103], v[16:31]
	ds_read_b128 v[92:95], v86 offset:32768
	ds_read_b128 v[96:99], v88 offset:49152
	ds_read_b128 v[100:103], v88 offset:53248
	s_waitcnt lgkmcnt(0)
	v_mfma_f32_32x32x16_bf16 v[32:47], v[92:95], v[96:99], v[32:47]
	v_mfma_f32_32x32x16_bf16 v[48:63], v[92:95], v[100:103], v[48:63]
	ds_read_b128 v[92:95], v86 offset:36864
	s_waitcnt lgkmcnt(0)
	v_mfma_f32_32x32x16_bf16 v[0:15], v[92:95], v[96:99], v[0:15]
	v_mfma_f32_32x32x16_bf16 v[16:31], v[92:95], v[100:103], v[16:31]
	ds_read_b128 v[92:95], v89 offset:32768
	ds_read_b128 v[96:99], v90 offset:49152
	ds_read_b128 v[100:103], v90 offset:53248
	s_waitcnt lgkmcnt(0)
	v_mfma_f32_32x32x16_bf16 v[32:47], v[92:95], v[96:99], v[32:47]
	v_mfma_f32_32x32x16_bf16 v[48:63], v[92:95], v[100:103], v[48:63]
	ds_read_b128 v[92:95], v89 offset:36864
	s_waitcnt vmcnt(0)
	s_waitcnt vmcnt(0) lgkmcnt(0)
	s_barrier
	global_load_lds_dwordx4 v[64:65], off
	v_lshl_add_u64 v[64:65], v[66:67], 0, s[38:39]
	s_mov_b32 m0, s57
	v_mfma_f32_32x32x16_bf16 v[0:15], v[92:95], v[96:99], v[0:15]
	global_load_lds_dwordx4 v[64:65], off sc1
	v_lshl_add_u64 v[64:65], v[68:69], 0, s[38:39]
	s_mov_b32 m0, s62
	s_cselect_b64 s[56:57], -1, 0
	global_load_lds_dwordx4 v[64:65], off
	v_lshl_add_u64 v[64:65], v[70:71], 0, s[38:39]
	s_mov_b32 m0, s63
	v_mfma_f32_32x32x16_bf16 v[16:31], v[92:95], v[100:103], v[16:31]
	global_load_lds_dwordx4 v[64:65], off sc1
	v_lshl_add_u64 v[64:65], v[72:73], 0, s[38:39]
	s_mov_b32 m0, s69
	s_nop 0
	global_load_lds_dwordx4 v[64:65], off
	v_lshl_add_u64 v[64:65], v[74:75], 0, s[38:39]
	s_mov_b32 m0, s70
	s_nop 0
	global_load_lds_dwordx4 v[64:65], off sc1
	v_lshl_add_u64 v[64:65], v[76:77], 0, s[38:39]
	s_mov_b32 m0, s71
	s_nop 0
	global_load_lds_dwordx4 v[64:65], off
	v_lshl_add_u64 v[64:65], v[78:79], 0, s[38:39]
	s_mov_b32 m0, s72
	s_nop 0
	global_load_lds_dwordx4 v[64:65], off sc1
	ds_read_b128 v[64:67], v83
	ds_read_b128 v[68:71], v85 offset:16384
	ds_read_b128 v[72:75], v85 offset:20480
	s_waitcnt lgkmcnt(0)
	v_mfma_f32_32x32x16_bf16 v[32:47], v[64:67], v[68:71], v[32:47]
	v_mfma_f32_32x32x16_bf16 v[48:63], v[64:67], v[72:75], v[48:63]
	ds_read_b128 v[64:67], v83 offset:4096
	s_waitcnt lgkmcnt(0)
	v_mfma_f32_32x32x16_bf16 v[0:15], v[64:67], v[68:71], v[0:15]
	v_mfma_f32_32x32x16_bf16 v[16:31], v[64:67], v[72:75], v[16:31]
	ds_read_b128 v[64:67], v84
	ds_read_b128 v[68:71], v87 offset:16384
	ds_read_b128 v[72:75], v87 offset:20480
	s_waitcnt lgkmcnt(0)
	v_mfma_f32_32x32x16_bf16 v[32:47], v[64:67], v[68:71], v[32:47]
	v_mfma_f32_32x32x16_bf16 v[48:63], v[64:67], v[72:75], v[48:63]
	ds_read_b128 v[64:67], v84 offset:4096
	s_waitcnt lgkmcnt(0)
	v_mfma_f32_32x32x16_bf16 v[0:15], v[64:67], v[68:71], v[0:15]
	v_mfma_f32_32x32x16_bf16 v[16:31], v[64:67], v[72:75], v[16:31]
	ds_read_b128 v[64:67], v86
	ds_read_b128 v[68:71], v88 offset:16384
	ds_read_b128 v[72:75], v88 offset:20480
	s_waitcnt lgkmcnt(0)
	v_mfma_f32_32x32x16_bf16 v[32:47], v[64:67], v[68:71], v[32:47]
	v_mfma_f32_32x32x16_bf16 v[48:63], v[64:67], v[72:75], v[48:63]
	ds_read_b128 v[64:67], v86 offset:4096
	s_waitcnt lgkmcnt(0)
	v_mfma_f32_32x32x16_bf16 v[0:15], v[64:67], v[68:71], v[0:15]
	v_mfma_f32_32x32x16_bf16 v[16:31], v[64:67], v[72:75], v[16:31]
	ds_read_b128 v[64:67], v89
	ds_read_b128 v[68:71], v90 offset:16384
	ds_read_b128 v[72:75], v90 offset:20480
	s_waitcnt lgkmcnt(0)
	v_mfma_f32_32x32x16_bf16 v[32:47], v[64:67], v[68:71], v[32:47]
	v_mfma_f32_32x32x16_bf16 v[48:63], v[64:67], v[72:75], v[48:63]
	ds_read_b128 v[64:67], v89 offset:4096
	s_waitcnt vmcnt(0)
	s_waitcnt vmcnt(0) lgkmcnt(0)
	s_barrier
; template <bool HALO, class AL, class BL>
; __device__ __forceinline__ void gemm_core(f32x16 (&acc)[2][2], f32x16& hacc, const AL& al, const BL& bl, int K, char* lds,
;                                           const u16* halo0, const u16* halo1, int brow0, int brow1) {
;     ...
;   for (int kt = 0; kt < nk; ++kt) {
;     asm volatile("s_waitcnt vmcnt(0)" ::: "memory");
;     __syncthreads();
;     if (kt + 1 < nk) ISSUE((kt + 1) * 64, (kt + 1) & 1);
;     const char* T = lds + (kt & 1) * BUF;
; #pragma unroll
;     for (int kk = 0; kk < 4; ++kk) {
;       const int c = kk * 2 + hi;
;       bf16x8 a0 = *(const bf16x8*)(T + oa + ((c ^ sa) << 4));
;       bf16x8 a1 = *(const bf16x8*)(T + oa + 4096 + ((c ^ sa) << 4));
;       bf16x8 b0 = *(const bf16x8*)(T + ob0 + ((c ^ sb0) << 4));
;       bf16x8 b1 = *(const bf16x8*)(T + ob1 + ((c ^ sb1) << 4));
;       acc[0][0] = MFMA(a0, b0, acc[0][0]); acc[0][1] = MFMA(a0, b1, acc[0][1]);
;       acc[1][0] = MFMA(a1, b0, acc[1][0]); acc[1][1] = MFMA(a1, b1, acc[1][1]);
;       if (HALO) { bf16x8 ah = *(const bf16x8*)(T + oh + ((c ^ sh) << 4)); hacc = MFMA(ah, b0, hacc); }
;     }
; __device__ __forceinline__ void phase_z(const P& p, int layer, char* lds) {
;     ...
;     const int span = tn * 2 + wc, colb = span * 64;
;     const bool rope = (span < 16) || (span >= 24 && span < 32);
;     const float sc = (span < 8 || (span >= 28 && span < 32)) ? 0.125f : 1.f;
;     const unsigned rb = (unsigned)(tm * 128 + wr * 64 + 4 * hi + opq());
;     if (rope) {
;       float cc[2][16], ss[2][16];
; #pragma unroll
;       for (int mi = 0; mi < 2; ++mi)
; #pragma unroll
;         for (int r = 0; r < 16; ++r) { const unsigned row = rb + mi * 32 + (r & 3) + 8 * (r >> 2); cc[mi][r] = ct[row * 32 + r32]; ss[mi][r] = st[row * 32 + r32]; }
; #pragma unroll
;       for (int mi = 0; mi < 2; ++mi) {
; #pragma unroll
;         for (int r = 0; r < 16; ++r) {
;           const unsigned row = rb + mi * 32 + (r & 3) + 8 * (r >> 2);
;           const float x1 = acc[mi][0][r], x2 = acc[mi][1][r];
;           const unsigned w = cvtpk((x1 * cc[mi][r] - x2 * ss[mi][r]) * sc, (x2 * cc[mi][r] + x1 * ss[mi][r]) * sc);
;           z[row * ZC + colb + r32] = (u16)w; z[row * ZC + colb + 32 + r32] = (u16)(w >> 16);
;         }
;         SBAR();
;       }
;     } else {
; #pragma unroll
;       for (int mi = 0; mi < 2; ++mi) {
; #pragma unroll
	v_mfma_f32_32x32x16_bf16 v[0:15], v[64:67], v[68:71], v[0:15]
	v_mfma_f32_32x32x16_bf16 v[16:31], v[64:67], v[72:75], v[16:31]
	ds_read_b128 v[64:67], v83 offset:32768
	ds_read_b128 v[68:71], v85 offset:49152
	ds_read_b128 v[72:75], v85 offset:53248
	s_waitcnt lgkmcnt(1)
	v_mfma_f32_32x32x16_bf16 v[32:47], v[64:67], v[68:71], v[32:47]
	s_waitcnt lgkmcnt(0)
	v_mfma_f32_32x32x16_bf16 v[48:63], v[64:67], v[72:75], v[48:63]
	ds_read_b128 v[64:67], v83 offset:36864
	v_lshl_or_b32 v83, s46, 1, v80
	v_cmp_lt_i32_e32 vcc, 15, v83
	s_and_b64 s[56:57], vcc, s[56:57]
	s_and_b32 s46, s46, 0x7ffffffe
	s_cmp_eq_u32 s46, 14
	v_cmp_gt_i32_e32 vcc, 8, v83
	s_waitcnt lgkmcnt(0)
	v_mfma_f32_32x32x16_bf16 v[0:15], v[64:67], v[68:71], v[0:15]
	s_cselect_b64 s[46:47], -1, 0
	s_or_b64 vcc, vcc, s[46:47]
	s_lshl_b32 s46, s48, 7
	v_mfma_f32_32x32x16_bf16 v[16:31], v[64:67], v[72:75], v[16:31]
	ds_read_b128 v[64:67], v84 offset:32768
	ds_read_b128 v[68:71], v87 offset:49152
	ds_read_b128 v[72:75], v87 offset:53248
	s_waitcnt lgkmcnt(1)
	v_mfma_f32_32x32x16_bf16 v[32:47], v[64:67], v[68:71], v[32:47]
	s_waitcnt lgkmcnt(0)
	v_mfma_f32_32x32x16_bf16 v[48:63], v[64:67], v[72:75], v[48:63]
	ds_read_b128 v[64:67], v84 offset:36864
	v_lshlrev_b32_e32 v84, 6, v83
	s_waitcnt lgkmcnt(0)
	v_mfma_f32_32x32x16_bf16 v[0:15], v[64:67], v[68:71], v[0:15]
	v_mfma_f32_32x32x16_bf16 v[16:31], v[64:67], v[72:75], v[16:31]
	ds_read_b128 v[64:67], v86 offset:32768
	ds_read_b128 v[68:71], v88 offset:49152
	ds_read_b128 v[72:75], v88 offset:53248
	s_waitcnt lgkmcnt(1)
	v_mfma_f32_32x32x16_bf16 v[32:47], v[64:67], v[68:71], v[32:47]
	s_waitcnt lgkmcnt(0)
	v_mfma_f32_32x32x16_bf16 v[48:63], v[64:67], v[72:75], v[48:63]
	ds_read_b128 v[64:67], v86 offset:36864
	s_waitcnt lgkmcnt(0)
	v_mfma_f32_32x32x16_bf16 v[0:15], v[64:67], v[68:71], v[0:15]
	v_mfma_f32_32x32x16_bf16 v[16:31], v[64:67], v[72:75], v[16:31]
	ds_read_b128 v[64:67], v89 offset:32768
	ds_read_b128 v[68:71], v90 offset:49152
	ds_read_b128 v[72:75], v90 offset:53248
	ds_read_b128 v[76:79], v89 offset:36864
	s_waitcnt lgkmcnt(2)
	v_mfma_f32_32x32x16_bf16 v[32:47], v[64:67], v[68:71], v[32:47]
	s_waitcnt lgkmcnt(1)
	v_mfma_f32_32x32x16_bf16 v[48:63], v[64:67], v[72:75], v[48:63]
	v_mov_b32_e32 v64, 0x3e000000
	v_cndmask_b32_e32 v66, 1.0, v64, vcc
	v_mov_b32_e32 v64, v201
	s_nop 0
	v_add3_u32 v65, v82, s46, v64
	v_or_b32_e32 v64, v84, v81
	s_waitcnt lgkmcnt(0)
	v_mfma_f32_32x32x16_bf16 v[0:15], v[76:79], v[68:71], v[0:15]
	v_mfma_f32_32x32x16_bf16 v[16:31], v[76:79], v[72:75], v[16:31]
	s_and_saveexec_b64 s[46:47], s[56:57]
	s_xor_b64 s[46:47], exec, s[46:47]
	s_cbranch_execz .LBB0_347
	v_mad_u64_u32 v[64:65], s[48:49], v65, s11, v[64:65]
	v_mov_b32_e32 v65, v201
	v_mul_f32_e32 v32, v66, v32
	v_lshl_add_u64 v[68:69], v[64:65], 1, s[40:41]
	v_or_b32_e32 v200, 32, v64
	v_mul_f32_e32 v48, v66, v48
	v_cvt_pk_bf16_f32 v32, v32, v48
	global_store_short v[68:69], v32, off
	v_lshl_add_u64 v[68:69], v[200:201], 1, s[40:41]
	global_store_short_d16_hi v[68:69], v32, off
	v_mul_f32_e32 v32, v66, v33
	v_mul_f32_e32 v33, v66, v49
	v_add_u32_e32 v200, 0xb00, v64
	v_cvt_pk_bf16_f32 v48, v32, v33
	v_lshl_add_u64 v[32:33], v[200:201], 1, s[40:41]
	v_add_u32_e32 v200, 0xb20, v64
	global_store_short v[32:33], v48, off
	v_lshl_add_u64 v[32:33], v[200:201], 1, s[40:41]
	global_store_short_d16_hi v[32:33], v48, off
	v_mul_f32_e32 v32, v66, v34
	v_mul_f32_e32 v33, v66, v50
	v_add_u32_e32 v200, 0x1600, v64
	v_cvt_pk_bf16_f32 v34, v32, v33
	v_lshl_add_u64 v[32:33], v[200:201], 1, s[40:41]
	v_add_u32_e32 v200, 0x1620, v64
	global_store_short v[32:33], v34, off
	v_lshl_add_u64 v[32:33], v[200:201], 1, s[40:41]
	global_store_short_d16_hi v[32:33], v34, off
	v_mul_f32_e32 v32, v66, v35
	v_mul_f32_e32 v33, v66, v51
	v_add_u32_e32 v200, 0x2100, v64
	v_cvt_pk_bf16_f32 v34, v32, v33
	v_lshl_add_u64 v[32:33], v[200:201], 1, s[40:41]
	v_add_u32_e32 v200, 0x2120, v64
	global_store_short v[32:33], v34, off
	v_lshl_add_u64 v[32:33], v[200:201], 1, s[40:41]
	global_store_short_d16_hi v[32:33], v34, off
	v_mul_f32_e32 v32, v66, v36
	v_mul_f32_e32 v33, v66, v52
	v_add_u32_e32 v200, 0x5800, v64
	v_cvt_pk_bf16_f32 v34, v32, v33
	v_lshl_add_u64 v[32:33], v[200:201], 1, s[40:41]
	v_add_u32_e32 v200, 0x5820, v64
	global_store_short v[32:33], v34, off
	v_lshl_add_u64 v[32:33], v[200:201], 1, s[40:41]
	global_store_short_d16_hi v[32:33], v34, off
	v_mul_f32_e32 v32, v66, v37
	v_mul_f32_e32 v33, v66, v53
	v_add_u32_e32 v200, 0x6300, v64
	v_cvt_pk_bf16_f32 v34, v32, v33
	v_lshl_add_u64 v[32:33], v[200:201], 1, s[40:41]
	v_add_u32_e32 v200, 0x6320, v64
	global_store_short v[32:33], v34, off
	v_lshl_add_u64 v[32:33], v[200:201], 1, s[40:41]
	global_store_short_d16_hi v[32:33], v34, off
	v_mul_f32_e32 v32, v66, v38
	v_mul_f32_e32 v33, v66, v54
	v_add_u32_e32 v200, 0x6e00, v64
	v_cvt_pk_bf16_f32 v34, v32, v33
	v_lshl_add_u64 v[32:33], v[200:201], 1, s[40:41]
	v_add_u32_e32 v200, 0x6e20, v64
	global_store_short v[32:33], v34, off
	v_lshl_add_u64 v[32:33], v[200:201], 1, s[40:41]
	global_store_short_d16_hi v[32:33], v34, off
	v_mul_f32_e32 v32, v66, v39
	v_mul_f32_e32 v33, v66, v55
	v_add_u32_e32 v200, 0x7900, v64
	v_cvt_pk_bf16_f32 v34, v32, v33
	v_lshl_add_u64 v[32:33], v[200:201], 1, s[40:41]
	v_add_u32_e32 v200, 0x7920, v64
	global_store_short v[32:33], v34, off
	v_lshl_add_u64 v[32:33], v[200:201], 1, s[40:41]
	global_store_short_d16_hi v[32:33], v34, off
	v_mul_f32_e32 v32, v66, v40
	v_mul_f32_e32 v33, v66, v56
	v_add_u32_e32 v200, 0xb000, v64
	v_cvt_pk_bf16_f32 v34, v32, v33
	v_lshl_add_u64 v[32:33], v[200:201], 1, s[40:41]
	v_add_u32_e32 v200, 0xb020, v64
; #define SBAR() __builtin_amdgcn_sched_barrier(0)
; __device__ __forceinline__ void phase_z(const P& p, int layer, char* lds) {
;     ...
; #pragma unroll
;       for (int mi = 0; mi < 2; ++mi) {
; #pragma unroll
;         for (int r = 0; r < 16; ++r) {
;           const unsigned row = rb + mi * 32 + (r & 3) + 8 * (r >> 2);
;           const unsigned w = cvtpk(acc[mi][0][r] * sc, acc[mi][1][r] * sc);
;           z[row * ZC + colb + r32] = (u16)w; z[row * ZC + colb + 32 + r32] = (u16)(w >> 16);
;         }
;         SBAR();
;       }
	global_store_short v[32:33], v34, off
	v_lshl_add_u64 v[32:33], v[200:201], 1, s[40:41]
	global_store_short_d16_hi v[32:33], v34, off
	v_mul_f32_e32 v32, v66, v41
	v_mul_f32_e32 v33, v66, v57
	v_add_u32_e32 v200, 0xbb00, v64
	v_cvt_pk_bf16_f32 v34, v32, v33
	v_lshl_add_u64 v[32:33], v[200:201], 1, s[40:41]
	v_add_u32_e32 v200, 0xbb20, v64
	global_store_short v[32:33], v34, off
	v_lshl_add_u64 v[32:33], v[200:201], 1, s[40:41]
	global_store_short_d16_hi v[32:33], v34, off
	v_mul_f32_e32 v32, v66, v42
	v_mul_f32_e32 v33, v66, v58
	v_add_u32_e32 v200, 0xc600, v64
	v_cvt_pk_bf16_f32 v34, v32, v33
	v_lshl_add_u64 v[32:33], v[200:201], 1, s[40:41]
	v_add_u32_e32 v200, 0xc620, v64
	global_store_short v[32:33], v34, off
	v_lshl_add_u64 v[32:33], v[200:201], 1, s[40:41]
	global_store_short_d16_hi v[32:33], v34, off
	v_mul_f32_e32 v32, v66, v43
	v_mul_f32_e32 v33, v66, v59
	v_add_u32_e32 v200, 0xd100, v64
	v_cvt_pk_bf16_f32 v34, v32, v33
	v_lshl_add_u64 v[32:33], v[200:201], 1, s[40:41]
	v_add_u32_e32 v200, 0xd120, v64
	global_store_short v[32:33], v34, off
	v_lshl_add_u64 v[32:33], v[200:201], 1, s[40:41]
	global_store_short_d16_hi v[32:33], v34, off
	v_mul_f32_e32 v32, v66, v44
	v_mul_f32_e32 v33, v66, v60
	v_add_u32_e32 v200, 0x10800, v64
	v_cvt_pk_bf16_f32 v34, v32, v33
	v_lshl_add_u64 v[32:33], v[200:201], 1, s[40:41]
	v_add_u32_e32 v200, 0x10820, v64
	global_store_short v[32:33], v34, off
	v_lshl_add_u64 v[32:33], v[200:201], 1, s[40:41]
	global_store_short_d16_hi v[32:33], v34, off
	v_mul_f32_e32 v32, v66, v45
	v_mul_f32_e32 v33, v66, v61
	v_add_u32_e32 v200, 0x11300, v64
	v_cvt_pk_bf16_f32 v34, v32, v33
	v_lshl_add_u64 v[32:33], v[200:201], 1, s[40:41]
	v_add_u32_e32 v200, 0x11320, v64
	global_store_short v[32:33], v34, off
	v_lshl_add_u64 v[32:33], v[200:201], 1, s[40:41]
	global_store_short_d16_hi v[32:33], v34, off
	v_mul_f32_e32 v32, v66, v46
	v_mul_f32_e32 v33, v66, v62
	v_add_u32_e32 v200, 0x11e00, v64
	v_cvt_pk_bf16_f32 v34, v32, v33
	v_lshl_add_u64 v[32:33], v[200:201], 1, s[40:41]
	v_add_u32_e32 v200, 0x11e20, v64
	global_store_short v[32:33], v34, off
	v_lshl_add_u64 v[32:33], v[200:201], 1, s[40:41]
	global_store_short_d16_hi v[32:33], v34, off
	v_mul_f32_e32 v32, v66, v47
	v_mul_f32_e32 v33, v66, v63
	v_add_u32_e32 v200, 0x12900, v64
	v_cvt_pk_bf16_f32 v34, v32, v33
	v_lshl_add_u64 v[32:33], v[200:201], 1, s[40:41]
	v_add_u32_e32 v200, 0x12920, v64
	global_store_short v[32:33], v34, off
	v_lshl_add_u64 v[32:33], v[200:201], 1, s[40:41]
	global_store_short_d16_hi v[32:33], v34, off
	v_add_u32_e32 v200, 0x16000, v64
	v_mul_f32_e32 v0, v66, v0
	v_lshl_add_u64 v[32:33], v[200:201], 1, s[40:41]
	v_add_u32_e32 v200, 0x16020, v64
	v_mul_f32_e32 v16, v66, v16
	v_cvt_pk_bf16_f32 v0, v0, v16
	global_store_short v[32:33], v0, off
	v_lshl_add_u64 v[32:33], v[200:201], 1, s[40:41]
	global_store_short_d16_hi v[32:33], v0, off
	v_mul_f32_e32 v0, v66, v1
	v_mul_f32_e32 v1, v66, v17
	v_add_u32_e32 v200, 0x16b00, v64
	v_cvt_pk_bf16_f32 v16, v0, v1
	v_lshl_add_u64 v[0:1], v[200:201], 1, s[40:41]
	v_add_u32_e32 v200, 0x16b20, v64
	global_store_short v[0:1], v16, off
	v_lshl_add_u64 v[0:1], v[200:201], 1, s[40:41]
	global_store_short_d16_hi v[0:1], v16, off
	v_mul_f32_e32 v0, v66, v2
	v_mul_f32_e32 v1, v66, v18
	v_add_u32_e32 v200, 0x17600, v64
	v_cvt_pk_bf16_f32 v2, v0, v1
	v_lshl_add_u64 v[0:1], v[200:201], 1, s[40:41]
	v_add_u32_e32 v200, 0x17620, v64
	global_store_short v[0:1], v2, off
	v_lshl_add_u64 v[0:1], v[200:201], 1, s[40:41]
	global_store_short_d16_hi v[0:1], v2, off
	v_mul_f32_e32 v0, v66, v3
	v_mul_f32_e32 v1, v66, v19
	v_add_u32_e32 v200, 0x18100, v64
	v_cvt_pk_bf16_f32 v2, v0, v1
	v_lshl_add_u64 v[0:1], v[200:201], 1, s[40:41]
	v_add_u32_e32 v200, 0x18120, v64
	global_store_short v[0:1], v2, off
	v_lshl_add_u64 v[0:1], v[200:201], 1, s[40:41]
	global_store_short_d16_hi v[0:1], v2, off
	v_mul_f32_e32 v0, v66, v4
; #define SBAR() __builtin_amdgcn_sched_barrier(0)
; __device__ __forceinline__ void phase_z(const P& p, int layer, char* lds) {
;     ...
; #pragma unroll
;       for (int mi = 0; mi < 2; ++mi) {
; #pragma unroll
;         for (int r = 0; r < 16; ++r) {
;           const unsigned row = rb + mi * 32 + (r & 3) + 8 * (r >> 2);
;           const unsigned w = cvtpk(acc[mi][0][r] * sc, acc[mi][1][r] * sc);
;           z[row * ZC + colb + r32] = (u16)w; z[row * ZC + colb + 32 + r32] = (u16)(w >> 16);
;         }
;         SBAR();
;       }
	v_mul_f32_e32 v1, v66, v20
	v_add_u32_e32 v200, 0x1b800, v64
	v_cvt_pk_bf16_f32 v2, v0, v1
	v_lshl_add_u64 v[0:1], v[200:201], 1, s[40:41]
	v_add_u32_e32 v200, 0x1b820, v64
	global_store_short v[0:1], v2, off
	v_lshl_add_u64 v[0:1], v[200:201], 1, s[40:41]
	global_store_short_d16_hi v[0:1], v2, off
	v_mul_f32_e32 v0, v66, v5
	v_mul_f32_e32 v1, v66, v21
	v_add_u32_e32 v200, 0x1c300, v64
	v_cvt_pk_bf16_f32 v2, v0, v1
	v_lshl_add_u64 v[0:1], v[200:201], 1, s[40:41]
	v_add_u32_e32 v200, 0x1c320, v64
	global_store_short v[0:1], v2, off
	v_lshl_add_u64 v[0:1], v[200:201], 1, s[40:41]
	global_store_short_d16_hi v[0:1], v2, off
	v_mul_f32_e32 v0, v66, v6
	v_mul_f32_e32 v1, v66, v22
	v_add_u32_e32 v200, 0x1ce00, v64
	v_cvt_pk_bf16_f32 v2, v0, v1
	v_lshl_add_u64 v[0:1], v[200:201], 1, s[40:41]
	v_add_u32_e32 v200, 0x1ce20, v64
	global_store_short v[0:1], v2, off
	v_lshl_add_u64 v[0:1], v[200:201], 1, s[40:41]
	global_store_short_d16_hi v[0:1], v2, off
	v_mul_f32_e32 v0, v66, v7
	v_mul_f32_e32 v1, v66, v23
	v_add_u32_e32 v200, 0x1d900, v64
	v_cvt_pk_bf16_f32 v2, v0, v1
	v_lshl_add_u64 v[0:1], v[200:201], 1, s[40:41]
	v_add_u32_e32 v200, 0x1d920, v64
	global_store_short v[0:1], v2, off
	v_lshl_add_u64 v[0:1], v[200:201], 1, s[40:41]
	global_store_short_d16_hi v[0:1], v2, off
	v_mul_f32_e32 v0, v66, v8
	v_mul_f32_e32 v1, v66, v24
	v_add_u32_e32 v200, 0x21000, v64
	v_cvt_pk_bf16_f32 v2, v0, v1
	v_lshl_add_u64 v[0:1], v[200:201], 1, s[40:41]
	v_add_u32_e32 v200, 0x21020, v64
	global_store_short v[0:1], v2, off
	v_lshl_add_u64 v[0:1], v[200:201], 1, s[40:41]
	global_store_short_d16_hi v[0:1], v2, off
	v_mul_f32_e32 v0, v66, v9
	v_mul_f32_e32 v1, v66, v25
	v_add_u32_e32 v200, 0x21b00, v64
	v_cvt_pk_bf16_f32 v2, v0, v1
	v_lshl_add_u64 v[0:1], v[200:201], 1, s[40:41]
	v_add_u32_e32 v200, 0x21b20, v64
	global_store_short v[0:1], v2, off
	v_lshl_add_u64 v[0:1], v[200:201], 1, s[40:41]
	global_store_short_d16_hi v[0:1], v2, off
	v_mul_f32_e32 v0, v66, v10
	v_mul_f32_e32 v1, v66, v26
	v_add_u32_e32 v200, 0x22600, v64
	v_cvt_pk_bf16_f32 v2, v0, v1
	v_lshl_add_u64 v[0:1], v[200:201], 1, s[40:41]
	v_add_u32_e32 v200, 0x22620, v64
	global_store_short v[0:1], v2, off
	v_lshl_add_u64 v[0:1], v[200:201], 1, s[40:41]
	global_store_short_d16_hi v[0:1], v2, off
	v_mul_f32_e32 v0, v66, v11
	v_mul_f32_e32 v1, v66, v27
	v_add_u32_e32 v200, 0x23100, v64
	v_cvt_pk_bf16_f32 v2, v0, v1
	v_lshl_add_u64 v[0:1], v[200:201], 1, s[40:41]
	v_add_u32_e32 v200, 0x23120, v64
	global_store_short v[0:1], v2, off
	v_lshl_add_u64 v[0:1], v[200:201], 1, s[40:41]
	global_store_short_d16_hi v[0:1], v2, off
	v_mul_f32_e32 v0, v66, v12
	v_mul_f32_e32 v1, v66, v28
	v_add_u32_e32 v200, 0x26800, v64
	v_cvt_pk_bf16_f32 v2, v0, v1
	v_lshl_add_u64 v[0:1], v[200:201], 1, s[40:41]
	v_add_u32_e32 v200, 0x26820, v64
	global_store_short v[0:1], v2, off
	v_lshl_add_u64 v[0:1], v[200:201], 1, s[40:41]
	global_store_short_d16_hi v[0:1], v2, off
	v_mul_f32_e32 v0, v66, v13
	v_mul_f32_e32 v1, v66, v29
	v_add_u32_e32 v200, 0x27300, v64
	v_cvt_pk_bf16_f32 v2, v0, v1
	v_lshl_add_u64 v[0:1], v[200:201], 1, s[40:41]
	v_add_u32_e32 v200, 0x27320, v64
	global_store_short v[0:1], v2, off
	v_lshl_add_u64 v[0:1], v[200:201], 1, s[40:41]
	global_store_short_d16_hi v[0:1], v2, off
	v_mul_f32_e32 v0, v66, v14
	v_mul_f32_e32 v1, v66, v30
	v_add_u32_e32 v200, 0x27e00, v64
	v_cvt_pk_bf16_f32 v2, v0, v1
	v_lshl_add_u64 v[0:1], v[200:201], 1, s[40:41]
	v_add_u32_e32 v200, 0x27e20, v64
	global_store_short v[0:1], v2, off
	v_lshl_add_u64 v[0:1], v[200:201], 1, s[40:41]
	global_store_short_d16_hi v[0:1], v2, off
	v_mul_f32_e32 v0, v66, v15
	v_mul_f32_e32 v1, v66, v31
	v_add_u32_e32 v200, 0x28900, v64
	v_cvt_pk_bf16_f32 v2, v0, v1
	v_lshl_add_u64 v[0:1], v[200:201], 1, s[40:41]
	v_add_u32_e32 v200, 0x28920, v64
	global_store_short v[0:1], v2, off
	v_lshl_add_u64 v[0:1], v[200:201], 1, s[40:41]
	global_store_short_d16_hi v[0:1], v2, off
